# nt (streaming) hint on the read-once loads of row1, row2 and the phase-0 transposes
# speedup vs baseline: 1.0056x; 1.0056x over previous
; #define TIDX tid_opaque()
; DI void transpose_tile4(const float* src, int lds_, half_t* dst, int ldd, float* tile) {
;   const int tid = TIDX;
;   {
;     const int k0 = tid >> 6, c4 = tid & 63;
;     const float* sp = src + (size_t)k0 * lds_ + c4 * 4;
;     float* tp = tile + (c4 >> 4) * 4352 + k0 * 68 + (c4 & 15) * 4;
; #pragma unroll
;     for (int i = 0; i < 16; i++) *(float4*)(tp + i * 4 * 68) = *(const float4*)(sp + (size_t)i * 4 * lds_);
;   }
;   __syncthreads();
; #pragma unroll
;   for (int i = 0; i < 8; i++) {
;     int idx = i * 256 + tid, j = idx >> 9, r = idx & 511, kc = r >> 6, n = r & 63;
;     const float* t = tile + j * 4352 + kc * 8 * 68 + n;
;     h8 o;
; #pragma unroll
.LBB0_5:
	v_mov_b32_e32 v7, v172
	v_ashrrev_i32_e32 v69, 6, v7
	v_mad_u64_u32 v[8:9], s[28:29], v69, s50, 0
	v_ashrrev_i32_e32 v71, 31, v69
	v_mov_b32_e32 v20, v9
	v_mad_u64_u32 v[92:93], s[28:29], v71, s50, v[20:21]
	v_and_b32_e32 v6, 63, v7
	v_mov_b32_e32 v9, v92
	v_lshl_add_u64 v[92:93], v[8:9], 2, s[48:49]
	v_lshlrev_b32_e32 v20, 4, v6
	v_lshl_add_u64 v[96:97], v[92:93], 0, v[20:21]
	global_load_dwordx4 a[0:3], v[96:97], off nt
	s_mul_i32 s78, s50, 4
	v_lshl_add_u64 v[92:93], s[78:79], 2, v[96:97]
	global_load_dwordx4 a[4:7], v[92:93], off nt
	s_mul_i32 s78, s50, 8
	v_lshl_add_u64 v[92:93], s[78:79], 2, v[96:97]
	global_load_dwordx4 a[8:11], v[92:93], off nt
	s_mul_i32 s78, s50, 12
	v_lshl_add_u64 v[92:93], s[78:79], 2, v[96:97]
	global_load_dwordx4 a[12:15], v[92:93], off nt
	s_mul_i32 s78, s50, 16
	v_lshl_add_u64 v[92:93], s[78:79], 2, v[96:97]
	global_load_dwordx4 a[16:19], v[92:93], off nt
	s_mul_i32 s78, s50, 20
	v_lshl_add_u64 v[92:93], s[78:79], 2, v[96:97]
	global_load_dwordx4 a[20:23], v[92:93], off nt
	s_mul_i32 s78, s50, 24
	v_lshl_add_u64 v[92:93], s[78:79], 2, v[96:97]
	global_load_dwordx4 a[24:27], v[92:93], off nt
	s_mul_i32 s78, s50, 28
	v_lshl_add_u64 v[92:93], s[78:79], 2, v[96:97]
	global_load_dwordx4 a[28:31], v[92:93], off nt
	s_mul_i32 s78, s50, 32
	v_lshl_add_u64 v[92:93], s[78:79], 2, v[96:97]
	global_load_dwordx4 a[32:35], v[92:93], off nt
	s_mul_i32 s78, s50, 36
	v_lshl_add_u64 v[92:93], s[78:79], 2, v[96:97]
	global_load_dwordx4 a[36:39], v[92:93], off nt
	s_mul_i32 s78, s50, 40
	v_lshl_add_u64 v[92:93], s[78:79], 2, v[96:97]
	global_load_dwordx4 a[40:43], v[92:93], off nt
	s_mul_i32 s78, s50, 44
	v_lshl_add_u64 v[92:93], s[78:79], 2, v[96:97]
	global_load_dwordx4 a[44:47], v[92:93], off nt
	s_mul_i32 s78, s50, 48
	v_lshl_add_u64 v[92:93], s[78:79], 2, v[96:97]
	global_load_dwordx4 a[48:51], v[92:93], off nt
	s_mul_i32 s78, s50, 52
	v_lshl_add_u64 v[92:93], s[78:79], 2, v[96:97]
	global_load_dwordx4 a[52:55], v[92:93], off nt
	s_mul_i32 s78, s50, 56
	v_lshl_add_u64 v[92:93], s[78:79], 2, v[96:97]
	global_load_dwordx4 a[56:59], v[92:93], off nt
	s_mul_i32 s78, s50, 60
	v_lshl_add_u64 v[92:93], s[78:79], 2, v[96:97]
	global_load_dwordx4 a[60:63], v[92:93], off nt
	s_movk_i32 s28, 0x110
	v_bfe_u32 v9, v7, 4, 2
	v_mul_lo_u32 v20, v69, s28
	v_lshlrev_b32_e32 v69, 4, v7
	v_mul_u32_u24_e32 v9, 0x4400, v9
	v_and_b32_e32 v69, 0xf0, v69
	v_add3_u32 v9, v9, v20, v69
	v_lshrrev_b32_e32 v69, 3, v7
	v_and_b32_e32 v69, 56, v69
	v_lshlrev_b32_e32 v8, 2, v6
	v_mul_u32_u24_e32 v71, 0x110, v69
	s_waitcnt vmcnt(15)
	ds_write_b128 v9, a[0:3]
	s_waitcnt vmcnt(14)
	ds_write_b128 v9, a[4:7] offset:1088
	s_waitcnt vmcnt(13)
	ds_write_b128 v9, a[8:11] offset:2176
	s_waitcnt vmcnt(12)
	ds_write_b128 v9, a[12:15] offset:3264
	s_waitcnt vmcnt(11)
	ds_write_b128 v9, a[16:19] offset:4352
	s_waitcnt vmcnt(10)
	ds_write_b128 v9, a[20:23] offset:5440
	s_waitcnt vmcnt(9)
	ds_write_b128 v9, a[24:27] offset:6528
	s_waitcnt vmcnt(8)
	ds_write_b128 v9, a[28:31] offset:7616
	s_waitcnt vmcnt(7)
	ds_write_b128 v9, a[32:35] offset:8704
	s_waitcnt vmcnt(6)
	ds_write_b128 v9, a[36:39] offset:9792
	s_waitcnt vmcnt(5)
	ds_write_b128 v9, a[40:43] offset:10880
	s_waitcnt vmcnt(4)
	ds_write_b128 v9, a[44:47] offset:11968
	s_waitcnt vmcnt(3)
	ds_write_b128 v9, a[48:51] offset:13056
	s_waitcnt vmcnt(2)
	ds_write_b128 v9, a[52:55] offset:14144
	s_waitcnt vmcnt(1)
	ds_write_b128 v9, a[56:59] offset:15232
	s_waitcnt vmcnt(0)
	ds_write_b128 v9, a[60:63] offset:16320
	v_ashrrev_i32_e32 v9, 9, v7
	v_mul_i32_i24_e32 v20, 0x4400, v9
	v_add3_u32 v20, v20, v71, v8
	s_waitcnt lgkmcnt(0)
	s_barrier
	ds_read2_b32 v[96:97], v20 offset1:68
	ds_read2_b32 v[92:93], v20 offset0:136 offset1:204
	v_add_u32_e32 v20, 0x400, v20
	ds_read2_b32 v[98:99], v20 offset0:16 offset1:84
	ds_read2_b32 v[94:95], v20 offset0:152 offset1:220
	v_lshl_or_b32 v20, v9, 6, v6
	v_ashrrev_i32_e32 v9, 31, v9
	s_waitcnt lgkmcnt(2)
	v_cvt_pk_f16_f32 v93, v92, v93
	v_cvt_pk_f16_f32 v92, v96, v97
	v_mul_lo_u32 v73, s47, v20
	v_mul_lo_u32 v9, s46, v9
	v_mad_u64_u32 v[96:97], s[28:29], s46, v20, 0
	v_add3_u32 v97, v97, v9, v73
	v_add_u32_e32 v9, 0x100, v7
	v_lshlrev_b32_e32 v20, 1, v69
	v_ashrrev_i32_e32 v69, 9, v9
	v_lshrrev_b32_e32 v9, 3, v9
	v_lshl_add_u64 v[96:97], v[96:97], 1, s[0:1]
	v_and_b32_e32 v9, 56, v9
	s_waitcnt lgkmcnt(0)
	v_cvt_pk_f16_f32 v95, v94, v95
	v_cvt_pk_f16_f32 v94, v98, v99
	v_lshl_add_u64 v[96:97], v[96:97], 0, v[20:21]
	v_mul_i32_i24_e32 v73, 0x4400, v69
	v_mul_u32_u24_e32 v75, 0x110, v9
	global_store_dwordx4 v[96:97], v[92:95], off
	v_add3_u32 v73, v73, v75, v8
	ds_read2_b32 v[96:97], v73 offset1:68
	ds_read2_b32 v[92:93], v73 offset0:136 offset1:204
	v_add_u32_e32 v73, 0x400, v73
	ds_read2_b32 v[98:99], v73 offset0:16 offset1:84
	ds_read2_b32 v[94:95], v73 offset0:152 offset1:220
	v_lshl_or_b32 v73, v69, 6, v6
	v_ashrrev_i32_e32 v69, 31, v69
	s_waitcnt lgkmcnt(2)
	v_cvt_pk_f16_f32 v93, v92, v93
	v_cvt_pk_f16_f32 v92, v96, v97
	v_mul_lo_u32 v75, s47, v73
	v_mul_lo_u32 v69, s46, v69
	v_mad_u64_u32 v[96:97], s[28:29], s46, v73, 0
	s_waitcnt lgkmcnt(0)
; DI void transpose_tile4(const float* src, int lds_, half_t* dst, int ldd, float* tile) {
;     ...
; #pragma unroll
;   for (int i = 0; i < 8; i++) {
;     int idx = i * 256 + tid, j = idx >> 9, r = idx & 511, kc = r >> 6, n = r & 63;
;     const float* t = tile + j * 4352 + kc * 8 * 68 + n;
;     h8 o;
; #pragma unroll
;     for (int u = 0; u < 8; u++) o[u] = (half_t)t[u * 68];
;     *(h8*)(dst + (size_t)(j * 64 + n) * ldd + kc * 8) = o;
;   }
;   __syncthreads();
	v_cvt_pk_f16_f32 v95, v94, v95
	v_cvt_pk_f16_f32 v94, v98, v99
	v_add3_u32 v97, v97, v69, v75
	v_lshlrev_b32_e32 v98, 1, v9
	v_add_u32_e32 v9, 0x200, v7
	v_lshl_add_u64 v[96:97], v[96:97], 1, s[0:1]
	v_mov_b32_e32 v99, v21
	v_ashrrev_i32_e32 v9, 9, v9
	v_lshl_add_u64 v[96:97], v[96:97], 0, v[98:99]
	v_mul_i32_i24_e32 v69, 0x4400, v9
	global_store_dwordx4 v[96:97], v[92:95], off
	v_add3_u32 v69, v69, v71, v8
	ds_read2_b32 v[96:97], v69 offset1:68
	ds_read2_b32 v[92:93], v69 offset0:136 offset1:204
	v_add_u32_e32 v69, 0x400, v69
	ds_read2_b32 v[98:99], v69 offset0:16 offset1:84
	ds_read2_b32 v[94:95], v69 offset0:152 offset1:220
	v_lshl_or_b32 v69, v9, 6, v6
	v_ashrrev_i32_e32 v9, 31, v9
	s_waitcnt lgkmcnt(2)
	v_cvt_pk_f16_f32 v93, v92, v93
	v_cvt_pk_f16_f32 v92, v96, v97
	v_mul_lo_u32 v73, s47, v69
	v_mul_lo_u32 v9, s46, v9
	v_mad_u64_u32 v[96:97], s[28:29], s46, v69, 0
	v_add3_u32 v97, v97, v9, v73
	v_add_u32_e32 v9, 0x300, v7
	v_ashrrev_i32_e32 v69, 9, v9
	v_lshrrev_b32_e32 v9, 3, v9
	v_lshl_add_u64 v[96:97], v[96:97], 1, s[0:1]
	v_and_b32_e32 v9, 56, v9
	s_waitcnt lgkmcnt(0)
	v_cvt_pk_f16_f32 v95, v94, v95
	v_cvt_pk_f16_f32 v94, v98, v99
	v_lshl_add_u64 v[96:97], v[96:97], 0, v[20:21]
	v_mul_i32_i24_e32 v73, 0x4400, v69
	v_mul_u32_u24_e32 v75, 0x110, v9
	global_store_dwordx4 v[96:97], v[92:95], off
	v_add3_u32 v73, v73, v75, v8
	ds_read2_b32 v[96:97], v73 offset1:68
	ds_read2_b32 v[92:93], v73 offset0:136 offset1:204
	v_add_u32_e32 v73, 0x400, v73
	ds_read2_b32 v[98:99], v73 offset0:16 offset1:84
	ds_read2_b32 v[94:95], v73 offset0:152 offset1:220
	v_lshl_or_b32 v73, v69, 6, v6
	v_ashrrev_i32_e32 v69, 31, v69
	s_waitcnt lgkmcnt(2)
	v_cvt_pk_f16_f32 v93, v92, v93
	v_cvt_pk_f16_f32 v92, v96, v97
	v_mul_lo_u32 v75, s47, v73
	v_mul_lo_u32 v69, s46, v69
	v_mad_u64_u32 v[96:97], s[28:29], s46, v73, 0
	s_waitcnt lgkmcnt(0)
	v_cvt_pk_f16_f32 v95, v94, v95
	v_cvt_pk_f16_f32 v94, v98, v99
	v_add3_u32 v97, v97, v69, v75
	v_lshlrev_b32_e32 v98, 1, v9
	v_add_u32_e32 v9, 0x400, v7
	v_lshl_add_u64 v[96:97], v[96:97], 1, s[0:1]
	v_mov_b32_e32 v99, v21
	v_ashrrev_i32_e32 v9, 9, v9
	v_lshl_add_u64 v[96:97], v[96:97], 0, v[98:99]
	v_mul_i32_i24_e32 v69, 0x4400, v9
	global_store_dwordx4 v[96:97], v[92:95], off
	v_add3_u32 v69, v69, v71, v8
	ds_read2_b32 v[96:97], v69 offset1:68
	ds_read2_b32 v[92:93], v69 offset0:136 offset1:204
	v_add_u32_e32 v69, 0x400, v69
	ds_read2_b32 v[98:99], v69 offset0:16 offset1:84
	ds_read2_b32 v[94:95], v69 offset0:152 offset1:220
	v_lshl_or_b32 v69, v9, 6, v6
	v_ashrrev_i32_e32 v9, 31, v9
	s_waitcnt lgkmcnt(2)
	v_cvt_pk_f16_f32 v93, v92, v93
	v_cvt_pk_f16_f32 v92, v96, v97
	v_mul_lo_u32 v73, s47, v69
	v_mul_lo_u32 v9, s46, v9
	v_mad_u64_u32 v[96:97], s[28:29], s46, v69, 0
	v_add3_u32 v97, v97, v9, v73
	v_add_u32_e32 v9, 0x500, v7
	v_ashrrev_i32_e32 v69, 9, v9
	v_lshrrev_b32_e32 v9, 3, v9
	v_lshl_add_u64 v[96:97], v[96:97], 1, s[0:1]
	v_and_b32_e32 v9, 56, v9
	s_waitcnt lgkmcnt(0)
	v_cvt_pk_f16_f32 v95, v94, v95
	v_cvt_pk_f16_f32 v94, v98, v99
	v_lshl_add_u64 v[96:97], v[96:97], 0, v[20:21]
	v_mul_i32_i24_e32 v73, 0x4400, v69
	v_mul_u32_u24_e32 v75, 0x110, v9
	global_store_dwordx4 v[96:97], v[92:95], off
	v_add3_u32 v73, v73, v75, v8
	ds_read2_b32 v[96:97], v73 offset1:68
	ds_read2_b32 v[92:93], v73 offset0:136 offset1:204
	v_add_u32_e32 v73, 0x400, v73
	ds_read2_b32 v[98:99], v73 offset0:16 offset1:84
	ds_read2_b32 v[94:95], v73 offset0:152 offset1:220
	v_lshl_or_b32 v73, v69, 6, v6
	v_ashrrev_i32_e32 v69, 31, v69
	s_waitcnt lgkmcnt(2)
	v_cvt_pk_f16_f32 v93, v92, v93
	v_cvt_pk_f16_f32 v92, v96, v97
	v_mul_lo_u32 v75, s47, v73
	v_mul_lo_u32 v69, s46, v69
	v_mad_u64_u32 v[96:97], s[28:29], s46, v73, 0
	s_waitcnt lgkmcnt(0)
	v_cvt_pk_f16_f32 v95, v94, v95
	v_cvt_pk_f16_f32 v94, v98, v99
	v_add3_u32 v97, v97, v69, v75
	v_lshlrev_b32_e32 v98, 1, v9
	v_add_u32_e32 v9, 0x600, v7
	v_lshl_add_u64 v[96:97], v[96:97], 1, s[0:1]
	v_mov_b32_e32 v99, v21
	v_ashrrev_i32_e32 v9, 9, v9
	v_lshl_add_u64 v[96:97], v[96:97], 0, v[98:99]
	v_mul_i32_i24_e32 v69, 0x4400, v9
	global_store_dwordx4 v[96:97], v[92:95], off
	v_add3_u32 v69, v69, v71, v8
	ds_read2_b32 v[96:97], v69 offset1:68
	ds_read2_b32 v[92:93], v69 offset0:136 offset1:204
	v_add_u32_e32 v69, 0x400, v69
	ds_read2_b32 v[98:99], v69 offset0:16 offset1:84
	ds_read2_b32 v[94:95], v69 offset0:152 offset1:220
	v_lshl_or_b32 v69, v9, 6, v6
	v_ashrrev_i32_e32 v9, 31, v9
	s_waitcnt lgkmcnt(2)
	v_cvt_pk_f16_f32 v93, v92, v93
	v_cvt_pk_f16_f32 v92, v96, v97
	v_mul_lo_u32 v71, s47, v69
	v_mul_lo_u32 v9, s46, v9
	v_mad_u64_u32 v[96:97], s[28:29], s46, v69, 0
	v_add3_u32 v97, v97, v9, v71
	v_lshl_add_u64 v[96:97], v[96:97], 1, s[0:1]
	v_add_u32_e32 v7, 0x700, v7
	v_lshl_add_u64 v[96:97], v[96:97], 0, v[20:21]
	v_ashrrev_i32_e32 v20, 9, v7
	v_lshrrev_b32_e32 v7, 3, v7
	v_and_b32_e32 v69, 56, v7
	s_waitcnt lgkmcnt(0)
	v_cvt_pk_f16_f32 v95, v94, v95
	v_cvt_pk_f16_f32 v94, v98, v99
	v_mul_i32_i24_e32 v9, 0x4400, v20
	v_mul_u32_u24_e32 v7, 0x110, v69
	global_store_dwordx4 v[96:97], v[92:95], off
	v_add3_u32 v7, v9, v7, v8
	ds_read2_b32 v[8:9], v7 offset1:68
	ds_read2_b32 v[92:93], v7 offset0:136 offset1:204
	v_add_u32_e32 v7, 0x400, v7
	ds_read2_b32 v[96:97], v7 offset0:16 offset1:84
	ds_read2_b32 v[94:95], v7 offset0:152 offset1:220
	v_lshl_or_b32 v6, v20, 6, v6
	v_ashrrev_i32_e32 v7, 31, v20
	s_waitcnt lgkmcnt(2)
	v_cvt_pk_f16_f32 v93, v92, v93
	v_cvt_pk_f16_f32 v92, v8, v9
	v_mul_lo_u32 v8, s47, v6
	v_mul_lo_u32 v9, s46, v7
	v_mad_u64_u32 v[6:7], s[28:29], s46, v6, 0
	v_add3_u32 v7, v7, v9, v8
	v_lshl_add_u64 v[6:7], v[6:7], 1, s[0:1]
	v_lshlrev_b32_e32 v20, 1, v69
	s_waitcnt lgkmcnt(0)
	v_cvt_pk_f16_f32 v95, v94, v95
	v_cvt_pk_f16_f32 v94, v96, v97
	v_lshl_add_u64 v[6:7], v[6:7], 0, v[20:21]
	global_store_dwordx4 v[6:7], v[92:95], off
	s_barrier

; DI void row1_phase(const Params& P, int combine_l, int norm_l, int r_begin) {
;     ...
;   auto load_row = [&](int r, float4 (&xv)[4], h4 (&ya)[4], h4 (&yb)[4]) {
;     if (combine_l < 0) {
;       const float* src = r < TC ? P.ctx + (size_t)r * D : P.x + (size_t)(r - TC) * D;
; #pragma unroll
;       for (int i = 0; i < 4; i++) xv[i] = *(const float4*)(src + i * 256 + lane * 4);
;     } else {
;       const float* xm = r < TC ? P.xcbuf + (size_t)r * D : P.out + (size_t)(r - TC) * D;
;       const half_t* y0 = P.yA + (size_t)(2 * r) * D; const half_t* y1 = y0 + D;
; #pragma unroll
;       for (int i = 0; i < 4; i++) { int c = i * 256 + lane * 4; xv[i] = *(const float4*)(xm + c); ya[i] = *(const h4*)(y0 + c); yb[i] = *(const h4*)(y1 + c); }
;     ...
;   const int nrows = TA - r_begin;
;   const int r_lo = r_begin + (int)(((long long)gw * nrows) / nw), r_hi = r_begin + (int)(((long long)(gw + 1) * nrows) / nw);
; #pragma unroll 1
;   for (int r = r_lo; r < r_hi; r += 4) {
;     float4 x0[4], x1[4], x2[4], x3[4]; h4 a0[4], b0[4], a1[4], b1[4], a2[4], b2[4], a3[4], b3[4];
;     const int r1 = r + 1, r2 = r + 2, r3 = r + 3;
;     load_row(r, x0, a0, b0);
;     if (r1 < r_hi) load_row(r1, x1, a1, b1);
;     if (r2 < r_hi) load_row(r2, x2, a2, b2);
;     if (r3 < r_hi) load_row(r3, x3, a3, b3);
.LBB0_151:
	s_cmp_eq_u32 s2, 0
	s_cbranch_scc1 .Lr1_modeA
	v_lshrrev_b32_e32 v152, 6, v172
	v_and_b32_e32 v153, 63, v172
	v_readfirstlane_b32 s5, v152
	v_readlane_b32 s4, v253, 0
	v_lshlrev_b32_e32 v150, 4, v153
	v_lshlrev_b32_e32 v151, 3, v153
	v_lshlrev_b32_e32 v159, 2, v153
	s_nop 2
	s_lshl_b32 s4, s4, 2
	s_add_u32 s4, s4, s5
	s_mul_i32 s5, s4, 66
	s_add_u32 s6, s5, 66
	s_add_u32 s52, s90, 0x28cbc700
	s_addc_u32 s53, s91, 0
	s_add_u32 s54, s90, 0xf8bc700
	s_addc_u32 s55, s91, 0
	s_add_u32 s56, s90, 0xce00000
	s_addc_u32 s57, s91, 0
	s_add_u32 s48, s90, 0xf05c700
	s_addc_u32 s49, s91, 0
	v_readlane_b32 s50, v253, 49
	v_readlane_b32 s51, v253, 50
	v_readlane_b32 s58, v255, 15
	v_readlane_b32 s59, v255, 16
	s_nop 3
	s_sub_u32 s50, s50, 0x800000
	s_subb_u32 s51, s51, 0
	s_add_u32 s58, s58, 0x1000
	s_addc_u32 s59, s59, 0
	s_mov_b32 s8, -1
	s_mov_b32 s7, s5
	s_cmp_lt_u32 s7, 0x800
	s_cselect_b64 s[60:61], s[48:49], s[50:51]
	s_lshl_b32 s10, s7, 12
	s_add_u32 s60, s60, s10
	s_addc_u32 s61, s61, 0
	global_load_dwordx4 a[0:3], v150, s[60:61] offset:0 nt
	global_load_dwordx4 a[4:7], v150, s[60:61] offset:1024 nt
	global_load_dwordx4 a[8:11], v150, s[60:61] offset:2048 nt
	global_load_dwordx4 a[12:15], v150, s[60:61] offset:3072 nt
	s_add_u32 s62, s52, s10
	s_addc_u32 s63, s53, 0
	global_load_dwordx2 a[16:17], v151, s[62:63] offset:0 nt
	global_load_dwordx2 a[18:19], v151, s[62:63] offset:512 nt
	global_load_dwordx2 a[20:21], v151, s[62:63] offset:1024 nt
	global_load_dwordx2 a[22:23], v151, s[62:63] offset:1536 nt
	global_load_dwordx2 a[24:25], v151, s[62:63] offset:2048 nt
	global_load_dwordx2 a[26:27], v151, s[62:63] offset:2560 nt
	global_load_dwordx2 a[28:29], v151, s[62:63] offset:3072 nt
	global_load_dwordx2 a[30:31], v151, s[62:63] offset:3584 nt
	s_add_u32 s7, s7, 1
	s_cmp_lt_u32 s7, 0x800
	s_cselect_b64 s[60:61], s[48:49], s[50:51]
	s_lshl_b32 s10, s7, 12
	s_add_u32 s60, s60, s10
	s_addc_u32 s61, s61, 0
	global_load_dwordx4 a[32:35], v150, s[60:61] offset:0 nt
	global_load_dwordx4 a[36:39], v150, s[60:61] offset:1024 nt
	global_load_dwordx4 a[40:43], v150, s[60:61] offset:2048 nt
	global_load_dwordx4 a[44:47], v150, s[60:61] offset:3072 nt
	s_add_u32 s62, s52, s10
	s_addc_u32 s63, s53, 0
	global_load_dwordx2 a[48:49], v151, s[62:63] offset:0 nt
	global_load_dwordx2 a[50:51], v151, s[62:63] offset:512 nt
	global_load_dwordx2 a[52:53], v151, s[62:63] offset:1024 nt
	global_load_dwordx2 a[54:55], v151, s[62:63] offset:1536 nt
	global_load_dwordx2 a[56:57], v151, s[62:63] offset:2048 nt
	global_load_dwordx2 a[58:59], v151, s[62:63] offset:2560 nt
	global_load_dwordx2 a[60:61], v151, s[62:63] offset:3072 nt
	global_load_dwordx2 a[62:63], v151, s[62:63] offset:3584 nt
	s_add_u32 s7, s7, 1
	s_cmp_lt_u32 s7, 0x800
	s_cselect_b64 s[60:61], s[48:49], s[50:51]
	s_lshl_b32 s10, s7, 12
	s_add_u32 s60, s60, s10
	s_addc_u32 s61, s61, 0
	global_load_dwordx4 a[64:67], v150, s[60:61] offset:0 nt
	global_load_dwordx4 a[68:71], v150, s[60:61] offset:1024 nt
	global_load_dwordx4 a[72:75], v150, s[60:61] offset:2048 nt
	global_load_dwordx4 a[76:79], v150, s[60:61] offset:3072 nt
	s_add_u32 s62, s52, s10
	s_addc_u32 s63, s53, 0
	global_load_dwordx2 a[80:81], v151, s[62:63] offset:0 nt
	global_load_dwordx2 a[82:83], v151, s[62:63] offset:512 nt
	global_load_dwordx2 a[84:85], v151, s[62:63] offset:1024 nt
	global_load_dwordx2 a[86:87], v151, s[62:63] offset:1536 nt
	global_load_dwordx2 a[88:89], v151, s[62:63] offset:2048 nt
	global_load_dwordx2 a[90:91], v151, s[62:63] offset:2560 nt
	global_load_dwordx2 a[92:93], v151, s[62:63] offset:3072 nt
	global_load_dwordx2 a[94:95], v151, s[62:63] offset:3584 nt
	s_add_u32 s7, s7, 1
	s_cmp_lt_u32 s7, 0x800
	s_cselect_b64 s[60:61], s[48:49], s[50:51]
	s_lshl_b32 s10, s7, 12
	s_add_u32 s60, s60, s10
	s_addc_u32 s61, s61, 0
	global_load_dwordx4 a[96:99], v150, s[60:61] offset:0 nt
	global_load_dwordx4 a[100:103], v150, s[60:61] offset:1024 nt
	global_load_dwordx4 a[104:107], v150, s[60:61] offset:2048 nt
	global_load_dwordx4 a[108:111], v150, s[60:61] offset:3072 nt
	s_add_u32 s62, s52, s10
	s_addc_u32 s63, s53, 0
	global_load_dwordx2 a[112:113], v151, s[62:63] offset:0 nt
	global_load_dwordx2 a[114:115], v151, s[62:63] offset:512 nt
	global_load_dwordx2 a[116:117], v151, s[62:63] offset:1024 nt
	global_load_dwordx2 a[118:119], v151, s[62:63] offset:1536 nt
	global_load_dwordx2 a[120:121], v151, s[62:63] offset:2048 nt
	global_load_dwordx2 a[122:123], v151, s[62:63] offset:2560 nt
	global_load_dwordx2 a[124:125], v151, s[62:63] offset:3072 nt
	global_load_dwordx2 a[126:127], v151, s[62:63] offset:3584 nt
	s_add_u32 s7, s7, 1
	s_mov_b32 s98, 15

; DI void row1_phase(const Params& P, int combine_l, int norm_l, int r_begin) {
;     ...
;       for (int i = 0; i < 4; i++) { int c = i * 256 + lane * 4; xv[i] = *(const float4*)(xm + c); ya[i] = *(const h4*)(y0 + c); yb[i] = *(const h4*)(y1 + c); }
;     }
;   };
;   auto process = [&](int r, float4 (&xv)[4], h4 (&ya)[4], h4 (&yb)[4]) {
;     const int n = row_mod(r);
;     if (combine_l >= 0) {
;       float* xm = r < TC ? P.xcbuf + (size_t)r * D : P.out + (size_t)(r - TC) * D;
;       const float* g2 = P.mod + (size_t)(combine_l * 9 + n) * 6144 + 5 * 1024;
; #pragma unroll
;       for (int i = 0; i < 4; i++) {
;         int c = i * 256 + lane * 4;
;         float4 g = *(const float4*)(g2 + c); float4 t = xv[i];
;         t.x += g.x * ((float)ya[i][0] + (float)yb[i][0]); t.y += g.y * ((float)ya[i][1] + (float)yb[i][1]);
;         t.z += g.z * ((float)ya[i][2] + (float)yb[i][2]); t.w += g.w * ((float)ya[i][3] + (float)yb[i][3]);
;         *(float4*)(xm + c) = t; xv[i] = t;
;       }
;     }
;     if (norm_l >= 0) {
;       float ss = 0.f;
; #pragma unroll
;       for (int i = 0; i < 4; i++) ss += xv[i].x * xv[i].x + xv[i].y * xv[i].y + xv[i].z * xv[i].z + xv[i].w * xv[i].w;
;       ss = wave_sum(ss);
.Lr1b_nr1:
	s_waitcnt vmcnt(44)
	v_accvgpr_read_b32 v54, a0
	v_accvgpr_read_b32 v55, a1
	v_accvgpr_read_b32 v56, a2
	v_accvgpr_read_b32 v57, a3
	v_accvgpr_read_b32 v58, a4
	v_accvgpr_read_b32 v59, a5
	v_accvgpr_read_b32 v60, a6
	v_accvgpr_read_b32 v61, a7
	v_accvgpr_read_b32 v62, a8
	v_accvgpr_read_b32 v63, a9
	v_accvgpr_read_b32 v64, a10
	v_accvgpr_read_b32 v65, a11
	v_accvgpr_read_b32 v66, a12
	v_accvgpr_read_b32 v67, a13
	v_accvgpr_read_b32 v68, a14
	v_accvgpr_read_b32 v69, a15
	v_accvgpr_read_b32 v70, a16
	v_accvgpr_read_b32 v71, a17
	v_accvgpr_read_b32 v72, a18
	v_accvgpr_read_b32 v73, a19
	v_accvgpr_read_b32 v74, a20
	v_accvgpr_read_b32 v75, a21
	v_accvgpr_read_b32 v76, a22
	v_accvgpr_read_b32 v77, a23
	v_accvgpr_read_b32 v78, a24
	v_accvgpr_read_b32 v79, a25
	v_accvgpr_read_b32 v80, a26
	v_accvgpr_read_b32 v81, a27
	v_accvgpr_read_b32 v82, a28
	v_accvgpr_read_b32 v83, a29
	v_accvgpr_read_b32 v84, a30
	v_accvgpr_read_b32 v85, a31
	s_lshl_b32 s10, s5, 12
	s_cmp_lt_u32 s5, 0x800
	s_cselect_b64 s[34:35], s[48:49], s[50:51]
	s_add_u32 s34, s34, s10
	s_addc_u32 s35, s35, 0
	s_lshr_b32 s10, s10, 1
	s_add_u32 s36, s54, s10
	s_addc_u32 s37, s55, 0
	s_cmp_lt_u32 s7, 0x800
	s_cselect_b64 s[60:61], s[48:49], s[50:51]
	s_lshl_b32 s10, s7, 12
	s_add_u32 s60, s60, s10
	s_addc_u32 s61, s61, 0
	global_load_dwordx4 a[0:3], v150, s[60:61] offset:0 nt
	global_load_dwordx4 a[4:7], v150, s[60:61] offset:1024 nt
	global_load_dwordx4 a[8:11], v150, s[60:61] offset:2048 nt
	global_load_dwordx4 a[12:15], v150, s[60:61] offset:3072 nt
	s_add_u32 s62, s52, s10
	s_addc_u32 s63, s53, 0
	global_load_dwordx2 a[16:17], v151, s[62:63] offset:0 nt
	global_load_dwordx2 a[18:19], v151, s[62:63] offset:512 nt
	global_load_dwordx2 a[20:21], v151, s[62:63] offset:1024 nt
	global_load_dwordx2 a[22:23], v151, s[62:63] offset:1536 nt
	global_load_dwordx2 a[24:25], v151, s[62:63] offset:2048 nt
	global_load_dwordx2 a[26:27], v151, s[62:63] offset:2560 nt
	global_load_dwordx2 a[28:29], v151, s[62:63] offset:3072 nt
	global_load_dwordx2 a[30:31], v151, s[62:63] offset:3584 nt
	s_add_u32 s7, s7, 1
	v_cvt_f32_f16_e32 v154, v70
	v_cvt_f32_f16_e32 v155, v78
	v_add_f32_e32 v154, v154, v155
	v_fmac_f32_e32 v54, v32, v154
	v_cvt_f32_f16_sdwa v156, v70 dst_sel:DWORD dst_unused:UNUSED_PAD src0_sel:WORD_1
	v_cvt_f32_f16_sdwa v157, v78 dst_sel:DWORD dst_unused:UNUSED_PAD src0_sel:WORD_1
	v_add_f32_e32 v156, v156, v157
	v_fmac_f32_e32 v55, v33, v156
	v_cvt_f32_f16_e32 v154, v71
	v_cvt_f32_f16_e32 v155, v79
	v_add_f32_e32 v154, v154, v155
	v_fmac_f32_e32 v56, v34, v154
	v_cvt_f32_f16_sdwa v156, v71 dst_sel:DWORD dst_unused:UNUSED_PAD src0_sel:WORD_1
	v_cvt_f32_f16_sdwa v157, v79 dst_sel:DWORD dst_unused:UNUSED_PAD src0_sel:WORD_1
	v_add_f32_e32 v156, v156, v157
	v_fmac_f32_e32 v57, v35, v156
	v_cvt_f32_f16_e32 v154, v72
	v_cvt_f32_f16_e32 v155, v80
	v_add_f32_e32 v154, v154, v155
	v_fmac_f32_e32 v58, v36, v154
	v_cvt_f32_f16_sdwa v156, v72 dst_sel:DWORD dst_unused:UNUSED_PAD src0_sel:WORD_1
	v_cvt_f32_f16_sdwa v157, v80 dst_sel:DWORD dst_unused:UNUSED_PAD src0_sel:WORD_1
	v_add_f32_e32 v156, v156, v157
	v_fmac_f32_e32 v59, v37, v156
	v_cvt_f32_f16_e32 v154, v73
	v_cvt_f32_f16_e32 v155, v81
	v_add_f32_e32 v154, v154, v155
	v_fmac_f32_e32 v60, v38, v154
	v_cvt_f32_f16_sdwa v156, v73 dst_sel:DWORD dst_unused:UNUSED_PAD src0_sel:WORD_1
	v_cvt_f32_f16_sdwa v157, v81 dst_sel:DWORD dst_unused:UNUSED_PAD src0_sel:WORD_1
	v_add_f32_e32 v156, v156, v157
	v_fmac_f32_e32 v61, v39, v156
	v_cvt_f32_f16_e32 v154, v74
	v_cvt_f32_f16_e32 v155, v82
	v_add_f32_e32 v154, v154, v155
	v_fmac_f32_e32 v62, v40, v154
	v_cvt_f32_f16_sdwa v156, v74 dst_sel:DWORD dst_unused:UNUSED_PAD src0_sel:WORD_1
	v_cvt_f32_f16_sdwa v157, v82 dst_sel:DWORD dst_unused:UNUSED_PAD src0_sel:WORD_1
	v_add_f32_e32 v156, v156, v157
	v_fmac_f32_e32 v63, v41, v156
	v_cvt_f32_f16_e32 v154, v75
	v_cvt_f32_f16_e32 v155, v83
	v_add_f32_e32 v154, v154, v155
	v_fmac_f32_e32 v64, v42, v154
	v_cvt_f32_f16_sdwa v156, v75 dst_sel:DWORD dst_unused:UNUSED_PAD src0_sel:WORD_1
	v_cvt_f32_f16_sdwa v157, v83 dst_sel:DWORD dst_unused:UNUSED_PAD src0_sel:WORD_1
	v_add_f32_e32 v156, v156, v157
	v_fmac_f32_e32 v65, v43, v156
	v_cvt_f32_f16_e32 v154, v76
	v_cvt_f32_f16_e32 v155, v84
	v_add_f32_e32 v154, v154, v155
	v_fmac_f32_e32 v66, v44, v154
	v_cvt_f32_f16_sdwa v156, v76 dst_sel:DWORD dst_unused:UNUSED_PAD src0_sel:WORD_1
	v_cvt_f32_f16_sdwa v157, v84 dst_sel:DWORD dst_unused:UNUSED_PAD src0_sel:WORD_1
	v_add_f32_e32 v156, v156, v157
	v_fmac_f32_e32 v67, v45, v156
	v_cvt_f32_f16_e32 v154, v77
	v_cvt_f32_f16_e32 v155, v85
	v_add_f32_e32 v154, v154, v155
	v_fmac_f32_e32 v68, v46, v154
	v_cvt_f32_f16_sdwa v156, v77 dst_sel:DWORD dst_unused:UNUSED_PAD src0_sel:WORD_1
	v_cvt_f32_f16_sdwa v157, v85 dst_sel:DWORD dst_unused:UNUSED_PAD src0_sel:WORD_1
	v_add_f32_e32 v156, v156, v157
	v_fmac_f32_e32 v69, v47, v156
	global_store_dwordx4 v150, v[54:57], s[34:35] offset:0
	global_store_dwordx4 v150, v[58:61], s[34:35] offset:1024
	global_store_dwordx4 v150, v[62:65], s[34:35] offset:2048
	global_store_dwordx4 v150, v[66:69], s[34:35] offset:3072
	v_mul_f32_e32 v152, v54, v54
	v_mul_f32_e32 v153, v55, v55
	v_fmac_f32_e32 v152, v56, v56
	v_fmac_f32_e32 v153, v57, v57
	v_fmac_f32_e32 v152, v58, v58
	v_fmac_f32_e32 v153, v59, v59
	v_fmac_f32_e32 v152, v60, v60
	v_fmac_f32_e32 v153, v61, v61
	v_fmac_f32_e32 v152, v62, v62
	v_fmac_f32_e32 v153, v63, v63
	v_fmac_f32_e32 v152, v64, v64
	v_fmac_f32_e32 v153, v65, v65
	v_fmac_f32_e32 v152, v66, v66
	v_fmac_f32_e32 v153, v67, v67
	v_fmac_f32_e32 v152, v68, v68
	v_fmac_f32_e32 v153, v69, v69
	v_add_f32_e32 v152, v152, v153
	v_xor_b32_e32 v158, 128, v159
	ds_bpermute_b32 v153, v158, v152
	s_waitcnt lgkmcnt(0)
; DI void row1_phase(const Params& P, int combine_l, int norm_l, int r_begin) {
;     ...
;     if (combine_l >= 0) {
;       float* xm = r < TC ? P.xcbuf + (size_t)r * D : P.out + (size_t)(r - TC) * D;
;       const float* g2 = P.mod + (size_t)(combine_l * 9 + n) * 6144 + 5 * 1024;
;     ...
;       ss = wave_sum(ss);
;       const float rstd = rsqrtf(ss * (1.f / 1024.f) + EPS);
;       const float* g = P.norm1_g + norm_l * 1024;
;       const float* sh = P.mod + (size_t)(norm_l * 9 + n) * 6144; const float* sc = sh + 1024;
; #pragma unroll
;       for (int i = 0; i < 4; i++) {
;         int c = i * 256 + lane * 4;
;         float4 gg = *(const float4*)(g + c), s1 = *(const float4*)(sc + c), s0 = *(const float4*)(sh + c);
;         h4 o;
;         o[0] = (half_t)(xv[i].x * rstd * gg.x * (1.f + s1.x) + s0.x); o[1] = (half_t)(xv[i].y * rstd * gg.y * (1.f + s1.y) + s0.y);
;         o[2] = (half_t)(xv[i].z * rstd * gg.z * (1.f + s1.z) + s0.z); o[3] = (half_t)(xv[i].w * rstd * gg.w * (1.f + s1.w) + s0.w);
;         *(h4*)(P.hx + (size_t)r * D + c) = o;
;       }
;     }
	v_add_f32_e32 v152, v152, v153
	v_xor_b32_e32 v158, 64, v159
	ds_bpermute_b32 v153, v158, v152
	s_waitcnt lgkmcnt(0)
	v_add_f32_e32 v152, v152, v153
	v_xor_b32_e32 v158, 32, v159
	ds_bpermute_b32 v153, v158, v152
	s_waitcnt lgkmcnt(0)
	v_add_f32_e32 v152, v152, v153
	v_xor_b32_e32 v158, 16, v159
	ds_bpermute_b32 v153, v158, v152
	s_waitcnt lgkmcnt(0)
	v_add_f32_e32 v152, v152, v153
	v_xor_b32_e32 v158, 8, v159
	ds_bpermute_b32 v153, v158, v152
	s_waitcnt lgkmcnt(0)
	v_add_f32_e32 v152, v152, v153
	v_xor_b32_e32 v158, 4, v159
	ds_bpermute_b32 v153, v158, v152
	s_waitcnt lgkmcnt(0)
	v_add_f32_e32 v152, v152, v153
	v_mov_b32_e32 v153, 0x358637bd
	v_fmamk_f32 v152, v152, 0x3a800000, v153
	v_rsq_f32_e32 v152, v152
	s_nop 1
	v_mul_f32_e32 v54, v54, v152
	v_mul_f32_e32 v55, v55, v152
	v_mul_f32_e32 v56, v56, v152
	v_mul_f32_e32 v57, v57, v152
	v_mul_f32_e32 v58, v58, v152
	v_mul_f32_e32 v59, v59, v152
	v_mul_f32_e32 v60, v60, v152
	v_mul_f32_e32 v61, v61, v152
	v_mul_f32_e32 v62, v62, v152
	v_mul_f32_e32 v63, v63, v152
	v_mul_f32_e32 v64, v64, v152
	v_mul_f32_e32 v65, v65, v152
	v_mul_f32_e32 v66, v66, v152
	v_mul_f32_e32 v67, v67, v152
	v_mul_f32_e32 v68, v68, v152
	v_mul_f32_e32 v69, v69, v152
	v_fma_f32 v54, v54, v0, v16
	v_fma_f32 v55, v55, v1, v17
	v_fma_f32 v56, v56, v2, v18
	v_fma_f32 v57, v57, v3, v19
	v_fma_f32 v58, v58, v4, v20
	v_fma_f32 v59, v59, v5, v21
	v_fma_f32 v60, v60, v6, v22
	v_fma_f32 v61, v61, v7, v23
	v_fma_f32 v62, v62, v8, v24
	v_fma_f32 v63, v63, v9, v25
	v_fma_f32 v64, v64, v10, v26
	v_fma_f32 v65, v65, v11, v27
	v_fma_f32 v66, v66, v12, v28
	v_fma_f32 v67, v67, v13, v29
	v_fma_f32 v68, v68, v14, v30
	v_fma_f32 v69, v69, v15, v31
	v_cvt_pk_f16_f32 v70, v54, v55
	v_cvt_pk_f16_f32 v71, v56, v57
	v_cvt_pk_f16_f32 v72, v58, v59
	v_cvt_pk_f16_f32 v73, v60, v61
	v_cvt_pk_f16_f32 v74, v62, v63
	v_cvt_pk_f16_f32 v75, v64, v65
	v_cvt_pk_f16_f32 v76, v66, v67
	v_cvt_pk_f16_f32 v77, v68, v69
	global_store_dwordx2 v151, v[70:71], s[36:37] offset:0
	global_store_dwordx2 v151, v[72:73], s[36:37] offset:512
	global_store_dwordx2 v151, v[74:75], s[36:37] offset:1024
	global_store_dwordx2 v151, v[76:77], s[36:37] offset:1536
	s_add_u32 s5, s5, 1
	s_sub_u32 s9, s5, 0x800
	s_lshr_b32 s9, s9, 13
	s_cmp_lt_u32 s5, 0x800
	s_cselect_b32 s9, 8, s9
	s_cmp_eq_u32 s9, s8
	s_cbranch_scc1 .Lr1b_nr2
	s_mov_b32 s8, s9
	s_waitcnt vmcnt(0)
	s_add_u32 s10, s9, 9
	s_mul_i32 s10, s10, 0x6000
	s_add_u32 s38, s56, s10
	s_addc_u32 s39, s57, 0
	global_load_dwordx4 v[54:57], v150, s[58:59] offset:0
	global_load_dwordx4 v[58:61], v150, s[58:59] offset:1024
	global_load_dwordx4 v[62:65], v150, s[58:59] offset:2048
	global_load_dwordx4 v[66:69], v150, s[58:59] offset:3072
	s_add_u32 s44, s38, 0x1000
	s_addc_u32 s45, s39, 0
	global_load_dwordx4 v[70:73], v150, s[44:45] offset:0
	global_load_dwordx4 v[74:77], v150, s[44:45] offset:1024
	global_load_dwordx4 v[78:81], v150, s[44:45] offset:2048
	global_load_dwordx4 v[82:85], v150, s[44:45] offset:3072
	global_load_dwordx4 v[16:19], v150, s[38:39] offset:0
	global_load_dwordx4 v[20:23], v150, s[38:39] offset:1024
	global_load_dwordx4 v[24:27], v150, s[38:39] offset:2048
	global_load_dwordx4 v[28:31], v150, s[38:39] offset:3072
	s_add_u32 s10, s9, 0
	s_mul_i32 s10, s10, 0x6000
	s_add_u32 s10, s10, 0x5000
	s_add_u32 s38, s56, s10
	s_addc_u32 s39, s57, 0
	global_load_dwordx4 v[32:35], v150, s[38:39] offset:0
	global_load_dwordx4 v[36:39], v150, s[38:39] offset:1024
	global_load_dwordx4 v[40:43], v150, s[38:39] offset:2048
	global_load_dwordx4 v[44:47], v150, s[38:39] offset:3072
	s_waitcnt vmcnt(0)
	v_add_f32_e32 v70, 1.0, v70
	v_add_f32_e32 v71, 1.0, v71
	v_add_f32_e32 v72, 1.0, v72
	v_add_f32_e32 v73, 1.0, v73
	v_add_f32_e32 v74, 1.0, v74
	v_add_f32_e32 v75, 1.0, v75
	v_add_f32_e32 v76, 1.0, v76
	v_add_f32_e32 v77, 1.0, v77
	v_add_f32_e32 v78, 1.0, v78
	v_add_f32_e32 v79, 1.0, v79
	v_add_f32_e32 v80, 1.0, v80
	v_add_f32_e32 v81, 1.0, v81
	v_add_f32_e32 v82, 1.0, v82
	v_add_f32_e32 v83, 1.0, v83
	v_add_f32_e32 v84, 1.0, v84
	v_add_f32_e32 v85, 1.0, v85
	v_mul_f32_e32 v0, v54, v70
	v_mul_f32_e32 v1, v55, v71
	v_mul_f32_e32 v2, v56, v72
	v_mul_f32_e32 v3, v57, v73
	v_mul_f32_e32 v4, v58, v74
	v_mul_f32_e32 v5, v59, v75
	v_mul_f32_e32 v6, v60, v76
	v_mul_f32_e32 v7, v61, v77
	v_mul_f32_e32 v8, v62, v78
	v_mul_f32_e32 v9, v63, v79
	v_mul_f32_e32 v10, v64, v80
	v_mul_f32_e32 v11, v65, v81
	v_mul_f32_e32 v12, v66, v82
	v_mul_f32_e32 v13, v67, v83
	v_mul_f32_e32 v14, v68, v84
	v_mul_f32_e32 v15, v69, v85
; DI void row1_phase(const Params& P, int combine_l, int norm_l, int r_begin) {
;     ...
;       for (int i = 0; i < 4; i++) { int c = i * 256 + lane * 4; xv[i] = *(const float4*)(xm + c); ya[i] = *(const h4*)(y0 + c); yb[i] = *(const h4*)(y1 + c); }
;     }
;   };
;   auto process = [&](int r, float4 (&xv)[4], h4 (&ya)[4], h4 (&yb)[4]) {
;     const int n = row_mod(r);
;     if (combine_l >= 0) {
;       float* xm = r < TC ? P.xcbuf + (size_t)r * D : P.out + (size_t)(r - TC) * D;
;       const float* g2 = P.mod + (size_t)(combine_l * 9 + n) * 6144 + 5 * 1024;
; #pragma unroll
;       for (int i = 0; i < 4; i++) {
;         int c = i * 256 + lane * 4;
;         float4 g = *(const float4*)(g2 + c); float4 t = xv[i];
;         t.x += g.x * ((float)ya[i][0] + (float)yb[i][0]); t.y += g.y * ((float)ya[i][1] + (float)yb[i][1]);
;         t.z += g.z * ((float)ya[i][2] + (float)yb[i][2]); t.w += g.w * ((float)ya[i][3] + (float)yb[i][3]);
;         *(float4*)(xm + c) = t; xv[i] = t;
;       }
;     }
;     if (norm_l >= 0) {
;       float ss = 0.f;
; #pragma unroll
;       for (int i = 0; i < 4; i++) ss += xv[i].x * xv[i].x + xv[i].y * xv[i].y + xv[i].z * xv[i].z + xv[i].w * xv[i].w;
;       ss = wave_sum(ss);
.Lr1b_nr2:
	s_waitcnt vmcnt(44)
	v_accvgpr_read_b32 v54, a32
	v_accvgpr_read_b32 v55, a33
	v_accvgpr_read_b32 v56, a34
	v_accvgpr_read_b32 v57, a35
	v_accvgpr_read_b32 v58, a36
	v_accvgpr_read_b32 v59, a37
	v_accvgpr_read_b32 v60, a38
	v_accvgpr_read_b32 v61, a39
	v_accvgpr_read_b32 v62, a40
	v_accvgpr_read_b32 v63, a41
	v_accvgpr_read_b32 v64, a42
	v_accvgpr_read_b32 v65, a43
	v_accvgpr_read_b32 v66, a44
	v_accvgpr_read_b32 v67, a45
	v_accvgpr_read_b32 v68, a46
	v_accvgpr_read_b32 v69, a47
	v_accvgpr_read_b32 v70, a48
	v_accvgpr_read_b32 v71, a49
	v_accvgpr_read_b32 v72, a50
	v_accvgpr_read_b32 v73, a51
	v_accvgpr_read_b32 v74, a52
	v_accvgpr_read_b32 v75, a53
	v_accvgpr_read_b32 v76, a54
	v_accvgpr_read_b32 v77, a55
	v_accvgpr_read_b32 v78, a56
	v_accvgpr_read_b32 v79, a57
	v_accvgpr_read_b32 v80, a58
	v_accvgpr_read_b32 v81, a59
	v_accvgpr_read_b32 v82, a60
	v_accvgpr_read_b32 v83, a61
	v_accvgpr_read_b32 v84, a62
	v_accvgpr_read_b32 v85, a63
	s_lshl_b32 s10, s5, 12
	s_cmp_lt_u32 s5, 0x800
	s_cselect_b64 s[34:35], s[48:49], s[50:51]
	s_add_u32 s34, s34, s10
	s_addc_u32 s35, s35, 0
	s_lshr_b32 s10, s10, 1
	s_add_u32 s36, s54, s10
	s_addc_u32 s37, s55, 0
	s_cmp_lt_u32 s7, 0x800
	s_cselect_b64 s[60:61], s[48:49], s[50:51]
	s_lshl_b32 s10, s7, 12
	s_add_u32 s60, s60, s10
	s_addc_u32 s61, s61, 0
	global_load_dwordx4 a[32:35], v150, s[60:61] offset:0 nt
	global_load_dwordx4 a[36:39], v150, s[60:61] offset:1024 nt
	global_load_dwordx4 a[40:43], v150, s[60:61] offset:2048 nt
	global_load_dwordx4 a[44:47], v150, s[60:61] offset:3072 nt
	s_add_u32 s62, s52, s10
	s_addc_u32 s63, s53, 0
	global_load_dwordx2 a[48:49], v151, s[62:63] offset:0 nt
	global_load_dwordx2 a[50:51], v151, s[62:63] offset:512 nt
	global_load_dwordx2 a[52:53], v151, s[62:63] offset:1024 nt
	global_load_dwordx2 a[54:55], v151, s[62:63] offset:1536 nt
	global_load_dwordx2 a[56:57], v151, s[62:63] offset:2048 nt
	global_load_dwordx2 a[58:59], v151, s[62:63] offset:2560 nt
	global_load_dwordx2 a[60:61], v151, s[62:63] offset:3072 nt
	global_load_dwordx2 a[62:63], v151, s[62:63] offset:3584 nt
	s_add_u32 s7, s7, 1
	v_cvt_f32_f16_e32 v154, v70
	v_cvt_f32_f16_e32 v155, v78
	v_add_f32_e32 v154, v154, v155
	v_fmac_f32_e32 v54, v32, v154
	v_cvt_f32_f16_sdwa v156, v70 dst_sel:DWORD dst_unused:UNUSED_PAD src0_sel:WORD_1
	v_cvt_f32_f16_sdwa v157, v78 dst_sel:DWORD dst_unused:UNUSED_PAD src0_sel:WORD_1
	v_add_f32_e32 v156, v156, v157
	v_fmac_f32_e32 v55, v33, v156
	v_cvt_f32_f16_e32 v154, v71
	v_cvt_f32_f16_e32 v155, v79
	v_add_f32_e32 v154, v154, v155
	v_fmac_f32_e32 v56, v34, v154
	v_cvt_f32_f16_sdwa v156, v71 dst_sel:DWORD dst_unused:UNUSED_PAD src0_sel:WORD_1
	v_cvt_f32_f16_sdwa v157, v79 dst_sel:DWORD dst_unused:UNUSED_PAD src0_sel:WORD_1
	v_add_f32_e32 v156, v156, v157
	v_fmac_f32_e32 v57, v35, v156
	v_cvt_f32_f16_e32 v154, v72
	v_cvt_f32_f16_e32 v155, v80
	v_add_f32_e32 v154, v154, v155
	v_fmac_f32_e32 v58, v36, v154
	v_cvt_f32_f16_sdwa v156, v72 dst_sel:DWORD dst_unused:UNUSED_PAD src0_sel:WORD_1
	v_cvt_f32_f16_sdwa v157, v80 dst_sel:DWORD dst_unused:UNUSED_PAD src0_sel:WORD_1
	v_add_f32_e32 v156, v156, v157
	v_fmac_f32_e32 v59, v37, v156
	v_cvt_f32_f16_e32 v154, v73
	v_cvt_f32_f16_e32 v155, v81
	v_add_f32_e32 v154, v154, v155
	v_fmac_f32_e32 v60, v38, v154
	v_cvt_f32_f16_sdwa v156, v73 dst_sel:DWORD dst_unused:UNUSED_PAD src0_sel:WORD_1
	v_cvt_f32_f16_sdwa v157, v81 dst_sel:DWORD dst_unused:UNUSED_PAD src0_sel:WORD_1
	v_add_f32_e32 v156, v156, v157
	v_fmac_f32_e32 v61, v39, v156
	v_cvt_f32_f16_e32 v154, v74
	v_cvt_f32_f16_e32 v155, v82
	v_add_f32_e32 v154, v154, v155
	v_fmac_f32_e32 v62, v40, v154
	v_cvt_f32_f16_sdwa v156, v74 dst_sel:DWORD dst_unused:UNUSED_PAD src0_sel:WORD_1
	v_cvt_f32_f16_sdwa v157, v82 dst_sel:DWORD dst_unused:UNUSED_PAD src0_sel:WORD_1
	v_add_f32_e32 v156, v156, v157
	v_fmac_f32_e32 v63, v41, v156
	v_cvt_f32_f16_e32 v154, v75
	v_cvt_f32_f16_e32 v155, v83
	v_add_f32_e32 v154, v154, v155
	v_fmac_f32_e32 v64, v42, v154
	v_cvt_f32_f16_sdwa v156, v75 dst_sel:DWORD dst_unused:UNUSED_PAD src0_sel:WORD_1
	v_cvt_f32_f16_sdwa v157, v83 dst_sel:DWORD dst_unused:UNUSED_PAD src0_sel:WORD_1
	v_add_f32_e32 v156, v156, v157
	v_fmac_f32_e32 v65, v43, v156
	v_cvt_f32_f16_e32 v154, v76
	v_cvt_f32_f16_e32 v155, v84
	v_add_f32_e32 v154, v154, v155
	v_fmac_f32_e32 v66, v44, v154
	v_cvt_f32_f16_sdwa v156, v76 dst_sel:DWORD dst_unused:UNUSED_PAD src0_sel:WORD_1
	v_cvt_f32_f16_sdwa v157, v84 dst_sel:DWORD dst_unused:UNUSED_PAD src0_sel:WORD_1
	v_add_f32_e32 v156, v156, v157
	v_fmac_f32_e32 v67, v45, v156
	v_cvt_f32_f16_e32 v154, v77
	v_cvt_f32_f16_e32 v155, v85
	v_add_f32_e32 v154, v154, v155
	v_fmac_f32_e32 v68, v46, v154
	v_cvt_f32_f16_sdwa v156, v77 dst_sel:DWORD dst_unused:UNUSED_PAD src0_sel:WORD_1
	v_cvt_f32_f16_sdwa v157, v85 dst_sel:DWORD dst_unused:UNUSED_PAD src0_sel:WORD_1
	v_add_f32_e32 v156, v156, v157
	v_fmac_f32_e32 v69, v47, v156
	global_store_dwordx4 v150, v[54:57], s[34:35] offset:0
	global_store_dwordx4 v150, v[58:61], s[34:35] offset:1024
	global_store_dwordx4 v150, v[62:65], s[34:35] offset:2048
	global_store_dwordx4 v150, v[66:69], s[34:35] offset:3072
	v_mul_f32_e32 v152, v54, v54
	v_mul_f32_e32 v153, v55, v55
	v_fmac_f32_e32 v152, v56, v56
	v_fmac_f32_e32 v153, v57, v57
	v_fmac_f32_e32 v152, v58, v58
	v_fmac_f32_e32 v153, v59, v59
	v_fmac_f32_e32 v152, v60, v60
	v_fmac_f32_e32 v153, v61, v61
	v_fmac_f32_e32 v152, v62, v62
	v_fmac_f32_e32 v153, v63, v63
	v_fmac_f32_e32 v152, v64, v64
	v_fmac_f32_e32 v153, v65, v65
	v_fmac_f32_e32 v152, v66, v66
	v_fmac_f32_e32 v153, v67, v67
	v_fmac_f32_e32 v152, v68, v68
	v_fmac_f32_e32 v153, v69, v69
	v_add_f32_e32 v152, v152, v153
	v_xor_b32_e32 v158, 128, v159
	ds_bpermute_b32 v153, v158, v152
	s_waitcnt lgkmcnt(0)
; DI void row1_phase(const Params& P, int combine_l, int norm_l, int r_begin) {
;     ...
;     if (combine_l >= 0) {
;       float* xm = r < TC ? P.xcbuf + (size_t)r * D : P.out + (size_t)(r - TC) * D;
;       const float* g2 = P.mod + (size_t)(combine_l * 9 + n) * 6144 + 5 * 1024;
;     ...
;       ss = wave_sum(ss);
;       const float rstd = rsqrtf(ss * (1.f / 1024.f) + EPS);
;       const float* g = P.norm1_g + norm_l * 1024;
;       const float* sh = P.mod + (size_t)(norm_l * 9 + n) * 6144; const float* sc = sh + 1024;
; #pragma unroll
;       for (int i = 0; i < 4; i++) {
;         int c = i * 256 + lane * 4;
;         float4 gg = *(const float4*)(g + c), s1 = *(const float4*)(sc + c), s0 = *(const float4*)(sh + c);
;         h4 o;
;         o[0] = (half_t)(xv[i].x * rstd * gg.x * (1.f + s1.x) + s0.x); o[1] = (half_t)(xv[i].y * rstd * gg.y * (1.f + s1.y) + s0.y);
;         o[2] = (half_t)(xv[i].z * rstd * gg.z * (1.f + s1.z) + s0.z); o[3] = (half_t)(xv[i].w * rstd * gg.w * (1.f + s1.w) + s0.w);
;         *(h4*)(P.hx + (size_t)r * D + c) = o;
;       }
;     }
	v_add_f32_e32 v152, v152, v153
	v_xor_b32_e32 v158, 64, v159
	ds_bpermute_b32 v153, v158, v152
	s_waitcnt lgkmcnt(0)
	v_add_f32_e32 v152, v152, v153
	v_xor_b32_e32 v158, 32, v159
	ds_bpermute_b32 v153, v158, v152
	s_waitcnt lgkmcnt(0)
	v_add_f32_e32 v152, v152, v153
	v_xor_b32_e32 v158, 16, v159
	ds_bpermute_b32 v153, v158, v152
	s_waitcnt lgkmcnt(0)
	v_add_f32_e32 v152, v152, v153
	v_xor_b32_e32 v158, 8, v159
	ds_bpermute_b32 v153, v158, v152
	s_waitcnt lgkmcnt(0)
	v_add_f32_e32 v152, v152, v153
	v_xor_b32_e32 v158, 4, v159
	ds_bpermute_b32 v153, v158, v152
	s_waitcnt lgkmcnt(0)
	v_add_f32_e32 v152, v152, v153
	v_mov_b32_e32 v153, 0x358637bd
	v_fmamk_f32 v152, v152, 0x3a800000, v153
	v_rsq_f32_e32 v152, v152
	s_nop 1
	v_mul_f32_e32 v54, v54, v152
	v_mul_f32_e32 v55, v55, v152
	v_mul_f32_e32 v56, v56, v152
	v_mul_f32_e32 v57, v57, v152
	v_mul_f32_e32 v58, v58, v152
	v_mul_f32_e32 v59, v59, v152
	v_mul_f32_e32 v60, v60, v152
	v_mul_f32_e32 v61, v61, v152
	v_mul_f32_e32 v62, v62, v152
	v_mul_f32_e32 v63, v63, v152
	v_mul_f32_e32 v64, v64, v152
	v_mul_f32_e32 v65, v65, v152
	v_mul_f32_e32 v66, v66, v152
	v_mul_f32_e32 v67, v67, v152
	v_mul_f32_e32 v68, v68, v152
	v_mul_f32_e32 v69, v69, v152
	v_fma_f32 v54, v54, v0, v16
	v_fma_f32 v55, v55, v1, v17
	v_fma_f32 v56, v56, v2, v18
	v_fma_f32 v57, v57, v3, v19
	v_fma_f32 v58, v58, v4, v20
	v_fma_f32 v59, v59, v5, v21
	v_fma_f32 v60, v60, v6, v22
	v_fma_f32 v61, v61, v7, v23
	v_fma_f32 v62, v62, v8, v24
	v_fma_f32 v63, v63, v9, v25
	v_fma_f32 v64, v64, v10, v26
	v_fma_f32 v65, v65, v11, v27
	v_fma_f32 v66, v66, v12, v28
	v_fma_f32 v67, v67, v13, v29
	v_fma_f32 v68, v68, v14, v30
	v_fma_f32 v69, v69, v15, v31
	v_cvt_pk_f16_f32 v70, v54, v55
	v_cvt_pk_f16_f32 v71, v56, v57
	v_cvt_pk_f16_f32 v72, v58, v59
	v_cvt_pk_f16_f32 v73, v60, v61
	v_cvt_pk_f16_f32 v74, v62, v63
	v_cvt_pk_f16_f32 v75, v64, v65
	v_cvt_pk_f16_f32 v76, v66, v67
	v_cvt_pk_f16_f32 v77, v68, v69
	global_store_dwordx2 v151, v[70:71], s[36:37] offset:0
	global_store_dwordx2 v151, v[72:73], s[36:37] offset:512
	global_store_dwordx2 v151, v[74:75], s[36:37] offset:1024
	global_store_dwordx2 v151, v[76:77], s[36:37] offset:1536
	s_add_u32 s5, s5, 1
	s_sub_u32 s9, s5, 0x800
	s_lshr_b32 s9, s9, 13
	s_cmp_lt_u32 s5, 0x800
	s_cselect_b32 s9, 8, s9
	s_cmp_eq_u32 s9, s8
	s_cbranch_scc1 .Lr1b_nr3
	s_mov_b32 s8, s9
	s_waitcnt vmcnt(0)
	s_add_u32 s10, s9, 9
	s_mul_i32 s10, s10, 0x6000
	s_add_u32 s38, s56, s10
	s_addc_u32 s39, s57, 0
	global_load_dwordx4 v[54:57], v150, s[58:59] offset:0
	global_load_dwordx4 v[58:61], v150, s[58:59] offset:1024
	global_load_dwordx4 v[62:65], v150, s[58:59] offset:2048
	global_load_dwordx4 v[66:69], v150, s[58:59] offset:3072
	s_add_u32 s44, s38, 0x1000
	s_addc_u32 s45, s39, 0
	global_load_dwordx4 v[70:73], v150, s[44:45] offset:0
	global_load_dwordx4 v[74:77], v150, s[44:45] offset:1024
	global_load_dwordx4 v[78:81], v150, s[44:45] offset:2048
	global_load_dwordx4 v[82:85], v150, s[44:45] offset:3072
	global_load_dwordx4 v[16:19], v150, s[38:39] offset:0
	global_load_dwordx4 v[20:23], v150, s[38:39] offset:1024
	global_load_dwordx4 v[24:27], v150, s[38:39] offset:2048
	global_load_dwordx4 v[28:31], v150, s[38:39] offset:3072
	s_add_u32 s10, s9, 0
	s_mul_i32 s10, s10, 0x6000
	s_add_u32 s10, s10, 0x5000
	s_add_u32 s38, s56, s10
	s_addc_u32 s39, s57, 0
	global_load_dwordx4 v[32:35], v150, s[38:39] offset:0
	global_load_dwordx4 v[36:39], v150, s[38:39] offset:1024
	global_load_dwordx4 v[40:43], v150, s[38:39] offset:2048
	global_load_dwordx4 v[44:47], v150, s[38:39] offset:3072
	s_waitcnt vmcnt(0)
	v_add_f32_e32 v70, 1.0, v70
	v_add_f32_e32 v71, 1.0, v71
	v_add_f32_e32 v72, 1.0, v72
	v_add_f32_e32 v73, 1.0, v73
	v_add_f32_e32 v74, 1.0, v74
	v_add_f32_e32 v75, 1.0, v75
	v_add_f32_e32 v76, 1.0, v76
	v_add_f32_e32 v77, 1.0, v77
	v_add_f32_e32 v78, 1.0, v78
	v_add_f32_e32 v79, 1.0, v79
	v_add_f32_e32 v80, 1.0, v80
	v_add_f32_e32 v81, 1.0, v81
	v_add_f32_e32 v82, 1.0, v82
	v_add_f32_e32 v83, 1.0, v83
	v_add_f32_e32 v84, 1.0, v84
	v_add_f32_e32 v85, 1.0, v85
	v_mul_f32_e32 v0, v54, v70
	v_mul_f32_e32 v1, v55, v71
	v_mul_f32_e32 v2, v56, v72
	v_mul_f32_e32 v3, v57, v73
	v_mul_f32_e32 v4, v58, v74
	v_mul_f32_e32 v5, v59, v75
	v_mul_f32_e32 v6, v60, v76
	v_mul_f32_e32 v7, v61, v77
	v_mul_f32_e32 v8, v62, v78
	v_mul_f32_e32 v9, v63, v79
	v_mul_f32_e32 v10, v64, v80
	v_mul_f32_e32 v11, v65, v81
	v_mul_f32_e32 v12, v66, v82
	v_mul_f32_e32 v13, v67, v83
	v_mul_f32_e32 v14, v68, v84
	v_mul_f32_e32 v15, v69, v85
; DI void row1_phase(const Params& P, int combine_l, int norm_l, int r_begin) {
;     ...
;       for (int i = 0; i < 4; i++) { int c = i * 256 + lane * 4; xv[i] = *(const float4*)(xm + c); ya[i] = *(const h4*)(y0 + c); yb[i] = *(const h4*)(y1 + c); }
;     }
;   };
;   auto process = [&](int r, float4 (&xv)[4], h4 (&ya)[4], h4 (&yb)[4]) {
;     const int n = row_mod(r);
;     if (combine_l >= 0) {
;       float* xm = r < TC ? P.xcbuf + (size_t)r * D : P.out + (size_t)(r - TC) * D;
;       const float* g2 = P.mod + (size_t)(combine_l * 9 + n) * 6144 + 5 * 1024;
; #pragma unroll
;       for (int i = 0; i < 4; i++) {
;         int c = i * 256 + lane * 4;
;         float4 g = *(const float4*)(g2 + c); float4 t = xv[i];
;         t.x += g.x * ((float)ya[i][0] + (float)yb[i][0]); t.y += g.y * ((float)ya[i][1] + (float)yb[i][1]);
;         t.z += g.z * ((float)ya[i][2] + (float)yb[i][2]); t.w += g.w * ((float)ya[i][3] + (float)yb[i][3]);
;         *(float4*)(xm + c) = t; xv[i] = t;
;       }
;     }
;     if (norm_l >= 0) {
;       float ss = 0.f;
; #pragma unroll
;       for (int i = 0; i < 4; i++) ss += xv[i].x * xv[i].x + xv[i].y * xv[i].y + xv[i].z * xv[i].z + xv[i].w * xv[i].w;
;       ss = wave_sum(ss);
.Lr1b_nr3:
	s_waitcnt vmcnt(44)
	v_accvgpr_read_b32 v54, a64
	v_accvgpr_read_b32 v55, a65
	v_accvgpr_read_b32 v56, a66
	v_accvgpr_read_b32 v57, a67
	v_accvgpr_read_b32 v58, a68
	v_accvgpr_read_b32 v59, a69
	v_accvgpr_read_b32 v60, a70
	v_accvgpr_read_b32 v61, a71
	v_accvgpr_read_b32 v62, a72
	v_accvgpr_read_b32 v63, a73
	v_accvgpr_read_b32 v64, a74
	v_accvgpr_read_b32 v65, a75
	v_accvgpr_read_b32 v66, a76
	v_accvgpr_read_b32 v67, a77
	v_accvgpr_read_b32 v68, a78
	v_accvgpr_read_b32 v69, a79
	v_accvgpr_read_b32 v70, a80
	v_accvgpr_read_b32 v71, a81
	v_accvgpr_read_b32 v72, a82
	v_accvgpr_read_b32 v73, a83
	v_accvgpr_read_b32 v74, a84
	v_accvgpr_read_b32 v75, a85
	v_accvgpr_read_b32 v76, a86
	v_accvgpr_read_b32 v77, a87
	v_accvgpr_read_b32 v78, a88
	v_accvgpr_read_b32 v79, a89
	v_accvgpr_read_b32 v80, a90
	v_accvgpr_read_b32 v81, a91
	v_accvgpr_read_b32 v82, a92
	v_accvgpr_read_b32 v83, a93
	v_accvgpr_read_b32 v84, a94
	v_accvgpr_read_b32 v85, a95
	s_lshl_b32 s10, s5, 12
	s_cmp_lt_u32 s5, 0x800
	s_cselect_b64 s[34:35], s[48:49], s[50:51]
	s_add_u32 s34, s34, s10
	s_addc_u32 s35, s35, 0
	s_lshr_b32 s10, s10, 1
	s_add_u32 s36, s54, s10
	s_addc_u32 s37, s55, 0
	s_cmp_lt_u32 s7, 0x800
	s_cselect_b64 s[60:61], s[48:49], s[50:51]
	s_lshl_b32 s10, s7, 12
	s_add_u32 s60, s60, s10
	s_addc_u32 s61, s61, 0
	global_load_dwordx4 a[64:67], v150, s[60:61] offset:0 nt
	global_load_dwordx4 a[68:71], v150, s[60:61] offset:1024 nt
	global_load_dwordx4 a[72:75], v150, s[60:61] offset:2048 nt
	global_load_dwordx4 a[76:79], v150, s[60:61] offset:3072 nt
	s_add_u32 s62, s52, s10
	s_addc_u32 s63, s53, 0
	global_load_dwordx2 a[80:81], v151, s[62:63] offset:0 nt
	global_load_dwordx2 a[82:83], v151, s[62:63] offset:512 nt
	global_load_dwordx2 a[84:85], v151, s[62:63] offset:1024 nt
	global_load_dwordx2 a[86:87], v151, s[62:63] offset:1536 nt
	global_load_dwordx2 a[88:89], v151, s[62:63] offset:2048 nt
	global_load_dwordx2 a[90:91], v151, s[62:63] offset:2560 nt
	global_load_dwordx2 a[92:93], v151, s[62:63] offset:3072 nt
	global_load_dwordx2 a[94:95], v151, s[62:63] offset:3584 nt
	s_add_u32 s7, s7, 1
	v_cvt_f32_f16_e32 v154, v70
	v_cvt_f32_f16_e32 v155, v78
	v_add_f32_e32 v154, v154, v155
	v_fmac_f32_e32 v54, v32, v154
	v_cvt_f32_f16_sdwa v156, v70 dst_sel:DWORD dst_unused:UNUSED_PAD src0_sel:WORD_1
	v_cvt_f32_f16_sdwa v157, v78 dst_sel:DWORD dst_unused:UNUSED_PAD src0_sel:WORD_1
	v_add_f32_e32 v156, v156, v157
	v_fmac_f32_e32 v55, v33, v156
	v_cvt_f32_f16_e32 v154, v71
	v_cvt_f32_f16_e32 v155, v79
	v_add_f32_e32 v154, v154, v155
	v_fmac_f32_e32 v56, v34, v154
	v_cvt_f32_f16_sdwa v156, v71 dst_sel:DWORD dst_unused:UNUSED_PAD src0_sel:WORD_1
	v_cvt_f32_f16_sdwa v157, v79 dst_sel:DWORD dst_unused:UNUSED_PAD src0_sel:WORD_1
	v_add_f32_e32 v156, v156, v157
	v_fmac_f32_e32 v57, v35, v156
	v_cvt_f32_f16_e32 v154, v72
	v_cvt_f32_f16_e32 v155, v80
	v_add_f32_e32 v154, v154, v155
	v_fmac_f32_e32 v58, v36, v154
	v_cvt_f32_f16_sdwa v156, v72 dst_sel:DWORD dst_unused:UNUSED_PAD src0_sel:WORD_1
	v_cvt_f32_f16_sdwa v157, v80 dst_sel:DWORD dst_unused:UNUSED_PAD src0_sel:WORD_1
	v_add_f32_e32 v156, v156, v157
	v_fmac_f32_e32 v59, v37, v156
	v_cvt_f32_f16_e32 v154, v73
	v_cvt_f32_f16_e32 v155, v81
	v_add_f32_e32 v154, v154, v155
	v_fmac_f32_e32 v60, v38, v154
	v_cvt_f32_f16_sdwa v156, v73 dst_sel:DWORD dst_unused:UNUSED_PAD src0_sel:WORD_1
	v_cvt_f32_f16_sdwa v157, v81 dst_sel:DWORD dst_unused:UNUSED_PAD src0_sel:WORD_1
	v_add_f32_e32 v156, v156, v157
	v_fmac_f32_e32 v61, v39, v156
	v_cvt_f32_f16_e32 v154, v74
	v_cvt_f32_f16_e32 v155, v82
	v_add_f32_e32 v154, v154, v155
	v_fmac_f32_e32 v62, v40, v154
	v_cvt_f32_f16_sdwa v156, v74 dst_sel:DWORD dst_unused:UNUSED_PAD src0_sel:WORD_1
	v_cvt_f32_f16_sdwa v157, v82 dst_sel:DWORD dst_unused:UNUSED_PAD src0_sel:WORD_1
	v_add_f32_e32 v156, v156, v157
	v_fmac_f32_e32 v63, v41, v156
	v_cvt_f32_f16_e32 v154, v75
	v_cvt_f32_f16_e32 v155, v83
	v_add_f32_e32 v154, v154, v155
	v_fmac_f32_e32 v64, v42, v154
	v_cvt_f32_f16_sdwa v156, v75 dst_sel:DWORD dst_unused:UNUSED_PAD src0_sel:WORD_1
	v_cvt_f32_f16_sdwa v157, v83 dst_sel:DWORD dst_unused:UNUSED_PAD src0_sel:WORD_1
	v_add_f32_e32 v156, v156, v157
	v_fmac_f32_e32 v65, v43, v156
	v_cvt_f32_f16_e32 v154, v76
	v_cvt_f32_f16_e32 v155, v84
	v_add_f32_e32 v154, v154, v155
	v_fmac_f32_e32 v66, v44, v154
	v_cvt_f32_f16_sdwa v156, v76 dst_sel:DWORD dst_unused:UNUSED_PAD src0_sel:WORD_1
	v_cvt_f32_f16_sdwa v157, v84 dst_sel:DWORD dst_unused:UNUSED_PAD src0_sel:WORD_1
	v_add_f32_e32 v156, v156, v157
	v_fmac_f32_e32 v67, v45, v156
	v_cvt_f32_f16_e32 v154, v77
	v_cvt_f32_f16_e32 v155, v85
	v_add_f32_e32 v154, v154, v155
	v_fmac_f32_e32 v68, v46, v154
	v_cvt_f32_f16_sdwa v156, v77 dst_sel:DWORD dst_unused:UNUSED_PAD src0_sel:WORD_1
	v_cvt_f32_f16_sdwa v157, v85 dst_sel:DWORD dst_unused:UNUSED_PAD src0_sel:WORD_1
	v_add_f32_e32 v156, v156, v157
	v_fmac_f32_e32 v69, v47, v156
	global_store_dwordx4 v150, v[54:57], s[34:35] offset:0
	global_store_dwordx4 v150, v[58:61], s[34:35] offset:1024
	global_store_dwordx4 v150, v[62:65], s[34:35] offset:2048
	global_store_dwordx4 v150, v[66:69], s[34:35] offset:3072
	v_mul_f32_e32 v152, v54, v54
	v_mul_f32_e32 v153, v55, v55
	v_fmac_f32_e32 v152, v56, v56
	v_fmac_f32_e32 v153, v57, v57
	v_fmac_f32_e32 v152, v58, v58
	v_fmac_f32_e32 v153, v59, v59
	v_fmac_f32_e32 v152, v60, v60
	v_fmac_f32_e32 v153, v61, v61
	v_fmac_f32_e32 v152, v62, v62
	v_fmac_f32_e32 v153, v63, v63
	v_fmac_f32_e32 v152, v64, v64
	v_fmac_f32_e32 v153, v65, v65
	v_fmac_f32_e32 v152, v66, v66
	v_fmac_f32_e32 v153, v67, v67
	v_fmac_f32_e32 v152, v68, v68
	v_fmac_f32_e32 v153, v69, v69
	v_add_f32_e32 v152, v152, v153
	v_xor_b32_e32 v158, 128, v159
	ds_bpermute_b32 v153, v158, v152
	s_waitcnt lgkmcnt(0)
; DI void row1_phase(const Params& P, int combine_l, int norm_l, int r_begin) {
;     ...
;     if (combine_l >= 0) {
;       float* xm = r < TC ? P.xcbuf + (size_t)r * D : P.out + (size_t)(r - TC) * D;
;       const float* g2 = P.mod + (size_t)(combine_l * 9 + n) * 6144 + 5 * 1024;
;     ...
;       ss = wave_sum(ss);
;       const float rstd = rsqrtf(ss * (1.f / 1024.f) + EPS);
;       const float* g = P.norm1_g + norm_l * 1024;
;       const float* sh = P.mod + (size_t)(norm_l * 9 + n) * 6144; const float* sc = sh + 1024;
; #pragma unroll
;       for (int i = 0; i < 4; i++) {
;         int c = i * 256 + lane * 4;
;         float4 gg = *(const float4*)(g + c), s1 = *(const float4*)(sc + c), s0 = *(const float4*)(sh + c);
;         h4 o;
;         o[0] = (half_t)(xv[i].x * rstd * gg.x * (1.f + s1.x) + s0.x); o[1] = (half_t)(xv[i].y * rstd * gg.y * (1.f + s1.y) + s0.y);
;         o[2] = (half_t)(xv[i].z * rstd * gg.z * (1.f + s1.z) + s0.z); o[3] = (half_t)(xv[i].w * rstd * gg.w * (1.f + s1.w) + s0.w);
;         *(h4*)(P.hx + (size_t)r * D + c) = o;
;       }
;     }
	v_add_f32_e32 v152, v152, v153
	v_xor_b32_e32 v158, 64, v159
	ds_bpermute_b32 v153, v158, v152
	s_waitcnt lgkmcnt(0)
	v_add_f32_e32 v152, v152, v153
	v_xor_b32_e32 v158, 32, v159
	ds_bpermute_b32 v153, v158, v152
	s_waitcnt lgkmcnt(0)
	v_add_f32_e32 v152, v152, v153
	v_xor_b32_e32 v158, 16, v159
	ds_bpermute_b32 v153, v158, v152
	s_waitcnt lgkmcnt(0)
	v_add_f32_e32 v152, v152, v153
	v_xor_b32_e32 v158, 8, v159
	ds_bpermute_b32 v153, v158, v152
	s_waitcnt lgkmcnt(0)
	v_add_f32_e32 v152, v152, v153
	v_xor_b32_e32 v158, 4, v159
	ds_bpermute_b32 v153, v158, v152
	s_waitcnt lgkmcnt(0)
	v_add_f32_e32 v152, v152, v153
	v_mov_b32_e32 v153, 0x358637bd
	v_fmamk_f32 v152, v152, 0x3a800000, v153
	v_rsq_f32_e32 v152, v152
	s_nop 1
	v_mul_f32_e32 v54, v54, v152
	v_mul_f32_e32 v55, v55, v152
	v_mul_f32_e32 v56, v56, v152
	v_mul_f32_e32 v57, v57, v152
	v_mul_f32_e32 v58, v58, v152
	v_mul_f32_e32 v59, v59, v152
	v_mul_f32_e32 v60, v60, v152
	v_mul_f32_e32 v61, v61, v152
	v_mul_f32_e32 v62, v62, v152
	v_mul_f32_e32 v63, v63, v152
	v_mul_f32_e32 v64, v64, v152
	v_mul_f32_e32 v65, v65, v152
	v_mul_f32_e32 v66, v66, v152
	v_mul_f32_e32 v67, v67, v152
	v_mul_f32_e32 v68, v68, v152
	v_mul_f32_e32 v69, v69, v152
	v_fma_f32 v54, v54, v0, v16
	v_fma_f32 v55, v55, v1, v17
	v_fma_f32 v56, v56, v2, v18
	v_fma_f32 v57, v57, v3, v19
	v_fma_f32 v58, v58, v4, v20
	v_fma_f32 v59, v59, v5, v21
	v_fma_f32 v60, v60, v6, v22
	v_fma_f32 v61, v61, v7, v23
	v_fma_f32 v62, v62, v8, v24
	v_fma_f32 v63, v63, v9, v25
	v_fma_f32 v64, v64, v10, v26
	v_fma_f32 v65, v65, v11, v27
	v_fma_f32 v66, v66, v12, v28
	v_fma_f32 v67, v67, v13, v29
	v_fma_f32 v68, v68, v14, v30
	v_fma_f32 v69, v69, v15, v31
	v_cvt_pk_f16_f32 v70, v54, v55
	v_cvt_pk_f16_f32 v71, v56, v57
	v_cvt_pk_f16_f32 v72, v58, v59
	v_cvt_pk_f16_f32 v73, v60, v61
	v_cvt_pk_f16_f32 v74, v62, v63
	v_cvt_pk_f16_f32 v75, v64, v65
	v_cvt_pk_f16_f32 v76, v66, v67
	v_cvt_pk_f16_f32 v77, v68, v69
	global_store_dwordx2 v151, v[70:71], s[36:37] offset:0
	global_store_dwordx2 v151, v[72:73], s[36:37] offset:512
	global_store_dwordx2 v151, v[74:75], s[36:37] offset:1024
	global_store_dwordx2 v151, v[76:77], s[36:37] offset:1536
	s_add_u32 s5, s5, 1
	s_sub_u32 s9, s5, 0x800
	s_lshr_b32 s9, s9, 13
	s_cmp_lt_u32 s5, 0x800
	s_cselect_b32 s9, 8, s9
	s_cmp_eq_u32 s9, s8
	s_cbranch_scc1 .Lr1b_nr4
	s_mov_b32 s8, s9
	s_waitcnt vmcnt(0)
	s_add_u32 s10, s9, 9
	s_mul_i32 s10, s10, 0x6000
	s_add_u32 s38, s56, s10
	s_addc_u32 s39, s57, 0
	global_load_dwordx4 v[54:57], v150, s[58:59] offset:0
	global_load_dwordx4 v[58:61], v150, s[58:59] offset:1024
	global_load_dwordx4 v[62:65], v150, s[58:59] offset:2048
	global_load_dwordx4 v[66:69], v150, s[58:59] offset:3072
	s_add_u32 s44, s38, 0x1000
	s_addc_u32 s45, s39, 0
	global_load_dwordx4 v[70:73], v150, s[44:45] offset:0
	global_load_dwordx4 v[74:77], v150, s[44:45] offset:1024
	global_load_dwordx4 v[78:81], v150, s[44:45] offset:2048
	global_load_dwordx4 v[82:85], v150, s[44:45] offset:3072
	global_load_dwordx4 v[16:19], v150, s[38:39] offset:0
	global_load_dwordx4 v[20:23], v150, s[38:39] offset:1024
	global_load_dwordx4 v[24:27], v150, s[38:39] offset:2048
	global_load_dwordx4 v[28:31], v150, s[38:39] offset:3072
	s_add_u32 s10, s9, 0
	s_mul_i32 s10, s10, 0x6000
	s_add_u32 s10, s10, 0x5000
	s_add_u32 s38, s56, s10
	s_addc_u32 s39, s57, 0
	global_load_dwordx4 v[32:35], v150, s[38:39] offset:0
	global_load_dwordx4 v[36:39], v150, s[38:39] offset:1024
	global_load_dwordx4 v[40:43], v150, s[38:39] offset:2048
	global_load_dwordx4 v[44:47], v150, s[38:39] offset:3072
	s_waitcnt vmcnt(0)
	v_add_f32_e32 v70, 1.0, v70
	v_add_f32_e32 v71, 1.0, v71
	v_add_f32_e32 v72, 1.0, v72
	v_add_f32_e32 v73, 1.0, v73
	v_add_f32_e32 v74, 1.0, v74
	v_add_f32_e32 v75, 1.0, v75
	v_add_f32_e32 v76, 1.0, v76
	v_add_f32_e32 v77, 1.0, v77
	v_add_f32_e32 v78, 1.0, v78
	v_add_f32_e32 v79, 1.0, v79
	v_add_f32_e32 v80, 1.0, v80
	v_add_f32_e32 v81, 1.0, v81
	v_add_f32_e32 v82, 1.0, v82
	v_add_f32_e32 v83, 1.0, v83
	v_add_f32_e32 v84, 1.0, v84
	v_add_f32_e32 v85, 1.0, v85
	v_mul_f32_e32 v0, v54, v70
	v_mul_f32_e32 v1, v55, v71
	v_mul_f32_e32 v2, v56, v72
	v_mul_f32_e32 v3, v57, v73
	v_mul_f32_e32 v4, v58, v74
	v_mul_f32_e32 v5, v59, v75
	v_mul_f32_e32 v6, v60, v76
	v_mul_f32_e32 v7, v61, v77
	v_mul_f32_e32 v8, v62, v78
	v_mul_f32_e32 v9, v63, v79
	v_mul_f32_e32 v10, v64, v80
	v_mul_f32_e32 v11, v65, v81
	v_mul_f32_e32 v12, v66, v82
	v_mul_f32_e32 v13, v67, v83
	v_mul_f32_e32 v14, v68, v84
	v_mul_f32_e32 v15, v69, v85
; DI void row1_phase(const Params& P, int combine_l, int norm_l, int r_begin) {
;     ...
;       for (int i = 0; i < 4; i++) { int c = i * 256 + lane * 4; xv[i] = *(const float4*)(xm + c); ya[i] = *(const h4*)(y0 + c); yb[i] = *(const h4*)(y1 + c); }
;     }
;   };
;   auto process = [&](int r, float4 (&xv)[4], h4 (&ya)[4], h4 (&yb)[4]) {
;     const int n = row_mod(r);
;     if (combine_l >= 0) {
;       float* xm = r < TC ? P.xcbuf + (size_t)r * D : P.out + (size_t)(r - TC) * D;
;       const float* g2 = P.mod + (size_t)(combine_l * 9 + n) * 6144 + 5 * 1024;
; #pragma unroll
;       for (int i = 0; i < 4; i++) {
;         int c = i * 256 + lane * 4;
;         float4 g = *(const float4*)(g2 + c); float4 t = xv[i];
;         t.x += g.x * ((float)ya[i][0] + (float)yb[i][0]); t.y += g.y * ((float)ya[i][1] + (float)yb[i][1]);
;         t.z += g.z * ((float)ya[i][2] + (float)yb[i][2]); t.w += g.w * ((float)ya[i][3] + (float)yb[i][3]);
;         *(float4*)(xm + c) = t; xv[i] = t;
;       }
;     }
;     if (norm_l >= 0) {
;       float ss = 0.f;
; #pragma unroll
;       for (int i = 0; i < 4; i++) ss += xv[i].x * xv[i].x + xv[i].y * xv[i].y + xv[i].z * xv[i].z + xv[i].w * xv[i].w;
;       ss = wave_sum(ss);
.Lr1b_nr4:
	s_waitcnt vmcnt(44)
	v_accvgpr_read_b32 v54, a96
	v_accvgpr_read_b32 v55, a97
	v_accvgpr_read_b32 v56, a98
	v_accvgpr_read_b32 v57, a99
	v_accvgpr_read_b32 v58, a100
	v_accvgpr_read_b32 v59, a101
	v_accvgpr_read_b32 v60, a102
	v_accvgpr_read_b32 v61, a103
	v_accvgpr_read_b32 v62, a104
	v_accvgpr_read_b32 v63, a105
	v_accvgpr_read_b32 v64, a106
	v_accvgpr_read_b32 v65, a107
	v_accvgpr_read_b32 v66, a108
	v_accvgpr_read_b32 v67, a109
	v_accvgpr_read_b32 v68, a110
	v_accvgpr_read_b32 v69, a111
	v_accvgpr_read_b32 v70, a112
	v_accvgpr_read_b32 v71, a113
	v_accvgpr_read_b32 v72, a114
	v_accvgpr_read_b32 v73, a115
	v_accvgpr_read_b32 v74, a116
	v_accvgpr_read_b32 v75, a117
	v_accvgpr_read_b32 v76, a118
	v_accvgpr_read_b32 v77, a119
	v_accvgpr_read_b32 v78, a120
	v_accvgpr_read_b32 v79, a121
	v_accvgpr_read_b32 v80, a122
	v_accvgpr_read_b32 v81, a123
	v_accvgpr_read_b32 v82, a124
	v_accvgpr_read_b32 v83, a125
	v_accvgpr_read_b32 v84, a126
	v_accvgpr_read_b32 v85, a127
	s_lshl_b32 s10, s5, 12
	s_cmp_lt_u32 s5, 0x800
	s_cselect_b64 s[34:35], s[48:49], s[50:51]
	s_add_u32 s34, s34, s10
	s_addc_u32 s35, s35, 0
	s_lshr_b32 s10, s10, 1
	s_add_u32 s36, s54, s10
	s_addc_u32 s37, s55, 0
	s_cmp_lt_u32 s7, 0x800
	s_cselect_b64 s[60:61], s[48:49], s[50:51]
	s_lshl_b32 s10, s7, 12
	s_add_u32 s60, s60, s10
	s_addc_u32 s61, s61, 0
	global_load_dwordx4 a[96:99], v150, s[60:61] offset:0 nt
	global_load_dwordx4 a[100:103], v150, s[60:61] offset:1024 nt
	global_load_dwordx4 a[104:107], v150, s[60:61] offset:2048 nt
	global_load_dwordx4 a[108:111], v150, s[60:61] offset:3072 nt
	s_add_u32 s62, s52, s10
	s_addc_u32 s63, s53, 0
	global_load_dwordx2 a[112:113], v151, s[62:63] offset:0 nt
	global_load_dwordx2 a[114:115], v151, s[62:63] offset:512 nt
	global_load_dwordx2 a[116:117], v151, s[62:63] offset:1024 nt
	global_load_dwordx2 a[118:119], v151, s[62:63] offset:1536 nt
	global_load_dwordx2 a[120:121], v151, s[62:63] offset:2048 nt
	global_load_dwordx2 a[122:123], v151, s[62:63] offset:2560 nt
	global_load_dwordx2 a[124:125], v151, s[62:63] offset:3072 nt
	global_load_dwordx2 a[126:127], v151, s[62:63] offset:3584 nt
	s_add_u32 s7, s7, 1
	v_cvt_f32_f16_e32 v154, v70
	v_cvt_f32_f16_e32 v155, v78
	v_add_f32_e32 v154, v154, v155
	v_fmac_f32_e32 v54, v32, v154
	v_cvt_f32_f16_sdwa v156, v70 dst_sel:DWORD dst_unused:UNUSED_PAD src0_sel:WORD_1
	v_cvt_f32_f16_sdwa v157, v78 dst_sel:DWORD dst_unused:UNUSED_PAD src0_sel:WORD_1
	v_add_f32_e32 v156, v156, v157
	v_fmac_f32_e32 v55, v33, v156
	v_cvt_f32_f16_e32 v154, v71
	v_cvt_f32_f16_e32 v155, v79
	v_add_f32_e32 v154, v154, v155
	v_fmac_f32_e32 v56, v34, v154
	v_cvt_f32_f16_sdwa v156, v71 dst_sel:DWORD dst_unused:UNUSED_PAD src0_sel:WORD_1
	v_cvt_f32_f16_sdwa v157, v79 dst_sel:DWORD dst_unused:UNUSED_PAD src0_sel:WORD_1
	v_add_f32_e32 v156, v156, v157
	v_fmac_f32_e32 v57, v35, v156
	v_cvt_f32_f16_e32 v154, v72
	v_cvt_f32_f16_e32 v155, v80
	v_add_f32_e32 v154, v154, v155
	v_fmac_f32_e32 v58, v36, v154
	v_cvt_f32_f16_sdwa v156, v72 dst_sel:DWORD dst_unused:UNUSED_PAD src0_sel:WORD_1
	v_cvt_f32_f16_sdwa v157, v80 dst_sel:DWORD dst_unused:UNUSED_PAD src0_sel:WORD_1
	v_add_f32_e32 v156, v156, v157
	v_fmac_f32_e32 v59, v37, v156
	v_cvt_f32_f16_e32 v154, v73
	v_cvt_f32_f16_e32 v155, v81
	v_add_f32_e32 v154, v154, v155
	v_fmac_f32_e32 v60, v38, v154
	v_cvt_f32_f16_sdwa v156, v73 dst_sel:DWORD dst_unused:UNUSED_PAD src0_sel:WORD_1
	v_cvt_f32_f16_sdwa v157, v81 dst_sel:DWORD dst_unused:UNUSED_PAD src0_sel:WORD_1
	v_add_f32_e32 v156, v156, v157
	v_fmac_f32_e32 v61, v39, v156
	v_cvt_f32_f16_e32 v154, v74
	v_cvt_f32_f16_e32 v155, v82
	v_add_f32_e32 v154, v154, v155
	v_fmac_f32_e32 v62, v40, v154
	v_cvt_f32_f16_sdwa v156, v74 dst_sel:DWORD dst_unused:UNUSED_PAD src0_sel:WORD_1
	v_cvt_f32_f16_sdwa v157, v82 dst_sel:DWORD dst_unused:UNUSED_PAD src0_sel:WORD_1
	v_add_f32_e32 v156, v156, v157
	v_fmac_f32_e32 v63, v41, v156
	v_cvt_f32_f16_e32 v154, v75
	v_cvt_f32_f16_e32 v155, v83
	v_add_f32_e32 v154, v154, v155
	v_fmac_f32_e32 v64, v42, v154
	v_cvt_f32_f16_sdwa v156, v75 dst_sel:DWORD dst_unused:UNUSED_PAD src0_sel:WORD_1
	v_cvt_f32_f16_sdwa v157, v83 dst_sel:DWORD dst_unused:UNUSED_PAD src0_sel:WORD_1
	v_add_f32_e32 v156, v156, v157
	v_fmac_f32_e32 v65, v43, v156
	v_cvt_f32_f16_e32 v154, v76
	v_cvt_f32_f16_e32 v155, v84
	v_add_f32_e32 v154, v154, v155
	v_fmac_f32_e32 v66, v44, v154
	v_cvt_f32_f16_sdwa v156, v76 dst_sel:DWORD dst_unused:UNUSED_PAD src0_sel:WORD_1
	v_cvt_f32_f16_sdwa v157, v84 dst_sel:DWORD dst_unused:UNUSED_PAD src0_sel:WORD_1
	v_add_f32_e32 v156, v156, v157
	v_fmac_f32_e32 v67, v45, v156
	v_cvt_f32_f16_e32 v154, v77
	v_cvt_f32_f16_e32 v155, v85
	v_add_f32_e32 v154, v154, v155
	v_fmac_f32_e32 v68, v46, v154
	v_cvt_f32_f16_sdwa v156, v77 dst_sel:DWORD dst_unused:UNUSED_PAD src0_sel:WORD_1
	v_cvt_f32_f16_sdwa v157, v85 dst_sel:DWORD dst_unused:UNUSED_PAD src0_sel:WORD_1
	v_add_f32_e32 v156, v156, v157
	v_fmac_f32_e32 v69, v47, v156
	global_store_dwordx4 v150, v[54:57], s[34:35] offset:0
	global_store_dwordx4 v150, v[58:61], s[34:35] offset:1024
	global_store_dwordx4 v150, v[62:65], s[34:35] offset:2048
	global_store_dwordx4 v150, v[66:69], s[34:35] offset:3072
	v_mul_f32_e32 v152, v54, v54
	v_mul_f32_e32 v153, v55, v55
	v_fmac_f32_e32 v152, v56, v56
	v_fmac_f32_e32 v153, v57, v57
	v_fmac_f32_e32 v152, v58, v58
	v_fmac_f32_e32 v153, v59, v59
	v_fmac_f32_e32 v152, v60, v60
	v_fmac_f32_e32 v153, v61, v61
	v_fmac_f32_e32 v152, v62, v62
	v_fmac_f32_e32 v153, v63, v63
	v_fmac_f32_e32 v152, v64, v64
	v_fmac_f32_e32 v153, v65, v65
	v_fmac_f32_e32 v152, v66, v66
	v_fmac_f32_e32 v153, v67, v67
	v_fmac_f32_e32 v152, v68, v68
	v_fmac_f32_e32 v153, v69, v69
	v_add_f32_e32 v152, v152, v153
	v_xor_b32_e32 v158, 128, v159
	ds_bpermute_b32 v153, v158, v152
	s_waitcnt lgkmcnt(0)
; DI void row1_phase(const Params& P, int combine_l, int norm_l, int r_begin) {
;     ...
;       ss = wave_sum(ss);
;       const float rstd = rsqrtf(ss * (1.f / 1024.f) + EPS);
;       const float* g = P.norm1_g + norm_l * 1024;
;       const float* sh = P.mod + (size_t)(norm_l * 9 + n) * 6144; const float* sc = sh + 1024;
; #pragma unroll
;       for (int i = 0; i < 4; i++) {
;         int c = i * 256 + lane * 4;
;         float4 gg = *(const float4*)(g + c), s1 = *(const float4*)(sc + c), s0 = *(const float4*)(sh + c);
;         h4 o;
;         o[0] = (half_t)(xv[i].x * rstd * gg.x * (1.f + s1.x) + s0.x); o[1] = (half_t)(xv[i].y * rstd * gg.y * (1.f + s1.y) + s0.y);
;         o[2] = (half_t)(xv[i].z * rstd * gg.z * (1.f + s1.z) + s0.z); o[3] = (half_t)(xv[i].w * rstd * gg.w * (1.f + s1.w) + s0.w);
;         *(h4*)(P.hx + (size_t)r * D + c) = o;
;       }
;     }
;   };
;   const int nrows = TA - r_begin;
;   const int r_lo = r_begin + (int)(((long long)gw * nrows) / nw), r_hi = r_begin + (int)(((long long)(gw + 1) * nrows) / nw);
; #pragma unroll 1
;   for (int r = r_lo; r < r_hi; r += 4) {
;     float4 x0[4], x1[4], x2[4], x3[4]; h4 a0[4], b0[4], a1[4], b1[4], a2[4], b2[4], a3[4], b3[4];
;     const int r1 = r + 1, r2 = r + 2, r3 = r + 3;
;     load_row(r, x0, a0, b0);
;     if (r1 < r_hi) load_row(r1, x1, a1, b1);
;     if (r2 < r_hi) load_row(r2, x2, a2, b2);
;     if (r3 < r_hi) load_row(r3, x3, a3, b3);
;     process(r, x0, a0, b0);
;     if (r1 < r_hi) process(r1, x1, a1, b1);
;     if (r2 < r_hi) process(r2, x2, a2, b2);
;     if (r3 < r_hi) process(r3, x3, a3, b3);
;   }
	v_add_f32_e32 v152, v152, v153
	v_xor_b32_e32 v158, 64, v159
	ds_bpermute_b32 v153, v158, v152
	s_waitcnt lgkmcnt(0)
	v_add_f32_e32 v152, v152, v153
	v_xor_b32_e32 v158, 32, v159
	ds_bpermute_b32 v153, v158, v152
	s_waitcnt lgkmcnt(0)
	v_add_f32_e32 v152, v152, v153
	v_xor_b32_e32 v158, 16, v159
	ds_bpermute_b32 v153, v158, v152
	s_waitcnt lgkmcnt(0)
	v_add_f32_e32 v152, v152, v153
	v_xor_b32_e32 v158, 8, v159
	ds_bpermute_b32 v153, v158, v152
	s_waitcnt lgkmcnt(0)
	v_add_f32_e32 v152, v152, v153
	v_xor_b32_e32 v158, 4, v159
	ds_bpermute_b32 v153, v158, v152
	s_waitcnt lgkmcnt(0)
	v_add_f32_e32 v152, v152, v153
	v_mov_b32_e32 v153, 0x358637bd
	v_fmamk_f32 v152, v152, 0x3a800000, v153
	v_rsq_f32_e32 v152, v152
	s_nop 1
	v_mul_f32_e32 v54, v54, v152
	v_mul_f32_e32 v55, v55, v152
	v_mul_f32_e32 v56, v56, v152
	v_mul_f32_e32 v57, v57, v152
	v_mul_f32_e32 v58, v58, v152
	v_mul_f32_e32 v59, v59, v152
	v_mul_f32_e32 v60, v60, v152
	v_mul_f32_e32 v61, v61, v152
	v_mul_f32_e32 v62, v62, v152
	v_mul_f32_e32 v63, v63, v152
	v_mul_f32_e32 v64, v64, v152
	v_mul_f32_e32 v65, v65, v152
	v_mul_f32_e32 v66, v66, v152
	v_mul_f32_e32 v67, v67, v152
	v_mul_f32_e32 v68, v68, v152
	v_mul_f32_e32 v69, v69, v152
	v_fma_f32 v54, v54, v0, v16
	v_fma_f32 v55, v55, v1, v17
	v_fma_f32 v56, v56, v2, v18
	v_fma_f32 v57, v57, v3, v19
	v_fma_f32 v58, v58, v4, v20
	v_fma_f32 v59, v59, v5, v21
	v_fma_f32 v60, v60, v6, v22
	v_fma_f32 v61, v61, v7, v23
	v_fma_f32 v62, v62, v8, v24
	v_fma_f32 v63, v63, v9, v25
	v_fma_f32 v64, v64, v10, v26
	v_fma_f32 v65, v65, v11, v27
	v_fma_f32 v66, v66, v12, v28
	v_fma_f32 v67, v67, v13, v29
	v_fma_f32 v68, v68, v14, v30
	v_fma_f32 v69, v69, v15, v31
	v_cvt_pk_f16_f32 v70, v54, v55
	v_cvt_pk_f16_f32 v71, v56, v57
	v_cvt_pk_f16_f32 v72, v58, v59
	v_cvt_pk_f16_f32 v73, v60, v61
	v_cvt_pk_f16_f32 v74, v62, v63
	v_cvt_pk_f16_f32 v75, v64, v65
	v_cvt_pk_f16_f32 v76, v66, v67
	v_cvt_pk_f16_f32 v77, v68, v69
	global_store_dwordx2 v151, v[70:71], s[36:37] offset:0
	global_store_dwordx2 v151, v[72:73], s[36:37] offset:512
	global_store_dwordx2 v151, v[74:75], s[36:37] offset:1024
	global_store_dwordx2 v151, v[76:77], s[36:37] offset:1536
	s_add_u32 s5, s5, 1
	s_sub_u32 s98, s98, 1
	s_cmp_lg_u32 s98, 0
	s_cbranch_scc1 .Lr1b_loop
	s_sub_u32 s9, s5, 0x800
	s_lshr_b32 s9, s9, 13
	s_cmp_lt_u32 s5, 0x800
	s_cselect_b32 s9, 8, s9
	s_cmp_eq_u32 s9, s8
	s_cbranch_scc1 .Lr1b_nr5
	s_mov_b32 s8, s9
	s_waitcnt vmcnt(0)
	s_add_u32 s10, s9, 9
	s_mul_i32 s10, s10, 0x6000
	s_add_u32 s38, s56, s10
	s_addc_u32 s39, s57, 0
	global_load_dwordx4 v[54:57], v150, s[58:59] offset:0
	global_load_dwordx4 v[58:61], v150, s[58:59] offset:1024
	global_load_dwordx4 v[62:65], v150, s[58:59] offset:2048
	global_load_dwordx4 v[66:69], v150, s[58:59] offset:3072
	s_add_u32 s44, s38, 0x1000
	s_addc_u32 s45, s39, 0
	global_load_dwordx4 v[70:73], v150, s[44:45] offset:0
	global_load_dwordx4 v[74:77], v150, s[44:45] offset:1024
	global_load_dwordx4 v[78:81], v150, s[44:45] offset:2048
	global_load_dwordx4 v[82:85], v150, s[44:45] offset:3072
	global_load_dwordx4 v[16:19], v150, s[38:39] offset:0
	global_load_dwordx4 v[20:23], v150, s[38:39] offset:1024
	global_load_dwordx4 v[24:27], v150, s[38:39] offset:2048
	global_load_dwordx4 v[28:31], v150, s[38:39] offset:3072
	s_add_u32 s10, s9, 0
	s_mul_i32 s10, s10, 0x6000
	s_add_u32 s10, s10, 0x5000
	s_add_u32 s38, s56, s10
	s_addc_u32 s39, s57, 0
	global_load_dwordx4 v[32:35], v150, s[38:39] offset:0
	global_load_dwordx4 v[36:39], v150, s[38:39] offset:1024
	global_load_dwordx4 v[40:43], v150, s[38:39] offset:2048
	global_load_dwordx4 v[44:47], v150, s[38:39] offset:3072
	s_waitcnt vmcnt(0)
	v_add_f32_e32 v70, 1.0, v70
	v_add_f32_e32 v71, 1.0, v71
	v_add_f32_e32 v72, 1.0, v72
	v_add_f32_e32 v73, 1.0, v73
	v_add_f32_e32 v74, 1.0, v74
	v_add_f32_e32 v75, 1.0, v75
	v_add_f32_e32 v76, 1.0, v76
	v_add_f32_e32 v77, 1.0, v77
	v_add_f32_e32 v78, 1.0, v78
	v_add_f32_e32 v79, 1.0, v79
	v_add_f32_e32 v80, 1.0, v80
	v_add_f32_e32 v81, 1.0, v81
	v_add_f32_e32 v82, 1.0, v82
	v_add_f32_e32 v83, 1.0, v83
	v_add_f32_e32 v84, 1.0, v84
	v_add_f32_e32 v85, 1.0, v85
	v_mul_f32_e32 v0, v54, v70
	v_mul_f32_e32 v1, v55, v71
	v_mul_f32_e32 v2, v56, v72
	v_mul_f32_e32 v3, v57, v73
	v_mul_f32_e32 v4, v58, v74
	v_mul_f32_e32 v5, v59, v75
	v_mul_f32_e32 v6, v60, v76
	v_mul_f32_e32 v7, v61, v77
	v_mul_f32_e32 v8, v62, v78
	v_mul_f32_e32 v9, v63, v79
	v_mul_f32_e32 v10, v64, v80
	v_mul_f32_e32 v11, v65, v81
	v_mul_f32_e32 v12, v66, v82
	v_mul_f32_e32 v13, v67, v83
	v_mul_f32_e32 v14, v68, v84
	v_mul_f32_e32 v15, v69, v85

; DI void row1_phase(const Params& P, int combine_l, int norm_l, int r_begin) {
;     ...
;   auto load_row = [&](int r, float4 (&xv)[4], h4 (&ya)[4], h4 (&yb)[4]) {
;     if (combine_l < 0) {
;       const float* src = r < TC ? P.ctx + (size_t)r * D : P.x + (size_t)(r - TC) * D;
; #pragma unroll
;       for (int i = 0; i < 4; i++) xv[i] = *(const float4*)(src + i * 256 + lane * 4);
;     ...
;   const int nrows = TA - r_begin;
;   const int r_lo = r_begin + (int)(((long long)gw * nrows) / nw), r_hi = r_begin + (int)(((long long)(gw + 1) * nrows) / nw);
; #pragma unroll 1
;   for (int r = r_lo; r < r_hi; r += 4) {
;     float4 x0[4], x1[4], x2[4], x3[4]; h4 a0[4], b0[4], a1[4], b1[4], a2[4], b2[4], a3[4], b3[4];
;     const int r1 = r + 1, r2 = r + 2, r3 = r + 3;
;     load_row(r, x0, a0, b0);
;     if (r1 < r_hi) load_row(r1, x1, a1, b1);
;     if (r2 < r_hi) load_row(r2, x2, a2, b2);
;     if (r3 < r_hi) load_row(r3, x3, a3, b3);
.Lr1_modeA:
	v_lshrrev_b32_e32 v152, 6, v172
	v_and_b32_e32 v153, 63, v172
	v_readfirstlane_b32 s5, v152
	v_readlane_b32 s4, v253, 0
	v_lshlrev_b32_e32 v150, 4, v153
	v_lshlrev_b32_e32 v151, 3, v153
	v_lshlrev_b32_e32 v159, 2, v153
	s_nop 2
	s_lshl_b32 s4, s4, 2
	s_add_u32 s4, s4, s5
	s_mul_i32 s5, s4, 66
	s_add_u32 s6, s5, 66
	s_add_u32 s52, s90, 0x28cbc700
	s_addc_u32 s53, s91, 0
	s_add_u32 s54, s90, 0xf8bc700
	s_addc_u32 s55, s91, 0
	s_add_u32 s56, s90, 0xce00000
	s_addc_u32 s57, s91, 0
	v_readlane_b32 s48, v255, 7
	v_readlane_b32 s49, v255, 8
	v_readlane_b32 s50, v255, 3
	v_readlane_b32 s51, v255, 4
	v_readlane_b32 s58, v255, 15
	v_readlane_b32 s59, v255, 16
	s_nop 3
	s_sub_u32 s50, s50, 0x800000
	s_subb_u32 s51, s51, 0
	s_mov_b32 s8, -1
	s_mov_b32 s7, s5
	s_cmp_lt_u32 s7, 0x800
	s_cselect_b64 s[60:61], s[48:49], s[50:51]
	s_lshl_b32 s10, s7, 12
	s_add_u32 s60, s60, s10
	s_addc_u32 s61, s61, 0
	global_load_dwordx4 a[0:3], v150, s[60:61] offset:0 nt
	global_load_dwordx4 a[4:7], v150, s[60:61] offset:1024 nt
	global_load_dwordx4 a[8:11], v150, s[60:61] offset:2048 nt
	global_load_dwordx4 a[12:15], v150, s[60:61] offset:3072 nt
	s_add_u32 s7, s7, 1
	s_cmp_lt_u32 s7, 0x800
	s_cselect_b64 s[60:61], s[48:49], s[50:51]
	s_lshl_b32 s10, s7, 12
	s_add_u32 s60, s60, s10
	s_addc_u32 s61, s61, 0
	global_load_dwordx4 a[32:35], v150, s[60:61] offset:0 nt
	global_load_dwordx4 a[36:39], v150, s[60:61] offset:1024 nt
	global_load_dwordx4 a[40:43], v150, s[60:61] offset:2048 nt
	global_load_dwordx4 a[44:47], v150, s[60:61] offset:3072 nt
	s_add_u32 s7, s7, 1
	s_cmp_lt_u32 s7, 0x800
	s_cselect_b64 s[60:61], s[48:49], s[50:51]
	s_lshl_b32 s10, s7, 12
	s_add_u32 s60, s60, s10
	s_addc_u32 s61, s61, 0
	global_load_dwordx4 a[64:67], v150, s[60:61] offset:0 nt
	global_load_dwordx4 a[68:71], v150, s[60:61] offset:1024 nt
	global_load_dwordx4 a[72:75], v150, s[60:61] offset:2048 nt
	global_load_dwordx4 a[76:79], v150, s[60:61] offset:3072 nt
	s_add_u32 s7, s7, 1
	s_cmp_lt_u32 s7, 0x800
	s_cselect_b64 s[60:61], s[48:49], s[50:51]
	s_lshl_b32 s10, s7, 12
	s_add_u32 s60, s60, s10
	s_addc_u32 s61, s61, 0
	global_load_dwordx4 a[96:99], v150, s[60:61] offset:0 nt
	global_load_dwordx4 a[100:103], v150, s[60:61] offset:1024 nt
	global_load_dwordx4 a[104:107], v150, s[60:61] offset:2048 nt
	global_load_dwordx4 a[108:111], v150, s[60:61] offset:3072 nt
	s_add_u32 s7, s7, 1
	s_mov_b32 s98, 15

; DI void row1_phase(const Params& P, int combine_l, int norm_l, int r_begin) {
;     ...
;     if (norm_l >= 0) {
;       float ss = 0.f;
; #pragma unroll
;       for (int i = 0; i < 4; i++) ss += xv[i].x * xv[i].x + xv[i].y * xv[i].y + xv[i].z * xv[i].z + xv[i].w * xv[i].w;
;       ss = wave_sum(ss);
;       const float rstd = rsqrtf(ss * (1.f / 1024.f) + EPS);
;       const float* g = P.norm1_g + norm_l * 1024;
;       const float* sh = P.mod + (size_t)(norm_l * 9 + n) * 6144; const float* sc = sh + 1024;
; #pragma unroll
;       for (int i = 0; i < 4; i++) {
;         int c = i * 256 + lane * 4;
;         float4 gg = *(const float4*)(g + c), s1 = *(const float4*)(sc + c), s0 = *(const float4*)(sh + c);
;         h4 o;
;         o[0] = (half_t)(xv[i].x * rstd * gg.x * (1.f + s1.x) + s0.x); o[1] = (half_t)(xv[i].y * rstd * gg.y * (1.f + s1.y) + s0.y);
;         o[2] = (half_t)(xv[i].z * rstd * gg.z * (1.f + s1.z) + s0.z); o[3] = (half_t)(xv[i].w * rstd * gg.w * (1.f + s1.w) + s0.w);
;         *(h4*)(P.hx + (size_t)r * D + c) = o;
;       }
;     }
.Lr1a_nr1:
	s_waitcnt vmcnt(16)
	v_accvgpr_read_b32 v54, a0
	v_accvgpr_read_b32 v55, a1
	v_accvgpr_read_b32 v56, a2
	v_accvgpr_read_b32 v57, a3
	v_accvgpr_read_b32 v58, a4
	v_accvgpr_read_b32 v59, a5
	v_accvgpr_read_b32 v60, a6
	v_accvgpr_read_b32 v61, a7
	v_accvgpr_read_b32 v62, a8
	v_accvgpr_read_b32 v63, a9
	v_accvgpr_read_b32 v64, a10
	v_accvgpr_read_b32 v65, a11
	v_accvgpr_read_b32 v66, a12
	v_accvgpr_read_b32 v67, a13
	v_accvgpr_read_b32 v68, a14
	v_accvgpr_read_b32 v69, a15
	s_lshl_b32 s10, s5, 12
	s_lshr_b32 s10, s10, 1
	s_add_u32 s36, s54, s10
	s_addc_u32 s37, s55, 0
	s_cmp_lt_u32 s7, 0x800
	s_cselect_b64 s[60:61], s[48:49], s[50:51]
	s_lshl_b32 s10, s7, 12
	s_add_u32 s60, s60, s10
	s_addc_u32 s61, s61, 0
	global_load_dwordx4 a[0:3], v150, s[60:61] offset:0 nt
	global_load_dwordx4 a[4:7], v150, s[60:61] offset:1024 nt
	global_load_dwordx4 a[8:11], v150, s[60:61] offset:2048 nt
	global_load_dwordx4 a[12:15], v150, s[60:61] offset:3072 nt
	s_add_u32 s7, s7, 1
	v_mul_f32_e32 v152, v54, v54
	v_mul_f32_e32 v153, v55, v55
	v_fmac_f32_e32 v152, v56, v56
	v_fmac_f32_e32 v153, v57, v57
	v_fmac_f32_e32 v152, v58, v58
	v_fmac_f32_e32 v153, v59, v59
	v_fmac_f32_e32 v152, v60, v60
	v_fmac_f32_e32 v153, v61, v61
	v_fmac_f32_e32 v152, v62, v62
	v_fmac_f32_e32 v153, v63, v63
	v_fmac_f32_e32 v152, v64, v64
	v_fmac_f32_e32 v153, v65, v65
	v_fmac_f32_e32 v152, v66, v66
	v_fmac_f32_e32 v153, v67, v67
	v_fmac_f32_e32 v152, v68, v68
	v_fmac_f32_e32 v153, v69, v69
	v_add_f32_e32 v152, v152, v153
	v_xor_b32_e32 v158, 128, v159
	ds_bpermute_b32 v153, v158, v152
	s_waitcnt lgkmcnt(0)
	v_add_f32_e32 v152, v152, v153
	v_xor_b32_e32 v158, 64, v159
	ds_bpermute_b32 v153, v158, v152
	s_waitcnt lgkmcnt(0)
	v_add_f32_e32 v152, v152, v153
	v_xor_b32_e32 v158, 32, v159
	ds_bpermute_b32 v153, v158, v152
	s_waitcnt lgkmcnt(0)
	v_add_f32_e32 v152, v152, v153
	v_xor_b32_e32 v158, 16, v159
	ds_bpermute_b32 v153, v158, v152
	s_waitcnt lgkmcnt(0)
	v_add_f32_e32 v152, v152, v153
	v_xor_b32_e32 v158, 8, v159
	ds_bpermute_b32 v153, v158, v152
	s_waitcnt lgkmcnt(0)
	v_add_f32_e32 v152, v152, v153
	v_xor_b32_e32 v158, 4, v159
	ds_bpermute_b32 v153, v158, v152
	s_waitcnt lgkmcnt(0)
	v_add_f32_e32 v152, v152, v153
	v_mov_b32_e32 v153, 0x358637bd
	v_fmamk_f32 v152, v152, 0x3a800000, v153
	v_rsq_f32_e32 v152, v152
	s_nop 1
	v_mul_f32_e32 v54, v54, v152
	v_mul_f32_e32 v55, v55, v152
	v_mul_f32_e32 v56, v56, v152
	v_mul_f32_e32 v57, v57, v152
	v_mul_f32_e32 v58, v58, v152
	v_mul_f32_e32 v59, v59, v152
	v_mul_f32_e32 v60, v60, v152
	v_mul_f32_e32 v61, v61, v152
	v_mul_f32_e32 v62, v62, v152
	v_mul_f32_e32 v63, v63, v152
	v_mul_f32_e32 v64, v64, v152
	v_mul_f32_e32 v65, v65, v152
	v_mul_f32_e32 v66, v66, v152
	v_mul_f32_e32 v67, v67, v152
	v_mul_f32_e32 v68, v68, v152
	v_mul_f32_e32 v69, v69, v152
	v_fma_f32 v54, v54, v0, v16
	v_fma_f32 v55, v55, v1, v17
	v_fma_f32 v56, v56, v2, v18
	v_fma_f32 v57, v57, v3, v19
	v_fma_f32 v58, v58, v4, v20
	v_fma_f32 v59, v59, v5, v21
	v_fma_f32 v60, v60, v6, v22
	v_fma_f32 v61, v61, v7, v23
	v_fma_f32 v62, v62, v8, v24
	v_fma_f32 v63, v63, v9, v25
	v_fma_f32 v64, v64, v10, v26
	v_fma_f32 v65, v65, v11, v27
	v_fma_f32 v66, v66, v12, v28
	v_fma_f32 v67, v67, v13, v29
	v_fma_f32 v68, v68, v14, v30
	v_fma_f32 v69, v69, v15, v31
	v_cvt_pk_f16_f32 v70, v54, v55
	v_cvt_pk_f16_f32 v71, v56, v57
	v_cvt_pk_f16_f32 v72, v58, v59
	v_cvt_pk_f16_f32 v73, v60, v61
	v_cvt_pk_f16_f32 v74, v62, v63
	v_cvt_pk_f16_f32 v75, v64, v65
	v_cvt_pk_f16_f32 v76, v66, v67
	v_cvt_pk_f16_f32 v77, v68, v69
	global_store_dwordx2 v151, v[70:71], s[36:37] offset:0
	global_store_dwordx2 v151, v[72:73], s[36:37] offset:512
	global_store_dwordx2 v151, v[74:75], s[36:37] offset:1024
	global_store_dwordx2 v151, v[76:77], s[36:37] offset:1536
	s_add_u32 s5, s5, 1
	s_sub_u32 s9, s5, 0x800
	s_lshr_b32 s9, s9, 13
	s_cmp_lt_u32 s5, 0x800
	s_cselect_b32 s9, 8, s9
	s_cmp_eq_u32 s9, s8
	s_cbranch_scc1 .Lr1a_nr2
	s_mov_b32 s8, s9
	s_waitcnt vmcnt(0)
	s_add_u32 s10, s9, 0
	s_mul_i32 s10, s10, 0x6000
	s_add_u32 s38, s56, s10
	s_addc_u32 s39, s57, 0
	global_load_dwordx4 v[54:57], v150, s[58:59] offset:0
	global_load_dwordx4 v[58:61], v150, s[58:59] offset:1024
	global_load_dwordx4 v[62:65], v150, s[58:59] offset:2048
	global_load_dwordx4 v[66:69], v150, s[58:59] offset:3072
	s_add_u32 s44, s38, 0x1000
	s_addc_u32 s45, s39, 0
	global_load_dwordx4 v[70:73], v150, s[44:45] offset:0
	global_load_dwordx4 v[74:77], v150, s[44:45] offset:1024
	global_load_dwordx4 v[78:81], v150, s[44:45] offset:2048
	global_load_dwordx4 v[82:85], v150, s[44:45] offset:3072
	global_load_dwordx4 v[16:19], v150, s[38:39] offset:0
	global_load_dwordx4 v[20:23], v150, s[38:39] offset:1024
	global_load_dwordx4 v[24:27], v150, s[38:39] offset:2048
	global_load_dwordx4 v[28:31], v150, s[38:39] offset:3072
	s_waitcnt vmcnt(0)
	v_add_f32_e32 v70, 1.0, v70
	v_add_f32_e32 v71, 1.0, v71
	v_add_f32_e32 v72, 1.0, v72
	v_add_f32_e32 v73, 1.0, v73
	v_add_f32_e32 v74, 1.0, v74
	v_add_f32_e32 v75, 1.0, v75
	v_add_f32_e32 v76, 1.0, v76
	v_add_f32_e32 v77, 1.0, v77
	v_add_f32_e32 v78, 1.0, v78
	v_add_f32_e32 v79, 1.0, v79
	v_add_f32_e32 v80, 1.0, v80
	v_add_f32_e32 v81, 1.0, v81
	v_add_f32_e32 v82, 1.0, v82
	v_add_f32_e32 v83, 1.0, v83
	v_add_f32_e32 v84, 1.0, v84
	v_add_f32_e32 v85, 1.0, v85
	v_mul_f32_e32 v0, v54, v70
	v_mul_f32_e32 v1, v55, v71
	v_mul_f32_e32 v2, v56, v72
	v_mul_f32_e32 v3, v57, v73
	v_mul_f32_e32 v4, v58, v74
	v_mul_f32_e32 v5, v59, v75
	v_mul_f32_e32 v6, v60, v76
	v_mul_f32_e32 v7, v61, v77
	v_mul_f32_e32 v8, v62, v78
	v_mul_f32_e32 v9, v63, v79
	v_mul_f32_e32 v10, v64, v80
	v_mul_f32_e32 v11, v65, v81
	v_mul_f32_e32 v12, v66, v82
	v_mul_f32_e32 v13, v67, v83
	v_mul_f32_e32 v14, v68, v84
	v_mul_f32_e32 v15, v69, v85
; DI void row1_phase(const Params& P, int combine_l, int norm_l, int r_begin) {
;     ...
;       const float* src = r < TC ? P.ctx + (size_t)r * D : P.x + (size_t)(r - TC) * D;
; #pragma unroll
;       for (int i = 0; i < 4; i++) xv[i] = *(const float4*)(src + i * 256 + lane * 4);
;     ...
;       float ss = 0.f;
; #pragma unroll
;       for (int i = 0; i < 4; i++) ss += xv[i].x * xv[i].x + xv[i].y * xv[i].y + xv[i].z * xv[i].z + xv[i].w * xv[i].w;
;       ss = wave_sum(ss);
;       const float rstd = rsqrtf(ss * (1.f / 1024.f) + EPS);
;       const float* g = P.norm1_g + norm_l * 1024;
;       const float* sh = P.mod + (size_t)(norm_l * 9 + n) * 6144; const float* sc = sh + 1024;
; #pragma unroll
;       for (int i = 0; i < 4; i++) {
;         int c = i * 256 + lane * 4;
;         float4 gg = *(const float4*)(g + c), s1 = *(const float4*)(sc + c), s0 = *(const float4*)(sh + c);
;         h4 o;
;         o[0] = (half_t)(xv[i].x * rstd * gg.x * (1.f + s1.x) + s0.x); o[1] = (half_t)(xv[i].y * rstd * gg.y * (1.f + s1.y) + s0.y);
;         o[2] = (half_t)(xv[i].z * rstd * gg.z * (1.f + s1.z) + s0.z); o[3] = (half_t)(xv[i].w * rstd * gg.w * (1.f + s1.w) + s0.w);
;         *(h4*)(P.hx + (size_t)r * D + c) = o;
;       }
.Lr1a_nr2:
	s_waitcnt vmcnt(16)
	v_accvgpr_read_b32 v54, a32
	v_accvgpr_read_b32 v55, a33
	v_accvgpr_read_b32 v56, a34
	v_accvgpr_read_b32 v57, a35
	v_accvgpr_read_b32 v58, a36
	v_accvgpr_read_b32 v59, a37
	v_accvgpr_read_b32 v60, a38
	v_accvgpr_read_b32 v61, a39
	v_accvgpr_read_b32 v62, a40
	v_accvgpr_read_b32 v63, a41
	v_accvgpr_read_b32 v64, a42
	v_accvgpr_read_b32 v65, a43
	v_accvgpr_read_b32 v66, a44
	v_accvgpr_read_b32 v67, a45
	v_accvgpr_read_b32 v68, a46
	v_accvgpr_read_b32 v69, a47
	s_lshl_b32 s10, s5, 12
	s_lshr_b32 s10, s10, 1
	s_add_u32 s36, s54, s10
	s_addc_u32 s37, s55, 0
	s_cmp_lt_u32 s7, 0x800
	s_cselect_b64 s[60:61], s[48:49], s[50:51]
	s_lshl_b32 s10, s7, 12
	s_add_u32 s60, s60, s10
	s_addc_u32 s61, s61, 0
	global_load_dwordx4 a[32:35], v150, s[60:61] offset:0 nt
	global_load_dwordx4 a[36:39], v150, s[60:61] offset:1024 nt
	global_load_dwordx4 a[40:43], v150, s[60:61] offset:2048 nt
	global_load_dwordx4 a[44:47], v150, s[60:61] offset:3072 nt
	s_add_u32 s7, s7, 1
	v_mul_f32_e32 v152, v54, v54
	v_mul_f32_e32 v153, v55, v55
	v_fmac_f32_e32 v152, v56, v56
	v_fmac_f32_e32 v153, v57, v57
	v_fmac_f32_e32 v152, v58, v58
	v_fmac_f32_e32 v153, v59, v59
	v_fmac_f32_e32 v152, v60, v60
	v_fmac_f32_e32 v153, v61, v61
	v_fmac_f32_e32 v152, v62, v62
	v_fmac_f32_e32 v153, v63, v63
	v_fmac_f32_e32 v152, v64, v64
	v_fmac_f32_e32 v153, v65, v65
	v_fmac_f32_e32 v152, v66, v66
	v_fmac_f32_e32 v153, v67, v67
	v_fmac_f32_e32 v152, v68, v68
	v_fmac_f32_e32 v153, v69, v69
	v_add_f32_e32 v152, v152, v153
	v_xor_b32_e32 v158, 128, v159
	ds_bpermute_b32 v153, v158, v152
	s_waitcnt lgkmcnt(0)
	v_add_f32_e32 v152, v152, v153
	v_xor_b32_e32 v158, 64, v159
	ds_bpermute_b32 v153, v158, v152
	s_waitcnt lgkmcnt(0)
	v_add_f32_e32 v152, v152, v153
	v_xor_b32_e32 v158, 32, v159
	ds_bpermute_b32 v153, v158, v152
	s_waitcnt lgkmcnt(0)
	v_add_f32_e32 v152, v152, v153
	v_xor_b32_e32 v158, 16, v159
	ds_bpermute_b32 v153, v158, v152
	s_waitcnt lgkmcnt(0)
	v_add_f32_e32 v152, v152, v153
	v_xor_b32_e32 v158, 8, v159
	ds_bpermute_b32 v153, v158, v152
	s_waitcnt lgkmcnt(0)
	v_add_f32_e32 v152, v152, v153
	v_xor_b32_e32 v158, 4, v159
	ds_bpermute_b32 v153, v158, v152
	s_waitcnt lgkmcnt(0)
	v_add_f32_e32 v152, v152, v153
	v_mov_b32_e32 v153, 0x358637bd
	v_fmamk_f32 v152, v152, 0x3a800000, v153
	v_rsq_f32_e32 v152, v152
	s_nop 1
	v_mul_f32_e32 v54, v54, v152
	v_mul_f32_e32 v55, v55, v152
	v_mul_f32_e32 v56, v56, v152
	v_mul_f32_e32 v57, v57, v152
	v_mul_f32_e32 v58, v58, v152
	v_mul_f32_e32 v59, v59, v152
	v_mul_f32_e32 v60, v60, v152
	v_mul_f32_e32 v61, v61, v152
	v_mul_f32_e32 v62, v62, v152
	v_mul_f32_e32 v63, v63, v152
	v_mul_f32_e32 v64, v64, v152
	v_mul_f32_e32 v65, v65, v152
	v_mul_f32_e32 v66, v66, v152
	v_mul_f32_e32 v67, v67, v152
	v_mul_f32_e32 v68, v68, v152
	v_mul_f32_e32 v69, v69, v152
	v_fma_f32 v54, v54, v0, v16
	v_fma_f32 v55, v55, v1, v17
	v_fma_f32 v56, v56, v2, v18
	v_fma_f32 v57, v57, v3, v19
	v_fma_f32 v58, v58, v4, v20
	v_fma_f32 v59, v59, v5, v21
	v_fma_f32 v60, v60, v6, v22
	v_fma_f32 v61, v61, v7, v23
	v_fma_f32 v62, v62, v8, v24
	v_fma_f32 v63, v63, v9, v25
	v_fma_f32 v64, v64, v10, v26
	v_fma_f32 v65, v65, v11, v27
	v_fma_f32 v66, v66, v12, v28
	v_fma_f32 v67, v67, v13, v29
	v_fma_f32 v68, v68, v14, v30
	v_fma_f32 v69, v69, v15, v31
	v_cvt_pk_f16_f32 v70, v54, v55
	v_cvt_pk_f16_f32 v71, v56, v57
	v_cvt_pk_f16_f32 v72, v58, v59
	v_cvt_pk_f16_f32 v73, v60, v61
	v_cvt_pk_f16_f32 v74, v62, v63
	v_cvt_pk_f16_f32 v75, v64, v65
	v_cvt_pk_f16_f32 v76, v66, v67
	v_cvt_pk_f16_f32 v77, v68, v69
	global_store_dwordx2 v151, v[70:71], s[36:37] offset:0
	global_store_dwordx2 v151, v[72:73], s[36:37] offset:512
	global_store_dwordx2 v151, v[74:75], s[36:37] offset:1024
	global_store_dwordx2 v151, v[76:77], s[36:37] offset:1536
	s_add_u32 s5, s5, 1
	s_sub_u32 s9, s5, 0x800
	s_lshr_b32 s9, s9, 13
	s_cmp_lt_u32 s5, 0x800
	s_cselect_b32 s9, 8, s9
	s_cmp_eq_u32 s9, s8
	s_cbranch_scc1 .Lr1a_nr3
	s_mov_b32 s8, s9
	s_waitcnt vmcnt(0)
	s_add_u32 s10, s9, 0
	s_mul_i32 s10, s10, 0x6000
	s_add_u32 s38, s56, s10
	s_addc_u32 s39, s57, 0
	global_load_dwordx4 v[54:57], v150, s[58:59] offset:0
	global_load_dwordx4 v[58:61], v150, s[58:59] offset:1024
	global_load_dwordx4 v[62:65], v150, s[58:59] offset:2048
	global_load_dwordx4 v[66:69], v150, s[58:59] offset:3072
	s_add_u32 s44, s38, 0x1000
	s_addc_u32 s45, s39, 0
	global_load_dwordx4 v[70:73], v150, s[44:45] offset:0
	global_load_dwordx4 v[74:77], v150, s[44:45] offset:1024
	global_load_dwordx4 v[78:81], v150, s[44:45] offset:2048
	global_load_dwordx4 v[82:85], v150, s[44:45] offset:3072
	global_load_dwordx4 v[16:19], v150, s[38:39] offset:0
	global_load_dwordx4 v[20:23], v150, s[38:39] offset:1024
	global_load_dwordx4 v[24:27], v150, s[38:39] offset:2048
	global_load_dwordx4 v[28:31], v150, s[38:39] offset:3072
	s_waitcnt vmcnt(0)
	v_add_f32_e32 v70, 1.0, v70
	v_add_f32_e32 v71, 1.0, v71
	v_add_f32_e32 v72, 1.0, v72
	v_add_f32_e32 v73, 1.0, v73
	v_add_f32_e32 v74, 1.0, v74
	v_add_f32_e32 v75, 1.0, v75
	v_add_f32_e32 v76, 1.0, v76
	v_add_f32_e32 v77, 1.0, v77
	v_add_f32_e32 v78, 1.0, v78
	v_add_f32_e32 v79, 1.0, v79
	v_add_f32_e32 v80, 1.0, v80
	v_add_f32_e32 v81, 1.0, v81
	v_add_f32_e32 v82, 1.0, v82
	v_add_f32_e32 v83, 1.0, v83
	v_add_f32_e32 v84, 1.0, v84
	v_add_f32_e32 v85, 1.0, v85
	v_mul_f32_e32 v0, v54, v70
	v_mul_f32_e32 v1, v55, v71
	v_mul_f32_e32 v2, v56, v72
	v_mul_f32_e32 v3, v57, v73
	v_mul_f32_e32 v4, v58, v74
	v_mul_f32_e32 v5, v59, v75
	v_mul_f32_e32 v6, v60, v76
	v_mul_f32_e32 v7, v61, v77
	v_mul_f32_e32 v8, v62, v78
	v_mul_f32_e32 v9, v63, v79
	v_mul_f32_e32 v10, v64, v80
	v_mul_f32_e32 v11, v65, v81
	v_mul_f32_e32 v12, v66, v82
	v_mul_f32_e32 v13, v67, v83
	v_mul_f32_e32 v14, v68, v84
	v_mul_f32_e32 v15, v69, v85
; DI void row1_phase(const Params& P, int combine_l, int norm_l, int r_begin) {
;     ...
;       const float* src = r < TC ? P.ctx + (size_t)r * D : P.x + (size_t)(r - TC) * D;
; #pragma unroll
;       for (int i = 0; i < 4; i++) xv[i] = *(const float4*)(src + i * 256 + lane * 4);
;     ...
;       float ss = 0.f;
; #pragma unroll
;       for (int i = 0; i < 4; i++) ss += xv[i].x * xv[i].x + xv[i].y * xv[i].y + xv[i].z * xv[i].z + xv[i].w * xv[i].w;
;       ss = wave_sum(ss);
;       const float rstd = rsqrtf(ss * (1.f / 1024.f) + EPS);
;       const float* g = P.norm1_g + norm_l * 1024;
;       const float* sh = P.mod + (size_t)(norm_l * 9 + n) * 6144; const float* sc = sh + 1024;
; #pragma unroll
;       for (int i = 0; i < 4; i++) {
;         int c = i * 256 + lane * 4;
;         float4 gg = *(const float4*)(g + c), s1 = *(const float4*)(sc + c), s0 = *(const float4*)(sh + c);
;         h4 o;
;         o[0] = (half_t)(xv[i].x * rstd * gg.x * (1.f + s1.x) + s0.x); o[1] = (half_t)(xv[i].y * rstd * gg.y * (1.f + s1.y) + s0.y);
;         o[2] = (half_t)(xv[i].z * rstd * gg.z * (1.f + s1.z) + s0.z); o[3] = (half_t)(xv[i].w * rstd * gg.w * (1.f + s1.w) + s0.w);
;         *(h4*)(P.hx + (size_t)r * D + c) = o;
;       }
.Lr1a_nr3:
	s_waitcnt vmcnt(16)
	v_accvgpr_read_b32 v54, a64
	v_accvgpr_read_b32 v55, a65
	v_accvgpr_read_b32 v56, a66
	v_accvgpr_read_b32 v57, a67
	v_accvgpr_read_b32 v58, a68
	v_accvgpr_read_b32 v59, a69
	v_accvgpr_read_b32 v60, a70
	v_accvgpr_read_b32 v61, a71
	v_accvgpr_read_b32 v62, a72
	v_accvgpr_read_b32 v63, a73
	v_accvgpr_read_b32 v64, a74
	v_accvgpr_read_b32 v65, a75
	v_accvgpr_read_b32 v66, a76
	v_accvgpr_read_b32 v67, a77
	v_accvgpr_read_b32 v68, a78
	v_accvgpr_read_b32 v69, a79
	s_lshl_b32 s10, s5, 12
	s_lshr_b32 s10, s10, 1
	s_add_u32 s36, s54, s10
	s_addc_u32 s37, s55, 0
	s_cmp_lt_u32 s7, 0x800
	s_cselect_b64 s[60:61], s[48:49], s[50:51]
	s_lshl_b32 s10, s7, 12
	s_add_u32 s60, s60, s10
	s_addc_u32 s61, s61, 0
	global_load_dwordx4 a[64:67], v150, s[60:61] offset:0 nt
	global_load_dwordx4 a[68:71], v150, s[60:61] offset:1024 nt
	global_load_dwordx4 a[72:75], v150, s[60:61] offset:2048 nt
	global_load_dwordx4 a[76:79], v150, s[60:61] offset:3072 nt
	s_add_u32 s7, s7, 1
	v_mul_f32_e32 v152, v54, v54
	v_mul_f32_e32 v153, v55, v55
	v_fmac_f32_e32 v152, v56, v56
	v_fmac_f32_e32 v153, v57, v57
	v_fmac_f32_e32 v152, v58, v58
	v_fmac_f32_e32 v153, v59, v59
	v_fmac_f32_e32 v152, v60, v60
	v_fmac_f32_e32 v153, v61, v61
	v_fmac_f32_e32 v152, v62, v62
	v_fmac_f32_e32 v153, v63, v63
	v_fmac_f32_e32 v152, v64, v64
	v_fmac_f32_e32 v153, v65, v65
	v_fmac_f32_e32 v152, v66, v66
	v_fmac_f32_e32 v153, v67, v67
	v_fmac_f32_e32 v152, v68, v68
	v_fmac_f32_e32 v153, v69, v69
	v_add_f32_e32 v152, v152, v153
	v_xor_b32_e32 v158, 128, v159
	ds_bpermute_b32 v153, v158, v152
	s_waitcnt lgkmcnt(0)
	v_add_f32_e32 v152, v152, v153
	v_xor_b32_e32 v158, 64, v159
	ds_bpermute_b32 v153, v158, v152
	s_waitcnt lgkmcnt(0)
	v_add_f32_e32 v152, v152, v153
	v_xor_b32_e32 v158, 32, v159
	ds_bpermute_b32 v153, v158, v152
	s_waitcnt lgkmcnt(0)
	v_add_f32_e32 v152, v152, v153
	v_xor_b32_e32 v158, 16, v159
	ds_bpermute_b32 v153, v158, v152
	s_waitcnt lgkmcnt(0)
	v_add_f32_e32 v152, v152, v153
	v_xor_b32_e32 v158, 8, v159
	ds_bpermute_b32 v153, v158, v152
	s_waitcnt lgkmcnt(0)
	v_add_f32_e32 v152, v152, v153
	v_xor_b32_e32 v158, 4, v159
	ds_bpermute_b32 v153, v158, v152
	s_waitcnt lgkmcnt(0)
	v_add_f32_e32 v152, v152, v153
	v_mov_b32_e32 v153, 0x358637bd
	v_fmamk_f32 v152, v152, 0x3a800000, v153
	v_rsq_f32_e32 v152, v152
	s_nop 1
	v_mul_f32_e32 v54, v54, v152
	v_mul_f32_e32 v55, v55, v152
	v_mul_f32_e32 v56, v56, v152
	v_mul_f32_e32 v57, v57, v152
	v_mul_f32_e32 v58, v58, v152
	v_mul_f32_e32 v59, v59, v152
	v_mul_f32_e32 v60, v60, v152
	v_mul_f32_e32 v61, v61, v152
	v_mul_f32_e32 v62, v62, v152
	v_mul_f32_e32 v63, v63, v152
	v_mul_f32_e32 v64, v64, v152
	v_mul_f32_e32 v65, v65, v152
	v_mul_f32_e32 v66, v66, v152
	v_mul_f32_e32 v67, v67, v152
	v_mul_f32_e32 v68, v68, v152
	v_mul_f32_e32 v69, v69, v152
	v_fma_f32 v54, v54, v0, v16
	v_fma_f32 v55, v55, v1, v17
	v_fma_f32 v56, v56, v2, v18
	v_fma_f32 v57, v57, v3, v19
	v_fma_f32 v58, v58, v4, v20
	v_fma_f32 v59, v59, v5, v21
	v_fma_f32 v60, v60, v6, v22
	v_fma_f32 v61, v61, v7, v23
	v_fma_f32 v62, v62, v8, v24
	v_fma_f32 v63, v63, v9, v25
	v_fma_f32 v64, v64, v10, v26
	v_fma_f32 v65, v65, v11, v27
	v_fma_f32 v66, v66, v12, v28
	v_fma_f32 v67, v67, v13, v29
	v_fma_f32 v68, v68, v14, v30
	v_fma_f32 v69, v69, v15, v31
	v_cvt_pk_f16_f32 v70, v54, v55
	v_cvt_pk_f16_f32 v71, v56, v57
	v_cvt_pk_f16_f32 v72, v58, v59
	v_cvt_pk_f16_f32 v73, v60, v61
	v_cvt_pk_f16_f32 v74, v62, v63
	v_cvt_pk_f16_f32 v75, v64, v65
	v_cvt_pk_f16_f32 v76, v66, v67
	v_cvt_pk_f16_f32 v77, v68, v69
	global_store_dwordx2 v151, v[70:71], s[36:37] offset:0
	global_store_dwordx2 v151, v[72:73], s[36:37] offset:512
	global_store_dwordx2 v151, v[74:75], s[36:37] offset:1024
	global_store_dwordx2 v151, v[76:77], s[36:37] offset:1536
	s_add_u32 s5, s5, 1
	s_sub_u32 s9, s5, 0x800
	s_lshr_b32 s9, s9, 13
	s_cmp_lt_u32 s5, 0x800
	s_cselect_b32 s9, 8, s9
	s_cmp_eq_u32 s9, s8
	s_cbranch_scc1 .Lr1a_nr4
	s_mov_b32 s8, s9
	s_waitcnt vmcnt(0)
	s_add_u32 s10, s9, 0
	s_mul_i32 s10, s10, 0x6000
	s_add_u32 s38, s56, s10
	s_addc_u32 s39, s57, 0
	global_load_dwordx4 v[54:57], v150, s[58:59] offset:0
	global_load_dwordx4 v[58:61], v150, s[58:59] offset:1024
	global_load_dwordx4 v[62:65], v150, s[58:59] offset:2048
	global_load_dwordx4 v[66:69], v150, s[58:59] offset:3072
	s_add_u32 s44, s38, 0x1000
	s_addc_u32 s45, s39, 0
	global_load_dwordx4 v[70:73], v150, s[44:45] offset:0
	global_load_dwordx4 v[74:77], v150, s[44:45] offset:1024
	global_load_dwordx4 v[78:81], v150, s[44:45] offset:2048
	global_load_dwordx4 v[82:85], v150, s[44:45] offset:3072
	global_load_dwordx4 v[16:19], v150, s[38:39] offset:0
	global_load_dwordx4 v[20:23], v150, s[38:39] offset:1024
	global_load_dwordx4 v[24:27], v150, s[38:39] offset:2048
	global_load_dwordx4 v[28:31], v150, s[38:39] offset:3072
	s_waitcnt vmcnt(0)
	v_add_f32_e32 v70, 1.0, v70
	v_add_f32_e32 v71, 1.0, v71
	v_add_f32_e32 v72, 1.0, v72
	v_add_f32_e32 v73, 1.0, v73
	v_add_f32_e32 v74, 1.0, v74
	v_add_f32_e32 v75, 1.0, v75
	v_add_f32_e32 v76, 1.0, v76
	v_add_f32_e32 v77, 1.0, v77
	v_add_f32_e32 v78, 1.0, v78
	v_add_f32_e32 v79, 1.0, v79
	v_add_f32_e32 v80, 1.0, v80
	v_add_f32_e32 v81, 1.0, v81
	v_add_f32_e32 v82, 1.0, v82
	v_add_f32_e32 v83, 1.0, v83
	v_add_f32_e32 v84, 1.0, v84
	v_add_f32_e32 v85, 1.0, v85
	v_mul_f32_e32 v0, v54, v70
	v_mul_f32_e32 v1, v55, v71
	v_mul_f32_e32 v2, v56, v72
	v_mul_f32_e32 v3, v57, v73
	v_mul_f32_e32 v4, v58, v74
	v_mul_f32_e32 v5, v59, v75
	v_mul_f32_e32 v6, v60, v76
	v_mul_f32_e32 v7, v61, v77
	v_mul_f32_e32 v8, v62, v78
	v_mul_f32_e32 v9, v63, v79
	v_mul_f32_e32 v10, v64, v80
	v_mul_f32_e32 v11, v65, v81
	v_mul_f32_e32 v12, v66, v82
	v_mul_f32_e32 v13, v67, v83
	v_mul_f32_e32 v14, v68, v84
	v_mul_f32_e32 v15, v69, v85
; DI void row1_phase(const Params& P, int combine_l, int norm_l, int r_begin) {
;     ...
;       const float* src = r < TC ? P.ctx + (size_t)r * D : P.x + (size_t)(r - TC) * D;
; #pragma unroll
;       for (int i = 0; i < 4; i++) xv[i] = *(const float4*)(src + i * 256 + lane * 4);
;     ...
;       float ss = 0.f;
; #pragma unroll
;       for (int i = 0; i < 4; i++) ss += xv[i].x * xv[i].x + xv[i].y * xv[i].y + xv[i].z * xv[i].z + xv[i].w * xv[i].w;
;       ss = wave_sum(ss);
;       const float rstd = rsqrtf(ss * (1.f / 1024.f) + EPS);
;       const float* g = P.norm1_g + norm_l * 1024;
;       const float* sh = P.mod + (size_t)(norm_l * 9 + n) * 6144; const float* sc = sh + 1024;
; #pragma unroll
;       for (int i = 0; i < 4; i++) {
;         int c = i * 256 + lane * 4;
;         float4 gg = *(const float4*)(g + c), s1 = *(const float4*)(sc + c), s0 = *(const float4*)(sh + c);
;         h4 o;
;         o[0] = (half_t)(xv[i].x * rstd * gg.x * (1.f + s1.x) + s0.x); o[1] = (half_t)(xv[i].y * rstd * gg.y * (1.f + s1.y) + s0.y);
;         o[2] = (half_t)(xv[i].z * rstd * gg.z * (1.f + s1.z) + s0.z); o[3] = (half_t)(xv[i].w * rstd * gg.w * (1.f + s1.w) + s0.w);
;         *(h4*)(P.hx + (size_t)r * D + c) = o;
;       }
;     ...
; #pragma unroll 1
;   for (int r = r_lo; r < r_hi; r += 4) {
.Lr1a_nr4:
	s_waitcnt vmcnt(16)
	v_accvgpr_read_b32 v54, a96
	v_accvgpr_read_b32 v55, a97
	v_accvgpr_read_b32 v56, a98
	v_accvgpr_read_b32 v57, a99
	v_accvgpr_read_b32 v58, a100
	v_accvgpr_read_b32 v59, a101
	v_accvgpr_read_b32 v60, a102
	v_accvgpr_read_b32 v61, a103
	v_accvgpr_read_b32 v62, a104
	v_accvgpr_read_b32 v63, a105
	v_accvgpr_read_b32 v64, a106
	v_accvgpr_read_b32 v65, a107
	v_accvgpr_read_b32 v66, a108
	v_accvgpr_read_b32 v67, a109
	v_accvgpr_read_b32 v68, a110
	v_accvgpr_read_b32 v69, a111
	s_lshl_b32 s10, s5, 12
	s_lshr_b32 s10, s10, 1
	s_add_u32 s36, s54, s10
	s_addc_u32 s37, s55, 0
	s_cmp_lt_u32 s7, 0x800
	s_cselect_b64 s[60:61], s[48:49], s[50:51]
	s_lshl_b32 s10, s7, 12
	s_add_u32 s60, s60, s10
	s_addc_u32 s61, s61, 0
	global_load_dwordx4 a[96:99], v150, s[60:61] offset:0 nt
	global_load_dwordx4 a[100:103], v150, s[60:61] offset:1024 nt
	global_load_dwordx4 a[104:107], v150, s[60:61] offset:2048 nt
	global_load_dwordx4 a[108:111], v150, s[60:61] offset:3072 nt
	s_add_u32 s7, s7, 1
	v_mul_f32_e32 v152, v54, v54
	v_mul_f32_e32 v153, v55, v55
	v_fmac_f32_e32 v152, v56, v56
	v_fmac_f32_e32 v153, v57, v57
	v_fmac_f32_e32 v152, v58, v58
	v_fmac_f32_e32 v153, v59, v59
	v_fmac_f32_e32 v152, v60, v60
	v_fmac_f32_e32 v153, v61, v61
	v_fmac_f32_e32 v152, v62, v62
	v_fmac_f32_e32 v153, v63, v63
	v_fmac_f32_e32 v152, v64, v64
	v_fmac_f32_e32 v153, v65, v65
	v_fmac_f32_e32 v152, v66, v66
	v_fmac_f32_e32 v153, v67, v67
	v_fmac_f32_e32 v152, v68, v68
	v_fmac_f32_e32 v153, v69, v69
	v_add_f32_e32 v152, v152, v153
	v_xor_b32_e32 v158, 128, v159
	ds_bpermute_b32 v153, v158, v152
	s_waitcnt lgkmcnt(0)
	v_add_f32_e32 v152, v152, v153
	v_xor_b32_e32 v158, 64, v159
	ds_bpermute_b32 v153, v158, v152
	s_waitcnt lgkmcnt(0)
	v_add_f32_e32 v152, v152, v153
	v_xor_b32_e32 v158, 32, v159
	ds_bpermute_b32 v153, v158, v152
	s_waitcnt lgkmcnt(0)
	v_add_f32_e32 v152, v152, v153
	v_xor_b32_e32 v158, 16, v159
	ds_bpermute_b32 v153, v158, v152
	s_waitcnt lgkmcnt(0)
	v_add_f32_e32 v152, v152, v153
	v_xor_b32_e32 v158, 8, v159
	ds_bpermute_b32 v153, v158, v152
	s_waitcnt lgkmcnt(0)
	v_add_f32_e32 v152, v152, v153
	v_xor_b32_e32 v158, 4, v159
	ds_bpermute_b32 v153, v158, v152
	s_waitcnt lgkmcnt(0)
	v_add_f32_e32 v152, v152, v153
	v_mov_b32_e32 v153, 0x358637bd
	v_fmamk_f32 v152, v152, 0x3a800000, v153
	v_rsq_f32_e32 v152, v152
	s_nop 1
	v_mul_f32_e32 v54, v54, v152
	v_mul_f32_e32 v55, v55, v152
	v_mul_f32_e32 v56, v56, v152
	v_mul_f32_e32 v57, v57, v152
	v_mul_f32_e32 v58, v58, v152
	v_mul_f32_e32 v59, v59, v152
	v_mul_f32_e32 v60, v60, v152
	v_mul_f32_e32 v61, v61, v152
	v_mul_f32_e32 v62, v62, v152
	v_mul_f32_e32 v63, v63, v152
	v_mul_f32_e32 v64, v64, v152
	v_mul_f32_e32 v65, v65, v152
	v_mul_f32_e32 v66, v66, v152
	v_mul_f32_e32 v67, v67, v152
	v_mul_f32_e32 v68, v68, v152
	v_mul_f32_e32 v69, v69, v152
	v_fma_f32 v54, v54, v0, v16
	v_fma_f32 v55, v55, v1, v17
	v_fma_f32 v56, v56, v2, v18
	v_fma_f32 v57, v57, v3, v19
	v_fma_f32 v58, v58, v4, v20
	v_fma_f32 v59, v59, v5, v21
	v_fma_f32 v60, v60, v6, v22
	v_fma_f32 v61, v61, v7, v23
	v_fma_f32 v62, v62, v8, v24
	v_fma_f32 v63, v63, v9, v25
	v_fma_f32 v64, v64, v10, v26
	v_fma_f32 v65, v65, v11, v27
	v_fma_f32 v66, v66, v12, v28
	v_fma_f32 v67, v67, v13, v29
	v_fma_f32 v68, v68, v14, v30
	v_fma_f32 v69, v69, v15, v31
	v_cvt_pk_f16_f32 v70, v54, v55
	v_cvt_pk_f16_f32 v71, v56, v57
	v_cvt_pk_f16_f32 v72, v58, v59
	v_cvt_pk_f16_f32 v73, v60, v61
	v_cvt_pk_f16_f32 v74, v62, v63
	v_cvt_pk_f16_f32 v75, v64, v65
	v_cvt_pk_f16_f32 v76, v66, v67
	v_cvt_pk_f16_f32 v77, v68, v69
	global_store_dwordx2 v151, v[70:71], s[36:37] offset:0
	global_store_dwordx2 v151, v[72:73], s[36:37] offset:512
	global_store_dwordx2 v151, v[74:75], s[36:37] offset:1024
	global_store_dwordx2 v151, v[76:77], s[36:37] offset:1536
	s_add_u32 s5, s5, 1
	s_sub_u32 s98, s98, 1
	s_cmp_lg_u32 s98, 0
	s_cbranch_scc1 .Lr1a_loop
	s_sub_u32 s9, s5, 0x800
	s_lshr_b32 s9, s9, 13
	s_cmp_lt_u32 s5, 0x800
	s_cselect_b32 s9, 8, s9
	s_cmp_eq_u32 s9, s8
	s_cbranch_scc1 .Lr1a_nr5
	s_mov_b32 s8, s9
	s_waitcnt vmcnt(0)
	s_add_u32 s10, s9, 0
	s_mul_i32 s10, s10, 0x6000
	s_add_u32 s38, s56, s10
	s_addc_u32 s39, s57, 0
	global_load_dwordx4 v[54:57], v150, s[58:59] offset:0
	global_load_dwordx4 v[58:61], v150, s[58:59] offset:1024
	global_load_dwordx4 v[62:65], v150, s[58:59] offset:2048
	global_load_dwordx4 v[66:69], v150, s[58:59] offset:3072
	s_add_u32 s44, s38, 0x1000
	s_addc_u32 s45, s39, 0
	global_load_dwordx4 v[70:73], v150, s[44:45] offset:0
	global_load_dwordx4 v[74:77], v150, s[44:45] offset:1024
	global_load_dwordx4 v[78:81], v150, s[44:45] offset:2048
	global_load_dwordx4 v[82:85], v150, s[44:45] offset:3072
	global_load_dwordx4 v[16:19], v150, s[38:39] offset:0
	global_load_dwordx4 v[20:23], v150, s[38:39] offset:1024
	global_load_dwordx4 v[24:27], v150, s[38:39] offset:2048
	global_load_dwordx4 v[28:31], v150, s[38:39] offset:3072
	s_waitcnt vmcnt(0)
	v_add_f32_e32 v70, 1.0, v70
	v_add_f32_e32 v71, 1.0, v71
	v_add_f32_e32 v72, 1.0, v72
	v_add_f32_e32 v73, 1.0, v73
	v_add_f32_e32 v74, 1.0, v74
	v_add_f32_e32 v75, 1.0, v75
	v_add_f32_e32 v76, 1.0, v76
	v_add_f32_e32 v77, 1.0, v77
	v_add_f32_e32 v78, 1.0, v78
	v_add_f32_e32 v79, 1.0, v79
	v_add_f32_e32 v80, 1.0, v80
	v_add_f32_e32 v81, 1.0, v81
	v_add_f32_e32 v82, 1.0, v82
	v_add_f32_e32 v83, 1.0, v83
	v_add_f32_e32 v84, 1.0, v84
	v_add_f32_e32 v85, 1.0, v85
	v_mul_f32_e32 v0, v54, v70
	v_mul_f32_e32 v1, v55, v71
	v_mul_f32_e32 v2, v56, v72
	v_mul_f32_e32 v3, v57, v73
	v_mul_f32_e32 v4, v58, v74
	v_mul_f32_e32 v5, v59, v75
	v_mul_f32_e32 v6, v60, v76
	v_mul_f32_e32 v7, v61, v77
	v_mul_f32_e32 v8, v62, v78
	v_mul_f32_e32 v9, v63, v79
	v_mul_f32_e32 v10, v64, v80
	v_mul_f32_e32 v11, v65, v81
	v_mul_f32_e32 v12, v66, v82
	v_mul_f32_e32 v13, v67, v83
	v_mul_f32_e32 v14, v68, v84
	v_mul_f32_e32 v15, v69, v85

; DI f4 mfma16(h8 a, h8 b, f4 c) { return __builtin_amdgcn_mfma_f32_16x16x32_f16(a, b, c, 0, 0, 0); }
; DI void row2_phase(const Params& P, int l, int r_begin, char* smem) {
;     ...
;     for (int kk = 0; kk < 32; kk++) {
;       const int k0 = kk * 32;
;       float x[8], g[8], s1[8], s0[8];
;       *(float4*)&x[0] = *(const float4*)(xm + k0); *(float4*)&x[4] = *(const float4*)(xm + k0 + 4);
;       *(float4*)&g[0] = *(const float4*)(gam + fq * 8 + k0); *(float4*)&g[4] = *(const float4*)(gam + fq * 8 + k0 + 4);
;       *(float4*)&s1[0] = *(const float4*)(sc + k0); *(float4*)&s1[4] = *(const float4*)(sc + k0 + 4);
;       *(float4*)&s0[0] = *(const float4*)(sh + k0); *(float4*)&s0[4] = *(const float4*)(sh + k0 + 4);
;       h8 hi, lo;
; #pragma unroll
;       for (int i = 0; i < 8; i++) {
;         float v = x[i] * rstd * g[i] * (1.f + s1[i]) + s0[i];
;         hi[i] = (half_t)v; lo[i] = (half_t)(v - (float)hi[i]);
;       }
;       *(h8*)(hxo + k0) = hi;
; #pragma unroll
;       for (int n3 = 0; n3 < 3; n3++) {
;         h8 bh = *(const h8*)(Whi + (size_t)(n3 * 16 + fr) * 1024 + k0 + fq * 8);
;         h8 bl = *(const h8*)(Wlo + (size_t)(n3 * 16 + fr) * 1024 + k0 + fq * 8);
;         acc[n3] = mfma16(hi, bh, acc[n3]); acc[n3] = mfma16(lo, bh, acc[n3]); acc[n3] = mfma16(hi, bl, acc[n3]);
;       }
;     }
.Lr2_tabok:
	global_load_dwordx4 a[16:19], v[22:23], off offset:0 nt
	global_load_dwordx4 a[20:23], v[22:23], off offset:16 nt
	global_load_dwordx4 a[24:27], v[22:23], off offset:128 nt
	global_load_dwordx4 a[28:31], v[22:23], off offset:144 nt
	global_load_dwordx4 a[32:35], v[22:23], off offset:256 nt
	global_load_dwordx4 a[36:39], v[22:23], off offset:272 nt
	global_load_dwordx4 a[40:43], v[22:23], off offset:384 nt
	global_load_dwordx4 a[44:47], v[22:23], off offset:400 nt
	global_load_dwordx4 a[48:51], v[22:23], off offset:512 nt
	global_load_dwordx4 a[52:55], v[22:23], off offset:528 nt
	global_load_dwordx4 a[56:59], v[22:23], off offset:640 nt
	global_load_dwordx4 a[60:63], v[22:23], off offset:656 nt
	global_load_dwordx4 a[64:67], v[22:23], off offset:768 nt
	global_load_dwordx4 a[68:71], v[22:23], off offset:784 nt
	global_load_dwordx4 a[72:75], v[22:23], off offset:896 nt
	global_load_dwordx4 a[76:79], v[22:23], off offset:912 nt
	global_load_dwordx4 a[180:183], v[22:23], off offset:1024 nt
	global_load_dwordx4 a[184:187], v[22:23], off offset:1040 nt
	global_load_dwordx4 a[196:199], v[22:23], off offset:1152 nt
	global_load_dwordx4 a[200:203], v[22:23], off offset:1168 nt
	global_load_dwordx4 a[80:83], v[90:91], off offset:0
	global_load_dwordx4 a[84:87], v[92:93], off offset:0
	global_load_dwordx4 a[88:91], v[94:95], off offset:0
	global_load_dwordx4 a[92:95], v[96:97], off offset:0
	global_load_dwordx4 a[96:99], v[98:99], off offset:0
	global_load_dwordx4 a[100:103], v[100:101], off offset:0
	global_load_dwordx4 a[104:107], v[90:91], off offset:64
	global_load_dwordx4 a[108:111], v[92:93], off offset:64
	global_load_dwordx4 a[112:115], v[94:95], off offset:64
	global_load_dwordx4 a[116:119], v[96:97], off offset:64
	global_load_dwordx4 a[120:123], v[98:99], off offset:64
	global_load_dwordx4 a[124:127], v[100:101], off offset:64
	global_load_dwordx4 a[128:131], v[90:91], off offset:128
	global_load_dwordx4 a[132:135], v[92:93], off offset:128
	global_load_dwordx4 a[136:139], v[94:95], off offset:128
	global_load_dwordx4 a[140:143], v[96:97], off offset:128
	global_load_dwordx4 a[144:147], v[98:99], off offset:128
	global_load_dwordx4 a[148:151], v[100:101], off offset:128
	global_load_dwordx4 a[152:155], v[90:91], off offset:192
	global_load_dwordx4 a[156:159], v[92:93], off offset:192
	global_load_dwordx4 a[160:163], v[94:95], off offset:192
	global_load_dwordx4 a[164:167], v[96:97], off offset:192
	global_load_dwordx4 a[168:171], v[98:99], off offset:192
	global_load_dwordx4 a[172:175], v[100:101], off offset:192
	global_load_dwordx4 a[204:207], v[90:91], off offset:256
	global_load_dwordx4 a[208:211], v[92:93], off offset:256
	global_load_dwordx4 a[212:215], v[94:95], off offset:256
	global_load_dwordx4 a[216:219], v[96:97], off offset:256
	global_load_dwordx4 a[220:223], v[98:99], off offset:256
	global_load_dwordx4 a[224:227], v[100:101], off offset:256
	global_load_dwordx4 a[228:231], v[90:91], off offset:320
	global_load_dwordx4 a[232:235], v[92:93], off offset:320
	global_load_dwordx4 a[236:239], v[94:95], off offset:320
	global_load_dwordx4 a[240:243], v[96:97], off offset:320
	global_load_dwordx4 a[244:247], v[98:99], off offset:320
	global_load_dwordx4 a[248:251], v[100:101], off offset:320
	ds_read_b128 v[32:35], v102 offset:0
	ds_read_b128 v[36:39], v102 offset:16
	ds_read_b128 v[40:43], v102 offset:4096
	ds_read_b128 v[44:47], v102 offset:4112
	ds_read_b128 v[58:61], v102 offset:8192
	ds_read_b128 v[62:65], v102 offset:8208
	s_waitcnt vmcnt(54)
	v_accvgpr_read_b32 v0, a16
	v_accvgpr_read_b32 v1, a17
	v_accvgpr_read_b32 v2, a18
	v_accvgpr_read_b32 v3, a19
	v_accvgpr_read_b32 v4, a20
	v_accvgpr_read_b32 v5, a21
	v_accvgpr_read_b32 v6, a22
	v_accvgpr_read_b32 v7, a23
	global_load_dwordx4 a[16:19], v[22:23], off offset:1280 nt
	global_load_dwordx4 a[20:23], v[22:23], off offset:1296 nt
	v_pk_mul_f32 v[0:1], v[28:29], v[0:1]
	v_pk_mul_f32 v[2:3], v[28:29], v[2:3]
	v_pk_mul_f32 v[4:5], v[28:29], v[4:5]
	v_pk_mul_f32 v[6:7], v[28:29], v[6:7]
	s_waitcnt lgkmcnt(0)
	v_pk_mul_f32 v[0:1], v[0:1], v[32:33]
	v_pk_mul_f32 v[2:3], v[2:3], v[34:35]
	v_pk_mul_f32 v[4:5], v[4:5], v[36:37]
	v_pk_mul_f32 v[6:7], v[6:7], v[38:39]
	v_pk_add_f32 v[40:41], v[40:41], 1.0 op_sel_hi:[1,0]
	v_pk_add_f32 v[42:43], v[42:43], 1.0 op_sel_hi:[1,0]
	v_pk_add_f32 v[44:45], v[44:45], 1.0 op_sel_hi:[1,0]
	v_pk_add_f32 v[46:47], v[46:47], 1.0 op_sel_hi:[1,0]
	v_pk_fma_f32 v[0:1], v[0:1], v[40:41], v[58:59]
	v_pk_fma_f32 v[2:3], v[2:3], v[42:43], v[60:61]
	v_pk_fma_f32 v[4:5], v[4:5], v[44:45], v[62:63]
	v_pk_fma_f32 v[6:7], v[6:7], v[46:47], v[64:65]
	ds_read_b128 v[32:35], v102 offset:128
	ds_read_b128 v[36:39], v102 offset:144
	ds_read_b128 v[40:43], v102 offset:4224
	ds_read_b128 v[44:47], v102 offset:4240
	ds_read_b128 v[58:61], v102 offset:8320
	ds_read_b128 v[62:65], v102 offset:8336
	v_cvt_pk_f16_f32 v74, v0, v1
	v_cvt_pk_f16_f32 v75, v2, v3
	v_cvt_pk_f16_f32 v76, v4, v5
	v_cvt_pk_f16_f32 v77, v6, v7
	v_cvt_f32_f16_e32 v66, v74
	v_cvt_f32_f16_sdwa v67, v74 dst_sel:DWORD dst_unused:UNUSED_PAD src0_sel:WORD_1
	v_cvt_f32_f16_e32 v68, v75
	v_cvt_f32_f16_sdwa v69, v75 dst_sel:DWORD dst_unused:UNUSED_PAD src0_sel:WORD_1
	v_cvt_f32_f16_e32 v70, v76
	v_cvt_f32_f16_sdwa v71, v76 dst_sel:DWORD dst_unused:UNUSED_PAD src0_sel:WORD_1
	v_cvt_f32_f16_e32 v72, v77
	v_cvt_f32_f16_sdwa v73, v77 dst_sel:DWORD dst_unused:UNUSED_PAD src0_sel:WORD_1
	v_pk_add_f32 v[0:1], v[0:1], v[66:67] neg_lo:[0,1] neg_hi:[0,1]
	v_pk_add_f32 v[2:3], v[2:3], v[68:69] neg_lo:[0,1] neg_hi:[0,1]
	v_pk_add_f32 v[4:5], v[4:5], v[70:71] neg_lo:[0,1] neg_hi:[0,1]
	v_pk_add_f32 v[6:7], v[6:7], v[72:73] neg_lo:[0,1] neg_hi:[0,1]
	s_nop 0
	v_cvt_pk_f16_f32 v78, v0, v1
	v_cvt_pk_f16_f32 v79, v2, v3
	v_cvt_pk_f16_f32 v80, v4, v5
	v_cvt_pk_f16_f32 v81, v6, v7
	global_store_dwordx4 v[88:89], v[74:77], off offset:0
	s_waitcnt vmcnt(33)
; DI f4 mfma16(h8 a, h8 b, f4 c) { return __builtin_amdgcn_mfma_f32_16x16x32_f16(a, b, c, 0, 0, 0); }
; DI void row2_phase(const Params& P, int l, int r_begin, char* smem) {
;     ...
;     for (int kk = 0; kk < 32; kk++) {
;       const int k0 = kk * 32;
;       float x[8], g[8], s1[8], s0[8];
;       *(float4*)&x[0] = *(const float4*)(xm + k0); *(float4*)&x[4] = *(const float4*)(xm + k0 + 4);
;       *(float4*)&g[0] = *(const float4*)(gam + fq * 8 + k0); *(float4*)&g[4] = *(const float4*)(gam + fq * 8 + k0 + 4);
;       *(float4*)&s1[0] = *(const float4*)(sc + k0); *(float4*)&s1[4] = *(const float4*)(sc + k0 + 4);
;       *(float4*)&s0[0] = *(const float4*)(sh + k0); *(float4*)&s0[4] = *(const float4*)(sh + k0 + 4);
;       h8 hi, lo;
; #pragma unroll
;       for (int i = 0; i < 8; i++) {
;         float v = x[i] * rstd * g[i] * (1.f + s1[i]) + s0[i];
;         hi[i] = (half_t)v; lo[i] = (half_t)(v - (float)hi[i]);
;       }
;       *(h8*)(hxo + k0) = hi;
; #pragma unroll
;       for (int n3 = 0; n3 < 3; n3++) {
;         h8 bh = *(const h8*)(Whi + (size_t)(n3 * 16 + fr) * 1024 + k0 + fq * 8);
;         h8 bl = *(const h8*)(Wlo + (size_t)(n3 * 16 + fr) * 1024 + k0 + fq * 8);
;         acc[n3] = mfma16(hi, bh, acc[n3]); acc[n3] = mfma16(lo, bh, acc[n3]); acc[n3] = mfma16(hi, bl, acc[n3]);
;       }
;     }
	v_mfma_f32_16x16x32_f16 a[8:11], v[74:77], a[80:83], a[8:11]
	v_mfma_f32_16x16x32_f16 a[8:11], v[78:81], a[80:83], a[8:11]
	v_mfma_f32_16x16x32_f16 a[8:11], v[74:77], a[84:87], a[8:11]
	v_mfma_f32_16x16x32_f16 a[4:7], v[74:77], a[88:91], a[4:7]
	v_mfma_f32_16x16x32_f16 a[4:7], v[78:81], a[88:91], a[4:7]
	v_mfma_f32_16x16x32_f16 a[4:7], v[74:77], a[92:95], a[4:7]
	v_mfma_f32_16x16x32_f16 a[0:3], v[74:77], a[96:99], a[0:3]
	v_mfma_f32_16x16x32_f16 a[0:3], v[78:81], a[96:99], a[0:3]
	v_mfma_f32_16x16x32_f16 a[0:3], v[74:77], a[100:103], a[0:3]
	global_load_dwordx4 a[80:83], v[90:91], off offset:384
	global_load_dwordx4 a[84:87], v[92:93], off offset:384
	global_load_dwordx4 a[88:91], v[94:95], off offset:384
	global_load_dwordx4 a[92:95], v[96:97], off offset:384
	global_load_dwordx4 a[96:99], v[98:99], off offset:384
	global_load_dwordx4 a[100:103], v[100:101], off offset:384
	s_waitcnt vmcnt(39)
	v_accvgpr_read_b32 v0, a24
	v_accvgpr_read_b32 v1, a25
	v_accvgpr_read_b32 v2, a26
	v_accvgpr_read_b32 v3, a27
	v_accvgpr_read_b32 v4, a28
	v_accvgpr_read_b32 v5, a29
	v_accvgpr_read_b32 v6, a30
	v_accvgpr_read_b32 v7, a31
	global_load_dwordx4 a[24:27], v[22:23], off offset:1408 nt
	global_load_dwordx4 a[28:31], v[22:23], off offset:1424 nt
	v_pk_mul_f32 v[0:1], v[28:29], v[0:1]
	v_pk_mul_f32 v[2:3], v[28:29], v[2:3]
	v_pk_mul_f32 v[4:5], v[28:29], v[4:5]
	v_pk_mul_f32 v[6:7], v[28:29], v[6:7]
	s_waitcnt lgkmcnt(0)
	v_pk_mul_f32 v[0:1], v[0:1], v[32:33]
	v_pk_mul_f32 v[2:3], v[2:3], v[34:35]
	v_pk_mul_f32 v[4:5], v[4:5], v[36:37]
	v_pk_mul_f32 v[6:7], v[6:7], v[38:39]
	v_pk_add_f32 v[40:41], v[40:41], 1.0 op_sel_hi:[1,0]
	v_pk_add_f32 v[42:43], v[42:43], 1.0 op_sel_hi:[1,0]
	v_pk_add_f32 v[44:45], v[44:45], 1.0 op_sel_hi:[1,0]
	v_pk_add_f32 v[46:47], v[46:47], 1.0 op_sel_hi:[1,0]
	v_pk_fma_f32 v[0:1], v[0:1], v[40:41], v[58:59]
	v_pk_fma_f32 v[2:3], v[2:3], v[42:43], v[60:61]
	v_pk_fma_f32 v[4:5], v[4:5], v[44:45], v[62:63]
	v_pk_fma_f32 v[6:7], v[6:7], v[46:47], v[64:65]
	ds_read_b128 v[32:35], v102 offset:256
	ds_read_b128 v[36:39], v102 offset:272
	ds_read_b128 v[40:43], v102 offset:4352
	ds_read_b128 v[44:47], v102 offset:4368
	ds_read_b128 v[58:61], v102 offset:8448
	ds_read_b128 v[62:65], v102 offset:8464
	v_cvt_pk_f16_f32 v74, v0, v1
	v_cvt_pk_f16_f32 v75, v2, v3
	v_cvt_pk_f16_f32 v76, v4, v5
	v_cvt_pk_f16_f32 v77, v6, v7
	v_cvt_f32_f16_e32 v66, v74
	v_cvt_f32_f16_sdwa v67, v74 dst_sel:DWORD dst_unused:UNUSED_PAD src0_sel:WORD_1
	v_cvt_f32_f16_e32 v68, v75
	v_cvt_f32_f16_sdwa v69, v75 dst_sel:DWORD dst_unused:UNUSED_PAD src0_sel:WORD_1
	v_cvt_f32_f16_e32 v70, v76
	v_cvt_f32_f16_sdwa v71, v76 dst_sel:DWORD dst_unused:UNUSED_PAD src0_sel:WORD_1
	v_cvt_f32_f16_e32 v72, v77
	v_cvt_f32_f16_sdwa v73, v77 dst_sel:DWORD dst_unused:UNUSED_PAD src0_sel:WORD_1
	v_pk_add_f32 v[0:1], v[0:1], v[66:67] neg_lo:[0,1] neg_hi:[0,1]
	v_pk_add_f32 v[2:3], v[2:3], v[68:69] neg_lo:[0,1] neg_hi:[0,1]
	v_pk_add_f32 v[4:5], v[4:5], v[70:71] neg_lo:[0,1] neg_hi:[0,1]
	v_pk_add_f32 v[6:7], v[6:7], v[72:73] neg_lo:[0,1] neg_hi:[0,1]
	s_nop 0
	v_cvt_pk_f16_f32 v78, v0, v1
	v_cvt_pk_f16_f32 v79, v2, v3
	v_cvt_pk_f16_f32 v80, v4, v5
	v_cvt_pk_f16_f32 v81, v6, v7
	global_store_dwordx4 v[88:89], v[74:77], off offset:64
	s_waitcnt vmcnt(36)
	v_mfma_f32_16x16x32_f16 a[8:11], v[74:77], a[104:107], a[8:11]
	v_mfma_f32_16x16x32_f16 a[8:11], v[78:81], a[104:107], a[8:11]
	v_mfma_f32_16x16x32_f16 a[8:11], v[74:77], a[108:111], a[8:11]
	v_mfma_f32_16x16x32_f16 a[4:7], v[74:77], a[112:115], a[4:7]
	v_mfma_f32_16x16x32_f16 a[4:7], v[78:81], a[112:115], a[4:7]
	v_mfma_f32_16x16x32_f16 a[4:7], v[74:77], a[116:119], a[4:7]
	v_mfma_f32_16x16x32_f16 a[0:3], v[74:77], a[120:123], a[0:3]
	v_mfma_f32_16x16x32_f16 a[0:3], v[78:81], a[120:123], a[0:3]
	v_mfma_f32_16x16x32_f16 a[0:3], v[74:77], a[124:127], a[0:3]
	global_load_dwordx4 a[104:107], v[90:91], off offset:448
	global_load_dwordx4 a[108:111], v[92:93], off offset:448
	global_load_dwordx4 a[112:115], v[94:95], off offset:448
	global_load_dwordx4 a[116:119], v[96:97], off offset:448
	global_load_dwordx4 a[120:123], v[98:99], off offset:448
	global_load_dwordx4 a[124:127], v[100:101], off offset:448
	s_waitcnt vmcnt(42)
	v_accvgpr_read_b32 v0, a32
	v_accvgpr_read_b32 v1, a33
	v_accvgpr_read_b32 v2, a34
	v_accvgpr_read_b32 v3, a35
	v_accvgpr_read_b32 v4, a36
	v_accvgpr_read_b32 v5, a37
	v_accvgpr_read_b32 v6, a38
	v_accvgpr_read_b32 v7, a39
	global_load_dwordx4 a[32:35], v[22:23], off offset:1536 nt
	global_load_dwordx4 a[36:39], v[22:23], off offset:1552 nt
	v_pk_mul_f32 v[0:1], v[28:29], v[0:1]
	v_pk_mul_f32 v[2:3], v[28:29], v[2:3]
	v_pk_mul_f32 v[4:5], v[28:29], v[4:5]
	v_pk_mul_f32 v[6:7], v[28:29], v[6:7]
	s_waitcnt lgkmcnt(0)
	v_pk_mul_f32 v[0:1], v[0:1], v[32:33]
	v_pk_mul_f32 v[2:3], v[2:3], v[34:35]
	v_pk_mul_f32 v[4:5], v[4:5], v[36:37]
	v_pk_mul_f32 v[6:7], v[6:7], v[38:39]
	v_pk_add_f32 v[40:41], v[40:41], 1.0 op_sel_hi:[1,0]
	v_pk_add_f32 v[42:43], v[42:43], 1.0 op_sel_hi:[1,0]
	v_pk_add_f32 v[44:45], v[44:45], 1.0 op_sel_hi:[1,0]
	v_pk_add_f32 v[46:47], v[46:47], 1.0 op_sel_hi:[1,0]
	v_pk_fma_f32 v[0:1], v[0:1], v[40:41], v[58:59]
	v_pk_fma_f32 v[2:3], v[2:3], v[42:43], v[60:61]
	v_pk_fma_f32 v[4:5], v[4:5], v[44:45], v[62:63]
	v_pk_fma_f32 v[6:7], v[6:7], v[46:47], v[64:65]
	ds_read_b128 v[32:35], v102 offset:384
	ds_read_b128 v[36:39], v102 offset:400
	ds_read_b128 v[40:43], v102 offset:4480
	ds_read_b128 v[44:47], v102 offset:4496
	ds_read_b128 v[58:61], v102 offset:8576
	ds_read_b128 v[62:65], v102 offset:8592
	v_cvt_pk_f16_f32 v74, v0, v1
	v_cvt_pk_f16_f32 v75, v2, v3
	v_cvt_pk_f16_f32 v76, v4, v5
	v_cvt_pk_f16_f32 v77, v6, v7
	v_cvt_f32_f16_e32 v66, v74
	v_cvt_f32_f16_sdwa v67, v74 dst_sel:DWORD dst_unused:UNUSED_PAD src0_sel:WORD_1
	v_cvt_f32_f16_e32 v68, v75
	v_cvt_f32_f16_sdwa v69, v75 dst_sel:DWORD dst_unused:UNUSED_PAD src0_sel:WORD_1
	v_cvt_f32_f16_e32 v70, v76
	v_cvt_f32_f16_sdwa v71, v76 dst_sel:DWORD dst_unused:UNUSED_PAD src0_sel:WORD_1
	v_cvt_f32_f16_e32 v72, v77
	v_cvt_f32_f16_sdwa v73, v77 dst_sel:DWORD dst_unused:UNUSED_PAD src0_sel:WORD_1
	v_pk_add_f32 v[0:1], v[0:1], v[66:67] neg_lo:[0,1] neg_hi:[0,1]
	v_pk_add_f32 v[2:3], v[2:3], v[68:69] neg_lo:[0,1] neg_hi:[0,1]
	v_pk_add_f32 v[4:5], v[4:5], v[70:71] neg_lo:[0,1] neg_hi:[0,1]
	v_pk_add_f32 v[6:7], v[6:7], v[72:73] neg_lo:[0,1] neg_hi:[0,1]
	s_nop 0
	v_cvt_pk_f16_f32 v78, v0, v1
	v_cvt_pk_f16_f32 v79, v2, v3
	v_cvt_pk_f16_f32 v80, v4, v5
	v_cvt_pk_f16_f32 v81, v6, v7
	global_store_dwordx4 v[88:89], v[74:77], off offset:128
	s_waitcnt vmcnt(39)
; DI f4 mfma16(h8 a, h8 b, f4 c) { return __builtin_amdgcn_mfma_f32_16x16x32_f16(a, b, c, 0, 0, 0); }
; DI void row2_phase(const Params& P, int l, int r_begin, char* smem) {
;     ...
;     for (int kk = 0; kk < 32; kk++) {
;       const int k0 = kk * 32;
;       float x[8], g[8], s1[8], s0[8];
;       *(float4*)&x[0] = *(const float4*)(xm + k0); *(float4*)&x[4] = *(const float4*)(xm + k0 + 4);
;       *(float4*)&g[0] = *(const float4*)(gam + fq * 8 + k0); *(float4*)&g[4] = *(const float4*)(gam + fq * 8 + k0 + 4);
;       *(float4*)&s1[0] = *(const float4*)(sc + k0); *(float4*)&s1[4] = *(const float4*)(sc + k0 + 4);
;       *(float4*)&s0[0] = *(const float4*)(sh + k0); *(float4*)&s0[4] = *(const float4*)(sh + k0 + 4);
;       h8 hi, lo;
; #pragma unroll
;       for (int i = 0; i < 8; i++) {
;         float v = x[i] * rstd * g[i] * (1.f + s1[i]) + s0[i];
;         hi[i] = (half_t)v; lo[i] = (half_t)(v - (float)hi[i]);
;       }
;       *(h8*)(hxo + k0) = hi;
; #pragma unroll
;       for (int n3 = 0; n3 < 3; n3++) {
;         h8 bh = *(const h8*)(Whi + (size_t)(n3 * 16 + fr) * 1024 + k0 + fq * 8);
;         h8 bl = *(const h8*)(Wlo + (size_t)(n3 * 16 + fr) * 1024 + k0 + fq * 8);
;         acc[n3] = mfma16(hi, bh, acc[n3]); acc[n3] = mfma16(lo, bh, acc[n3]); acc[n3] = mfma16(hi, bl, acc[n3]);
;       }
;     }
	v_mfma_f32_16x16x32_f16 a[8:11], v[74:77], a[128:131], a[8:11]
	v_mfma_f32_16x16x32_f16 a[8:11], v[78:81], a[128:131], a[8:11]
	v_mfma_f32_16x16x32_f16 a[8:11], v[74:77], a[132:135], a[8:11]
	v_mfma_f32_16x16x32_f16 a[4:7], v[74:77], a[136:139], a[4:7]
	v_mfma_f32_16x16x32_f16 a[4:7], v[78:81], a[136:139], a[4:7]
	v_mfma_f32_16x16x32_f16 a[4:7], v[74:77], a[140:143], a[4:7]
	v_mfma_f32_16x16x32_f16 a[0:3], v[74:77], a[144:147], a[0:3]
	v_mfma_f32_16x16x32_f16 a[0:3], v[78:81], a[144:147], a[0:3]
	v_mfma_f32_16x16x32_f16 a[0:3], v[74:77], a[148:151], a[0:3]
	global_load_dwordx4 a[128:131], v[90:91], off offset:512
	global_load_dwordx4 a[132:135], v[92:93], off offset:512
	global_load_dwordx4 a[136:139], v[94:95], off offset:512
	global_load_dwordx4 a[140:143], v[96:97], off offset:512
	global_load_dwordx4 a[144:147], v[98:99], off offset:512
	global_load_dwordx4 a[148:151], v[100:101], off offset:512
	s_waitcnt vmcnt(45)
	v_accvgpr_read_b32 v0, a40
	v_accvgpr_read_b32 v1, a41
	v_accvgpr_read_b32 v2, a42
	v_accvgpr_read_b32 v3, a43
	v_accvgpr_read_b32 v4, a44
	v_accvgpr_read_b32 v5, a45
	v_accvgpr_read_b32 v6, a46
	v_accvgpr_read_b32 v7, a47
	global_load_dwordx4 a[40:43], v[22:23], off offset:1664 nt
	global_load_dwordx4 a[44:47], v[22:23], off offset:1680 nt
	v_pk_mul_f32 v[0:1], v[28:29], v[0:1]
	v_pk_mul_f32 v[2:3], v[28:29], v[2:3]
	v_pk_mul_f32 v[4:5], v[28:29], v[4:5]
	v_pk_mul_f32 v[6:7], v[28:29], v[6:7]
	s_waitcnt lgkmcnt(0)
	v_pk_mul_f32 v[0:1], v[0:1], v[32:33]
	v_pk_mul_f32 v[2:3], v[2:3], v[34:35]
	v_pk_mul_f32 v[4:5], v[4:5], v[36:37]
	v_pk_mul_f32 v[6:7], v[6:7], v[38:39]
	v_pk_add_f32 v[40:41], v[40:41], 1.0 op_sel_hi:[1,0]
	v_pk_add_f32 v[42:43], v[42:43], 1.0 op_sel_hi:[1,0]
	v_pk_add_f32 v[44:45], v[44:45], 1.0 op_sel_hi:[1,0]
	v_pk_add_f32 v[46:47], v[46:47], 1.0 op_sel_hi:[1,0]
	v_pk_fma_f32 v[0:1], v[0:1], v[40:41], v[58:59]
	v_pk_fma_f32 v[2:3], v[2:3], v[42:43], v[60:61]
	v_pk_fma_f32 v[4:5], v[4:5], v[44:45], v[62:63]
	v_pk_fma_f32 v[6:7], v[6:7], v[46:47], v[64:65]
	ds_read_b128 v[32:35], v102 offset:512
	ds_read_b128 v[36:39], v102 offset:528
	ds_read_b128 v[40:43], v102 offset:4608
	ds_read_b128 v[44:47], v102 offset:4624
	ds_read_b128 v[58:61], v102 offset:8704
	ds_read_b128 v[62:65], v102 offset:8720
	v_cvt_pk_f16_f32 v74, v0, v1
	v_cvt_pk_f16_f32 v75, v2, v3
	v_cvt_pk_f16_f32 v76, v4, v5
	v_cvt_pk_f16_f32 v77, v6, v7
	v_cvt_f32_f16_e32 v66, v74
	v_cvt_f32_f16_sdwa v67, v74 dst_sel:DWORD dst_unused:UNUSED_PAD src0_sel:WORD_1
	v_cvt_f32_f16_e32 v68, v75
	v_cvt_f32_f16_sdwa v69, v75 dst_sel:DWORD dst_unused:UNUSED_PAD src0_sel:WORD_1
	v_cvt_f32_f16_e32 v70, v76
	v_cvt_f32_f16_sdwa v71, v76 dst_sel:DWORD dst_unused:UNUSED_PAD src0_sel:WORD_1
	v_cvt_f32_f16_e32 v72, v77
	v_cvt_f32_f16_sdwa v73, v77 dst_sel:DWORD dst_unused:UNUSED_PAD src0_sel:WORD_1
	v_pk_add_f32 v[0:1], v[0:1], v[66:67] neg_lo:[0,1] neg_hi:[0,1]
	v_pk_add_f32 v[2:3], v[2:3], v[68:69] neg_lo:[0,1] neg_hi:[0,1]
	v_pk_add_f32 v[4:5], v[4:5], v[70:71] neg_lo:[0,1] neg_hi:[0,1]
	v_pk_add_f32 v[6:7], v[6:7], v[72:73] neg_lo:[0,1] neg_hi:[0,1]
	s_nop 0
	v_cvt_pk_f16_f32 v78, v0, v1
	v_cvt_pk_f16_f32 v79, v2, v3
	v_cvt_pk_f16_f32 v80, v4, v5
	v_cvt_pk_f16_f32 v81, v6, v7
	global_store_dwordx4 v[88:89], v[74:77], off offset:192
	s_waitcnt vmcnt(42)
	v_mfma_f32_16x16x32_f16 a[8:11], v[74:77], a[152:155], a[8:11]
	v_mfma_f32_16x16x32_f16 a[8:11], v[78:81], a[152:155], a[8:11]
	v_mfma_f32_16x16x32_f16 a[8:11], v[74:77], a[156:159], a[8:11]
	v_mfma_f32_16x16x32_f16 a[4:7], v[74:77], a[160:163], a[4:7]
	v_mfma_f32_16x16x32_f16 a[4:7], v[78:81], a[160:163], a[4:7]
	v_mfma_f32_16x16x32_f16 a[4:7], v[74:77], a[164:167], a[4:7]
	v_mfma_f32_16x16x32_f16 a[0:3], v[74:77], a[168:171], a[0:3]
	v_mfma_f32_16x16x32_f16 a[0:3], v[78:81], a[168:171], a[0:3]
	v_mfma_f32_16x16x32_f16 a[0:3], v[74:77], a[172:175], a[0:3]
	global_load_dwordx4 a[152:155], v[90:91], off offset:576
	global_load_dwordx4 a[156:159], v[92:93], off offset:576
	global_load_dwordx4 a[160:163], v[94:95], off offset:576
	global_load_dwordx4 a[164:167], v[96:97], off offset:576
	global_load_dwordx4 a[168:171], v[98:99], off offset:576
	global_load_dwordx4 a[172:175], v[100:101], off offset:576
	s_waitcnt vmcnt(48)
	v_accvgpr_read_b32 v0, a48
	v_accvgpr_read_b32 v1, a49
	v_accvgpr_read_b32 v2, a50
	v_accvgpr_read_b32 v3, a51
	v_accvgpr_read_b32 v4, a52
	v_accvgpr_read_b32 v5, a53
	v_accvgpr_read_b32 v6, a54
	v_accvgpr_read_b32 v7, a55
	global_load_dwordx4 a[48:51], v[22:23], off offset:1792 nt
	global_load_dwordx4 a[52:55], v[22:23], off offset:1808 nt
	v_pk_mul_f32 v[0:1], v[28:29], v[0:1]
	v_pk_mul_f32 v[2:3], v[28:29], v[2:3]
	v_pk_mul_f32 v[4:5], v[28:29], v[4:5]
	v_pk_mul_f32 v[6:7], v[28:29], v[6:7]
	s_waitcnt lgkmcnt(0)
; DI f4 mfma16(h8 a, h8 b, f4 c) { return __builtin_amdgcn_mfma_f32_16x16x32_f16(a, b, c, 0, 0, 0); }
; DI void row2_phase(const Params& P, int l, int r_begin, char* smem) {
;     ...
;     for (int kk = 0; kk < 32; kk++) {
;       const int k0 = kk * 32;
;       float x[8], g[8], s1[8], s0[8];
;       *(float4*)&x[0] = *(const float4*)(xm + k0); *(float4*)&x[4] = *(const float4*)(xm + k0 + 4);
;       *(float4*)&g[0] = *(const float4*)(gam + fq * 8 + k0); *(float4*)&g[4] = *(const float4*)(gam + fq * 8 + k0 + 4);
;       *(float4*)&s1[0] = *(const float4*)(sc + k0); *(float4*)&s1[4] = *(const float4*)(sc + k0 + 4);
;       *(float4*)&s0[0] = *(const float4*)(sh + k0); *(float4*)&s0[4] = *(const float4*)(sh + k0 + 4);
;       h8 hi, lo;
; #pragma unroll
;       for (int i = 0; i < 8; i++) {
;         float v = x[i] * rstd * g[i] * (1.f + s1[i]) + s0[i];
;         hi[i] = (half_t)v; lo[i] = (half_t)(v - (float)hi[i]);
;       }
;       *(h8*)(hxo + k0) = hi;
; #pragma unroll
;       for (int n3 = 0; n3 < 3; n3++) {
;         h8 bh = *(const h8*)(Whi + (size_t)(n3 * 16 + fr) * 1024 + k0 + fq * 8);
;         h8 bl = *(const h8*)(Wlo + (size_t)(n3 * 16 + fr) * 1024 + k0 + fq * 8);
;         acc[n3] = mfma16(hi, bh, acc[n3]); acc[n3] = mfma16(lo, bh, acc[n3]); acc[n3] = mfma16(hi, bl, acc[n3]);
;       }
;     }
	v_pk_mul_f32 v[0:1], v[0:1], v[32:33]
	v_pk_mul_f32 v[2:3], v[2:3], v[34:35]
	v_pk_mul_f32 v[4:5], v[4:5], v[36:37]
	v_pk_mul_f32 v[6:7], v[6:7], v[38:39]
	v_pk_add_f32 v[40:41], v[40:41], 1.0 op_sel_hi:[1,0]
	v_pk_add_f32 v[42:43], v[42:43], 1.0 op_sel_hi:[1,0]
	v_pk_add_f32 v[44:45], v[44:45], 1.0 op_sel_hi:[1,0]
	v_pk_add_f32 v[46:47], v[46:47], 1.0 op_sel_hi:[1,0]
	v_pk_fma_f32 v[0:1], v[0:1], v[40:41], v[58:59]
	v_pk_fma_f32 v[2:3], v[2:3], v[42:43], v[60:61]
	v_pk_fma_f32 v[4:5], v[4:5], v[44:45], v[62:63]
	v_pk_fma_f32 v[6:7], v[6:7], v[46:47], v[64:65]
	ds_read_b128 v[32:35], v102 offset:640
	ds_read_b128 v[36:39], v102 offset:656
	ds_read_b128 v[40:43], v102 offset:4736
	ds_read_b128 v[44:47], v102 offset:4752
	ds_read_b128 v[58:61], v102 offset:8832
	ds_read_b128 v[62:65], v102 offset:8848
	v_cvt_pk_f16_f32 v74, v0, v1
	v_cvt_pk_f16_f32 v75, v2, v3
	v_cvt_pk_f16_f32 v76, v4, v5
	v_cvt_pk_f16_f32 v77, v6, v7
	v_cvt_f32_f16_e32 v66, v74
	v_cvt_f32_f16_sdwa v67, v74 dst_sel:DWORD dst_unused:UNUSED_PAD src0_sel:WORD_1
	v_cvt_f32_f16_e32 v68, v75
	v_cvt_f32_f16_sdwa v69, v75 dst_sel:DWORD dst_unused:UNUSED_PAD src0_sel:WORD_1
	v_cvt_f32_f16_e32 v70, v76
	v_cvt_f32_f16_sdwa v71, v76 dst_sel:DWORD dst_unused:UNUSED_PAD src0_sel:WORD_1
	v_cvt_f32_f16_e32 v72, v77
	v_cvt_f32_f16_sdwa v73, v77 dst_sel:DWORD dst_unused:UNUSED_PAD src0_sel:WORD_1
	v_pk_add_f32 v[0:1], v[0:1], v[66:67] neg_lo:[0,1] neg_hi:[0,1]
	v_pk_add_f32 v[2:3], v[2:3], v[68:69] neg_lo:[0,1] neg_hi:[0,1]
	v_pk_add_f32 v[4:5], v[4:5], v[70:71] neg_lo:[0,1] neg_hi:[0,1]
	v_pk_add_f32 v[6:7], v[6:7], v[72:73] neg_lo:[0,1] neg_hi:[0,1]
	s_nop 0
	v_cvt_pk_f16_f32 v78, v0, v1
	v_cvt_pk_f16_f32 v79, v2, v3
	v_cvt_pk_f16_f32 v80, v4, v5
	v_cvt_pk_f16_f32 v81, v6, v7
	global_store_dwordx4 v[88:89], v[74:77], off offset:256
	s_waitcnt vmcnt(45)
	v_mfma_f32_16x16x32_f16 a[8:11], v[74:77], a[204:207], a[8:11]
	v_mfma_f32_16x16x32_f16 a[8:11], v[78:81], a[204:207], a[8:11]
	v_mfma_f32_16x16x32_f16 a[8:11], v[74:77], a[208:211], a[8:11]
	v_mfma_f32_16x16x32_f16 a[4:7], v[74:77], a[212:215], a[4:7]
	v_mfma_f32_16x16x32_f16 a[4:7], v[78:81], a[212:215], a[4:7]
	v_mfma_f32_16x16x32_f16 a[4:7], v[74:77], a[216:219], a[4:7]
	v_mfma_f32_16x16x32_f16 a[0:3], v[74:77], a[220:223], a[0:3]
	v_mfma_f32_16x16x32_f16 a[0:3], v[78:81], a[220:223], a[0:3]
	v_mfma_f32_16x16x32_f16 a[0:3], v[74:77], a[224:227], a[0:3]
	global_load_dwordx4 a[204:207], v[90:91], off offset:640
	global_load_dwordx4 a[208:211], v[92:93], off offset:640
	global_load_dwordx4 a[212:215], v[94:95], off offset:640
	global_load_dwordx4 a[216:219], v[96:97], off offset:640
	global_load_dwordx4 a[220:223], v[98:99], off offset:640
	global_load_dwordx4 a[224:227], v[100:101], off offset:640
	s_waitcnt vmcnt(51)
	v_accvgpr_read_b32 v0, a56
	v_accvgpr_read_b32 v1, a57
	v_accvgpr_read_b32 v2, a58
	v_accvgpr_read_b32 v3, a59
	v_accvgpr_read_b32 v4, a60
	v_accvgpr_read_b32 v5, a61
	v_accvgpr_read_b32 v6, a62
	v_accvgpr_read_b32 v7, a63
	global_load_dwordx4 a[56:59], v[22:23], off offset:1920 nt
	global_load_dwordx4 a[60:63], v[22:23], off offset:1936 nt
	v_pk_mul_f32 v[0:1], v[28:29], v[0:1]
	v_pk_mul_f32 v[2:3], v[28:29], v[2:3]
	v_pk_mul_f32 v[4:5], v[28:29], v[4:5]
	v_pk_mul_f32 v[6:7], v[28:29], v[6:7]
	s_waitcnt lgkmcnt(0)
	v_pk_mul_f32 v[0:1], v[0:1], v[32:33]
	v_pk_mul_f32 v[2:3], v[2:3], v[34:35]
	v_pk_mul_f32 v[4:5], v[4:5], v[36:37]
	v_pk_mul_f32 v[6:7], v[6:7], v[38:39]
	v_pk_add_f32 v[40:41], v[40:41], 1.0 op_sel_hi:[1,0]
	v_pk_add_f32 v[42:43], v[42:43], 1.0 op_sel_hi:[1,0]
	v_pk_add_f32 v[44:45], v[44:45], 1.0 op_sel_hi:[1,0]
	v_pk_add_f32 v[46:47], v[46:47], 1.0 op_sel_hi:[1,0]
	v_pk_fma_f32 v[0:1], v[0:1], v[40:41], v[58:59]
	v_pk_fma_f32 v[2:3], v[2:3], v[42:43], v[60:61]
	v_pk_fma_f32 v[4:5], v[4:5], v[44:45], v[62:63]
	v_pk_fma_f32 v[6:7], v[6:7], v[46:47], v[64:65]
	ds_read_b128 v[32:35], v102 offset:768
	ds_read_b128 v[36:39], v102 offset:784
	ds_read_b128 v[40:43], v102 offset:4864
	ds_read_b128 v[44:47], v102 offset:4880
	ds_read_b128 v[58:61], v102 offset:8960
	ds_read_b128 v[62:65], v102 offset:8976
	v_cvt_pk_f16_f32 v74, v0, v1
	v_cvt_pk_f16_f32 v75, v2, v3
	v_cvt_pk_f16_f32 v76, v4, v5
	v_cvt_pk_f16_f32 v77, v6, v7
	v_cvt_f32_f16_e32 v66, v74
	v_cvt_f32_f16_sdwa v67, v74 dst_sel:DWORD dst_unused:UNUSED_PAD src0_sel:WORD_1
	v_cvt_f32_f16_e32 v68, v75
	v_cvt_f32_f16_sdwa v69, v75 dst_sel:DWORD dst_unused:UNUSED_PAD src0_sel:WORD_1
	v_cvt_f32_f16_e32 v70, v76
	v_cvt_f32_f16_sdwa v71, v76 dst_sel:DWORD dst_unused:UNUSED_PAD src0_sel:WORD_1
	v_cvt_f32_f16_e32 v72, v77
	v_cvt_f32_f16_sdwa v73, v77 dst_sel:DWORD dst_unused:UNUSED_PAD src0_sel:WORD_1
	v_pk_add_f32 v[0:1], v[0:1], v[66:67] neg_lo:[0,1] neg_hi:[0,1]
	v_pk_add_f32 v[2:3], v[2:3], v[68:69] neg_lo:[0,1] neg_hi:[0,1]
	v_pk_add_f32 v[4:5], v[4:5], v[70:71] neg_lo:[0,1] neg_hi:[0,1]
	v_pk_add_f32 v[6:7], v[6:7], v[72:73] neg_lo:[0,1] neg_hi:[0,1]
	s_nop 0
	v_cvt_pk_f16_f32 v78, v0, v1
	v_cvt_pk_f16_f32 v79, v2, v3
	v_cvt_pk_f16_f32 v80, v4, v5
	v_cvt_pk_f16_f32 v81, v6, v7
	global_store_dwordx4 v[88:89], v[74:77], off offset:320
	s_waitcnt vmcnt(48)
	v_mfma_f32_16x16x32_f16 a[8:11], v[74:77], a[228:231], a[8:11]
	v_mfma_f32_16x16x32_f16 a[8:11], v[78:81], a[228:231], a[8:11]
	v_mfma_f32_16x16x32_f16 a[8:11], v[74:77], a[232:235], a[8:11]
	v_mfma_f32_16x16x32_f16 a[4:7], v[74:77], a[236:239], a[4:7]
	v_mfma_f32_16x16x32_f16 a[4:7], v[78:81], a[236:239], a[4:7]
	v_mfma_f32_16x16x32_f16 a[4:7], v[74:77], a[240:243], a[4:7]
	v_mfma_f32_16x16x32_f16 a[0:3], v[74:77], a[244:247], a[0:3]
	v_mfma_f32_16x16x32_f16 a[0:3], v[78:81], a[244:247], a[0:3]
	v_mfma_f32_16x16x32_f16 a[0:3], v[74:77], a[248:251], a[0:3]
	global_load_dwordx4 a[228:231], v[90:91], off offset:704
	global_load_dwordx4 a[232:235], v[92:93], off offset:704
	global_load_dwordx4 a[236:239], v[94:95], off offset:704
	global_load_dwordx4 a[240:243], v[96:97], off offset:704
	global_load_dwordx4 a[244:247], v[98:99], off offset:704
	global_load_dwordx4 a[248:251], v[100:101], off offset:704
	s_waitcnt vmcnt(54)
; DI f4 mfma16(h8 a, h8 b, f4 c) { return __builtin_amdgcn_mfma_f32_16x16x32_f16(a, b, c, 0, 0, 0); }
; DI void row2_phase(const Params& P, int l, int r_begin, char* smem) {
;     ...
;     for (int kk = 0; kk < 32; kk++) {
;       const int k0 = kk * 32;
;       float x[8], g[8], s1[8], s0[8];
;       *(float4*)&x[0] = *(const float4*)(xm + k0); *(float4*)&x[4] = *(const float4*)(xm + k0 + 4);
;       *(float4*)&g[0] = *(const float4*)(gam + fq * 8 + k0); *(float4*)&g[4] = *(const float4*)(gam + fq * 8 + k0 + 4);
;       *(float4*)&s1[0] = *(const float4*)(sc + k0); *(float4*)&s1[4] = *(const float4*)(sc + k0 + 4);
;       *(float4*)&s0[0] = *(const float4*)(sh + k0); *(float4*)&s0[4] = *(const float4*)(sh + k0 + 4);
;       h8 hi, lo;
; #pragma unroll
;       for (int i = 0; i < 8; i++) {
;         float v = x[i] * rstd * g[i] * (1.f + s1[i]) + s0[i];
;         hi[i] = (half_t)v; lo[i] = (half_t)(v - (float)hi[i]);
;       }
;       *(h8*)(hxo + k0) = hi;
; #pragma unroll
;       for (int n3 = 0; n3 < 3; n3++) {
;         h8 bh = *(const h8*)(Whi + (size_t)(n3 * 16 + fr) * 1024 + k0 + fq * 8);
;         h8 bl = *(const h8*)(Wlo + (size_t)(n3 * 16 + fr) * 1024 + k0 + fq * 8);
;         acc[n3] = mfma16(hi, bh, acc[n3]); acc[n3] = mfma16(lo, bh, acc[n3]); acc[n3] = mfma16(hi, bl, acc[n3]);
;       }
;     }
	v_accvgpr_read_b32 v0, a64
	v_accvgpr_read_b32 v1, a65
	v_accvgpr_read_b32 v2, a66
	v_accvgpr_read_b32 v3, a67
	v_accvgpr_read_b32 v4, a68
	v_accvgpr_read_b32 v5, a69
	v_accvgpr_read_b32 v6, a70
	v_accvgpr_read_b32 v7, a71
	global_load_dwordx4 a[64:67], v[22:23], off offset:2048 nt
	global_load_dwordx4 a[68:71], v[22:23], off offset:2064 nt
	v_pk_mul_f32 v[0:1], v[28:29], v[0:1]
	v_pk_mul_f32 v[2:3], v[28:29], v[2:3]
	v_pk_mul_f32 v[4:5], v[28:29], v[4:5]
	v_pk_mul_f32 v[6:7], v[28:29], v[6:7]
	s_waitcnt lgkmcnt(0)
	v_pk_mul_f32 v[0:1], v[0:1], v[32:33]
	v_pk_mul_f32 v[2:3], v[2:3], v[34:35]
	v_pk_mul_f32 v[4:5], v[4:5], v[36:37]
	v_pk_mul_f32 v[6:7], v[6:7], v[38:39]
	v_pk_add_f32 v[40:41], v[40:41], 1.0 op_sel_hi:[1,0]
	v_pk_add_f32 v[42:43], v[42:43], 1.0 op_sel_hi:[1,0]
	v_pk_add_f32 v[44:45], v[44:45], 1.0 op_sel_hi:[1,0]
	v_pk_add_f32 v[46:47], v[46:47], 1.0 op_sel_hi:[1,0]
	v_pk_fma_f32 v[0:1], v[0:1], v[40:41], v[58:59]
	v_pk_fma_f32 v[2:3], v[2:3], v[42:43], v[60:61]
	v_pk_fma_f32 v[4:5], v[4:5], v[44:45], v[62:63]
	v_pk_fma_f32 v[6:7], v[6:7], v[46:47], v[64:65]
	ds_read_b128 v[32:35], v102 offset:896
	ds_read_b128 v[36:39], v102 offset:912
	ds_read_b128 v[40:43], v102 offset:4992
	ds_read_b128 v[44:47], v102 offset:5008
	ds_read_b128 v[58:61], v102 offset:9088
	ds_read_b128 v[62:65], v102 offset:9104
	v_cvt_pk_f16_f32 v74, v0, v1
	v_cvt_pk_f16_f32 v75, v2, v3
	v_cvt_pk_f16_f32 v76, v4, v5
	v_cvt_pk_f16_f32 v77, v6, v7
	v_cvt_f32_f16_e32 v66, v74
	v_cvt_f32_f16_sdwa v67, v74 dst_sel:DWORD dst_unused:UNUSED_PAD src0_sel:WORD_1
	v_cvt_f32_f16_e32 v68, v75
	v_cvt_f32_f16_sdwa v69, v75 dst_sel:DWORD dst_unused:UNUSED_PAD src0_sel:WORD_1
	v_cvt_f32_f16_e32 v70, v76
	v_cvt_f32_f16_sdwa v71, v76 dst_sel:DWORD dst_unused:UNUSED_PAD src0_sel:WORD_1
	v_cvt_f32_f16_e32 v72, v77
	v_cvt_f32_f16_sdwa v73, v77 dst_sel:DWORD dst_unused:UNUSED_PAD src0_sel:WORD_1
	v_pk_add_f32 v[0:1], v[0:1], v[66:67] neg_lo:[0,1] neg_hi:[0,1]
	v_pk_add_f32 v[2:3], v[2:3], v[68:69] neg_lo:[0,1] neg_hi:[0,1]
	v_pk_add_f32 v[4:5], v[4:5], v[70:71] neg_lo:[0,1] neg_hi:[0,1]
	v_pk_add_f32 v[6:7], v[6:7], v[72:73] neg_lo:[0,1] neg_hi:[0,1]
	s_nop 0
	v_cvt_pk_f16_f32 v78, v0, v1
	v_cvt_pk_f16_f32 v79, v2, v3
	v_cvt_pk_f16_f32 v80, v4, v5
	v_cvt_pk_f16_f32 v81, v6, v7
	global_store_dwordx4 v[88:89], v[74:77], off offset:384
	s_waitcnt vmcnt(48)
	v_mfma_f32_16x16x32_f16 a[8:11], v[74:77], a[80:83], a[8:11]
	v_mfma_f32_16x16x32_f16 a[8:11], v[78:81], a[80:83], a[8:11]
	v_mfma_f32_16x16x32_f16 a[8:11], v[74:77], a[84:87], a[8:11]
	v_mfma_f32_16x16x32_f16 a[4:7], v[74:77], a[88:91], a[4:7]
	v_mfma_f32_16x16x32_f16 a[4:7], v[78:81], a[88:91], a[4:7]
	v_mfma_f32_16x16x32_f16 a[4:7], v[74:77], a[92:95], a[4:7]
	v_mfma_f32_16x16x32_f16 a[0:3], v[74:77], a[96:99], a[0:3]
	v_mfma_f32_16x16x32_f16 a[0:3], v[78:81], a[96:99], a[0:3]
	v_mfma_f32_16x16x32_f16 a[0:3], v[74:77], a[100:103], a[0:3]
	global_load_dwordx4 a[80:83], v[90:91], off offset:768
	global_load_dwordx4 a[84:87], v[92:93], off offset:768
	global_load_dwordx4 a[88:91], v[94:95], off offset:768
	global_load_dwordx4 a[92:95], v[96:97], off offset:768
	global_load_dwordx4 a[96:99], v[98:99], off offset:768
	global_load_dwordx4 a[100:103], v[100:101], off offset:768
	s_waitcnt vmcnt(54)
	v_accvgpr_read_b32 v0, a72
	v_accvgpr_read_b32 v1, a73
	v_accvgpr_read_b32 v2, a74
	v_accvgpr_read_b32 v3, a75
	v_accvgpr_read_b32 v4, a76
	v_accvgpr_read_b32 v5, a77
	v_accvgpr_read_b32 v6, a78
	v_accvgpr_read_b32 v7, a79
	global_load_dwordx4 a[72:75], v[22:23], off offset:2176 nt
	global_load_dwordx4 a[76:79], v[22:23], off offset:2192 nt
	v_pk_mul_f32 v[0:1], v[28:29], v[0:1]
	v_pk_mul_f32 v[2:3], v[28:29], v[2:3]
	v_pk_mul_f32 v[4:5], v[28:29], v[4:5]
	v_pk_mul_f32 v[6:7], v[28:29], v[6:7]
	s_waitcnt lgkmcnt(0)
	v_pk_mul_f32 v[0:1], v[0:1], v[32:33]
	v_pk_mul_f32 v[2:3], v[2:3], v[34:35]
	v_pk_mul_f32 v[4:5], v[4:5], v[36:37]
	v_pk_mul_f32 v[6:7], v[6:7], v[38:39]
	v_pk_add_f32 v[40:41], v[40:41], 1.0 op_sel_hi:[1,0]
	v_pk_add_f32 v[42:43], v[42:43], 1.0 op_sel_hi:[1,0]
	v_pk_add_f32 v[44:45], v[44:45], 1.0 op_sel_hi:[1,0]
	v_pk_add_f32 v[46:47], v[46:47], 1.0 op_sel_hi:[1,0]
	v_pk_fma_f32 v[0:1], v[0:1], v[40:41], v[58:59]
	v_pk_fma_f32 v[2:3], v[2:3], v[42:43], v[60:61]
	v_pk_fma_f32 v[4:5], v[4:5], v[44:45], v[62:63]
	v_pk_fma_f32 v[6:7], v[6:7], v[46:47], v[64:65]
	ds_read_b128 v[32:35], v102 offset:1024
	ds_read_b128 v[36:39], v102 offset:1040
	ds_read_b128 v[40:43], v102 offset:5120
	ds_read_b128 v[44:47], v102 offset:5136
	ds_read_b128 v[58:61], v102 offset:9216
	ds_read_b128 v[62:65], v102 offset:9232
	v_cvt_pk_f16_f32 v74, v0, v1
	v_cvt_pk_f16_f32 v75, v2, v3
	v_cvt_pk_f16_f32 v76, v4, v5
	v_cvt_pk_f16_f32 v77, v6, v7
	v_cvt_f32_f16_e32 v66, v74
	v_cvt_f32_f16_sdwa v67, v74 dst_sel:DWORD dst_unused:UNUSED_PAD src0_sel:WORD_1
	v_cvt_f32_f16_e32 v68, v75
	v_cvt_f32_f16_sdwa v69, v75 dst_sel:DWORD dst_unused:UNUSED_PAD src0_sel:WORD_1
	v_cvt_f32_f16_e32 v70, v76
	v_cvt_f32_f16_sdwa v71, v76 dst_sel:DWORD dst_unused:UNUSED_PAD src0_sel:WORD_1
	v_cvt_f32_f16_e32 v72, v77
	v_cvt_f32_f16_sdwa v73, v77 dst_sel:DWORD dst_unused:UNUSED_PAD src0_sel:WORD_1
	v_pk_add_f32 v[0:1], v[0:1], v[66:67] neg_lo:[0,1] neg_hi:[0,1]
	v_pk_add_f32 v[2:3], v[2:3], v[68:69] neg_lo:[0,1] neg_hi:[0,1]
	v_pk_add_f32 v[4:5], v[4:5], v[70:71] neg_lo:[0,1] neg_hi:[0,1]
	v_pk_add_f32 v[6:7], v[6:7], v[72:73] neg_lo:[0,1] neg_hi:[0,1]
	s_nop 0
	v_cvt_pk_f16_f32 v78, v0, v1
	v_cvt_pk_f16_f32 v79, v2, v3
	v_cvt_pk_f16_f32 v80, v4, v5
	v_cvt_pk_f16_f32 v81, v6, v7
	global_store_dwordx4 v[88:89], v[74:77], off offset:448
	s_waitcnt vmcnt(48)
; DI f4 mfma16(h8 a, h8 b, f4 c) { return __builtin_amdgcn_mfma_f32_16x16x32_f16(a, b, c, 0, 0, 0); }
; DI void row2_phase(const Params& P, int l, int r_begin, char* smem) {
;     ...
;     for (int kk = 0; kk < 32; kk++) {
;       const int k0 = kk * 32;
;       float x[8], g[8], s1[8], s0[8];
;       *(float4*)&x[0] = *(const float4*)(xm + k0); *(float4*)&x[4] = *(const float4*)(xm + k0 + 4);
;       *(float4*)&g[0] = *(const float4*)(gam + fq * 8 + k0); *(float4*)&g[4] = *(const float4*)(gam + fq * 8 + k0 + 4);
;       *(float4*)&s1[0] = *(const float4*)(sc + k0); *(float4*)&s1[4] = *(const float4*)(sc + k0 + 4);
;       *(float4*)&s0[0] = *(const float4*)(sh + k0); *(float4*)&s0[4] = *(const float4*)(sh + k0 + 4);
;       h8 hi, lo;
; #pragma unroll
;       for (int i = 0; i < 8; i++) {
;         float v = x[i] * rstd * g[i] * (1.f + s1[i]) + s0[i];
;         hi[i] = (half_t)v; lo[i] = (half_t)(v - (float)hi[i]);
;       }
;       *(h8*)(hxo + k0) = hi;
; #pragma unroll
;       for (int n3 = 0; n3 < 3; n3++) {
;         h8 bh = *(const h8*)(Whi + (size_t)(n3 * 16 + fr) * 1024 + k0 + fq * 8);
;         h8 bl = *(const h8*)(Wlo + (size_t)(n3 * 16 + fr) * 1024 + k0 + fq * 8);
;         acc[n3] = mfma16(hi, bh, acc[n3]); acc[n3] = mfma16(lo, bh, acc[n3]); acc[n3] = mfma16(hi, bl, acc[n3]);
;       }
;     }
	v_mfma_f32_16x16x32_f16 a[8:11], v[74:77], a[104:107], a[8:11]
	v_mfma_f32_16x16x32_f16 a[8:11], v[78:81], a[104:107], a[8:11]
	v_mfma_f32_16x16x32_f16 a[8:11], v[74:77], a[108:111], a[8:11]
	v_mfma_f32_16x16x32_f16 a[4:7], v[74:77], a[112:115], a[4:7]
	v_mfma_f32_16x16x32_f16 a[4:7], v[78:81], a[112:115], a[4:7]
	v_mfma_f32_16x16x32_f16 a[4:7], v[74:77], a[116:119], a[4:7]
	v_mfma_f32_16x16x32_f16 a[0:3], v[74:77], a[120:123], a[0:3]
	v_mfma_f32_16x16x32_f16 a[0:3], v[78:81], a[120:123], a[0:3]
	v_mfma_f32_16x16x32_f16 a[0:3], v[74:77], a[124:127], a[0:3]
	global_load_dwordx4 a[104:107], v[90:91], off offset:832
	global_load_dwordx4 a[108:111], v[92:93], off offset:832
	global_load_dwordx4 a[112:115], v[94:95], off offset:832
	global_load_dwordx4 a[116:119], v[96:97], off offset:832
	global_load_dwordx4 a[120:123], v[98:99], off offset:832
	global_load_dwordx4 a[124:127], v[100:101], off offset:832
	s_waitcnt vmcnt(54)
	v_accvgpr_read_b32 v0, a180
	v_accvgpr_read_b32 v1, a181
	v_accvgpr_read_b32 v2, a182
	v_accvgpr_read_b32 v3, a183
	v_accvgpr_read_b32 v4, a184
	v_accvgpr_read_b32 v5, a185
	v_accvgpr_read_b32 v6, a186
	v_accvgpr_read_b32 v7, a187
	global_load_dwordx4 a[180:183], v[22:23], off offset:2304 nt
	global_load_dwordx4 a[184:187], v[22:23], off offset:2320 nt
	v_pk_mul_f32 v[0:1], v[28:29], v[0:1]
	v_pk_mul_f32 v[2:3], v[28:29], v[2:3]
	v_pk_mul_f32 v[4:5], v[28:29], v[4:5]
	v_pk_mul_f32 v[6:7], v[28:29], v[6:7]
	s_waitcnt lgkmcnt(0)
	v_pk_mul_f32 v[0:1], v[0:1], v[32:33]
	v_pk_mul_f32 v[2:3], v[2:3], v[34:35]
	v_pk_mul_f32 v[4:5], v[4:5], v[36:37]
	v_pk_mul_f32 v[6:7], v[6:7], v[38:39]
	v_pk_add_f32 v[40:41], v[40:41], 1.0 op_sel_hi:[1,0]
	v_pk_add_f32 v[42:43], v[42:43], 1.0 op_sel_hi:[1,0]
	v_pk_add_f32 v[44:45], v[44:45], 1.0 op_sel_hi:[1,0]
	v_pk_add_f32 v[46:47], v[46:47], 1.0 op_sel_hi:[1,0]
	v_pk_fma_f32 v[0:1], v[0:1], v[40:41], v[58:59]
	v_pk_fma_f32 v[2:3], v[2:3], v[42:43], v[60:61]
	v_pk_fma_f32 v[4:5], v[4:5], v[44:45], v[62:63]
	v_pk_fma_f32 v[6:7], v[6:7], v[46:47], v[64:65]
	ds_read_b128 v[32:35], v102 offset:1152
	ds_read_b128 v[36:39], v102 offset:1168
	ds_read_b128 v[40:43], v102 offset:5248
	ds_read_b128 v[44:47], v102 offset:5264
	ds_read_b128 v[58:61], v102 offset:9344
	ds_read_b128 v[62:65], v102 offset:9360
	v_cvt_pk_f16_f32 v74, v0, v1
	v_cvt_pk_f16_f32 v75, v2, v3
	v_cvt_pk_f16_f32 v76, v4, v5
	v_cvt_pk_f16_f32 v77, v6, v7
	v_cvt_f32_f16_e32 v66, v74
	v_cvt_f32_f16_sdwa v67, v74 dst_sel:DWORD dst_unused:UNUSED_PAD src0_sel:WORD_1
	v_cvt_f32_f16_e32 v68, v75
	v_cvt_f32_f16_sdwa v69, v75 dst_sel:DWORD dst_unused:UNUSED_PAD src0_sel:WORD_1
	v_cvt_f32_f16_e32 v70, v76
	v_cvt_f32_f16_sdwa v71, v76 dst_sel:DWORD dst_unused:UNUSED_PAD src0_sel:WORD_1
	v_cvt_f32_f16_e32 v72, v77
	v_cvt_f32_f16_sdwa v73, v77 dst_sel:DWORD dst_unused:UNUSED_PAD src0_sel:WORD_1
	v_pk_add_f32 v[0:1], v[0:1], v[66:67] neg_lo:[0,1] neg_hi:[0,1]
	v_pk_add_f32 v[2:3], v[2:3], v[68:69] neg_lo:[0,1] neg_hi:[0,1]
	v_pk_add_f32 v[4:5], v[4:5], v[70:71] neg_lo:[0,1] neg_hi:[0,1]
	v_pk_add_f32 v[6:7], v[6:7], v[72:73] neg_lo:[0,1] neg_hi:[0,1]
	s_nop 0
	v_cvt_pk_f16_f32 v78, v0, v1
	v_cvt_pk_f16_f32 v79, v2, v3
	v_cvt_pk_f16_f32 v80, v4, v5
	v_cvt_pk_f16_f32 v81, v6, v7
	global_store_dwordx4 v[88:89], v[74:77], off offset:512
	s_waitcnt vmcnt(48)
	v_mfma_f32_16x16x32_f16 a[8:11], v[74:77], a[128:131], a[8:11]
	v_mfma_f32_16x16x32_f16 a[8:11], v[78:81], a[128:131], a[8:11]
	v_mfma_f32_16x16x32_f16 a[8:11], v[74:77], a[132:135], a[8:11]
	v_mfma_f32_16x16x32_f16 a[4:7], v[74:77], a[136:139], a[4:7]
	v_mfma_f32_16x16x32_f16 a[4:7], v[78:81], a[136:139], a[4:7]
	v_mfma_f32_16x16x32_f16 a[4:7], v[74:77], a[140:143], a[4:7]
	v_mfma_f32_16x16x32_f16 a[0:3], v[74:77], a[144:147], a[0:3]
	v_mfma_f32_16x16x32_f16 a[0:3], v[78:81], a[144:147], a[0:3]
	v_mfma_f32_16x16x32_f16 a[0:3], v[74:77], a[148:151], a[0:3]
	global_load_dwordx4 a[128:131], v[90:91], off offset:896
	global_load_dwordx4 a[132:135], v[92:93], off offset:896
	global_load_dwordx4 a[136:139], v[94:95], off offset:896
	global_load_dwordx4 a[140:143], v[96:97], off offset:896
	global_load_dwordx4 a[144:147], v[98:99], off offset:896
	global_load_dwordx4 a[148:151], v[100:101], off offset:896
	s_waitcnt vmcnt(54)
	v_accvgpr_read_b32 v0, a196
	v_accvgpr_read_b32 v1, a197
	v_accvgpr_read_b32 v2, a198
	v_accvgpr_read_b32 v3, a199
	v_accvgpr_read_b32 v4, a200
	v_accvgpr_read_b32 v5, a201
	v_accvgpr_read_b32 v6, a202
	v_accvgpr_read_b32 v7, a203
	global_load_dwordx4 a[196:199], v[22:23], off offset:2432 nt
	global_load_dwordx4 a[200:203], v[22:23], off offset:2448 nt
	v_pk_mul_f32 v[0:1], v[28:29], v[0:1]
	v_pk_mul_f32 v[2:3], v[28:29], v[2:3]
	v_pk_mul_f32 v[4:5], v[28:29], v[4:5]
	v_pk_mul_f32 v[6:7], v[28:29], v[6:7]
	s_waitcnt lgkmcnt(0)
; DI f4 mfma16(h8 a, h8 b, f4 c) { return __builtin_amdgcn_mfma_f32_16x16x32_f16(a, b, c, 0, 0, 0); }
; DI void row2_phase(const Params& P, int l, int r_begin, char* smem) {
;     ...
;     for (int kk = 0; kk < 32; kk++) {
;       const int k0 = kk * 32;
;       float x[8], g[8], s1[8], s0[8];
;       *(float4*)&x[0] = *(const float4*)(xm + k0); *(float4*)&x[4] = *(const float4*)(xm + k0 + 4);
;       *(float4*)&g[0] = *(const float4*)(gam + fq * 8 + k0); *(float4*)&g[4] = *(const float4*)(gam + fq * 8 + k0 + 4);
;       *(float4*)&s1[0] = *(const float4*)(sc + k0); *(float4*)&s1[4] = *(const float4*)(sc + k0 + 4);
;       *(float4*)&s0[0] = *(const float4*)(sh + k0); *(float4*)&s0[4] = *(const float4*)(sh + k0 + 4);
;       h8 hi, lo;
; #pragma unroll
;       for (int i = 0; i < 8; i++) {
;         float v = x[i] * rstd * g[i] * (1.f + s1[i]) + s0[i];
;         hi[i] = (half_t)v; lo[i] = (half_t)(v - (float)hi[i]);
;       }
;       *(h8*)(hxo + k0) = hi;
; #pragma unroll
;       for (int n3 = 0; n3 < 3; n3++) {
;         h8 bh = *(const h8*)(Whi + (size_t)(n3 * 16 + fr) * 1024 + k0 + fq * 8);
;         h8 bl = *(const h8*)(Wlo + (size_t)(n3 * 16 + fr) * 1024 + k0 + fq * 8);
;         acc[n3] = mfma16(hi, bh, acc[n3]); acc[n3] = mfma16(lo, bh, acc[n3]); acc[n3] = mfma16(hi, bl, acc[n3]);
;       }
;     }
	v_pk_mul_f32 v[0:1], v[0:1], v[32:33]
	v_pk_mul_f32 v[2:3], v[2:3], v[34:35]
	v_pk_mul_f32 v[4:5], v[4:5], v[36:37]
	v_pk_mul_f32 v[6:7], v[6:7], v[38:39]
	v_pk_add_f32 v[40:41], v[40:41], 1.0 op_sel_hi:[1,0]
	v_pk_add_f32 v[42:43], v[42:43], 1.0 op_sel_hi:[1,0]
	v_pk_add_f32 v[44:45], v[44:45], 1.0 op_sel_hi:[1,0]
	v_pk_add_f32 v[46:47], v[46:47], 1.0 op_sel_hi:[1,0]
	v_pk_fma_f32 v[0:1], v[0:1], v[40:41], v[58:59]
	v_pk_fma_f32 v[2:3], v[2:3], v[42:43], v[60:61]
	v_pk_fma_f32 v[4:5], v[4:5], v[44:45], v[62:63]
	v_pk_fma_f32 v[6:7], v[6:7], v[46:47], v[64:65]
	ds_read_b128 v[32:35], v102 offset:1280
	ds_read_b128 v[36:39], v102 offset:1296
	ds_read_b128 v[40:43], v102 offset:5376
	ds_read_b128 v[44:47], v102 offset:5392
	ds_read_b128 v[58:61], v102 offset:9472
	ds_read_b128 v[62:65], v102 offset:9488
	v_cvt_pk_f16_f32 v74, v0, v1
	v_cvt_pk_f16_f32 v75, v2, v3
	v_cvt_pk_f16_f32 v76, v4, v5
	v_cvt_pk_f16_f32 v77, v6, v7
	v_cvt_f32_f16_e32 v66, v74
	v_cvt_f32_f16_sdwa v67, v74 dst_sel:DWORD dst_unused:UNUSED_PAD src0_sel:WORD_1
	v_cvt_f32_f16_e32 v68, v75
	v_cvt_f32_f16_sdwa v69, v75 dst_sel:DWORD dst_unused:UNUSED_PAD src0_sel:WORD_1
	v_cvt_f32_f16_e32 v70, v76
	v_cvt_f32_f16_sdwa v71, v76 dst_sel:DWORD dst_unused:UNUSED_PAD src0_sel:WORD_1
	v_cvt_f32_f16_e32 v72, v77
	v_cvt_f32_f16_sdwa v73, v77 dst_sel:DWORD dst_unused:UNUSED_PAD src0_sel:WORD_1
	v_pk_add_f32 v[0:1], v[0:1], v[66:67] neg_lo:[0,1] neg_hi:[0,1]
	v_pk_add_f32 v[2:3], v[2:3], v[68:69] neg_lo:[0,1] neg_hi:[0,1]
	v_pk_add_f32 v[4:5], v[4:5], v[70:71] neg_lo:[0,1] neg_hi:[0,1]
	v_pk_add_f32 v[6:7], v[6:7], v[72:73] neg_lo:[0,1] neg_hi:[0,1]
	s_nop 0
	v_cvt_pk_f16_f32 v78, v0, v1
	v_cvt_pk_f16_f32 v79, v2, v3
	v_cvt_pk_f16_f32 v80, v4, v5
	v_cvt_pk_f16_f32 v81, v6, v7
	global_store_dwordx4 v[88:89], v[74:77], off offset:576
	s_waitcnt vmcnt(48)
	v_mfma_f32_16x16x32_f16 a[8:11], v[74:77], a[152:155], a[8:11]
	v_mfma_f32_16x16x32_f16 a[8:11], v[78:81], a[152:155], a[8:11]
	v_mfma_f32_16x16x32_f16 a[8:11], v[74:77], a[156:159], a[8:11]
	v_mfma_f32_16x16x32_f16 a[4:7], v[74:77], a[160:163], a[4:7]
	v_mfma_f32_16x16x32_f16 a[4:7], v[78:81], a[160:163], a[4:7]
	v_mfma_f32_16x16x32_f16 a[4:7], v[74:77], a[164:167], a[4:7]
	v_mfma_f32_16x16x32_f16 a[0:3], v[74:77], a[168:171], a[0:3]
	v_mfma_f32_16x16x32_f16 a[0:3], v[78:81], a[168:171], a[0:3]
	v_mfma_f32_16x16x32_f16 a[0:3], v[74:77], a[172:175], a[0:3]
	global_load_dwordx4 a[152:155], v[90:91], off offset:960
	global_load_dwordx4 a[156:159], v[92:93], off offset:960
	global_load_dwordx4 a[160:163], v[94:95], off offset:960
	global_load_dwordx4 a[164:167], v[96:97], off offset:960
	global_load_dwordx4 a[168:171], v[98:99], off offset:960
	global_load_dwordx4 a[172:175], v[100:101], off offset:960
	s_waitcnt vmcnt(54)
	v_accvgpr_read_b32 v0, a16
	v_accvgpr_read_b32 v1, a17
	v_accvgpr_read_b32 v2, a18
	v_accvgpr_read_b32 v3, a19
	v_accvgpr_read_b32 v4, a20
	v_accvgpr_read_b32 v5, a21
	v_accvgpr_read_b32 v6, a22
	v_accvgpr_read_b32 v7, a23
	global_load_dwordx4 a[16:19], v[22:23], off offset:2560 nt
	global_load_dwordx4 a[20:23], v[22:23], off offset:2576 nt
	v_pk_mul_f32 v[0:1], v[28:29], v[0:1]
	v_pk_mul_f32 v[2:3], v[28:29], v[2:3]
	v_pk_mul_f32 v[4:5], v[28:29], v[4:5]
	v_pk_mul_f32 v[6:7], v[28:29], v[6:7]
	s_waitcnt lgkmcnt(0)
	v_pk_mul_f32 v[0:1], v[0:1], v[32:33]
	v_pk_mul_f32 v[2:3], v[2:3], v[34:35]
	v_pk_mul_f32 v[4:5], v[4:5], v[36:37]
	v_pk_mul_f32 v[6:7], v[6:7], v[38:39]
	v_pk_add_f32 v[40:41], v[40:41], 1.0 op_sel_hi:[1,0]
	v_pk_add_f32 v[42:43], v[42:43], 1.0 op_sel_hi:[1,0]
	v_pk_add_f32 v[44:45], v[44:45], 1.0 op_sel_hi:[1,0]
	v_pk_add_f32 v[46:47], v[46:47], 1.0 op_sel_hi:[1,0]
	v_pk_fma_f32 v[0:1], v[0:1], v[40:41], v[58:59]
	v_pk_fma_f32 v[2:3], v[2:3], v[42:43], v[60:61]
	v_pk_fma_f32 v[4:5], v[4:5], v[44:45], v[62:63]
	v_pk_fma_f32 v[6:7], v[6:7], v[46:47], v[64:65]
	ds_read_b128 v[32:35], v102 offset:1408
	ds_read_b128 v[36:39], v102 offset:1424
	ds_read_b128 v[40:43], v102 offset:5504
	ds_read_b128 v[44:47], v102 offset:5520
	ds_read_b128 v[58:61], v102 offset:9600
	ds_read_b128 v[62:65], v102 offset:9616
	v_cvt_pk_f16_f32 v74, v0, v1
	v_cvt_pk_f16_f32 v75, v2, v3
	v_cvt_pk_f16_f32 v76, v4, v5
	v_cvt_pk_f16_f32 v77, v6, v7
	v_cvt_f32_f16_e32 v66, v74
	v_cvt_f32_f16_sdwa v67, v74 dst_sel:DWORD dst_unused:UNUSED_PAD src0_sel:WORD_1
	v_cvt_f32_f16_e32 v68, v75
	v_cvt_f32_f16_sdwa v69, v75 dst_sel:DWORD dst_unused:UNUSED_PAD src0_sel:WORD_1
	v_cvt_f32_f16_e32 v70, v76
	v_cvt_f32_f16_sdwa v71, v76 dst_sel:DWORD dst_unused:UNUSED_PAD src0_sel:WORD_1
	v_cvt_f32_f16_e32 v72, v77
	v_cvt_f32_f16_sdwa v73, v77 dst_sel:DWORD dst_unused:UNUSED_PAD src0_sel:WORD_1
	v_pk_add_f32 v[0:1], v[0:1], v[66:67] neg_lo:[0,1] neg_hi:[0,1]
	v_pk_add_f32 v[2:3], v[2:3], v[68:69] neg_lo:[0,1] neg_hi:[0,1]
	v_pk_add_f32 v[4:5], v[4:5], v[70:71] neg_lo:[0,1] neg_hi:[0,1]
	v_pk_add_f32 v[6:7], v[6:7], v[72:73] neg_lo:[0,1] neg_hi:[0,1]
	s_nop 0
	v_cvt_pk_f16_f32 v78, v0, v1
	v_cvt_pk_f16_f32 v79, v2, v3
	v_cvt_pk_f16_f32 v80, v4, v5
	v_cvt_pk_f16_f32 v81, v6, v7
	global_store_dwordx4 v[88:89], v[74:77], off offset:640
	s_waitcnt vmcnt(48)
	v_mfma_f32_16x16x32_f16 a[8:11], v[74:77], a[204:207], a[8:11]
	v_mfma_f32_16x16x32_f16 a[8:11], v[78:81], a[204:207], a[8:11]
	v_mfma_f32_16x16x32_f16 a[8:11], v[74:77], a[208:211], a[8:11]
	v_mfma_f32_16x16x32_f16 a[4:7], v[74:77], a[212:215], a[4:7]
	v_mfma_f32_16x16x32_f16 a[4:7], v[78:81], a[212:215], a[4:7]
	v_mfma_f32_16x16x32_f16 a[4:7], v[74:77], a[216:219], a[4:7]
	v_mfma_f32_16x16x32_f16 a[0:3], v[74:77], a[220:223], a[0:3]
	v_mfma_f32_16x16x32_f16 a[0:3], v[78:81], a[220:223], a[0:3]
	v_mfma_f32_16x16x32_f16 a[0:3], v[74:77], a[224:227], a[0:3]
	global_load_dwordx4 a[204:207], v[90:91], off offset:1024
	global_load_dwordx4 a[208:211], v[92:93], off offset:1024
	global_load_dwordx4 a[212:215], v[94:95], off offset:1024
	global_load_dwordx4 a[216:219], v[96:97], off offset:1024
	global_load_dwordx4 a[220:223], v[98:99], off offset:1024
	global_load_dwordx4 a[224:227], v[100:101], off offset:1024
	s_waitcnt vmcnt(54)
; DI f4 mfma16(h8 a, h8 b, f4 c) { return __builtin_amdgcn_mfma_f32_16x16x32_f16(a, b, c, 0, 0, 0); }
; DI void row2_phase(const Params& P, int l, int r_begin, char* smem) {
;     ...
;     for (int kk = 0; kk < 32; kk++) {
;       const int k0 = kk * 32;
;       float x[8], g[8], s1[8], s0[8];
;       *(float4*)&x[0] = *(const float4*)(xm + k0); *(float4*)&x[4] = *(const float4*)(xm + k0 + 4);
;       *(float4*)&g[0] = *(const float4*)(gam + fq * 8 + k0); *(float4*)&g[4] = *(const float4*)(gam + fq * 8 + k0 + 4);
;       *(float4*)&s1[0] = *(const float4*)(sc + k0); *(float4*)&s1[4] = *(const float4*)(sc + k0 + 4);
;       *(float4*)&s0[0] = *(const float4*)(sh + k0); *(float4*)&s0[4] = *(const float4*)(sh + k0 + 4);
;       h8 hi, lo;
; #pragma unroll
;       for (int i = 0; i < 8; i++) {
;         float v = x[i] * rstd * g[i] * (1.f + s1[i]) + s0[i];
;         hi[i] = (half_t)v; lo[i] = (half_t)(v - (float)hi[i]);
;       }
;       *(h8*)(hxo + k0) = hi;
; #pragma unroll
;       for (int n3 = 0; n3 < 3; n3++) {
;         h8 bh = *(const h8*)(Whi + (size_t)(n3 * 16 + fr) * 1024 + k0 + fq * 8);
;         h8 bl = *(const h8*)(Wlo + (size_t)(n3 * 16 + fr) * 1024 + k0 + fq * 8);
;         acc[n3] = mfma16(hi, bh, acc[n3]); acc[n3] = mfma16(lo, bh, acc[n3]); acc[n3] = mfma16(hi, bl, acc[n3]);
;       }
;     }
	v_accvgpr_read_b32 v0, a24
	v_accvgpr_read_b32 v1, a25
	v_accvgpr_read_b32 v2, a26
	v_accvgpr_read_b32 v3, a27
	v_accvgpr_read_b32 v4, a28
	v_accvgpr_read_b32 v5, a29
	v_accvgpr_read_b32 v6, a30
	v_accvgpr_read_b32 v7, a31
	global_load_dwordx4 a[24:27], v[22:23], off offset:2688 nt
	global_load_dwordx4 a[28:31], v[22:23], off offset:2704 nt
	v_pk_mul_f32 v[0:1], v[28:29], v[0:1]
	v_pk_mul_f32 v[2:3], v[28:29], v[2:3]
	v_pk_mul_f32 v[4:5], v[28:29], v[4:5]
	v_pk_mul_f32 v[6:7], v[28:29], v[6:7]
	s_waitcnt lgkmcnt(0)
	v_pk_mul_f32 v[0:1], v[0:1], v[32:33]
	v_pk_mul_f32 v[2:3], v[2:3], v[34:35]
	v_pk_mul_f32 v[4:5], v[4:5], v[36:37]
	v_pk_mul_f32 v[6:7], v[6:7], v[38:39]
	v_pk_add_f32 v[40:41], v[40:41], 1.0 op_sel_hi:[1,0]
	v_pk_add_f32 v[42:43], v[42:43], 1.0 op_sel_hi:[1,0]
	v_pk_add_f32 v[44:45], v[44:45], 1.0 op_sel_hi:[1,0]
	v_pk_add_f32 v[46:47], v[46:47], 1.0 op_sel_hi:[1,0]
	v_pk_fma_f32 v[0:1], v[0:1], v[40:41], v[58:59]
	v_pk_fma_f32 v[2:3], v[2:3], v[42:43], v[60:61]
	v_pk_fma_f32 v[4:5], v[4:5], v[44:45], v[62:63]
	v_pk_fma_f32 v[6:7], v[6:7], v[46:47], v[64:65]
	ds_read_b128 v[32:35], v102 offset:1536
	ds_read_b128 v[36:39], v102 offset:1552
	ds_read_b128 v[40:43], v102 offset:5632
	ds_read_b128 v[44:47], v102 offset:5648
	ds_read_b128 v[58:61], v102 offset:9728
	ds_read_b128 v[62:65], v102 offset:9744
	v_cvt_pk_f16_f32 v74, v0, v1
	v_cvt_pk_f16_f32 v75, v2, v3
	v_cvt_pk_f16_f32 v76, v4, v5
	v_cvt_pk_f16_f32 v77, v6, v7
	v_cvt_f32_f16_e32 v66, v74
	v_cvt_f32_f16_sdwa v67, v74 dst_sel:DWORD dst_unused:UNUSED_PAD src0_sel:WORD_1
	v_cvt_f32_f16_e32 v68, v75
	v_cvt_f32_f16_sdwa v69, v75 dst_sel:DWORD dst_unused:UNUSED_PAD src0_sel:WORD_1
	v_cvt_f32_f16_e32 v70, v76
	v_cvt_f32_f16_sdwa v71, v76 dst_sel:DWORD dst_unused:UNUSED_PAD src0_sel:WORD_1
	v_cvt_f32_f16_e32 v72, v77
	v_cvt_f32_f16_sdwa v73, v77 dst_sel:DWORD dst_unused:UNUSED_PAD src0_sel:WORD_1
	v_pk_add_f32 v[0:1], v[0:1], v[66:67] neg_lo:[0,1] neg_hi:[0,1]
	v_pk_add_f32 v[2:3], v[2:3], v[68:69] neg_lo:[0,1] neg_hi:[0,1]
	v_pk_add_f32 v[4:5], v[4:5], v[70:71] neg_lo:[0,1] neg_hi:[0,1]
	v_pk_add_f32 v[6:7], v[6:7], v[72:73] neg_lo:[0,1] neg_hi:[0,1]
	s_nop 0
	v_cvt_pk_f16_f32 v78, v0, v1
	v_cvt_pk_f16_f32 v79, v2, v3
	v_cvt_pk_f16_f32 v80, v4, v5
	v_cvt_pk_f16_f32 v81, v6, v7
	global_store_dwordx4 v[88:89], v[74:77], off offset:704
	s_waitcnt vmcnt(48)
	v_mfma_f32_16x16x32_f16 a[8:11], v[74:77], a[228:231], a[8:11]
	v_mfma_f32_16x16x32_f16 a[8:11], v[78:81], a[228:231], a[8:11]
	v_mfma_f32_16x16x32_f16 a[8:11], v[74:77], a[232:235], a[8:11]
	v_mfma_f32_16x16x32_f16 a[4:7], v[74:77], a[236:239], a[4:7]
	v_mfma_f32_16x16x32_f16 a[4:7], v[78:81], a[236:239], a[4:7]
	v_mfma_f32_16x16x32_f16 a[4:7], v[74:77], a[240:243], a[4:7]
	v_mfma_f32_16x16x32_f16 a[0:3], v[74:77], a[244:247], a[0:3]
	v_mfma_f32_16x16x32_f16 a[0:3], v[78:81], a[244:247], a[0:3]
	v_mfma_f32_16x16x32_f16 a[0:3], v[74:77], a[248:251], a[0:3]
	global_load_dwordx4 a[228:231], v[90:91], off offset:1088
	global_load_dwordx4 a[232:235], v[92:93], off offset:1088
	global_load_dwordx4 a[236:239], v[94:95], off offset:1088
	global_load_dwordx4 a[240:243], v[96:97], off offset:1088
	global_load_dwordx4 a[244:247], v[98:99], off offset:1088
	global_load_dwordx4 a[248:251], v[100:101], off offset:1088
	s_waitcnt vmcnt(54)
	v_accvgpr_read_b32 v0, a32
	v_accvgpr_read_b32 v1, a33
	v_accvgpr_read_b32 v2, a34
	v_accvgpr_read_b32 v3, a35
	v_accvgpr_read_b32 v4, a36
	v_accvgpr_read_b32 v5, a37
	v_accvgpr_read_b32 v6, a38
	v_accvgpr_read_b32 v7, a39
	global_load_dwordx4 a[32:35], v[22:23], off offset:2816 nt
	global_load_dwordx4 a[36:39], v[22:23], off offset:2832 nt
	v_pk_mul_f32 v[0:1], v[28:29], v[0:1]
	v_pk_mul_f32 v[2:3], v[28:29], v[2:3]
	v_pk_mul_f32 v[4:5], v[28:29], v[4:5]
	v_pk_mul_f32 v[6:7], v[28:29], v[6:7]
	s_waitcnt lgkmcnt(0)
	v_pk_mul_f32 v[0:1], v[0:1], v[32:33]
	v_pk_mul_f32 v[2:3], v[2:3], v[34:35]
	v_pk_mul_f32 v[4:5], v[4:5], v[36:37]
	v_pk_mul_f32 v[6:7], v[6:7], v[38:39]
	v_pk_add_f32 v[40:41], v[40:41], 1.0 op_sel_hi:[1,0]
	v_pk_add_f32 v[42:43], v[42:43], 1.0 op_sel_hi:[1,0]
	v_pk_add_f32 v[44:45], v[44:45], 1.0 op_sel_hi:[1,0]
	v_pk_add_f32 v[46:47], v[46:47], 1.0 op_sel_hi:[1,0]
	v_pk_fma_f32 v[0:1], v[0:1], v[40:41], v[58:59]
	v_pk_fma_f32 v[2:3], v[2:3], v[42:43], v[60:61]
	v_pk_fma_f32 v[4:5], v[4:5], v[44:45], v[62:63]
	v_pk_fma_f32 v[6:7], v[6:7], v[46:47], v[64:65]
	ds_read_b128 v[32:35], v102 offset:1664
	ds_read_b128 v[36:39], v102 offset:1680
	ds_read_b128 v[40:43], v102 offset:5760
	ds_read_b128 v[44:47], v102 offset:5776
	ds_read_b128 v[58:61], v102 offset:9856
	ds_read_b128 v[62:65], v102 offset:9872
	v_cvt_pk_f16_f32 v74, v0, v1
	v_cvt_pk_f16_f32 v75, v2, v3
	v_cvt_pk_f16_f32 v76, v4, v5
	v_cvt_pk_f16_f32 v77, v6, v7
	v_cvt_f32_f16_e32 v66, v74
	v_cvt_f32_f16_sdwa v67, v74 dst_sel:DWORD dst_unused:UNUSED_PAD src0_sel:WORD_1
	v_cvt_f32_f16_e32 v68, v75
	v_cvt_f32_f16_sdwa v69, v75 dst_sel:DWORD dst_unused:UNUSED_PAD src0_sel:WORD_1
	v_cvt_f32_f16_e32 v70, v76
	v_cvt_f32_f16_sdwa v71, v76 dst_sel:DWORD dst_unused:UNUSED_PAD src0_sel:WORD_1
	v_cvt_f32_f16_e32 v72, v77
	v_cvt_f32_f16_sdwa v73, v77 dst_sel:DWORD dst_unused:UNUSED_PAD src0_sel:WORD_1
	v_pk_add_f32 v[0:1], v[0:1], v[66:67] neg_lo:[0,1] neg_hi:[0,1]
	v_pk_add_f32 v[2:3], v[2:3], v[68:69] neg_lo:[0,1] neg_hi:[0,1]
	v_pk_add_f32 v[4:5], v[4:5], v[70:71] neg_lo:[0,1] neg_hi:[0,1]
	v_pk_add_f32 v[6:7], v[6:7], v[72:73] neg_lo:[0,1] neg_hi:[0,1]
	s_nop 0
	v_cvt_pk_f16_f32 v78, v0, v1
	v_cvt_pk_f16_f32 v79, v2, v3
	v_cvt_pk_f16_f32 v80, v4, v5
	v_cvt_pk_f16_f32 v81, v6, v7
	global_store_dwordx4 v[88:89], v[74:77], off offset:768
	s_waitcnt vmcnt(48)
; DI f4 mfma16(h8 a, h8 b, f4 c) { return __builtin_amdgcn_mfma_f32_16x16x32_f16(a, b, c, 0, 0, 0); }
; DI void row2_phase(const Params& P, int l, int r_begin, char* smem) {
;     ...
;     for (int kk = 0; kk < 32; kk++) {
;       const int k0 = kk * 32;
;       float x[8], g[8], s1[8], s0[8];
;       *(float4*)&x[0] = *(const float4*)(xm + k0); *(float4*)&x[4] = *(const float4*)(xm + k0 + 4);
;       *(float4*)&g[0] = *(const float4*)(gam + fq * 8 + k0); *(float4*)&g[4] = *(const float4*)(gam + fq * 8 + k0 + 4);
;       *(float4*)&s1[0] = *(const float4*)(sc + k0); *(float4*)&s1[4] = *(const float4*)(sc + k0 + 4);
;       *(float4*)&s0[0] = *(const float4*)(sh + k0); *(float4*)&s0[4] = *(const float4*)(sh + k0 + 4);
;       h8 hi, lo;
; #pragma unroll
;       for (int i = 0; i < 8; i++) {
;         float v = x[i] * rstd * g[i] * (1.f + s1[i]) + s0[i];
;         hi[i] = (half_t)v; lo[i] = (half_t)(v - (float)hi[i]);
;       }
;       *(h8*)(hxo + k0) = hi;
; #pragma unroll
;       for (int n3 = 0; n3 < 3; n3++) {
;         h8 bh = *(const h8*)(Whi + (size_t)(n3 * 16 + fr) * 1024 + k0 + fq * 8);
;         h8 bl = *(const h8*)(Wlo + (size_t)(n3 * 16 + fr) * 1024 + k0 + fq * 8);
;         acc[n3] = mfma16(hi, bh, acc[n3]); acc[n3] = mfma16(lo, bh, acc[n3]); acc[n3] = mfma16(hi, bl, acc[n3]);
;       }
;     }
	v_mfma_f32_16x16x32_f16 a[8:11], v[74:77], a[80:83], a[8:11]
	v_mfma_f32_16x16x32_f16 a[8:11], v[78:81], a[80:83], a[8:11]
	v_mfma_f32_16x16x32_f16 a[8:11], v[74:77], a[84:87], a[8:11]
	v_mfma_f32_16x16x32_f16 a[4:7], v[74:77], a[88:91], a[4:7]
	v_mfma_f32_16x16x32_f16 a[4:7], v[78:81], a[88:91], a[4:7]
	v_mfma_f32_16x16x32_f16 a[4:7], v[74:77], a[92:95], a[4:7]
	v_mfma_f32_16x16x32_f16 a[0:3], v[74:77], a[96:99], a[0:3]
	v_mfma_f32_16x16x32_f16 a[0:3], v[78:81], a[96:99], a[0:3]
	v_mfma_f32_16x16x32_f16 a[0:3], v[74:77], a[100:103], a[0:3]
	global_load_dwordx4 a[80:83], v[90:91], off offset:1152
	global_load_dwordx4 a[84:87], v[92:93], off offset:1152
	global_load_dwordx4 a[88:91], v[94:95], off offset:1152
	global_load_dwordx4 a[92:95], v[96:97], off offset:1152
	global_load_dwordx4 a[96:99], v[98:99], off offset:1152
	global_load_dwordx4 a[100:103], v[100:101], off offset:1152
	s_waitcnt vmcnt(54)
	v_accvgpr_read_b32 v0, a40
	v_accvgpr_read_b32 v1, a41
	v_accvgpr_read_b32 v2, a42
	v_accvgpr_read_b32 v3, a43
	v_accvgpr_read_b32 v4, a44
	v_accvgpr_read_b32 v5, a45
	v_accvgpr_read_b32 v6, a46
	v_accvgpr_read_b32 v7, a47
	global_load_dwordx4 a[40:43], v[22:23], off offset:2944 nt
	global_load_dwordx4 a[44:47], v[22:23], off offset:2960 nt
	v_pk_mul_f32 v[0:1], v[28:29], v[0:1]
	v_pk_mul_f32 v[2:3], v[28:29], v[2:3]
	v_pk_mul_f32 v[4:5], v[28:29], v[4:5]
	v_pk_mul_f32 v[6:7], v[28:29], v[6:7]
	s_waitcnt lgkmcnt(0)
	v_pk_mul_f32 v[0:1], v[0:1], v[32:33]
	v_pk_mul_f32 v[2:3], v[2:3], v[34:35]
	v_pk_mul_f32 v[4:5], v[4:5], v[36:37]
	v_pk_mul_f32 v[6:7], v[6:7], v[38:39]
	v_pk_add_f32 v[40:41], v[40:41], 1.0 op_sel_hi:[1,0]
	v_pk_add_f32 v[42:43], v[42:43], 1.0 op_sel_hi:[1,0]
	v_pk_add_f32 v[44:45], v[44:45], 1.0 op_sel_hi:[1,0]
	v_pk_add_f32 v[46:47], v[46:47], 1.0 op_sel_hi:[1,0]
	v_pk_fma_f32 v[0:1], v[0:1], v[40:41], v[58:59]
	v_pk_fma_f32 v[2:3], v[2:3], v[42:43], v[60:61]
	v_pk_fma_f32 v[4:5], v[4:5], v[44:45], v[62:63]
	v_pk_fma_f32 v[6:7], v[6:7], v[46:47], v[64:65]
	ds_read_b128 v[32:35], v102 offset:1792
	ds_read_b128 v[36:39], v102 offset:1808
	ds_read_b128 v[40:43], v102 offset:5888
	ds_read_b128 v[44:47], v102 offset:5904
	ds_read_b128 v[58:61], v102 offset:9984
	ds_read_b128 v[62:65], v102 offset:10000
	v_cvt_pk_f16_f32 v74, v0, v1
	v_cvt_pk_f16_f32 v75, v2, v3
	v_cvt_pk_f16_f32 v76, v4, v5
	v_cvt_pk_f16_f32 v77, v6, v7
	v_cvt_f32_f16_e32 v66, v74
	v_cvt_f32_f16_sdwa v67, v74 dst_sel:DWORD dst_unused:UNUSED_PAD src0_sel:WORD_1
	v_cvt_f32_f16_e32 v68, v75
	v_cvt_f32_f16_sdwa v69, v75 dst_sel:DWORD dst_unused:UNUSED_PAD src0_sel:WORD_1
	v_cvt_f32_f16_e32 v70, v76
	v_cvt_f32_f16_sdwa v71, v76 dst_sel:DWORD dst_unused:UNUSED_PAD src0_sel:WORD_1
	v_cvt_f32_f16_e32 v72, v77
	v_cvt_f32_f16_sdwa v73, v77 dst_sel:DWORD dst_unused:UNUSED_PAD src0_sel:WORD_1
	v_pk_add_f32 v[0:1], v[0:1], v[66:67] neg_lo:[0,1] neg_hi:[0,1]
	v_pk_add_f32 v[2:3], v[2:3], v[68:69] neg_lo:[0,1] neg_hi:[0,1]
	v_pk_add_f32 v[4:5], v[4:5], v[70:71] neg_lo:[0,1] neg_hi:[0,1]
	v_pk_add_f32 v[6:7], v[6:7], v[72:73] neg_lo:[0,1] neg_hi:[0,1]
	s_nop 0
	v_cvt_pk_f16_f32 v78, v0, v1
	v_cvt_pk_f16_f32 v79, v2, v3
	v_cvt_pk_f16_f32 v80, v4, v5
	v_cvt_pk_f16_f32 v81, v6, v7
	global_store_dwordx4 v[88:89], v[74:77], off offset:832
	s_waitcnt vmcnt(48)
	v_mfma_f32_16x16x32_f16 a[8:11], v[74:77], a[104:107], a[8:11]
	v_mfma_f32_16x16x32_f16 a[8:11], v[78:81], a[104:107], a[8:11]
	v_mfma_f32_16x16x32_f16 a[8:11], v[74:77], a[108:111], a[8:11]
	v_mfma_f32_16x16x32_f16 a[4:7], v[74:77], a[112:115], a[4:7]
	v_mfma_f32_16x16x32_f16 a[4:7], v[78:81], a[112:115], a[4:7]
	v_mfma_f32_16x16x32_f16 a[4:7], v[74:77], a[116:119], a[4:7]
	v_mfma_f32_16x16x32_f16 a[0:3], v[74:77], a[120:123], a[0:3]
	v_mfma_f32_16x16x32_f16 a[0:3], v[78:81], a[120:123], a[0:3]
	v_mfma_f32_16x16x32_f16 a[0:3], v[74:77], a[124:127], a[0:3]
	global_load_dwordx4 a[104:107], v[90:91], off offset:1216
	global_load_dwordx4 a[108:111], v[92:93], off offset:1216
	global_load_dwordx4 a[112:115], v[94:95], off offset:1216
	global_load_dwordx4 a[116:119], v[96:97], off offset:1216
	global_load_dwordx4 a[120:123], v[98:99], off offset:1216
	global_load_dwordx4 a[124:127], v[100:101], off offset:1216
	s_waitcnt vmcnt(54)
	v_accvgpr_read_b32 v0, a48
	v_accvgpr_read_b32 v1, a49
	v_accvgpr_read_b32 v2, a50
	v_accvgpr_read_b32 v3, a51
	v_accvgpr_read_b32 v4, a52
	v_accvgpr_read_b32 v5, a53
	v_accvgpr_read_b32 v6, a54
	v_accvgpr_read_b32 v7, a55
	global_load_dwordx4 a[48:51], v[22:23], off offset:3072 nt
	global_load_dwordx4 a[52:55], v[22:23], off offset:3088 nt
	v_pk_mul_f32 v[0:1], v[28:29], v[0:1]
	v_pk_mul_f32 v[2:3], v[28:29], v[2:3]
	v_pk_mul_f32 v[4:5], v[28:29], v[4:5]
	v_pk_mul_f32 v[6:7], v[28:29], v[6:7]
	s_waitcnt lgkmcnt(0)
; DI f4 mfma16(h8 a, h8 b, f4 c) { return __builtin_amdgcn_mfma_f32_16x16x32_f16(a, b, c, 0, 0, 0); }
; DI void row2_phase(const Params& P, int l, int r_begin, char* smem) {
;     ...
;     for (int kk = 0; kk < 32; kk++) {
;       const int k0 = kk * 32;
;       float x[8], g[8], s1[8], s0[8];
;       *(float4*)&x[0] = *(const float4*)(xm + k0); *(float4*)&x[4] = *(const float4*)(xm + k0 + 4);
;       *(float4*)&g[0] = *(const float4*)(gam + fq * 8 + k0); *(float4*)&g[4] = *(const float4*)(gam + fq * 8 + k0 + 4);
;       *(float4*)&s1[0] = *(const float4*)(sc + k0); *(float4*)&s1[4] = *(const float4*)(sc + k0 + 4);
;       *(float4*)&s0[0] = *(const float4*)(sh + k0); *(float4*)&s0[4] = *(const float4*)(sh + k0 + 4);
;       h8 hi, lo;
; #pragma unroll
;       for (int i = 0; i < 8; i++) {
;         float v = x[i] * rstd * g[i] * (1.f + s1[i]) + s0[i];
;         hi[i] = (half_t)v; lo[i] = (half_t)(v - (float)hi[i]);
;       }
;       *(h8*)(hxo + k0) = hi;
; #pragma unroll
;       for (int n3 = 0; n3 < 3; n3++) {
;         h8 bh = *(const h8*)(Whi + (size_t)(n3 * 16 + fr) * 1024 + k0 + fq * 8);
;         h8 bl = *(const h8*)(Wlo + (size_t)(n3 * 16 + fr) * 1024 + k0 + fq * 8);
;         acc[n3] = mfma16(hi, bh, acc[n3]); acc[n3] = mfma16(lo, bh, acc[n3]); acc[n3] = mfma16(hi, bl, acc[n3]);
;       }
;     }
	v_pk_mul_f32 v[0:1], v[0:1], v[32:33]
	v_pk_mul_f32 v[2:3], v[2:3], v[34:35]
	v_pk_mul_f32 v[4:5], v[4:5], v[36:37]
	v_pk_mul_f32 v[6:7], v[6:7], v[38:39]
	v_pk_add_f32 v[40:41], v[40:41], 1.0 op_sel_hi:[1,0]
	v_pk_add_f32 v[42:43], v[42:43], 1.0 op_sel_hi:[1,0]
	v_pk_add_f32 v[44:45], v[44:45], 1.0 op_sel_hi:[1,0]
	v_pk_add_f32 v[46:47], v[46:47], 1.0 op_sel_hi:[1,0]
	v_pk_fma_f32 v[0:1], v[0:1], v[40:41], v[58:59]
	v_pk_fma_f32 v[2:3], v[2:3], v[42:43], v[60:61]
	v_pk_fma_f32 v[4:5], v[4:5], v[44:45], v[62:63]
	v_pk_fma_f32 v[6:7], v[6:7], v[46:47], v[64:65]
	ds_read_b128 v[32:35], v102 offset:1920
	ds_read_b128 v[36:39], v102 offset:1936
	ds_read_b128 v[40:43], v102 offset:6016
	ds_read_b128 v[44:47], v102 offset:6032
	ds_read_b128 v[58:61], v102 offset:10112
	ds_read_b128 v[62:65], v102 offset:10128
	v_cvt_pk_f16_f32 v74, v0, v1
	v_cvt_pk_f16_f32 v75, v2, v3
	v_cvt_pk_f16_f32 v76, v4, v5
	v_cvt_pk_f16_f32 v77, v6, v7
	v_cvt_f32_f16_e32 v66, v74
	v_cvt_f32_f16_sdwa v67, v74 dst_sel:DWORD dst_unused:UNUSED_PAD src0_sel:WORD_1
	v_cvt_f32_f16_e32 v68, v75
	v_cvt_f32_f16_sdwa v69, v75 dst_sel:DWORD dst_unused:UNUSED_PAD src0_sel:WORD_1
	v_cvt_f32_f16_e32 v70, v76
	v_cvt_f32_f16_sdwa v71, v76 dst_sel:DWORD dst_unused:UNUSED_PAD src0_sel:WORD_1
	v_cvt_f32_f16_e32 v72, v77
	v_cvt_f32_f16_sdwa v73, v77 dst_sel:DWORD dst_unused:UNUSED_PAD src0_sel:WORD_1
	v_pk_add_f32 v[0:1], v[0:1], v[66:67] neg_lo:[0,1] neg_hi:[0,1]
	v_pk_add_f32 v[2:3], v[2:3], v[68:69] neg_lo:[0,1] neg_hi:[0,1]
	v_pk_add_f32 v[4:5], v[4:5], v[70:71] neg_lo:[0,1] neg_hi:[0,1]
	v_pk_add_f32 v[6:7], v[6:7], v[72:73] neg_lo:[0,1] neg_hi:[0,1]
	s_nop 0
	v_cvt_pk_f16_f32 v78, v0, v1
	v_cvt_pk_f16_f32 v79, v2, v3
	v_cvt_pk_f16_f32 v80, v4, v5
	v_cvt_pk_f16_f32 v81, v6, v7
	global_store_dwordx4 v[88:89], v[74:77], off offset:896
	s_waitcnt vmcnt(48)
	v_mfma_f32_16x16x32_f16 a[8:11], v[74:77], a[128:131], a[8:11]
	v_mfma_f32_16x16x32_f16 a[8:11], v[78:81], a[128:131], a[8:11]
	v_mfma_f32_16x16x32_f16 a[8:11], v[74:77], a[132:135], a[8:11]
	v_mfma_f32_16x16x32_f16 a[4:7], v[74:77], a[136:139], a[4:7]
	v_mfma_f32_16x16x32_f16 a[4:7], v[78:81], a[136:139], a[4:7]
	v_mfma_f32_16x16x32_f16 a[4:7], v[74:77], a[140:143], a[4:7]
	v_mfma_f32_16x16x32_f16 a[0:3], v[74:77], a[144:147], a[0:3]
	v_mfma_f32_16x16x32_f16 a[0:3], v[78:81], a[144:147], a[0:3]
	v_mfma_f32_16x16x32_f16 a[0:3], v[74:77], a[148:151], a[0:3]
	global_load_dwordx4 a[128:131], v[90:91], off offset:1280
	global_load_dwordx4 a[132:135], v[92:93], off offset:1280
	global_load_dwordx4 a[136:139], v[94:95], off offset:1280
	global_load_dwordx4 a[140:143], v[96:97], off offset:1280
	global_load_dwordx4 a[144:147], v[98:99], off offset:1280
	global_load_dwordx4 a[148:151], v[100:101], off offset:1280
	s_waitcnt vmcnt(54)
	v_accvgpr_read_b32 v0, a56
	v_accvgpr_read_b32 v1, a57
	v_accvgpr_read_b32 v2, a58
	v_accvgpr_read_b32 v3, a59
	v_accvgpr_read_b32 v4, a60
	v_accvgpr_read_b32 v5, a61
	v_accvgpr_read_b32 v6, a62
	v_accvgpr_read_b32 v7, a63
	global_load_dwordx4 a[56:59], v[22:23], off offset:3200 nt
	global_load_dwordx4 a[60:63], v[22:23], off offset:3216 nt
	v_pk_mul_f32 v[0:1], v[28:29], v[0:1]
	v_pk_mul_f32 v[2:3], v[28:29], v[2:3]
	v_pk_mul_f32 v[4:5], v[28:29], v[4:5]
	v_pk_mul_f32 v[6:7], v[28:29], v[6:7]
	s_waitcnt lgkmcnt(0)
	v_pk_mul_f32 v[0:1], v[0:1], v[32:33]
	v_pk_mul_f32 v[2:3], v[2:3], v[34:35]
	v_pk_mul_f32 v[4:5], v[4:5], v[36:37]
	v_pk_mul_f32 v[6:7], v[6:7], v[38:39]
	v_pk_add_f32 v[40:41], v[40:41], 1.0 op_sel_hi:[1,0]
	v_pk_add_f32 v[42:43], v[42:43], 1.0 op_sel_hi:[1,0]
	v_pk_add_f32 v[44:45], v[44:45], 1.0 op_sel_hi:[1,0]
	v_pk_add_f32 v[46:47], v[46:47], 1.0 op_sel_hi:[1,0]
	v_pk_fma_f32 v[0:1], v[0:1], v[40:41], v[58:59]
	v_pk_fma_f32 v[2:3], v[2:3], v[42:43], v[60:61]
	v_pk_fma_f32 v[4:5], v[4:5], v[44:45], v[62:63]
	v_pk_fma_f32 v[6:7], v[6:7], v[46:47], v[64:65]
	ds_read_b128 v[32:35], v102 offset:2048
	ds_read_b128 v[36:39], v102 offset:2064
	ds_read_b128 v[40:43], v102 offset:6144
	ds_read_b128 v[44:47], v102 offset:6160
	ds_read_b128 v[58:61], v102 offset:10240
	ds_read_b128 v[62:65], v102 offset:10256
	v_cvt_pk_f16_f32 v74, v0, v1
	v_cvt_pk_f16_f32 v75, v2, v3
	v_cvt_pk_f16_f32 v76, v4, v5
	v_cvt_pk_f16_f32 v77, v6, v7
	v_cvt_f32_f16_e32 v66, v74
	v_cvt_f32_f16_sdwa v67, v74 dst_sel:DWORD dst_unused:UNUSED_PAD src0_sel:WORD_1
	v_cvt_f32_f16_e32 v68, v75
	v_cvt_f32_f16_sdwa v69, v75 dst_sel:DWORD dst_unused:UNUSED_PAD src0_sel:WORD_1
	v_cvt_f32_f16_e32 v70, v76
	v_cvt_f32_f16_sdwa v71, v76 dst_sel:DWORD dst_unused:UNUSED_PAD src0_sel:WORD_1
	v_cvt_f32_f16_e32 v72, v77
	v_cvt_f32_f16_sdwa v73, v77 dst_sel:DWORD dst_unused:UNUSED_PAD src0_sel:WORD_1
	v_pk_add_f32 v[0:1], v[0:1], v[66:67] neg_lo:[0,1] neg_hi:[0,1]
	v_pk_add_f32 v[2:3], v[2:3], v[68:69] neg_lo:[0,1] neg_hi:[0,1]
	v_pk_add_f32 v[4:5], v[4:5], v[70:71] neg_lo:[0,1] neg_hi:[0,1]
	v_pk_add_f32 v[6:7], v[6:7], v[72:73] neg_lo:[0,1] neg_hi:[0,1]
	s_nop 0
	v_cvt_pk_f16_f32 v78, v0, v1
	v_cvt_pk_f16_f32 v79, v2, v3
	v_cvt_pk_f16_f32 v80, v4, v5
	v_cvt_pk_f16_f32 v81, v6, v7
	global_store_dwordx4 v[88:89], v[74:77], off offset:960
	s_waitcnt vmcnt(48)
	v_mfma_f32_16x16x32_f16 a[8:11], v[74:77], a[152:155], a[8:11]
	v_mfma_f32_16x16x32_f16 a[8:11], v[78:81], a[152:155], a[8:11]
	v_mfma_f32_16x16x32_f16 a[8:11], v[74:77], a[156:159], a[8:11]
	v_mfma_f32_16x16x32_f16 a[4:7], v[74:77], a[160:163], a[4:7]
	v_mfma_f32_16x16x32_f16 a[4:7], v[78:81], a[160:163], a[4:7]
	v_mfma_f32_16x16x32_f16 a[4:7], v[74:77], a[164:167], a[4:7]
	v_mfma_f32_16x16x32_f16 a[0:3], v[74:77], a[168:171], a[0:3]
	v_mfma_f32_16x16x32_f16 a[0:3], v[78:81], a[168:171], a[0:3]
	v_mfma_f32_16x16x32_f16 a[0:3], v[74:77], a[172:175], a[0:3]
	global_load_dwordx4 a[152:155], v[90:91], off offset:1344
	global_load_dwordx4 a[156:159], v[92:93], off offset:1344
	global_load_dwordx4 a[160:163], v[94:95], off offset:1344
	global_load_dwordx4 a[164:167], v[96:97], off offset:1344
	global_load_dwordx4 a[168:171], v[98:99], off offset:1344
	global_load_dwordx4 a[172:175], v[100:101], off offset:1344
	s_waitcnt vmcnt(54)
; DI f4 mfma16(h8 a, h8 b, f4 c) { return __builtin_amdgcn_mfma_f32_16x16x32_f16(a, b, c, 0, 0, 0); }
; DI void row2_phase(const Params& P, int l, int r_begin, char* smem) {
;     ...
;     for (int kk = 0; kk < 32; kk++) {
;       const int k0 = kk * 32;
;       float x[8], g[8], s1[8], s0[8];
;       *(float4*)&x[0] = *(const float4*)(xm + k0); *(float4*)&x[4] = *(const float4*)(xm + k0 + 4);
;       *(float4*)&g[0] = *(const float4*)(gam + fq * 8 + k0); *(float4*)&g[4] = *(const float4*)(gam + fq * 8 + k0 + 4);
;       *(float4*)&s1[0] = *(const float4*)(sc + k0); *(float4*)&s1[4] = *(const float4*)(sc + k0 + 4);
;       *(float4*)&s0[0] = *(const float4*)(sh + k0); *(float4*)&s0[4] = *(const float4*)(sh + k0 + 4);
;       h8 hi, lo;
; #pragma unroll
;       for (int i = 0; i < 8; i++) {
;         float v = x[i] * rstd * g[i] * (1.f + s1[i]) + s0[i];
;         hi[i] = (half_t)v; lo[i] = (half_t)(v - (float)hi[i]);
;       }
;       *(h8*)(hxo + k0) = hi;
; #pragma unroll
;       for (int n3 = 0; n3 < 3; n3++) {
;         h8 bh = *(const h8*)(Whi + (size_t)(n3 * 16 + fr) * 1024 + k0 + fq * 8);
;         h8 bl = *(const h8*)(Wlo + (size_t)(n3 * 16 + fr) * 1024 + k0 + fq * 8);
;         acc[n3] = mfma16(hi, bh, acc[n3]); acc[n3] = mfma16(lo, bh, acc[n3]); acc[n3] = mfma16(hi, bl, acc[n3]);
;       }
;     }
	v_accvgpr_read_b32 v0, a64
	v_accvgpr_read_b32 v1, a65
	v_accvgpr_read_b32 v2, a66
	v_accvgpr_read_b32 v3, a67
	v_accvgpr_read_b32 v4, a68
	v_accvgpr_read_b32 v5, a69
	v_accvgpr_read_b32 v6, a70
	v_accvgpr_read_b32 v7, a71
	global_load_dwordx4 a[64:67], v[22:23], off offset:3328 nt
	global_load_dwordx4 a[68:71], v[22:23], off offset:3344 nt
	v_pk_mul_f32 v[0:1], v[28:29], v[0:1]
	v_pk_mul_f32 v[2:3], v[28:29], v[2:3]
	v_pk_mul_f32 v[4:5], v[28:29], v[4:5]
	v_pk_mul_f32 v[6:7], v[28:29], v[6:7]
	s_waitcnt lgkmcnt(0)
	v_pk_mul_f32 v[0:1], v[0:1], v[32:33]
	v_pk_mul_f32 v[2:3], v[2:3], v[34:35]
	v_pk_mul_f32 v[4:5], v[4:5], v[36:37]
	v_pk_mul_f32 v[6:7], v[6:7], v[38:39]
	v_pk_add_f32 v[40:41], v[40:41], 1.0 op_sel_hi:[1,0]
	v_pk_add_f32 v[42:43], v[42:43], 1.0 op_sel_hi:[1,0]
	v_pk_add_f32 v[44:45], v[44:45], 1.0 op_sel_hi:[1,0]
	v_pk_add_f32 v[46:47], v[46:47], 1.0 op_sel_hi:[1,0]
	v_pk_fma_f32 v[0:1], v[0:1], v[40:41], v[58:59]
	v_pk_fma_f32 v[2:3], v[2:3], v[42:43], v[60:61]
	v_pk_fma_f32 v[4:5], v[4:5], v[44:45], v[62:63]
	v_pk_fma_f32 v[6:7], v[6:7], v[46:47], v[64:65]
	ds_read_b128 v[32:35], v102 offset:2176
	ds_read_b128 v[36:39], v102 offset:2192
	ds_read_b128 v[40:43], v102 offset:6272
	ds_read_b128 v[44:47], v102 offset:6288
	ds_read_b128 v[58:61], v102 offset:10368
	ds_read_b128 v[62:65], v102 offset:10384
	v_cvt_pk_f16_f32 v74, v0, v1
	v_cvt_pk_f16_f32 v75, v2, v3
	v_cvt_pk_f16_f32 v76, v4, v5
	v_cvt_pk_f16_f32 v77, v6, v7
	v_cvt_f32_f16_e32 v66, v74
	v_cvt_f32_f16_sdwa v67, v74 dst_sel:DWORD dst_unused:UNUSED_PAD src0_sel:WORD_1
	v_cvt_f32_f16_e32 v68, v75
	v_cvt_f32_f16_sdwa v69, v75 dst_sel:DWORD dst_unused:UNUSED_PAD src0_sel:WORD_1
	v_cvt_f32_f16_e32 v70, v76
	v_cvt_f32_f16_sdwa v71, v76 dst_sel:DWORD dst_unused:UNUSED_PAD src0_sel:WORD_1
	v_cvt_f32_f16_e32 v72, v77
	v_cvt_f32_f16_sdwa v73, v77 dst_sel:DWORD dst_unused:UNUSED_PAD src0_sel:WORD_1
	v_pk_add_f32 v[0:1], v[0:1], v[66:67] neg_lo:[0,1] neg_hi:[0,1]
	v_pk_add_f32 v[2:3], v[2:3], v[68:69] neg_lo:[0,1] neg_hi:[0,1]
	v_pk_add_f32 v[4:5], v[4:5], v[70:71] neg_lo:[0,1] neg_hi:[0,1]
	v_pk_add_f32 v[6:7], v[6:7], v[72:73] neg_lo:[0,1] neg_hi:[0,1]
	s_nop 0
	v_cvt_pk_f16_f32 v78, v0, v1
	v_cvt_pk_f16_f32 v79, v2, v3
	v_cvt_pk_f16_f32 v80, v4, v5
	v_cvt_pk_f16_f32 v81, v6, v7
	global_store_dwordx4 v[88:89], v[74:77], off offset:1024
	s_waitcnt vmcnt(48)
	v_mfma_f32_16x16x32_f16 a[8:11], v[74:77], a[204:207], a[8:11]
	v_mfma_f32_16x16x32_f16 a[8:11], v[78:81], a[204:207], a[8:11]
	v_mfma_f32_16x16x32_f16 a[8:11], v[74:77], a[208:211], a[8:11]
	v_mfma_f32_16x16x32_f16 a[4:7], v[74:77], a[212:215], a[4:7]
	v_mfma_f32_16x16x32_f16 a[4:7], v[78:81], a[212:215], a[4:7]
	v_mfma_f32_16x16x32_f16 a[4:7], v[74:77], a[216:219], a[4:7]
	v_mfma_f32_16x16x32_f16 a[0:3], v[74:77], a[220:223], a[0:3]
	v_mfma_f32_16x16x32_f16 a[0:3], v[78:81], a[220:223], a[0:3]
	v_mfma_f32_16x16x32_f16 a[0:3], v[74:77], a[224:227], a[0:3]
	global_load_dwordx4 a[204:207], v[90:91], off offset:1408
	global_load_dwordx4 a[208:211], v[92:93], off offset:1408
	global_load_dwordx4 a[212:215], v[94:95], off offset:1408
	global_load_dwordx4 a[216:219], v[96:97], off offset:1408
	global_load_dwordx4 a[220:223], v[98:99], off offset:1408
	global_load_dwordx4 a[224:227], v[100:101], off offset:1408
	s_waitcnt vmcnt(54)
	v_accvgpr_read_b32 v0, a72
	v_accvgpr_read_b32 v1, a73
	v_accvgpr_read_b32 v2, a74
	v_accvgpr_read_b32 v3, a75
	v_accvgpr_read_b32 v4, a76
	v_accvgpr_read_b32 v5, a77
	v_accvgpr_read_b32 v6, a78
	v_accvgpr_read_b32 v7, a79
	global_load_dwordx4 a[72:75], v[22:23], off offset:3456 nt
	global_load_dwordx4 a[76:79], v[22:23], off offset:3472 nt
	v_pk_mul_f32 v[0:1], v[28:29], v[0:1]
	v_pk_mul_f32 v[2:3], v[28:29], v[2:3]
	v_pk_mul_f32 v[4:5], v[28:29], v[4:5]
	v_pk_mul_f32 v[6:7], v[28:29], v[6:7]
	s_waitcnt lgkmcnt(0)
	v_pk_mul_f32 v[0:1], v[0:1], v[32:33]
	v_pk_mul_f32 v[2:3], v[2:3], v[34:35]
	v_pk_mul_f32 v[4:5], v[4:5], v[36:37]
	v_pk_mul_f32 v[6:7], v[6:7], v[38:39]
	v_pk_add_f32 v[40:41], v[40:41], 1.0 op_sel_hi:[1,0]
	v_pk_add_f32 v[42:43], v[42:43], 1.0 op_sel_hi:[1,0]
	v_pk_add_f32 v[44:45], v[44:45], 1.0 op_sel_hi:[1,0]
	v_pk_add_f32 v[46:47], v[46:47], 1.0 op_sel_hi:[1,0]
	v_pk_fma_f32 v[0:1], v[0:1], v[40:41], v[58:59]
	v_pk_fma_f32 v[2:3], v[2:3], v[42:43], v[60:61]
	v_pk_fma_f32 v[4:5], v[4:5], v[44:45], v[62:63]
	v_pk_fma_f32 v[6:7], v[6:7], v[46:47], v[64:65]
	ds_read_b128 v[32:35], v102 offset:2304
	ds_read_b128 v[36:39], v102 offset:2320
	ds_read_b128 v[40:43], v102 offset:6400
	ds_read_b128 v[44:47], v102 offset:6416
	ds_read_b128 v[58:61], v102 offset:10496
	ds_read_b128 v[62:65], v102 offset:10512
	v_cvt_pk_f16_f32 v74, v0, v1
	v_cvt_pk_f16_f32 v75, v2, v3
	v_cvt_pk_f16_f32 v76, v4, v5
	v_cvt_pk_f16_f32 v77, v6, v7
	v_cvt_f32_f16_e32 v66, v74
	v_cvt_f32_f16_sdwa v67, v74 dst_sel:DWORD dst_unused:UNUSED_PAD src0_sel:WORD_1
	v_cvt_f32_f16_e32 v68, v75
	v_cvt_f32_f16_sdwa v69, v75 dst_sel:DWORD dst_unused:UNUSED_PAD src0_sel:WORD_1
	v_cvt_f32_f16_e32 v70, v76
	v_cvt_f32_f16_sdwa v71, v76 dst_sel:DWORD dst_unused:UNUSED_PAD src0_sel:WORD_1
	v_cvt_f32_f16_e32 v72, v77
	v_cvt_f32_f16_sdwa v73, v77 dst_sel:DWORD dst_unused:UNUSED_PAD src0_sel:WORD_1
	v_pk_add_f32 v[0:1], v[0:1], v[66:67] neg_lo:[0,1] neg_hi:[0,1]
	v_pk_add_f32 v[2:3], v[2:3], v[68:69] neg_lo:[0,1] neg_hi:[0,1]
	v_pk_add_f32 v[4:5], v[4:5], v[70:71] neg_lo:[0,1] neg_hi:[0,1]
	v_pk_add_f32 v[6:7], v[6:7], v[72:73] neg_lo:[0,1] neg_hi:[0,1]
	s_nop 0
	v_cvt_pk_f16_f32 v78, v0, v1
	v_cvt_pk_f16_f32 v79, v2, v3
	v_cvt_pk_f16_f32 v80, v4, v5
	v_cvt_pk_f16_f32 v81, v6, v7
	global_store_dwordx4 v[88:89], v[74:77], off offset:1088
	s_waitcnt vmcnt(48)
; DI f4 mfma16(h8 a, h8 b, f4 c) { return __builtin_amdgcn_mfma_f32_16x16x32_f16(a, b, c, 0, 0, 0); }
; DI void row2_phase(const Params& P, int l, int r_begin, char* smem) {
;     ...
;     for (int kk = 0; kk < 32; kk++) {
;       const int k0 = kk * 32;
;       float x[8], g[8], s1[8], s0[8];
;       *(float4*)&x[0] = *(const float4*)(xm + k0); *(float4*)&x[4] = *(const float4*)(xm + k0 + 4);
;       *(float4*)&g[0] = *(const float4*)(gam + fq * 8 + k0); *(float4*)&g[4] = *(const float4*)(gam + fq * 8 + k0 + 4);
;       *(float4*)&s1[0] = *(const float4*)(sc + k0); *(float4*)&s1[4] = *(const float4*)(sc + k0 + 4);
;       *(float4*)&s0[0] = *(const float4*)(sh + k0); *(float4*)&s0[4] = *(const float4*)(sh + k0 + 4);
;       h8 hi, lo;
; #pragma unroll
;       for (int i = 0; i < 8; i++) {
;         float v = x[i] * rstd * g[i] * (1.f + s1[i]) + s0[i];
;         hi[i] = (half_t)v; lo[i] = (half_t)(v - (float)hi[i]);
;       }
;       *(h8*)(hxo + k0) = hi;
; #pragma unroll
;       for (int n3 = 0; n3 < 3; n3++) {
;         h8 bh = *(const h8*)(Whi + (size_t)(n3 * 16 + fr) * 1024 + k0 + fq * 8);
;         h8 bl = *(const h8*)(Wlo + (size_t)(n3 * 16 + fr) * 1024 + k0 + fq * 8);
;         acc[n3] = mfma16(hi, bh, acc[n3]); acc[n3] = mfma16(lo, bh, acc[n3]); acc[n3] = mfma16(hi, bl, acc[n3]);
;       }
;     }
	v_mfma_f32_16x16x32_f16 a[8:11], v[74:77], a[228:231], a[8:11]
	v_mfma_f32_16x16x32_f16 a[8:11], v[78:81], a[228:231], a[8:11]
	v_mfma_f32_16x16x32_f16 a[8:11], v[74:77], a[232:235], a[8:11]
	v_mfma_f32_16x16x32_f16 a[4:7], v[74:77], a[236:239], a[4:7]
	v_mfma_f32_16x16x32_f16 a[4:7], v[78:81], a[236:239], a[4:7]
	v_mfma_f32_16x16x32_f16 a[4:7], v[74:77], a[240:243], a[4:7]
	v_mfma_f32_16x16x32_f16 a[0:3], v[74:77], a[244:247], a[0:3]
	v_mfma_f32_16x16x32_f16 a[0:3], v[78:81], a[244:247], a[0:3]
	v_mfma_f32_16x16x32_f16 a[0:3], v[74:77], a[248:251], a[0:3]
	global_load_dwordx4 a[228:231], v[90:91], off offset:1472
	global_load_dwordx4 a[232:235], v[92:93], off offset:1472
	global_load_dwordx4 a[236:239], v[94:95], off offset:1472
	global_load_dwordx4 a[240:243], v[96:97], off offset:1472
	global_load_dwordx4 a[244:247], v[98:99], off offset:1472
	global_load_dwordx4 a[248:251], v[100:101], off offset:1472
	s_waitcnt vmcnt(54)
	v_accvgpr_read_b32 v0, a180
	v_accvgpr_read_b32 v1, a181
	v_accvgpr_read_b32 v2, a182
	v_accvgpr_read_b32 v3, a183
	v_accvgpr_read_b32 v4, a184
	v_accvgpr_read_b32 v5, a185
	v_accvgpr_read_b32 v6, a186
	v_accvgpr_read_b32 v7, a187
	global_load_dwordx4 a[180:183], v[22:23], off offset:3584 nt
	global_load_dwordx4 a[184:187], v[22:23], off offset:3600 nt
	v_pk_mul_f32 v[0:1], v[28:29], v[0:1]
	v_pk_mul_f32 v[2:3], v[28:29], v[2:3]
	v_pk_mul_f32 v[4:5], v[28:29], v[4:5]
	v_pk_mul_f32 v[6:7], v[28:29], v[6:7]
	s_waitcnt lgkmcnt(0)
	v_pk_mul_f32 v[0:1], v[0:1], v[32:33]
	v_pk_mul_f32 v[2:3], v[2:3], v[34:35]
	v_pk_mul_f32 v[4:5], v[4:5], v[36:37]
	v_pk_mul_f32 v[6:7], v[6:7], v[38:39]
	v_pk_add_f32 v[40:41], v[40:41], 1.0 op_sel_hi:[1,0]
	v_pk_add_f32 v[42:43], v[42:43], 1.0 op_sel_hi:[1,0]
	v_pk_add_f32 v[44:45], v[44:45], 1.0 op_sel_hi:[1,0]
	v_pk_add_f32 v[46:47], v[46:47], 1.0 op_sel_hi:[1,0]
	v_pk_fma_f32 v[0:1], v[0:1], v[40:41], v[58:59]
	v_pk_fma_f32 v[2:3], v[2:3], v[42:43], v[60:61]
	v_pk_fma_f32 v[4:5], v[4:5], v[44:45], v[62:63]
	v_pk_fma_f32 v[6:7], v[6:7], v[46:47], v[64:65]
	ds_read_b128 v[32:35], v102 offset:2432
	ds_read_b128 v[36:39], v102 offset:2448
	ds_read_b128 v[40:43], v102 offset:6528
	ds_read_b128 v[44:47], v102 offset:6544
	ds_read_b128 v[58:61], v102 offset:10624
	ds_read_b128 v[62:65], v102 offset:10640
	v_cvt_pk_f16_f32 v74, v0, v1
	v_cvt_pk_f16_f32 v75, v2, v3
	v_cvt_pk_f16_f32 v76, v4, v5
	v_cvt_pk_f16_f32 v77, v6, v7
	v_cvt_f32_f16_e32 v66, v74
	v_cvt_f32_f16_sdwa v67, v74 dst_sel:DWORD dst_unused:UNUSED_PAD src0_sel:WORD_1
	v_cvt_f32_f16_e32 v68, v75
	v_cvt_f32_f16_sdwa v69, v75 dst_sel:DWORD dst_unused:UNUSED_PAD src0_sel:WORD_1
	v_cvt_f32_f16_e32 v70, v76
	v_cvt_f32_f16_sdwa v71, v76 dst_sel:DWORD dst_unused:UNUSED_PAD src0_sel:WORD_1
	v_cvt_f32_f16_e32 v72, v77
	v_cvt_f32_f16_sdwa v73, v77 dst_sel:DWORD dst_unused:UNUSED_PAD src0_sel:WORD_1
	v_pk_add_f32 v[0:1], v[0:1], v[66:67] neg_lo:[0,1] neg_hi:[0,1]
	v_pk_add_f32 v[2:3], v[2:3], v[68:69] neg_lo:[0,1] neg_hi:[0,1]
	v_pk_add_f32 v[4:5], v[4:5], v[70:71] neg_lo:[0,1] neg_hi:[0,1]
	v_pk_add_f32 v[6:7], v[6:7], v[72:73] neg_lo:[0,1] neg_hi:[0,1]
	s_nop 0
	v_cvt_pk_f16_f32 v78, v0, v1
	v_cvt_pk_f16_f32 v79, v2, v3
	v_cvt_pk_f16_f32 v80, v4, v5
	v_cvt_pk_f16_f32 v81, v6, v7
	global_store_dwordx4 v[88:89], v[74:77], off offset:1152
	s_waitcnt vmcnt(48)
	v_mfma_f32_16x16x32_f16 a[8:11], v[74:77], a[80:83], a[8:11]
	v_mfma_f32_16x16x32_f16 a[8:11], v[78:81], a[80:83], a[8:11]
	v_mfma_f32_16x16x32_f16 a[8:11], v[74:77], a[84:87], a[8:11]
	v_mfma_f32_16x16x32_f16 a[4:7], v[74:77], a[88:91], a[4:7]
	v_mfma_f32_16x16x32_f16 a[4:7], v[78:81], a[88:91], a[4:7]
	v_mfma_f32_16x16x32_f16 a[4:7], v[74:77], a[92:95], a[4:7]
	v_mfma_f32_16x16x32_f16 a[0:3], v[74:77], a[96:99], a[0:3]
	v_mfma_f32_16x16x32_f16 a[0:3], v[78:81], a[96:99], a[0:3]
	v_mfma_f32_16x16x32_f16 a[0:3], v[74:77], a[100:103], a[0:3]
	global_load_dwordx4 a[80:83], v[90:91], off offset:1536
	global_load_dwordx4 a[84:87], v[92:93], off offset:1536
	global_load_dwordx4 a[88:91], v[94:95], off offset:1536
	global_load_dwordx4 a[92:95], v[96:97], off offset:1536
	global_load_dwordx4 a[96:99], v[98:99], off offset:1536
	global_load_dwordx4 a[100:103], v[100:101], off offset:1536
	s_waitcnt vmcnt(54)
	v_accvgpr_read_b32 v0, a196
	v_accvgpr_read_b32 v1, a197
	v_accvgpr_read_b32 v2, a198
	v_accvgpr_read_b32 v3, a199
	v_accvgpr_read_b32 v4, a200
	v_accvgpr_read_b32 v5, a201
	v_accvgpr_read_b32 v6, a202
	v_accvgpr_read_b32 v7, a203
	global_load_dwordx4 a[196:199], v[22:23], off offset:3712 nt
	global_load_dwordx4 a[200:203], v[22:23], off offset:3728 nt
	v_pk_mul_f32 v[0:1], v[28:29], v[0:1]
	v_pk_mul_f32 v[2:3], v[28:29], v[2:3]
	v_pk_mul_f32 v[4:5], v[28:29], v[4:5]
	v_pk_mul_f32 v[6:7], v[28:29], v[6:7]
	s_waitcnt lgkmcnt(0)
; DI f4 mfma16(h8 a, h8 b, f4 c) { return __builtin_amdgcn_mfma_f32_16x16x32_f16(a, b, c, 0, 0, 0); }
; DI void row2_phase(const Params& P, int l, int r_begin, char* smem) {
;     ...
;     for (int kk = 0; kk < 32; kk++) {
;       const int k0 = kk * 32;
;       float x[8], g[8], s1[8], s0[8];
;       *(float4*)&x[0] = *(const float4*)(xm + k0); *(float4*)&x[4] = *(const float4*)(xm + k0 + 4);
;       *(float4*)&g[0] = *(const float4*)(gam + fq * 8 + k0); *(float4*)&g[4] = *(const float4*)(gam + fq * 8 + k0 + 4);
;       *(float4*)&s1[0] = *(const float4*)(sc + k0); *(float4*)&s1[4] = *(const float4*)(sc + k0 + 4);
;       *(float4*)&s0[0] = *(const float4*)(sh + k0); *(float4*)&s0[4] = *(const float4*)(sh + k0 + 4);
;       h8 hi, lo;
; #pragma unroll
;       for (int i = 0; i < 8; i++) {
;         float v = x[i] * rstd * g[i] * (1.f + s1[i]) + s0[i];
;         hi[i] = (half_t)v; lo[i] = (half_t)(v - (float)hi[i]);
;       }
;       *(h8*)(hxo + k0) = hi;
; #pragma unroll
;       for (int n3 = 0; n3 < 3; n3++) {
;         h8 bh = *(const h8*)(Whi + (size_t)(n3 * 16 + fr) * 1024 + k0 + fq * 8);
;         h8 bl = *(const h8*)(Wlo + (size_t)(n3 * 16 + fr) * 1024 + k0 + fq * 8);
;         acc[n3] = mfma16(hi, bh, acc[n3]); acc[n3] = mfma16(lo, bh, acc[n3]); acc[n3] = mfma16(hi, bl, acc[n3]);
;       }
;     }
	v_pk_mul_f32 v[0:1], v[0:1], v[32:33]
	v_pk_mul_f32 v[2:3], v[2:3], v[34:35]
	v_pk_mul_f32 v[4:5], v[4:5], v[36:37]
	v_pk_mul_f32 v[6:7], v[6:7], v[38:39]
	v_pk_add_f32 v[40:41], v[40:41], 1.0 op_sel_hi:[1,0]
	v_pk_add_f32 v[42:43], v[42:43], 1.0 op_sel_hi:[1,0]
	v_pk_add_f32 v[44:45], v[44:45], 1.0 op_sel_hi:[1,0]
	v_pk_add_f32 v[46:47], v[46:47], 1.0 op_sel_hi:[1,0]
	v_pk_fma_f32 v[0:1], v[0:1], v[40:41], v[58:59]
	v_pk_fma_f32 v[2:3], v[2:3], v[42:43], v[60:61]
	v_pk_fma_f32 v[4:5], v[4:5], v[44:45], v[62:63]
	v_pk_fma_f32 v[6:7], v[6:7], v[46:47], v[64:65]
	ds_read_b128 v[32:35], v102 offset:2560
	ds_read_b128 v[36:39], v102 offset:2576
	ds_read_b128 v[40:43], v102 offset:6656
	ds_read_b128 v[44:47], v102 offset:6672
	ds_read_b128 v[58:61], v102 offset:10752
	ds_read_b128 v[62:65], v102 offset:10768
	v_cvt_pk_f16_f32 v74, v0, v1
	v_cvt_pk_f16_f32 v75, v2, v3
	v_cvt_pk_f16_f32 v76, v4, v5
	v_cvt_pk_f16_f32 v77, v6, v7
	v_cvt_f32_f16_e32 v66, v74
	v_cvt_f32_f16_sdwa v67, v74 dst_sel:DWORD dst_unused:UNUSED_PAD src0_sel:WORD_1
	v_cvt_f32_f16_e32 v68, v75
	v_cvt_f32_f16_sdwa v69, v75 dst_sel:DWORD dst_unused:UNUSED_PAD src0_sel:WORD_1
	v_cvt_f32_f16_e32 v70, v76
	v_cvt_f32_f16_sdwa v71, v76 dst_sel:DWORD dst_unused:UNUSED_PAD src0_sel:WORD_1
	v_cvt_f32_f16_e32 v72, v77
	v_cvt_f32_f16_sdwa v73, v77 dst_sel:DWORD dst_unused:UNUSED_PAD src0_sel:WORD_1
	v_pk_add_f32 v[0:1], v[0:1], v[66:67] neg_lo:[0,1] neg_hi:[0,1]
	v_pk_add_f32 v[2:3], v[2:3], v[68:69] neg_lo:[0,1] neg_hi:[0,1]
	v_pk_add_f32 v[4:5], v[4:5], v[70:71] neg_lo:[0,1] neg_hi:[0,1]
	v_pk_add_f32 v[6:7], v[6:7], v[72:73] neg_lo:[0,1] neg_hi:[0,1]
	s_nop 0
	v_cvt_pk_f16_f32 v78, v0, v1
	v_cvt_pk_f16_f32 v79, v2, v3
	v_cvt_pk_f16_f32 v80, v4, v5
	v_cvt_pk_f16_f32 v81, v6, v7
	global_store_dwordx4 v[88:89], v[74:77], off offset:1216
	s_waitcnt vmcnt(48)
	v_mfma_f32_16x16x32_f16 a[8:11], v[74:77], a[104:107], a[8:11]
	v_mfma_f32_16x16x32_f16 a[8:11], v[78:81], a[104:107], a[8:11]
	v_mfma_f32_16x16x32_f16 a[8:11], v[74:77], a[108:111], a[8:11]
	v_mfma_f32_16x16x32_f16 a[4:7], v[74:77], a[112:115], a[4:7]
	v_mfma_f32_16x16x32_f16 a[4:7], v[78:81], a[112:115], a[4:7]
	v_mfma_f32_16x16x32_f16 a[4:7], v[74:77], a[116:119], a[4:7]
	v_mfma_f32_16x16x32_f16 a[0:3], v[74:77], a[120:123], a[0:3]
	v_mfma_f32_16x16x32_f16 a[0:3], v[78:81], a[120:123], a[0:3]
	v_mfma_f32_16x16x32_f16 a[0:3], v[74:77], a[124:127], a[0:3]
	global_load_dwordx4 a[104:107], v[90:91], off offset:1600
	global_load_dwordx4 a[108:111], v[92:93], off offset:1600
	global_load_dwordx4 a[112:115], v[94:95], off offset:1600
	global_load_dwordx4 a[116:119], v[96:97], off offset:1600
	global_load_dwordx4 a[120:123], v[98:99], off offset:1600
	global_load_dwordx4 a[124:127], v[100:101], off offset:1600
	s_waitcnt vmcnt(54)
	v_accvgpr_read_b32 v0, a16
	v_accvgpr_read_b32 v1, a17
	v_accvgpr_read_b32 v2, a18
	v_accvgpr_read_b32 v3, a19
	v_accvgpr_read_b32 v4, a20
	v_accvgpr_read_b32 v5, a21
	v_accvgpr_read_b32 v6, a22
	v_accvgpr_read_b32 v7, a23
	global_load_dwordx4 a[16:19], v[22:23], off offset:3840 nt
	global_load_dwordx4 a[20:23], v[22:23], off offset:3856 nt
	v_pk_mul_f32 v[0:1], v[28:29], v[0:1]
	v_pk_mul_f32 v[2:3], v[28:29], v[2:3]
	v_pk_mul_f32 v[4:5], v[28:29], v[4:5]
	v_pk_mul_f32 v[6:7], v[28:29], v[6:7]
	s_waitcnt lgkmcnt(0)
	v_pk_mul_f32 v[0:1], v[0:1], v[32:33]
	v_pk_mul_f32 v[2:3], v[2:3], v[34:35]
	v_pk_mul_f32 v[4:5], v[4:5], v[36:37]
	v_pk_mul_f32 v[6:7], v[6:7], v[38:39]
	v_pk_add_f32 v[40:41], v[40:41], 1.0 op_sel_hi:[1,0]
	v_pk_add_f32 v[42:43], v[42:43], 1.0 op_sel_hi:[1,0]
	v_pk_add_f32 v[44:45], v[44:45], 1.0 op_sel_hi:[1,0]
	v_pk_add_f32 v[46:47], v[46:47], 1.0 op_sel_hi:[1,0]
	v_pk_fma_f32 v[0:1], v[0:1], v[40:41], v[58:59]
	v_pk_fma_f32 v[2:3], v[2:3], v[42:43], v[60:61]
	v_pk_fma_f32 v[4:5], v[4:5], v[44:45], v[62:63]
	v_pk_fma_f32 v[6:7], v[6:7], v[46:47], v[64:65]
	ds_read_b128 v[32:35], v102 offset:2688
	ds_read_b128 v[36:39], v102 offset:2704
	ds_read_b128 v[40:43], v102 offset:6784
	ds_read_b128 v[44:47], v102 offset:6800
	ds_read_b128 v[58:61], v102 offset:10880
	ds_read_b128 v[62:65], v102 offset:10896
	v_cvt_pk_f16_f32 v74, v0, v1
	v_cvt_pk_f16_f32 v75, v2, v3
	v_cvt_pk_f16_f32 v76, v4, v5
	v_cvt_pk_f16_f32 v77, v6, v7
	v_cvt_f32_f16_e32 v66, v74
	v_cvt_f32_f16_sdwa v67, v74 dst_sel:DWORD dst_unused:UNUSED_PAD src0_sel:WORD_1
	v_cvt_f32_f16_e32 v68, v75
	v_cvt_f32_f16_sdwa v69, v75 dst_sel:DWORD dst_unused:UNUSED_PAD src0_sel:WORD_1
	v_cvt_f32_f16_e32 v70, v76
	v_cvt_f32_f16_sdwa v71, v76 dst_sel:DWORD dst_unused:UNUSED_PAD src0_sel:WORD_1
	v_cvt_f32_f16_e32 v72, v77
	v_cvt_f32_f16_sdwa v73, v77 dst_sel:DWORD dst_unused:UNUSED_PAD src0_sel:WORD_1
	v_pk_add_f32 v[0:1], v[0:1], v[66:67] neg_lo:[0,1] neg_hi:[0,1]
	v_pk_add_f32 v[2:3], v[2:3], v[68:69] neg_lo:[0,1] neg_hi:[0,1]
	v_pk_add_f32 v[4:5], v[4:5], v[70:71] neg_lo:[0,1] neg_hi:[0,1]
	v_pk_add_f32 v[6:7], v[6:7], v[72:73] neg_lo:[0,1] neg_hi:[0,1]
	s_nop 0
	v_cvt_pk_f16_f32 v78, v0, v1
	v_cvt_pk_f16_f32 v79, v2, v3
	v_cvt_pk_f16_f32 v80, v4, v5
	v_cvt_pk_f16_f32 v81, v6, v7
	global_store_dwordx4 v[88:89], v[74:77], off offset:1280
	s_waitcnt vmcnt(48)
	v_mfma_f32_16x16x32_f16 a[8:11], v[74:77], a[128:131], a[8:11]
	v_mfma_f32_16x16x32_f16 a[8:11], v[78:81], a[128:131], a[8:11]
	v_mfma_f32_16x16x32_f16 a[8:11], v[74:77], a[132:135], a[8:11]
	v_mfma_f32_16x16x32_f16 a[4:7], v[74:77], a[136:139], a[4:7]
	v_mfma_f32_16x16x32_f16 a[4:7], v[78:81], a[136:139], a[4:7]
	v_mfma_f32_16x16x32_f16 a[4:7], v[74:77], a[140:143], a[4:7]
	v_mfma_f32_16x16x32_f16 a[0:3], v[74:77], a[144:147], a[0:3]
	v_mfma_f32_16x16x32_f16 a[0:3], v[78:81], a[144:147], a[0:3]
	v_mfma_f32_16x16x32_f16 a[0:3], v[74:77], a[148:151], a[0:3]
	global_load_dwordx4 a[128:131], v[90:91], off offset:1664
	global_load_dwordx4 a[132:135], v[92:93], off offset:1664
	global_load_dwordx4 a[136:139], v[94:95], off offset:1664
	global_load_dwordx4 a[140:143], v[96:97], off offset:1664
	global_load_dwordx4 a[144:147], v[98:99], off offset:1664
	global_load_dwordx4 a[148:151], v[100:101], off offset:1664
	s_waitcnt vmcnt(54)
; DI f4 mfma16(h8 a, h8 b, f4 c) { return __builtin_amdgcn_mfma_f32_16x16x32_f16(a, b, c, 0, 0, 0); }
; DI void row2_phase(const Params& P, int l, int r_begin, char* smem) {
;     ...
;     for (int kk = 0; kk < 32; kk++) {
;       const int k0 = kk * 32;
;       float x[8], g[8], s1[8], s0[8];
;       *(float4*)&x[0] = *(const float4*)(xm + k0); *(float4*)&x[4] = *(const float4*)(xm + k0 + 4);
;       *(float4*)&g[0] = *(const float4*)(gam + fq * 8 + k0); *(float4*)&g[4] = *(const float4*)(gam + fq * 8 + k0 + 4);
;       *(float4*)&s1[0] = *(const float4*)(sc + k0); *(float4*)&s1[4] = *(const float4*)(sc + k0 + 4);
;       *(float4*)&s0[0] = *(const float4*)(sh + k0); *(float4*)&s0[4] = *(const float4*)(sh + k0 + 4);
;       h8 hi, lo;
; #pragma unroll
;       for (int i = 0; i < 8; i++) {
;         float v = x[i] * rstd * g[i] * (1.f + s1[i]) + s0[i];
;         hi[i] = (half_t)v; lo[i] = (half_t)(v - (float)hi[i]);
;       }
;       *(h8*)(hxo + k0) = hi;
; #pragma unroll
;       for (int n3 = 0; n3 < 3; n3++) {
;         h8 bh = *(const h8*)(Whi + (size_t)(n3 * 16 + fr) * 1024 + k0 + fq * 8);
;         h8 bl = *(const h8*)(Wlo + (size_t)(n3 * 16 + fr) * 1024 + k0 + fq * 8);
;         acc[n3] = mfma16(hi, bh, acc[n3]); acc[n3] = mfma16(lo, bh, acc[n3]); acc[n3] = mfma16(hi, bl, acc[n3]);
;       }
;     }
	v_accvgpr_read_b32 v0, a24
	v_accvgpr_read_b32 v1, a25
	v_accvgpr_read_b32 v2, a26
	v_accvgpr_read_b32 v3, a27
	v_accvgpr_read_b32 v4, a28
	v_accvgpr_read_b32 v5, a29
	v_accvgpr_read_b32 v6, a30
	v_accvgpr_read_b32 v7, a31
	global_load_dwordx4 a[24:27], v[22:23], off offset:3968 nt
	global_load_dwordx4 a[28:31], v[22:23], off offset:3984 nt
	v_pk_mul_f32 v[0:1], v[28:29], v[0:1]
	v_pk_mul_f32 v[2:3], v[28:29], v[2:3]
	v_pk_mul_f32 v[4:5], v[28:29], v[4:5]
	v_pk_mul_f32 v[6:7], v[28:29], v[6:7]
	s_waitcnt lgkmcnt(0)
	v_pk_mul_f32 v[0:1], v[0:1], v[32:33]
	v_pk_mul_f32 v[2:3], v[2:3], v[34:35]
	v_pk_mul_f32 v[4:5], v[4:5], v[36:37]
	v_pk_mul_f32 v[6:7], v[6:7], v[38:39]
	v_pk_add_f32 v[40:41], v[40:41], 1.0 op_sel_hi:[1,0]
	v_pk_add_f32 v[42:43], v[42:43], 1.0 op_sel_hi:[1,0]
	v_pk_add_f32 v[44:45], v[44:45], 1.0 op_sel_hi:[1,0]
	v_pk_add_f32 v[46:47], v[46:47], 1.0 op_sel_hi:[1,0]
	v_pk_fma_f32 v[0:1], v[0:1], v[40:41], v[58:59]
	v_pk_fma_f32 v[2:3], v[2:3], v[42:43], v[60:61]
	v_pk_fma_f32 v[4:5], v[4:5], v[44:45], v[62:63]
	v_pk_fma_f32 v[6:7], v[6:7], v[46:47], v[64:65]
	ds_read_b128 v[32:35], v102 offset:2816
	ds_read_b128 v[36:39], v102 offset:2832
	ds_read_b128 v[40:43], v102 offset:6912
	ds_read_b128 v[44:47], v102 offset:6928
	ds_read_b128 v[58:61], v102 offset:11008
	ds_read_b128 v[62:65], v102 offset:11024
	v_cvt_pk_f16_f32 v74, v0, v1
	v_cvt_pk_f16_f32 v75, v2, v3
	v_cvt_pk_f16_f32 v76, v4, v5
	v_cvt_pk_f16_f32 v77, v6, v7
	v_cvt_f32_f16_e32 v66, v74
	v_cvt_f32_f16_sdwa v67, v74 dst_sel:DWORD dst_unused:UNUSED_PAD src0_sel:WORD_1
	v_cvt_f32_f16_e32 v68, v75
	v_cvt_f32_f16_sdwa v69, v75 dst_sel:DWORD dst_unused:UNUSED_PAD src0_sel:WORD_1
	v_cvt_f32_f16_e32 v70, v76
	v_cvt_f32_f16_sdwa v71, v76 dst_sel:DWORD dst_unused:UNUSED_PAD src0_sel:WORD_1
	v_cvt_f32_f16_e32 v72, v77
	v_cvt_f32_f16_sdwa v73, v77 dst_sel:DWORD dst_unused:UNUSED_PAD src0_sel:WORD_1
	v_pk_add_f32 v[0:1], v[0:1], v[66:67] neg_lo:[0,1] neg_hi:[0,1]
	v_pk_add_f32 v[2:3], v[2:3], v[68:69] neg_lo:[0,1] neg_hi:[0,1]
	v_pk_add_f32 v[4:5], v[4:5], v[70:71] neg_lo:[0,1] neg_hi:[0,1]
	v_pk_add_f32 v[6:7], v[6:7], v[72:73] neg_lo:[0,1] neg_hi:[0,1]
	s_nop 0
	v_cvt_pk_f16_f32 v78, v0, v1
	v_cvt_pk_f16_f32 v79, v2, v3
	v_cvt_pk_f16_f32 v80, v4, v5
	v_cvt_pk_f16_f32 v81, v6, v7
	global_store_dwordx4 v[88:89], v[74:77], off offset:1344
	s_waitcnt vmcnt(48)
	v_mfma_f32_16x16x32_f16 a[8:11], v[74:77], a[152:155], a[8:11]
	v_mfma_f32_16x16x32_f16 a[8:11], v[78:81], a[152:155], a[8:11]
	v_mfma_f32_16x16x32_f16 a[8:11], v[74:77], a[156:159], a[8:11]
	v_mfma_f32_16x16x32_f16 a[4:7], v[74:77], a[160:163], a[4:7]
	v_mfma_f32_16x16x32_f16 a[4:7], v[78:81], a[160:163], a[4:7]
	v_mfma_f32_16x16x32_f16 a[4:7], v[74:77], a[164:167], a[4:7]
	v_mfma_f32_16x16x32_f16 a[0:3], v[74:77], a[168:171], a[0:3]
	v_mfma_f32_16x16x32_f16 a[0:3], v[78:81], a[168:171], a[0:3]
	v_mfma_f32_16x16x32_f16 a[0:3], v[74:77], a[172:175], a[0:3]
	global_load_dwordx4 a[152:155], v[90:91], off offset:1728
	global_load_dwordx4 a[156:159], v[92:93], off offset:1728
	global_load_dwordx4 a[160:163], v[94:95], off offset:1728
	global_load_dwordx4 a[164:167], v[96:97], off offset:1728
	global_load_dwordx4 a[168:171], v[98:99], off offset:1728
	global_load_dwordx4 a[172:175], v[100:101], off offset:1728
	s_waitcnt vmcnt(54)
	v_accvgpr_read_b32 v0, a32
	v_accvgpr_read_b32 v1, a33
	v_accvgpr_read_b32 v2, a34
	v_accvgpr_read_b32 v3, a35
	v_accvgpr_read_b32 v4, a36
	v_accvgpr_read_b32 v5, a37
	v_accvgpr_read_b32 v6, a38
	v_accvgpr_read_b32 v7, a39
	v_pk_mul_f32 v[0:1], v[28:29], v[0:1]
	v_pk_mul_f32 v[2:3], v[28:29], v[2:3]
	v_pk_mul_f32 v[4:5], v[28:29], v[4:5]
	v_pk_mul_f32 v[6:7], v[28:29], v[6:7]
	s_waitcnt lgkmcnt(0)
	v_pk_mul_f32 v[0:1], v[0:1], v[32:33]
	v_pk_mul_f32 v[2:3], v[2:3], v[34:35]
	v_pk_mul_f32 v[4:5], v[4:5], v[36:37]
	v_pk_mul_f32 v[6:7], v[6:7], v[38:39]
	v_pk_add_f32 v[40:41], v[40:41], 1.0 op_sel_hi:[1,0]
	v_pk_add_f32 v[42:43], v[42:43], 1.0 op_sel_hi:[1,0]
	v_pk_add_f32 v[44:45], v[44:45], 1.0 op_sel_hi:[1,0]
	v_pk_add_f32 v[46:47], v[46:47], 1.0 op_sel_hi:[1,0]
	v_pk_fma_f32 v[0:1], v[0:1], v[40:41], v[58:59]
	v_pk_fma_f32 v[2:3], v[2:3], v[42:43], v[60:61]
	v_pk_fma_f32 v[4:5], v[4:5], v[44:45], v[62:63]
	v_pk_fma_f32 v[6:7], v[6:7], v[46:47], v[64:65]
	ds_read_b128 v[32:35], v102 offset:2944
	ds_read_b128 v[36:39], v102 offset:2960
	ds_read_b128 v[40:43], v102 offset:7040
	ds_read_b128 v[44:47], v102 offset:7056
	ds_read_b128 v[58:61], v102 offset:11136
	ds_read_b128 v[62:65], v102 offset:11152
	v_cvt_pk_f16_f32 v74, v0, v1
	v_cvt_pk_f16_f32 v75, v2, v3
	v_cvt_pk_f16_f32 v76, v4, v5
	v_cvt_pk_f16_f32 v77, v6, v7
	v_cvt_f32_f16_e32 v66, v74
	v_cvt_f32_f16_sdwa v67, v74 dst_sel:DWORD dst_unused:UNUSED_PAD src0_sel:WORD_1
	v_cvt_f32_f16_e32 v68, v75
	v_cvt_f32_f16_sdwa v69, v75 dst_sel:DWORD dst_unused:UNUSED_PAD src0_sel:WORD_1
	v_cvt_f32_f16_e32 v70, v76
	v_cvt_f32_f16_sdwa v71, v76 dst_sel:DWORD dst_unused:UNUSED_PAD src0_sel:WORD_1
	v_cvt_f32_f16_e32 v72, v77
	v_cvt_f32_f16_sdwa v73, v77 dst_sel:DWORD dst_unused:UNUSED_PAD src0_sel:WORD_1
	v_pk_add_f32 v[0:1], v[0:1], v[66:67] neg_lo:[0,1] neg_hi:[0,1]
	v_pk_add_f32 v[2:3], v[2:3], v[68:69] neg_lo:[0,1] neg_hi:[0,1]
	v_pk_add_f32 v[4:5], v[4:5], v[70:71] neg_lo:[0,1] neg_hi:[0,1]
	v_pk_add_f32 v[6:7], v[6:7], v[72:73] neg_lo:[0,1] neg_hi:[0,1]
	s_nop 0
	v_cvt_pk_f16_f32 v78, v0, v1
	v_cvt_pk_f16_f32 v79, v2, v3
	v_cvt_pk_f16_f32 v80, v4, v5
	v_cvt_pk_f16_f32 v81, v6, v7
	global_store_dwordx4 v[88:89], v[74:77], off offset:1408
	s_waitcnt vmcnt(46)
; DI f4 mfma16(h8 a, h8 b, f4 c) { return __builtin_amdgcn_mfma_f32_16x16x32_f16(a, b, c, 0, 0, 0); }
; DI void row2_phase(const Params& P, int l, int r_begin, char* smem) {
;     ...
;     for (int kk = 0; kk < 32; kk++) {
;       const int k0 = kk * 32;
;       float x[8], g[8], s1[8], s0[8];
;       *(float4*)&x[0] = *(const float4*)(xm + k0); *(float4*)&x[4] = *(const float4*)(xm + k0 + 4);
;       *(float4*)&g[0] = *(const float4*)(gam + fq * 8 + k0); *(float4*)&g[4] = *(const float4*)(gam + fq * 8 + k0 + 4);
;       *(float4*)&s1[0] = *(const float4*)(sc + k0); *(float4*)&s1[4] = *(const float4*)(sc + k0 + 4);
;       *(float4*)&s0[0] = *(const float4*)(sh + k0); *(float4*)&s0[4] = *(const float4*)(sh + k0 + 4);
;       h8 hi, lo;
; #pragma unroll
;       for (int i = 0; i < 8; i++) {
;         float v = x[i] * rstd * g[i] * (1.f + s1[i]) + s0[i];
;         hi[i] = (half_t)v; lo[i] = (half_t)(v - (float)hi[i]);
;       }
;       *(h8*)(hxo + k0) = hi;
; #pragma unroll
;       for (int n3 = 0; n3 < 3; n3++) {
;         h8 bh = *(const h8*)(Whi + (size_t)(n3 * 16 + fr) * 1024 + k0 + fq * 8);
;         h8 bl = *(const h8*)(Wlo + (size_t)(n3 * 16 + fr) * 1024 + k0 + fq * 8);
;         acc[n3] = mfma16(hi, bh, acc[n3]); acc[n3] = mfma16(lo, bh, acc[n3]); acc[n3] = mfma16(hi, bl, acc[n3]);
;       }
;     }
	v_mfma_f32_16x16x32_f16 a[8:11], v[74:77], a[204:207], a[8:11]
	v_mfma_f32_16x16x32_f16 a[8:11], v[78:81], a[204:207], a[8:11]
	v_mfma_f32_16x16x32_f16 a[8:11], v[74:77], a[208:211], a[8:11]
	v_mfma_f32_16x16x32_f16 a[4:7], v[74:77], a[212:215], a[4:7]
	v_mfma_f32_16x16x32_f16 a[4:7], v[78:81], a[212:215], a[4:7]
	v_mfma_f32_16x16x32_f16 a[4:7], v[74:77], a[216:219], a[4:7]
	v_mfma_f32_16x16x32_f16 a[0:3], v[74:77], a[220:223], a[0:3]
	v_mfma_f32_16x16x32_f16 a[0:3], v[78:81], a[220:223], a[0:3]
	v_mfma_f32_16x16x32_f16 a[0:3], v[74:77], a[224:227], a[0:3]
	global_load_dwordx4 a[204:207], v[90:91], off offset:1792
	global_load_dwordx4 a[208:211], v[92:93], off offset:1792
	global_load_dwordx4 a[212:215], v[94:95], off offset:1792
	global_load_dwordx4 a[216:219], v[96:97], off offset:1792
	global_load_dwordx4 a[220:223], v[98:99], off offset:1792
	global_load_dwordx4 a[224:227], v[100:101], off offset:1792
	s_waitcnt vmcnt(52)
	v_accvgpr_read_b32 v0, a40
	v_accvgpr_read_b32 v1, a41
	v_accvgpr_read_b32 v2, a42
	v_accvgpr_read_b32 v3, a43
	v_accvgpr_read_b32 v4, a44
	v_accvgpr_read_b32 v5, a45
	v_accvgpr_read_b32 v6, a46
	v_accvgpr_read_b32 v7, a47
	v_pk_mul_f32 v[0:1], v[28:29], v[0:1]
	v_pk_mul_f32 v[2:3], v[28:29], v[2:3]
	v_pk_mul_f32 v[4:5], v[28:29], v[4:5]
	v_pk_mul_f32 v[6:7], v[28:29], v[6:7]
	s_waitcnt lgkmcnt(0)
	v_pk_mul_f32 v[0:1], v[0:1], v[32:33]
	v_pk_mul_f32 v[2:3], v[2:3], v[34:35]
	v_pk_mul_f32 v[4:5], v[4:5], v[36:37]
	v_pk_mul_f32 v[6:7], v[6:7], v[38:39]
	v_pk_add_f32 v[40:41], v[40:41], 1.0 op_sel_hi:[1,0]
	v_pk_add_f32 v[42:43], v[42:43], 1.0 op_sel_hi:[1,0]
	v_pk_add_f32 v[44:45], v[44:45], 1.0 op_sel_hi:[1,0]
	v_pk_add_f32 v[46:47], v[46:47], 1.0 op_sel_hi:[1,0]
	v_pk_fma_f32 v[0:1], v[0:1], v[40:41], v[58:59]
	v_pk_fma_f32 v[2:3], v[2:3], v[42:43], v[60:61]
	v_pk_fma_f32 v[4:5], v[4:5], v[44:45], v[62:63]
	v_pk_fma_f32 v[6:7], v[6:7], v[46:47], v[64:65]
	ds_read_b128 v[32:35], v102 offset:3072
	ds_read_b128 v[36:39], v102 offset:3088
	ds_read_b128 v[40:43], v102 offset:7168
	ds_read_b128 v[44:47], v102 offset:7184
	ds_read_b128 v[58:61], v102 offset:11264
	ds_read_b128 v[62:65], v102 offset:11280
	v_cvt_pk_f16_f32 v74, v0, v1
	v_cvt_pk_f16_f32 v75, v2, v3
	v_cvt_pk_f16_f32 v76, v4, v5
	v_cvt_pk_f16_f32 v77, v6, v7
	v_cvt_f32_f16_e32 v66, v74
	v_cvt_f32_f16_sdwa v67, v74 dst_sel:DWORD dst_unused:UNUSED_PAD src0_sel:WORD_1
	v_cvt_f32_f16_e32 v68, v75
	v_cvt_f32_f16_sdwa v69, v75 dst_sel:DWORD dst_unused:UNUSED_PAD src0_sel:WORD_1
	v_cvt_f32_f16_e32 v70, v76
	v_cvt_f32_f16_sdwa v71, v76 dst_sel:DWORD dst_unused:UNUSED_PAD src0_sel:WORD_1
	v_cvt_f32_f16_e32 v72, v77
	v_cvt_f32_f16_sdwa v73, v77 dst_sel:DWORD dst_unused:UNUSED_PAD src0_sel:WORD_1
	v_pk_add_f32 v[0:1], v[0:1], v[66:67] neg_lo:[0,1] neg_hi:[0,1]
	v_pk_add_f32 v[2:3], v[2:3], v[68:69] neg_lo:[0,1] neg_hi:[0,1]
	v_pk_add_f32 v[4:5], v[4:5], v[70:71] neg_lo:[0,1] neg_hi:[0,1]
	v_pk_add_f32 v[6:7], v[6:7], v[72:73] neg_lo:[0,1] neg_hi:[0,1]
	s_nop 0
	v_cvt_pk_f16_f32 v78, v0, v1
	v_cvt_pk_f16_f32 v79, v2, v3
	v_cvt_pk_f16_f32 v80, v4, v5
	v_cvt_pk_f16_f32 v81, v6, v7
	global_store_dwordx4 v[88:89], v[74:77], off offset:1472
	s_waitcnt vmcnt(44)
	v_mfma_f32_16x16x32_f16 a[8:11], v[74:77], a[228:231], a[8:11]
	v_mfma_f32_16x16x32_f16 a[8:11], v[78:81], a[228:231], a[8:11]
	v_mfma_f32_16x16x32_f16 a[8:11], v[74:77], a[232:235], a[8:11]
	v_mfma_f32_16x16x32_f16 a[4:7], v[74:77], a[236:239], a[4:7]
	v_mfma_f32_16x16x32_f16 a[4:7], v[78:81], a[236:239], a[4:7]
	v_mfma_f32_16x16x32_f16 a[4:7], v[74:77], a[240:243], a[4:7]
	v_mfma_f32_16x16x32_f16 a[0:3], v[74:77], a[244:247], a[0:3]
	v_mfma_f32_16x16x32_f16 a[0:3], v[78:81], a[244:247], a[0:3]
	v_mfma_f32_16x16x32_f16 a[0:3], v[74:77], a[248:251], a[0:3]
	global_load_dwordx4 a[228:231], v[90:91], off offset:1856
	global_load_dwordx4 a[232:235], v[92:93], off offset:1856
	global_load_dwordx4 a[236:239], v[94:95], off offset:1856
	global_load_dwordx4 a[240:243], v[96:97], off offset:1856
	global_load_dwordx4 a[244:247], v[98:99], off offset:1856
	global_load_dwordx4 a[248:251], v[100:101], off offset:1856
	s_waitcnt vmcnt(50)
	v_accvgpr_read_b32 v0, a48
	v_accvgpr_read_b32 v1, a49
	v_accvgpr_read_b32 v2, a50
	v_accvgpr_read_b32 v3, a51
	v_accvgpr_read_b32 v4, a52
	v_accvgpr_read_b32 v5, a53
	v_accvgpr_read_b32 v6, a54
	v_accvgpr_read_b32 v7, a55
	v_pk_mul_f32 v[0:1], v[28:29], v[0:1]
	v_pk_mul_f32 v[2:3], v[28:29], v[2:3]
	v_pk_mul_f32 v[4:5], v[28:29], v[4:5]
	v_pk_mul_f32 v[6:7], v[28:29], v[6:7]
	s_waitcnt lgkmcnt(0)
	v_pk_mul_f32 v[0:1], v[0:1], v[32:33]
	v_pk_mul_f32 v[2:3], v[2:3], v[34:35]
	v_pk_mul_f32 v[4:5], v[4:5], v[36:37]
	v_pk_mul_f32 v[6:7], v[6:7], v[38:39]
	v_pk_add_f32 v[40:41], v[40:41], 1.0 op_sel_hi:[1,0]
	v_pk_add_f32 v[42:43], v[42:43], 1.0 op_sel_hi:[1,0]
	v_pk_add_f32 v[44:45], v[44:45], 1.0 op_sel_hi:[1,0]
	v_pk_add_f32 v[46:47], v[46:47], 1.0 op_sel_hi:[1,0]
	v_pk_fma_f32 v[0:1], v[0:1], v[40:41], v[58:59]
	v_pk_fma_f32 v[2:3], v[2:3], v[42:43], v[60:61]
	v_pk_fma_f32 v[4:5], v[4:5], v[44:45], v[62:63]
	v_pk_fma_f32 v[6:7], v[6:7], v[46:47], v[64:65]
	ds_read_b128 v[32:35], v102 offset:3200
	ds_read_b128 v[36:39], v102 offset:3216
	ds_read_b128 v[40:43], v102 offset:7296
	ds_read_b128 v[44:47], v102 offset:7312
	ds_read_b128 v[58:61], v102 offset:11392
	ds_read_b128 v[62:65], v102 offset:11408
	v_cvt_pk_f16_f32 v74, v0, v1
	v_cvt_pk_f16_f32 v75, v2, v3
	v_cvt_pk_f16_f32 v76, v4, v5
	v_cvt_pk_f16_f32 v77, v6, v7
	v_cvt_f32_f16_e32 v66, v74
	v_cvt_f32_f16_sdwa v67, v74 dst_sel:DWORD dst_unused:UNUSED_PAD src0_sel:WORD_1
	v_cvt_f32_f16_e32 v68, v75
	v_cvt_f32_f16_sdwa v69, v75 dst_sel:DWORD dst_unused:UNUSED_PAD src0_sel:WORD_1
	v_cvt_f32_f16_e32 v70, v76
	v_cvt_f32_f16_sdwa v71, v76 dst_sel:DWORD dst_unused:UNUSED_PAD src0_sel:WORD_1
	v_cvt_f32_f16_e32 v72, v77
	v_cvt_f32_f16_sdwa v73, v77 dst_sel:DWORD dst_unused:UNUSED_PAD src0_sel:WORD_1
	v_pk_add_f32 v[0:1], v[0:1], v[66:67] neg_lo:[0,1] neg_hi:[0,1]
	v_pk_add_f32 v[2:3], v[2:3], v[68:69] neg_lo:[0,1] neg_hi:[0,1]
	v_pk_add_f32 v[4:5], v[4:5], v[70:71] neg_lo:[0,1] neg_hi:[0,1]
	v_pk_add_f32 v[6:7], v[6:7], v[72:73] neg_lo:[0,1] neg_hi:[0,1]
	s_nop 0
	v_cvt_pk_f16_f32 v78, v0, v1
	v_cvt_pk_f16_f32 v79, v2, v3
	v_cvt_pk_f16_f32 v80, v4, v5
	v_cvt_pk_f16_f32 v81, v6, v7
	global_store_dwordx4 v[88:89], v[74:77], off offset:1536
	s_waitcnt vmcnt(42)
; DI f4 mfma16(h8 a, h8 b, f4 c) { return __builtin_amdgcn_mfma_f32_16x16x32_f16(a, b, c, 0, 0, 0); }
; DI void row2_phase(const Params& P, int l, int r_begin, char* smem) {
;     ...
;     for (int kk = 0; kk < 32; kk++) {
;       const int k0 = kk * 32;
;       float x[8], g[8], s1[8], s0[8];
;       *(float4*)&x[0] = *(const float4*)(xm + k0); *(float4*)&x[4] = *(const float4*)(xm + k0 + 4);
;       *(float4*)&g[0] = *(const float4*)(gam + fq * 8 + k0); *(float4*)&g[4] = *(const float4*)(gam + fq * 8 + k0 + 4);
;       *(float4*)&s1[0] = *(const float4*)(sc + k0); *(float4*)&s1[4] = *(const float4*)(sc + k0 + 4);
;       *(float4*)&s0[0] = *(const float4*)(sh + k0); *(float4*)&s0[4] = *(const float4*)(sh + k0 + 4);
;       h8 hi, lo;
; #pragma unroll
;       for (int i = 0; i < 8; i++) {
;         float v = x[i] * rstd * g[i] * (1.f + s1[i]) + s0[i];
;         hi[i] = (half_t)v; lo[i] = (half_t)(v - (float)hi[i]);
;       }
;       *(h8*)(hxo + k0) = hi;
; #pragma unroll
;       for (int n3 = 0; n3 < 3; n3++) {
;         h8 bh = *(const h8*)(Whi + (size_t)(n3 * 16 + fr) * 1024 + k0 + fq * 8);
;         h8 bl = *(const h8*)(Wlo + (size_t)(n3 * 16 + fr) * 1024 + k0 + fq * 8);
;         acc[n3] = mfma16(hi, bh, acc[n3]); acc[n3] = mfma16(lo, bh, acc[n3]); acc[n3] = mfma16(hi, bl, acc[n3]);
;       }
;     }
	v_mfma_f32_16x16x32_f16 a[8:11], v[74:77], a[80:83], a[8:11]
	v_mfma_f32_16x16x32_f16 a[8:11], v[78:81], a[80:83], a[8:11]
	v_mfma_f32_16x16x32_f16 a[8:11], v[74:77], a[84:87], a[8:11]
	v_mfma_f32_16x16x32_f16 a[4:7], v[74:77], a[88:91], a[4:7]
	v_mfma_f32_16x16x32_f16 a[4:7], v[78:81], a[88:91], a[4:7]
	v_mfma_f32_16x16x32_f16 a[4:7], v[74:77], a[92:95], a[4:7]
	v_mfma_f32_16x16x32_f16 a[0:3], v[74:77], a[96:99], a[0:3]
	v_mfma_f32_16x16x32_f16 a[0:3], v[78:81], a[96:99], a[0:3]
	v_mfma_f32_16x16x32_f16 a[0:3], v[74:77], a[100:103], a[0:3]
	global_load_dwordx4 a[80:83], v[90:91], off offset:1920
	global_load_dwordx4 a[84:87], v[92:93], off offset:1920
	global_load_dwordx4 a[88:91], v[94:95], off offset:1920
	global_load_dwordx4 a[92:95], v[96:97], off offset:1920
	global_load_dwordx4 a[96:99], v[98:99], off offset:1920
	global_load_dwordx4 a[100:103], v[100:101], off offset:1920
	s_waitcnt vmcnt(48)
	v_accvgpr_read_b32 v0, a56
	v_accvgpr_read_b32 v1, a57
	v_accvgpr_read_b32 v2, a58
	v_accvgpr_read_b32 v3, a59
	v_accvgpr_read_b32 v4, a60
	v_accvgpr_read_b32 v5, a61
	v_accvgpr_read_b32 v6, a62
	v_accvgpr_read_b32 v7, a63
	v_pk_mul_f32 v[0:1], v[28:29], v[0:1]
	v_pk_mul_f32 v[2:3], v[28:29], v[2:3]
	v_pk_mul_f32 v[4:5], v[28:29], v[4:5]
	v_pk_mul_f32 v[6:7], v[28:29], v[6:7]
	s_waitcnt lgkmcnt(0)
	v_pk_mul_f32 v[0:1], v[0:1], v[32:33]
	v_pk_mul_f32 v[2:3], v[2:3], v[34:35]
	v_pk_mul_f32 v[4:5], v[4:5], v[36:37]
	v_pk_mul_f32 v[6:7], v[6:7], v[38:39]
	v_pk_add_f32 v[40:41], v[40:41], 1.0 op_sel_hi:[1,0]
	v_pk_add_f32 v[42:43], v[42:43], 1.0 op_sel_hi:[1,0]
	v_pk_add_f32 v[44:45], v[44:45], 1.0 op_sel_hi:[1,0]
	v_pk_add_f32 v[46:47], v[46:47], 1.0 op_sel_hi:[1,0]
	v_pk_fma_f32 v[0:1], v[0:1], v[40:41], v[58:59]
	v_pk_fma_f32 v[2:3], v[2:3], v[42:43], v[60:61]
	v_pk_fma_f32 v[4:5], v[4:5], v[44:45], v[62:63]
	v_pk_fma_f32 v[6:7], v[6:7], v[46:47], v[64:65]
	ds_read_b128 v[32:35], v102 offset:3328
	ds_read_b128 v[36:39], v102 offset:3344
	ds_read_b128 v[40:43], v102 offset:7424
	ds_read_b128 v[44:47], v102 offset:7440
	ds_read_b128 v[58:61], v102 offset:11520
	ds_read_b128 v[62:65], v102 offset:11536
	v_cvt_pk_f16_f32 v74, v0, v1
	v_cvt_pk_f16_f32 v75, v2, v3
	v_cvt_pk_f16_f32 v76, v4, v5
	v_cvt_pk_f16_f32 v77, v6, v7
	v_cvt_f32_f16_e32 v66, v74
	v_cvt_f32_f16_sdwa v67, v74 dst_sel:DWORD dst_unused:UNUSED_PAD src0_sel:WORD_1
	v_cvt_f32_f16_e32 v68, v75
	v_cvt_f32_f16_sdwa v69, v75 dst_sel:DWORD dst_unused:UNUSED_PAD src0_sel:WORD_1
	v_cvt_f32_f16_e32 v70, v76
	v_cvt_f32_f16_sdwa v71, v76 dst_sel:DWORD dst_unused:UNUSED_PAD src0_sel:WORD_1
	v_cvt_f32_f16_e32 v72, v77
	v_cvt_f32_f16_sdwa v73, v77 dst_sel:DWORD dst_unused:UNUSED_PAD src0_sel:WORD_1
	v_pk_add_f32 v[0:1], v[0:1], v[66:67] neg_lo:[0,1] neg_hi:[0,1]
	v_pk_add_f32 v[2:3], v[2:3], v[68:69] neg_lo:[0,1] neg_hi:[0,1]
	v_pk_add_f32 v[4:5], v[4:5], v[70:71] neg_lo:[0,1] neg_hi:[0,1]
	v_pk_add_f32 v[6:7], v[6:7], v[72:73] neg_lo:[0,1] neg_hi:[0,1]
	s_nop 0
	v_cvt_pk_f16_f32 v78, v0, v1
	v_cvt_pk_f16_f32 v79, v2, v3
	v_cvt_pk_f16_f32 v80, v4, v5
	v_cvt_pk_f16_f32 v81, v6, v7
	global_store_dwordx4 v[88:89], v[74:77], off offset:1600
	s_waitcnt vmcnt(40)
	v_mfma_f32_16x16x32_f16 a[8:11], v[74:77], a[104:107], a[8:11]
	v_mfma_f32_16x16x32_f16 a[8:11], v[78:81], a[104:107], a[8:11]
	v_mfma_f32_16x16x32_f16 a[8:11], v[74:77], a[108:111], a[8:11]
	v_mfma_f32_16x16x32_f16 a[4:7], v[74:77], a[112:115], a[4:7]
	v_mfma_f32_16x16x32_f16 a[4:7], v[78:81], a[112:115], a[4:7]
	v_mfma_f32_16x16x32_f16 a[4:7], v[74:77], a[116:119], a[4:7]
	v_mfma_f32_16x16x32_f16 a[0:3], v[74:77], a[120:123], a[0:3]
	v_mfma_f32_16x16x32_f16 a[0:3], v[78:81], a[120:123], a[0:3]
	v_mfma_f32_16x16x32_f16 a[0:3], v[74:77], a[124:127], a[0:3]
	global_load_dwordx4 a[104:107], v[90:91], off offset:1984
	global_load_dwordx4 a[108:111], v[92:93], off offset:1984
	global_load_dwordx4 a[112:115], v[94:95], off offset:1984
	global_load_dwordx4 a[116:119], v[96:97], off offset:1984
	global_load_dwordx4 a[120:123], v[98:99], off offset:1984
	global_load_dwordx4 a[124:127], v[100:101], off offset:1984
	s_waitcnt vmcnt(46)
	v_accvgpr_read_b32 v0, a64
	v_accvgpr_read_b32 v1, a65
	v_accvgpr_read_b32 v2, a66
	v_accvgpr_read_b32 v3, a67
	v_accvgpr_read_b32 v4, a68
	v_accvgpr_read_b32 v5, a69
	v_accvgpr_read_b32 v6, a70
	v_accvgpr_read_b32 v7, a71
	v_pk_mul_f32 v[0:1], v[28:29], v[0:1]
	v_pk_mul_f32 v[2:3], v[28:29], v[2:3]
	v_pk_mul_f32 v[4:5], v[28:29], v[4:5]
	v_pk_mul_f32 v[6:7], v[28:29], v[6:7]
	s_waitcnt lgkmcnt(0)
	v_pk_mul_f32 v[0:1], v[0:1], v[32:33]
	v_pk_mul_f32 v[2:3], v[2:3], v[34:35]
	v_pk_mul_f32 v[4:5], v[4:5], v[36:37]
	v_pk_mul_f32 v[6:7], v[6:7], v[38:39]
	v_pk_add_f32 v[40:41], v[40:41], 1.0 op_sel_hi:[1,0]
	v_pk_add_f32 v[42:43], v[42:43], 1.0 op_sel_hi:[1,0]
	v_pk_add_f32 v[44:45], v[44:45], 1.0 op_sel_hi:[1,0]
	v_pk_add_f32 v[46:47], v[46:47], 1.0 op_sel_hi:[1,0]
	v_pk_fma_f32 v[0:1], v[0:1], v[40:41], v[58:59]
	v_pk_fma_f32 v[2:3], v[2:3], v[42:43], v[60:61]
	v_pk_fma_f32 v[4:5], v[4:5], v[44:45], v[62:63]
	v_pk_fma_f32 v[6:7], v[6:7], v[46:47], v[64:65]
	ds_read_b128 v[32:35], v102 offset:3456
	ds_read_b128 v[36:39], v102 offset:3472
	ds_read_b128 v[40:43], v102 offset:7552
	ds_read_b128 v[44:47], v102 offset:7568
	ds_read_b128 v[58:61], v102 offset:11648
	ds_read_b128 v[62:65], v102 offset:11664
	v_cvt_pk_f16_f32 v74, v0, v1
	v_cvt_pk_f16_f32 v75, v2, v3
	v_cvt_pk_f16_f32 v76, v4, v5
	v_cvt_pk_f16_f32 v77, v6, v7
	v_cvt_f32_f16_e32 v66, v74
	v_cvt_f32_f16_sdwa v67, v74 dst_sel:DWORD dst_unused:UNUSED_PAD src0_sel:WORD_1
	v_cvt_f32_f16_e32 v68, v75
	v_cvt_f32_f16_sdwa v69, v75 dst_sel:DWORD dst_unused:UNUSED_PAD src0_sel:WORD_1
	v_cvt_f32_f16_e32 v70, v76
	v_cvt_f32_f16_sdwa v71, v76 dst_sel:DWORD dst_unused:UNUSED_PAD src0_sel:WORD_1
	v_cvt_f32_f16_e32 v72, v77
	v_cvt_f32_f16_sdwa v73, v77 dst_sel:DWORD dst_unused:UNUSED_PAD src0_sel:WORD_1
	v_pk_add_f32 v[0:1], v[0:1], v[66:67] neg_lo:[0,1] neg_hi:[0,1]
	v_pk_add_f32 v[2:3], v[2:3], v[68:69] neg_lo:[0,1] neg_hi:[0,1]
	v_pk_add_f32 v[4:5], v[4:5], v[70:71] neg_lo:[0,1] neg_hi:[0,1]
	v_pk_add_f32 v[6:7], v[6:7], v[72:73] neg_lo:[0,1] neg_hi:[0,1]
	s_nop 0
	v_cvt_pk_f16_f32 v78, v0, v1
	v_cvt_pk_f16_f32 v79, v2, v3
	v_cvt_pk_f16_f32 v80, v4, v5
	v_cvt_pk_f16_f32 v81, v6, v7
	global_store_dwordx4 v[88:89], v[74:77], off offset:1664
	s_waitcnt vmcnt(38)
; DI f4 mfma16(h8 a, h8 b, f4 c) { return __builtin_amdgcn_mfma_f32_16x16x32_f16(a, b, c, 0, 0, 0); }
; DI void row2_phase(const Params& P, int l, int r_begin, char* smem) {
;     ...
;     for (int kk = 0; kk < 32; kk++) {
;       const int k0 = kk * 32;
;       float x[8], g[8], s1[8], s0[8];
;       *(float4*)&x[0] = *(const float4*)(xm + k0); *(float4*)&x[4] = *(const float4*)(xm + k0 + 4);
;       *(float4*)&g[0] = *(const float4*)(gam + fq * 8 + k0); *(float4*)&g[4] = *(const float4*)(gam + fq * 8 + k0 + 4);
;       *(float4*)&s1[0] = *(const float4*)(sc + k0); *(float4*)&s1[4] = *(const float4*)(sc + k0 + 4);
;       *(float4*)&s0[0] = *(const float4*)(sh + k0); *(float4*)&s0[4] = *(const float4*)(sh + k0 + 4);
;       h8 hi, lo;
; #pragma unroll
;       for (int i = 0; i < 8; i++) {
;         float v = x[i] * rstd * g[i] * (1.f + s1[i]) + s0[i];
;         hi[i] = (half_t)v; lo[i] = (half_t)(v - (float)hi[i]);
;       }
;       *(h8*)(hxo + k0) = hi;
; #pragma unroll
;       for (int n3 = 0; n3 < 3; n3++) {
;         h8 bh = *(const h8*)(Whi + (size_t)(n3 * 16 + fr) * 1024 + k0 + fq * 8);
;         h8 bl = *(const h8*)(Wlo + (size_t)(n3 * 16 + fr) * 1024 + k0 + fq * 8);
;         acc[n3] = mfma16(hi, bh, acc[n3]); acc[n3] = mfma16(lo, bh, acc[n3]); acc[n3] = mfma16(hi, bl, acc[n3]);
;       }
;     }
	v_mfma_f32_16x16x32_f16 a[8:11], v[74:77], a[128:131], a[8:11]
	v_mfma_f32_16x16x32_f16 a[8:11], v[78:81], a[128:131], a[8:11]
	v_mfma_f32_16x16x32_f16 a[8:11], v[74:77], a[132:135], a[8:11]
	v_mfma_f32_16x16x32_f16 a[4:7], v[74:77], a[136:139], a[4:7]
	v_mfma_f32_16x16x32_f16 a[4:7], v[78:81], a[136:139], a[4:7]
	v_mfma_f32_16x16x32_f16 a[4:7], v[74:77], a[140:143], a[4:7]
	v_mfma_f32_16x16x32_f16 a[0:3], v[74:77], a[144:147], a[0:3]
	v_mfma_f32_16x16x32_f16 a[0:3], v[78:81], a[144:147], a[0:3]
	v_mfma_f32_16x16x32_f16 a[0:3], v[74:77], a[148:151], a[0:3]
	s_waitcnt vmcnt(38)
	v_accvgpr_read_b32 v0, a72
	v_accvgpr_read_b32 v1, a73
	v_accvgpr_read_b32 v2, a74
	v_accvgpr_read_b32 v3, a75
	v_accvgpr_read_b32 v4, a76
	v_accvgpr_read_b32 v5, a77
	v_accvgpr_read_b32 v6, a78
	v_accvgpr_read_b32 v7, a79
	v_pk_mul_f32 v[0:1], v[28:29], v[0:1]
	v_pk_mul_f32 v[2:3], v[28:29], v[2:3]
	v_pk_mul_f32 v[4:5], v[28:29], v[4:5]
	v_pk_mul_f32 v[6:7], v[28:29], v[6:7]
	s_waitcnt lgkmcnt(0)
	v_pk_mul_f32 v[0:1], v[0:1], v[32:33]
	v_pk_mul_f32 v[2:3], v[2:3], v[34:35]
	v_pk_mul_f32 v[4:5], v[4:5], v[36:37]
	v_pk_mul_f32 v[6:7], v[6:7], v[38:39]
	v_pk_add_f32 v[40:41], v[40:41], 1.0 op_sel_hi:[1,0]
	v_pk_add_f32 v[42:43], v[42:43], 1.0 op_sel_hi:[1,0]
	v_pk_add_f32 v[44:45], v[44:45], 1.0 op_sel_hi:[1,0]
	v_pk_add_f32 v[46:47], v[46:47], 1.0 op_sel_hi:[1,0]
	v_pk_fma_f32 v[0:1], v[0:1], v[40:41], v[58:59]
	v_pk_fma_f32 v[2:3], v[2:3], v[42:43], v[60:61]
	v_pk_fma_f32 v[4:5], v[4:5], v[44:45], v[62:63]
	v_pk_fma_f32 v[6:7], v[6:7], v[46:47], v[64:65]
	ds_read_b128 v[32:35], v102 offset:3584
	ds_read_b128 v[36:39], v102 offset:3600
	ds_read_b128 v[40:43], v102 offset:7680
	ds_read_b128 v[44:47], v102 offset:7696
	ds_read_b128 v[58:61], v102 offset:11776
	ds_read_b128 v[62:65], v102 offset:11792
	v_cvt_pk_f16_f32 v74, v0, v1
	v_cvt_pk_f16_f32 v75, v2, v3
	v_cvt_pk_f16_f32 v76, v4, v5
	v_cvt_pk_f16_f32 v77, v6, v7
	v_cvt_f32_f16_e32 v66, v74
	v_cvt_f32_f16_sdwa v67, v74 dst_sel:DWORD dst_unused:UNUSED_PAD src0_sel:WORD_1
	v_cvt_f32_f16_e32 v68, v75
	v_cvt_f32_f16_sdwa v69, v75 dst_sel:DWORD dst_unused:UNUSED_PAD src0_sel:WORD_1
	v_cvt_f32_f16_e32 v70, v76
	v_cvt_f32_f16_sdwa v71, v76 dst_sel:DWORD dst_unused:UNUSED_PAD src0_sel:WORD_1
	v_cvt_f32_f16_e32 v72, v77
	v_cvt_f32_f16_sdwa v73, v77 dst_sel:DWORD dst_unused:UNUSED_PAD src0_sel:WORD_1
	v_pk_add_f32 v[0:1], v[0:1], v[66:67] neg_lo:[0,1] neg_hi:[0,1]
	v_pk_add_f32 v[2:3], v[2:3], v[68:69] neg_lo:[0,1] neg_hi:[0,1]
	v_pk_add_f32 v[4:5], v[4:5], v[70:71] neg_lo:[0,1] neg_hi:[0,1]
	v_pk_add_f32 v[6:7], v[6:7], v[72:73] neg_lo:[0,1] neg_hi:[0,1]
	s_nop 0
	v_cvt_pk_f16_f32 v78, v0, v1
	v_cvt_pk_f16_f32 v79, v2, v3
	v_cvt_pk_f16_f32 v80, v4, v5
	v_cvt_pk_f16_f32 v81, v6, v7
	global_store_dwordx4 v[88:89], v[74:77], off offset:1728
	s_waitcnt vmcnt(30)
	v_mfma_f32_16x16x32_f16 a[8:11], v[74:77], a[152:155], a[8:11]
	v_mfma_f32_16x16x32_f16 a[8:11], v[78:81], a[152:155], a[8:11]
	v_mfma_f32_16x16x32_f16 a[8:11], v[74:77], a[156:159], a[8:11]
	v_mfma_f32_16x16x32_f16 a[4:7], v[74:77], a[160:163], a[4:7]
	v_mfma_f32_16x16x32_f16 a[4:7], v[78:81], a[160:163], a[4:7]
	v_mfma_f32_16x16x32_f16 a[4:7], v[74:77], a[164:167], a[4:7]
	v_mfma_f32_16x16x32_f16 a[0:3], v[74:77], a[168:171], a[0:3]
	v_mfma_f32_16x16x32_f16 a[0:3], v[78:81], a[168:171], a[0:3]
	v_mfma_f32_16x16x32_f16 a[0:3], v[74:77], a[172:175], a[0:3]
	s_waitcnt vmcnt(30)
	v_accvgpr_read_b32 v0, a180
	v_accvgpr_read_b32 v1, a181
	v_accvgpr_read_b32 v2, a182
	v_accvgpr_read_b32 v3, a183
	v_accvgpr_read_b32 v4, a184
	v_accvgpr_read_b32 v5, a185
	v_accvgpr_read_b32 v6, a186
	v_accvgpr_read_b32 v7, a187
	v_pk_mul_f32 v[0:1], v[28:29], v[0:1]
	v_pk_mul_f32 v[2:3], v[28:29], v[2:3]
	v_pk_mul_f32 v[4:5], v[28:29], v[4:5]
	v_pk_mul_f32 v[6:7], v[28:29], v[6:7]
	s_waitcnt lgkmcnt(0)
	v_pk_mul_f32 v[0:1], v[0:1], v[32:33]
	v_pk_mul_f32 v[2:3], v[2:3], v[34:35]
	v_pk_mul_f32 v[4:5], v[4:5], v[36:37]
	v_pk_mul_f32 v[6:7], v[6:7], v[38:39]
	v_pk_add_f32 v[40:41], v[40:41], 1.0 op_sel_hi:[1,0]
	v_pk_add_f32 v[42:43], v[42:43], 1.0 op_sel_hi:[1,0]
	v_pk_add_f32 v[44:45], v[44:45], 1.0 op_sel_hi:[1,0]
	v_pk_add_f32 v[46:47], v[46:47], 1.0 op_sel_hi:[1,0]
	v_pk_fma_f32 v[0:1], v[0:1], v[40:41], v[58:59]
	v_pk_fma_f32 v[2:3], v[2:3], v[42:43], v[60:61]
	v_pk_fma_f32 v[4:5], v[4:5], v[44:45], v[62:63]
	v_pk_fma_f32 v[6:7], v[6:7], v[46:47], v[64:65]
	ds_read_b128 v[32:35], v102 offset:3712
	ds_read_b128 v[36:39], v102 offset:3728
	ds_read_b128 v[40:43], v102 offset:7808
	ds_read_b128 v[44:47], v102 offset:7824
	ds_read_b128 v[58:61], v102 offset:11904
	ds_read_b128 v[62:65], v102 offset:11920
	v_cvt_pk_f16_f32 v74, v0, v1
	v_cvt_pk_f16_f32 v75, v2, v3
	v_cvt_pk_f16_f32 v76, v4, v5
	v_cvt_pk_f16_f32 v77, v6, v7
	v_cvt_f32_f16_e32 v66, v74
	v_cvt_f32_f16_sdwa v67, v74 dst_sel:DWORD dst_unused:UNUSED_PAD src0_sel:WORD_1
	v_cvt_f32_f16_e32 v68, v75
	v_cvt_f32_f16_sdwa v69, v75 dst_sel:DWORD dst_unused:UNUSED_PAD src0_sel:WORD_1
	v_cvt_f32_f16_e32 v70, v76
	v_cvt_f32_f16_sdwa v71, v76 dst_sel:DWORD dst_unused:UNUSED_PAD src0_sel:WORD_1
	v_cvt_f32_f16_e32 v72, v77
	v_cvt_f32_f16_sdwa v73, v77 dst_sel:DWORD dst_unused:UNUSED_PAD src0_sel:WORD_1
	v_pk_add_f32 v[0:1], v[0:1], v[66:67] neg_lo:[0,1] neg_hi:[0,1]
	v_pk_add_f32 v[2:3], v[2:3], v[68:69] neg_lo:[0,1] neg_hi:[0,1]
	v_pk_add_f32 v[4:5], v[4:5], v[70:71] neg_lo:[0,1] neg_hi:[0,1]
	v_pk_add_f32 v[6:7], v[6:7], v[72:73] neg_lo:[0,1] neg_hi:[0,1]
	s_nop 0
	v_cvt_pk_f16_f32 v78, v0, v1
	v_cvt_pk_f16_f32 v79, v2, v3
	v_cvt_pk_f16_f32 v80, v4, v5
	v_cvt_pk_f16_f32 v81, v6, v7
	global_store_dwordx4 v[88:89], v[74:77], off offset:1792
	s_waitcnt vmcnt(24)
; DI f4 mfma16(h8 a, h8 b, f4 c) { return __builtin_amdgcn_mfma_f32_16x16x32_f16(a, b, c, 0, 0, 0); }
; DI void row2_phase(const Params& P, int l, int r_begin, char* smem) {
;     ...
;     for (int kk = 0; kk < 32; kk++) {
;       const int k0 = kk * 32;
;       float x[8], g[8], s1[8], s0[8];
;       *(float4*)&x[0] = *(const float4*)(xm + k0); *(float4*)&x[4] = *(const float4*)(xm + k0 + 4);
;       *(float4*)&g[0] = *(const float4*)(gam + fq * 8 + k0); *(float4*)&g[4] = *(const float4*)(gam + fq * 8 + k0 + 4);
;       *(float4*)&s1[0] = *(const float4*)(sc + k0); *(float4*)&s1[4] = *(const float4*)(sc + k0 + 4);
;       *(float4*)&s0[0] = *(const float4*)(sh + k0); *(float4*)&s0[4] = *(const float4*)(sh + k0 + 4);
;       h8 hi, lo;
; #pragma unroll
;       for (int i = 0; i < 8; i++) {
;         float v = x[i] * rstd * g[i] * (1.f + s1[i]) + s0[i];
;         hi[i] = (half_t)v; lo[i] = (half_t)(v - (float)hi[i]);
;       }
;       *(h8*)(hxo + k0) = hi;
; #pragma unroll
;       for (int n3 = 0; n3 < 3; n3++) {
;         h8 bh = *(const h8*)(Whi + (size_t)(n3 * 16 + fr) * 1024 + k0 + fq * 8);
;         h8 bl = *(const h8*)(Wlo + (size_t)(n3 * 16 + fr) * 1024 + k0 + fq * 8);
;         acc[n3] = mfma16(hi, bh, acc[n3]); acc[n3] = mfma16(lo, bh, acc[n3]); acc[n3] = mfma16(hi, bl, acc[n3]);
;       }
;     }
	v_mfma_f32_16x16x32_f16 a[8:11], v[74:77], a[204:207], a[8:11]
	v_mfma_f32_16x16x32_f16 a[8:11], v[78:81], a[204:207], a[8:11]
	v_mfma_f32_16x16x32_f16 a[8:11], v[74:77], a[208:211], a[8:11]
	v_mfma_f32_16x16x32_f16 a[4:7], v[74:77], a[212:215], a[4:7]
	v_mfma_f32_16x16x32_f16 a[4:7], v[78:81], a[212:215], a[4:7]
	v_mfma_f32_16x16x32_f16 a[4:7], v[74:77], a[216:219], a[4:7]
	v_mfma_f32_16x16x32_f16 a[0:3], v[74:77], a[220:223], a[0:3]
	v_mfma_f32_16x16x32_f16 a[0:3], v[78:81], a[220:223], a[0:3]
	v_mfma_f32_16x16x32_f16 a[0:3], v[74:77], a[224:227], a[0:3]
	s_waitcnt vmcnt(24)
	v_accvgpr_read_b32 v0, a196
	v_accvgpr_read_b32 v1, a197
	v_accvgpr_read_b32 v2, a198
	v_accvgpr_read_b32 v3, a199
	v_accvgpr_read_b32 v4, a200
	v_accvgpr_read_b32 v5, a201
	v_accvgpr_read_b32 v6, a202
	v_accvgpr_read_b32 v7, a203
	v_pk_mul_f32 v[0:1], v[28:29], v[0:1]
	v_pk_mul_f32 v[2:3], v[28:29], v[2:3]
	v_pk_mul_f32 v[4:5], v[28:29], v[4:5]
	v_pk_mul_f32 v[6:7], v[28:29], v[6:7]
	s_waitcnt lgkmcnt(0)
	v_pk_mul_f32 v[0:1], v[0:1], v[32:33]
	v_pk_mul_f32 v[2:3], v[2:3], v[34:35]
	v_pk_mul_f32 v[4:5], v[4:5], v[36:37]
	v_pk_mul_f32 v[6:7], v[6:7], v[38:39]
	v_pk_add_f32 v[40:41], v[40:41], 1.0 op_sel_hi:[1,0]
	v_pk_add_f32 v[42:43], v[42:43], 1.0 op_sel_hi:[1,0]
	v_pk_add_f32 v[44:45], v[44:45], 1.0 op_sel_hi:[1,0]
	v_pk_add_f32 v[46:47], v[46:47], 1.0 op_sel_hi:[1,0]
	v_pk_fma_f32 v[0:1], v[0:1], v[40:41], v[58:59]
	v_pk_fma_f32 v[2:3], v[2:3], v[42:43], v[60:61]
	v_pk_fma_f32 v[4:5], v[4:5], v[44:45], v[62:63]
	v_pk_fma_f32 v[6:7], v[6:7], v[46:47], v[64:65]
	ds_read_b128 v[32:35], v102 offset:3840
	ds_read_b128 v[36:39], v102 offset:3856
	ds_read_b128 v[40:43], v102 offset:7936
	ds_read_b128 v[44:47], v102 offset:7952
	ds_read_b128 v[58:61], v102 offset:12032
	ds_read_b128 v[62:65], v102 offset:12048
	v_cvt_pk_f16_f32 v74, v0, v1
	v_cvt_pk_f16_f32 v75, v2, v3
	v_cvt_pk_f16_f32 v76, v4, v5
	v_cvt_pk_f16_f32 v77, v6, v7
	v_cvt_f32_f16_e32 v66, v74
	v_cvt_f32_f16_sdwa v67, v74 dst_sel:DWORD dst_unused:UNUSED_PAD src0_sel:WORD_1
	v_cvt_f32_f16_e32 v68, v75
	v_cvt_f32_f16_sdwa v69, v75 dst_sel:DWORD dst_unused:UNUSED_PAD src0_sel:WORD_1
	v_cvt_f32_f16_e32 v70, v76
	v_cvt_f32_f16_sdwa v71, v76 dst_sel:DWORD dst_unused:UNUSED_PAD src0_sel:WORD_1
	v_cvt_f32_f16_e32 v72, v77
	v_cvt_f32_f16_sdwa v73, v77 dst_sel:DWORD dst_unused:UNUSED_PAD src0_sel:WORD_1
	v_pk_add_f32 v[0:1], v[0:1], v[66:67] neg_lo:[0,1] neg_hi:[0,1]
	v_pk_add_f32 v[2:3], v[2:3], v[68:69] neg_lo:[0,1] neg_hi:[0,1]
	v_pk_add_f32 v[4:5], v[4:5], v[70:71] neg_lo:[0,1] neg_hi:[0,1]
	v_pk_add_f32 v[6:7], v[6:7], v[72:73] neg_lo:[0,1] neg_hi:[0,1]
	s_nop 0
	v_cvt_pk_f16_f32 v78, v0, v1
	v_cvt_pk_f16_f32 v79, v2, v3
	v_cvt_pk_f16_f32 v80, v4, v5
	v_cvt_pk_f16_f32 v81, v6, v7
	global_store_dwordx4 v[88:89], v[74:77], off offset:1856
	s_waitcnt vmcnt(18)
	v_mfma_f32_16x16x32_f16 a[8:11], v[74:77], a[228:231], a[8:11]
	v_mfma_f32_16x16x32_f16 a[8:11], v[78:81], a[228:231], a[8:11]
	v_mfma_f32_16x16x32_f16 a[8:11], v[74:77], a[232:235], a[8:11]
	v_mfma_f32_16x16x32_f16 a[4:7], v[74:77], a[236:239], a[4:7]
	v_mfma_f32_16x16x32_f16 a[4:7], v[78:81], a[236:239], a[4:7]
	v_mfma_f32_16x16x32_f16 a[4:7], v[74:77], a[240:243], a[4:7]
	v_mfma_f32_16x16x32_f16 a[0:3], v[74:77], a[244:247], a[0:3]
	v_mfma_f32_16x16x32_f16 a[0:3], v[78:81], a[244:247], a[0:3]
	v_mfma_f32_16x16x32_f16 a[0:3], v[74:77], a[248:251], a[0:3]
	s_waitcnt vmcnt(18)
	v_accvgpr_read_b32 v0, a16
	v_accvgpr_read_b32 v1, a17
	v_accvgpr_read_b32 v2, a18
	v_accvgpr_read_b32 v3, a19
	v_accvgpr_read_b32 v4, a20
	v_accvgpr_read_b32 v5, a21
	v_accvgpr_read_b32 v6, a22
	v_accvgpr_read_b32 v7, a23
	v_pk_mul_f32 v[0:1], v[28:29], v[0:1]
	v_pk_mul_f32 v[2:3], v[28:29], v[2:3]
	v_pk_mul_f32 v[4:5], v[28:29], v[4:5]
	v_pk_mul_f32 v[6:7], v[28:29], v[6:7]
	s_waitcnt lgkmcnt(0)
	v_pk_mul_f32 v[0:1], v[0:1], v[32:33]
	v_pk_mul_f32 v[2:3], v[2:3], v[34:35]
	v_pk_mul_f32 v[4:5], v[4:5], v[36:37]
	v_pk_mul_f32 v[6:7], v[6:7], v[38:39]
	v_pk_add_f32 v[40:41], v[40:41], 1.0 op_sel_hi:[1,0]
	v_pk_add_f32 v[42:43], v[42:43], 1.0 op_sel_hi:[1,0]
	v_pk_add_f32 v[44:45], v[44:45], 1.0 op_sel_hi:[1,0]
	v_pk_add_f32 v[46:47], v[46:47], 1.0 op_sel_hi:[1,0]
	v_pk_fma_f32 v[0:1], v[0:1], v[40:41], v[58:59]
	v_pk_fma_f32 v[2:3], v[2:3], v[42:43], v[60:61]
	v_pk_fma_f32 v[4:5], v[4:5], v[44:45], v[62:63]
	v_pk_fma_f32 v[6:7], v[6:7], v[46:47], v[64:65]
	ds_read_b128 v[32:35], v102 offset:3968
	ds_read_b128 v[36:39], v102 offset:3984
	ds_read_b128 v[40:43], v102 offset:8064
	ds_read_b128 v[44:47], v102 offset:8080
	ds_read_b128 v[58:61], v102 offset:12160
	ds_read_b128 v[62:65], v102 offset:12176
	v_cvt_pk_f16_f32 v74, v0, v1
	v_cvt_pk_f16_f32 v75, v2, v3
	v_cvt_pk_f16_f32 v76, v4, v5
	v_cvt_pk_f16_f32 v77, v6, v7
	v_cvt_f32_f16_e32 v66, v74
	v_cvt_f32_f16_sdwa v67, v74 dst_sel:DWORD dst_unused:UNUSED_PAD src0_sel:WORD_1
	v_cvt_f32_f16_e32 v68, v75
	v_cvt_f32_f16_sdwa v69, v75 dst_sel:DWORD dst_unused:UNUSED_PAD src0_sel:WORD_1
	v_cvt_f32_f16_e32 v70, v76
	v_cvt_f32_f16_sdwa v71, v76 dst_sel:DWORD dst_unused:UNUSED_PAD src0_sel:WORD_1
	v_cvt_f32_f16_e32 v72, v77
	v_cvt_f32_f16_sdwa v73, v77 dst_sel:DWORD dst_unused:UNUSED_PAD src0_sel:WORD_1
	v_pk_add_f32 v[0:1], v[0:1], v[66:67] neg_lo:[0,1] neg_hi:[0,1]
	v_pk_add_f32 v[2:3], v[2:3], v[68:69] neg_lo:[0,1] neg_hi:[0,1]
	v_pk_add_f32 v[4:5], v[4:5], v[70:71] neg_lo:[0,1] neg_hi:[0,1]
	v_pk_add_f32 v[6:7], v[6:7], v[72:73] neg_lo:[0,1] neg_hi:[0,1]
	s_nop 0
	v_cvt_pk_f16_f32 v78, v0, v1
	v_cvt_pk_f16_f32 v79, v2, v3
	v_cvt_pk_f16_f32 v80, v4, v5
	v_cvt_pk_f16_f32 v81, v6, v7
	global_store_dwordx4 v[88:89], v[74:77], off offset:1920
	s_waitcnt vmcnt(12)
; DI f4 mfma16(h8 a, h8 b, f4 c) { return __builtin_amdgcn_mfma_f32_16x16x32_f16(a, b, c, 0, 0, 0); }
; DI void row2_phase(const Params& P, int l, int r_begin, char* smem) {
;     ...
;     for (int kk = 0; kk < 32; kk++) {
;       const int k0 = kk * 32;
;       float x[8], g[8], s1[8], s0[8];
;       *(float4*)&x[0] = *(const float4*)(xm + k0); *(float4*)&x[4] = *(const float4*)(xm + k0 + 4);
;       *(float4*)&g[0] = *(const float4*)(gam + fq * 8 + k0); *(float4*)&g[4] = *(const float4*)(gam + fq * 8 + k0 + 4);
;       *(float4*)&s1[0] = *(const float4*)(sc + k0); *(float4*)&s1[4] = *(const float4*)(sc + k0 + 4);
;       *(float4*)&s0[0] = *(const float4*)(sh + k0); *(float4*)&s0[4] = *(const float4*)(sh + k0 + 4);
;       h8 hi, lo;
; #pragma unroll
;       for (int i = 0; i < 8; i++) {
;         float v = x[i] * rstd * g[i] * (1.f + s1[i]) + s0[i];
;         hi[i] = (half_t)v; lo[i] = (half_t)(v - (float)hi[i]);
;       }
;       *(h8*)(hxo + k0) = hi;
; #pragma unroll
;       for (int n3 = 0; n3 < 3; n3++) {
;         h8 bh = *(const h8*)(Whi + (size_t)(n3 * 16 + fr) * 1024 + k0 + fq * 8);
;         h8 bl = *(const h8*)(Wlo + (size_t)(n3 * 16 + fr) * 1024 + k0 + fq * 8);
;         acc[n3] = mfma16(hi, bh, acc[n3]); acc[n3] = mfma16(lo, bh, acc[n3]); acc[n3] = mfma16(hi, bl, acc[n3]);
;       }
;     }
;     __builtin_amdgcn_wave_barrier();
; #pragma unroll
;     for (int n3 = 0; n3 < 3; n3++)
; #pragma unroll
;       for (int j = 0; j < 4; j++) lg[(fq * 4 + j) * 48 + n3 * 16 + fr] = acc[n3][j];
;     __builtin_amdgcn_wave_barrier();
;     if (lane < 16) {
;       const int r = r0 + lane;
;       const float* L = lg + lane * 48;
;       float gl[4]; int gi = 0;
; #pragma unroll
;       for (int j = 0; j < 4; j++) gl[j] = L[j] + P.b_group[l * 4 + j];
	v_mfma_f32_16x16x32_f16 a[8:11], v[74:77], a[80:83], a[8:11]
	v_mfma_f32_16x16x32_f16 a[8:11], v[78:81], a[80:83], a[8:11]
	v_mfma_f32_16x16x32_f16 a[8:11], v[74:77], a[84:87], a[8:11]
	v_mfma_f32_16x16x32_f16 a[4:7], v[74:77], a[88:91], a[4:7]
	v_mfma_f32_16x16x32_f16 a[4:7], v[78:81], a[88:91], a[4:7]
	v_mfma_f32_16x16x32_f16 a[4:7], v[74:77], a[92:95], a[4:7]
	v_mfma_f32_16x16x32_f16 a[0:3], v[74:77], a[96:99], a[0:3]
	v_mfma_f32_16x16x32_f16 a[0:3], v[78:81], a[96:99], a[0:3]
	v_mfma_f32_16x16x32_f16 a[0:3], v[74:77], a[100:103], a[0:3]
	s_waitcnt vmcnt(12)
	v_accvgpr_read_b32 v0, a24
	v_accvgpr_read_b32 v1, a25
	v_accvgpr_read_b32 v2, a26
	v_accvgpr_read_b32 v3, a27
	v_accvgpr_read_b32 v4, a28
	v_accvgpr_read_b32 v5, a29
	v_accvgpr_read_b32 v6, a30
	v_accvgpr_read_b32 v7, a31
	v_pk_mul_f32 v[0:1], v[28:29], v[0:1]
	v_pk_mul_f32 v[2:3], v[28:29], v[2:3]
	v_pk_mul_f32 v[4:5], v[28:29], v[4:5]
	v_pk_mul_f32 v[6:7], v[28:29], v[6:7]
	s_waitcnt lgkmcnt(0)
	v_pk_mul_f32 v[0:1], v[0:1], v[32:33]
	v_pk_mul_f32 v[2:3], v[2:3], v[34:35]
	v_pk_mul_f32 v[4:5], v[4:5], v[36:37]
	v_pk_mul_f32 v[6:7], v[6:7], v[38:39]
	v_pk_add_f32 v[40:41], v[40:41], 1.0 op_sel_hi:[1,0]
	v_pk_add_f32 v[42:43], v[42:43], 1.0 op_sel_hi:[1,0]
	v_pk_add_f32 v[44:45], v[44:45], 1.0 op_sel_hi:[1,0]
	v_pk_add_f32 v[46:47], v[46:47], 1.0 op_sel_hi:[1,0]
	v_pk_fma_f32 v[0:1], v[0:1], v[40:41], v[58:59]
	v_pk_fma_f32 v[2:3], v[2:3], v[42:43], v[60:61]
	v_pk_fma_f32 v[4:5], v[4:5], v[44:45], v[62:63]
	v_pk_fma_f32 v[6:7], v[6:7], v[46:47], v[64:65]
	v_cvt_pk_f16_f32 v74, v0, v1
	v_cvt_pk_f16_f32 v75, v2, v3
	v_cvt_pk_f16_f32 v76, v4, v5
	v_cvt_pk_f16_f32 v77, v6, v7
	v_cvt_f32_f16_e32 v66, v74
	v_cvt_f32_f16_sdwa v67, v74 dst_sel:DWORD dst_unused:UNUSED_PAD src0_sel:WORD_1
	v_cvt_f32_f16_e32 v68, v75
	v_cvt_f32_f16_sdwa v69, v75 dst_sel:DWORD dst_unused:UNUSED_PAD src0_sel:WORD_1
	v_cvt_f32_f16_e32 v70, v76
	v_cvt_f32_f16_sdwa v71, v76 dst_sel:DWORD dst_unused:UNUSED_PAD src0_sel:WORD_1
	v_cvt_f32_f16_e32 v72, v77
	v_cvt_f32_f16_sdwa v73, v77 dst_sel:DWORD dst_unused:UNUSED_PAD src0_sel:WORD_1
	v_pk_add_f32 v[0:1], v[0:1], v[66:67] neg_lo:[0,1] neg_hi:[0,1]
	v_pk_add_f32 v[2:3], v[2:3], v[68:69] neg_lo:[0,1] neg_hi:[0,1]
	v_pk_add_f32 v[4:5], v[4:5], v[70:71] neg_lo:[0,1] neg_hi:[0,1]
	v_pk_add_f32 v[6:7], v[6:7], v[72:73] neg_lo:[0,1] neg_hi:[0,1]
	s_nop 0
	v_cvt_pk_f16_f32 v78, v0, v1
	v_cvt_pk_f16_f32 v79, v2, v3
	v_cvt_pk_f16_f32 v80, v4, v5
	v_cvt_pk_f16_f32 v81, v6, v7
	global_store_dwordx4 v[88:89], v[74:77], off offset:1984
	s_waitcnt vmcnt(6)
	v_mfma_f32_16x16x32_f16 a[8:11], v[74:77], a[104:107], a[8:11]
	v_mfma_f32_16x16x32_f16 a[8:11], v[78:81], a[104:107], a[8:11]
	v_mfma_f32_16x16x32_f16 a[8:11], v[74:77], a[108:111], a[8:11]
	v_mfma_f32_16x16x32_f16 a[4:7], v[74:77], a[112:115], a[4:7]
	v_mfma_f32_16x16x32_f16 a[4:7], v[78:81], a[112:115], a[4:7]
	v_mfma_f32_16x16x32_f16 a[4:7], v[74:77], a[116:119], a[4:7]
	v_mfma_f32_16x16x32_f16 a[0:3], v[74:77], a[120:123], a[0:3]
	v_mfma_f32_16x16x32_f16 a[0:3], v[78:81], a[120:123], a[0:3]
	v_mfma_f32_16x16x32_f16 a[0:3], v[74:77], a[124:127], a[0:3]
	s_nop 7
	s_nop 6
	v_accvgpr_read_b32 v0, a0
	v_accvgpr_read_b32 v4, a4
	v_accvgpr_read_b32 v8, a8
	v_accvgpr_read_b32 v1, a1
	v_accvgpr_read_b32 v2, a2
	v_accvgpr_read_b32 v3, a3
	v_accvgpr_read_b32 v5, a5
	v_accvgpr_read_b32 v6, a6
	v_accvgpr_read_b32 v7, a7
	v_accvgpr_read_b32 v9, a9
	v_accvgpr_read_b32 v10, a10
	v_accvgpr_read_b32 v11, a11
	ds_write2_b32 v55, v8, v4 offset1:16
	ds_write2_b32 v55, v10, v6 offset0:96 offset1:112
	ds_write2_b32 v55, v0, v9 offset0:32 offset1:48
	ds_write2_b32 v55, v5, v1 offset0:64 offset1:80
	ds_write2_b32 v55, v2, v11 offset0:128 offset1:144
	ds_write2_b32 v55, v7, v3 offset0:160 offset1:176
	s_and_saveexec_b64 s[34:35], s[2:3]
	s_cbranch_execz .LBB0_544
	global_load_dwordx4 v[4:7], v149, s[8:9]
	ds_read_b128 v[0:3], v13
	s_mov_b32 s28, 0x3fb8aa3b
	s_mov_b32 s38, 0xc2ce8ed0
	s_mov_b32 s39, 0x42b17218
	v_mov_b32_e32 v33, 0x7f800000
	v_readlane_b32 s48, v253, 35
	v_readlane_b32 s54, v253, 41
	v_readlane_b32 s55, v253, 42
	v_readlane_b32 s49, v253, 36
	v_readlane_b32 s50, v253, 37
	v_readlane_b32 s51, v253, 38
	v_readlane_b32 s52, v253, 39
	v_readlane_b32 s53, v253, 40
	v_readlane_b32 s56, v253, 43
	v_readlane_b32 s57, v253, 44
	v_readlane_b32 s58, v253, 45
	v_readlane_b32 s59, v253, 46
	v_readlane_b32 s60, v253, 47
	v_readlane_b32 s61, v253, 48
	v_readlane_b32 s62, v253, 49
	v_readlane_b32 s63, v253, 50
	s_waitcnt vmcnt(0) lgkmcnt(0)
; DI void row2_phase(const Params& P, int l, int r_begin, char* smem) {
;     ...
;     if (lane < 16) {
;       const int r = r0 + lane;
;       const float* L = lg + lane * 48;
;       float gl[4]; int gi = 0;
; #pragma unroll
;       for (int j = 0; j < 4; j++) gl[j] = L[j] + P.b_group[l * 4 + j];
;       float gm = gl[0];
; #pragma unroll
;       for (int j = 1; j < 4; j++) if (gl[j] > gm) { gm = gl[j]; gi = j; }
;       float gs = 0.f;
; #pragma unroll
;       for (int j = 0; j < 4; j++) gs += expf(gl[j] - gm);
;       const float pg = 1.f / gs;
;       float el[8];
; #pragma unroll
;       for (int j = 0; j < 8; j++) el[j] = L[4 + gi * 8 + j] + P.b_router[l * 32 + gi * 8 + j];
	v_pk_add_f32 v[0:1], v[0:1], v[4:5]
	s_nop 0
	v_cmp_gt_f32_e32 vcc, v1, v0
	v_add_f32_e32 v2, v2, v6
	v_add_f32_e32 v3, v3, v7
	v_cndmask_b32_e32 v4, v0, v1, vcc
	v_cmp_gt_f32_e64 s[0:1], v2, v4
	s_nop 1
	v_cndmask_b32_e64 v4, v4, v2, s[0:1]
	v_cmp_gt_f32_e64 s[4:5], v3, v4
	s_nop 1
	v_cndmask_b32_e64 v4, v4, v3, s[4:5]
	v_sub_f32_e32 v5, v0, v4
	v_sub_f32_e32 v0, v1, v4
	v_mul_f32_e32 v1, 0x3fb8aa3b, v0
	v_fma_f32 v6, v0, s28, -v1
	v_rndne_f32_e32 v7, v1
	v_fmac_f32_e32 v6, 0x32a5705f, v0
	v_sub_f32_e32 v1, v1, v7
	v_add_f32_e32 v1, v1, v6
	v_exp_f32_e32 v1, v1
	v_cvt_i32_f32_e32 v6, v7
	v_cmp_ngt_f32_e64 s[6:7], s38, v0
	v_ldexp_f32 v1, v1, v6
	s_nop 0
	v_cndmask_b32_e64 v1, 0, v1, s[6:7]
	v_cmp_nlt_f32_e64 s[6:7], s39, v0
	v_sub_f32_e32 v0, v2, v4
	s_nop 0
	v_cndmask_b32_e64 v21, v33, v1, s[6:7]
	v_mul_f32_e32 v1, 0x3fb8aa3b, v0
	v_fma_f32 v2, v0, s28, -v1
	v_rndne_f32_e32 v6, v1
	v_fmac_f32_e32 v2, 0x32a5705f, v0
	v_sub_f32_e32 v1, v1, v6
	v_add_f32_e32 v1, v1, v2
	v_exp_f32_e32 v1, v1
	v_cvt_i32_f32_e32 v2, v6
	v_cmp_ngt_f32_e64 s[6:7], s38, v0
	v_ldexp_f32 v1, v1, v2
	s_nop 0
	v_cndmask_b32_e64 v1, 0, v1, s[6:7]
	v_cmp_nlt_f32_e64 s[6:7], s39, v0
	v_sub_f32_e32 v0, v3, v4
	v_or_b32_e32 v4, v56, v53
	v_cndmask_b32_e64 v30, v33, v1, s[6:7]
	v_mul_f32_e32 v1, 0x3fb8aa3b, v0
	v_fma_f32 v2, v0, s28, -v1
	v_rndne_f32_e32 v3, v1
	v_fmac_f32_e32 v2, 0x32a5705f, v0
	v_sub_f32_e32 v1, v1, v3
	v_add_f32_e32 v1, v1, v2
	v_exp_f32_e32 v1, v1
	v_cvt_i32_f32_e32 v2, v3
	v_cmp_ngt_f32_e64 s[6:7], s38, v0
	v_ldexp_f32 v1, v1, v2
	s_nop 0
	v_cndmask_b32_e64 v1, 0, v1, s[6:7]
	v_cmp_nlt_f32_e64 s[6:7], s39, v0
	v_cndmask_b32_e64 v0, 0, 8, vcc
	v_cndmask_b32_e64 v0, v0, 16, s[0:1]
	v_cndmask_b32_e64 v32, v0, 24, s[4:5]
	v_cndmask_b32_e64 v31, v33, v1, s[6:7]
	v_or_b32_e32 v0, s23, v32
	v_mov_b32_e32 v1, v149
	v_lshl_add_u32 v6, v32, 2, v13
	v_lshl_add_u64 v[10:11], v[0:1], 2, s[54:55]
	ds_read_b128 v[0:3], v6 offset:16
	ds_read_b128 v[6:9], v6 offset:32
	global_load_dwordx4 v[22:25], v[10:11], off offset:16
	global_load_dwordx4 v[26:29], v[10:11], off
	v_mul_f32_e32 v10, 0x3fb8aa3b, v5
	v_fma_f32 v11, v5, s28, -v10
	v_fmac_f32_e32 v11, 0x32a5705f, v5
	v_cmp_ngt_f32_e32 vcc, s38, v5
	s_mov_b32 s6, 0xff61b1e6
	s_waitcnt vmcnt(1) lgkmcnt(0)
	v_add_f32_e32 v6, v6, v22
	v_rndne_f32_e32 v22, v10
	v_sub_f32_e32 v10, v10, v22
	v_add_f32_e32 v10, v10, v11
	v_exp_f32_e32 v10, v10
	v_cvt_i32_f32_e32 v11, v22
	s_waitcnt vmcnt(0)
; DI void row2_phase(const Params& P, int l, int r_begin, char* smem) {
;     ...
;       int i0 = 0; float v0 = el[0];
; #pragma unroll
;       for (int j = 1; j < 8; j++) if (el[j] > v0) { v0 = el[j]; i0 = j; }
;       int i1 = -1; float v1 = -3.0e38f;
; #pragma unroll
;       for (int j = 0; j < 8; j++) if (j != i0 && el[j] > v1) { v1 = el[j]; i1 = j; }
;       const float ex = expf(v1 - v0);
;       const float w0 = pg / (1.f + ex), w1 = pg * ex / (1.f + ex);
;       const int e0 = gi * 8 + i0, e1 = gi * 8 + i1;
;       int p0 = atomicAdd(&P.cnt[l * 32 + e0], 1); P.list[(size_t)e0 * LCAP + p0] = 2 * r; P.listW[(size_t)e0 * LCAP + p0] = w0;
;       int p1 = atomicAdd(&P.cnt[l * 32 + e1], 1); P.list[(size_t)e1 * LCAP + p1] = 2 * r + 1; P.listW[(size_t)e1 * LCAP + p1] = w1;
	v_pk_add_f32 v[0:1], v[0:1], v[26:27]
	v_add_f32_e32 v2, v2, v28
	v_add_f32_e32 v3, v3, v29
	v_ldexp_f32 v10, v10, v11
	v_cndmask_b32_e32 v10, 0, v10, vcc
	v_cmp_nlt_f32_e32 vcc, s39, v5
	v_add_f32_e32 v7, v7, v23
	v_add_f32_e32 v8, v8, v24
	v_cndmask_b32_e32 v5, v33, v10, vcc
	v_cmp_gt_f32_e32 vcc, v1, v0
	v_add_f32_e32 v9, v9, v25
	v_cmp_nlt_f32_e64 s[6:7], s6, v0
	v_cndmask_b32_e32 v11, v0, v1, vcc
	v_cndmask_b32_e64 v10, 0, 1, vcc
	v_cmp_gt_f32_e32 vcc, v2, v11
	v_mov_b32_e32 v22, 0xff61b1e6
	v_add_f32_e32 v5, v5, v21
	v_cndmask_b32_e32 v11, v11, v2, vcc
	v_cndmask_b32_e64 v10, v10, 2, vcc
	v_cmp_gt_f32_e32 vcc, v3, v11
	v_add_f32_e32 v5, v30, v5
	v_add_f32_e32 v5, v31, v5
	v_cndmask_b32_e32 v11, v11, v3, vcc
	v_cndmask_b32_e64 v10, v10, 3, vcc
	v_cmp_gt_f32_e32 vcc, v6, v11
	s_nop 1
	v_cndmask_b32_e32 v11, v11, v6, vcc
	v_cndmask_b32_e64 v10, v10, 4, vcc
	v_cmp_gt_f32_e32 vcc, v7, v11
	s_nop 1
	v_cndmask_b32_e32 v11, v11, v7, vcc
	v_cndmask_b32_e64 v10, v10, 5, vcc
	v_cmp_gt_f32_e32 vcc, v8, v11
	s_nop 1
	v_cndmask_b32_e32 v11, v11, v8, vcc
	v_cndmask_b32_e64 v10, v10, 6, vcc
	v_cmp_ngt_f32_e64 s[0:1], v9, v11
	s_nop 1
	v_cndmask_b32_e64 v10, 7, v10, s[0:1]
	v_cmp_eq_u32_e64 s[4:5], 0, v10
	s_or_b64 s[4:5], s[4:5], s[6:7]
	v_cndmask_b32_e64 v11, v9, v11, s[0:1]
	v_cndmask_b32_e64 v0, v0, v22, s[4:5]
	v_cndmask_b32_e64 v21, 0, -1, s[4:5]
	v_cmp_ne_u32_e64 s[4:5], 1, v10
	v_cmp_gt_f32_e64 s[6:7], v1, v0
	s_and_b64 s[4:5], s[4:5], s[6:7]
	v_cndmask_b32_e64 v0, v0, v1, s[4:5]
	v_cndmask_b32_e64 v21, v21, 1, s[4:5]
	v_cmp_ne_u32_e64 s[4:5], 2, v10
	v_cmp_gt_f32_e64 s[6:7], v2, v0
	s_and_b64 s[4:5], s[4:5], s[6:7]
	v_cndmask_b32_e64 v0, v0, v2, s[4:5]
	v_cndmask_b32_e64 v1, v21, 2, s[4:5]
	v_cmp_ne_u32_e64 s[4:5], 3, v10
	v_cmp_gt_f32_e64 s[6:7], v3, v0
	s_and_b64 s[4:5], s[4:5], s[6:7]
	v_cndmask_b32_e64 v0, v0, v3, s[4:5]
	v_cndmask_b32_e64 v1, v1, 3, s[4:5]
	v_cmp_ne_u32_e64 s[4:5], 4, v10
	v_cmp_gt_f32_e64 s[6:7], v6, v0
	s_and_b64 s[4:5], s[4:5], s[6:7]
	v_cndmask_b32_e64 v0, v0, v6, s[4:5]
	v_cndmask_b32_e64 v1, v1, 4, s[4:5]
	v_cmp_ne_u32_e64 s[4:5], 5, v10
	v_cmp_gt_f32_e64 s[6:7], v7, v0
	s_and_b64 s[4:5], s[4:5], s[6:7]
	v_cndmask_b32_e64 v0, v0, v7, s[4:5]
	v_cndmask_b32_e64 v1, v1, 5, s[4:5]
	s_and_b64 s[4:5], vcc, s[0:1]
	v_cmp_ngt_f32_e32 vcc, v8, v0
	s_or_b64 vcc, s[4:5], vcc
	v_readlane_b32 s4, v255, 24
	v_cndmask_b32_e32 v0, v8, v0, vcc
	v_cndmask_b32_e32 v1, 6, v1, vcc
	v_cmp_gt_f32_e32 vcc, v9, v0
	s_and_b64 vcc, s[0:1], vcc
	v_div_scale_f32 v2, s[0:1], v5, v5, 1.0
	v_rcp_f32_e32 v3, v2
	v_cndmask_b32_e64 v1, v1, 7, vcc
	v_cndmask_b32_e32 v0, v0, v9, vcc
	v_sub_f32_e32 v0, v0, v11
	v_fma_f32 v6, -v2, v3, 1.0
	v_fmac_f32_e32 v3, v6, v3
	v_div_scale_f32 v6, vcc, 1.0, v5, 1.0
	v_mul_f32_e32 v7, v6, v3
	v_fma_f32 v8, -v2, v7, v6
	v_fmac_f32_e32 v7, v8, v3
	v_fma_f32 v2, -v2, v7, v6
	v_div_fmas_f32 v2, v2, v3, v7
	v_mul_f32_e32 v3, 0x3fb8aa3b, v0
	v_div_fixup_f32 v2, v2, v5, 1.0
	v_fma_f32 v5, v0, s28, -v3
	v_rndne_f32_e32 v6, v3
	v_fmac_f32_e32 v5, 0x32a5705f, v0
	v_sub_f32_e32 v3, v3, v6
	v_add_f32_e32 v3, v3, v5
	v_exp_f32_e32 v3, v3
	v_cvt_i32_f32_e32 v5, v6
	v_cmp_ngt_f32_e32 vcc, s38, v0
	s_mov_b32 s28, 0x21000
	v_readlane_b32 s6, v254, 0
	v_ldexp_f32 v3, v3, v5
	v_cndmask_b32_e32 v3, 0, v3, vcc
	v_cmp_nlt_f32_e32 vcc, s39, v0
	v_readlane_b32 s5, v255, 25
	v_readlane_b32 s7, v254, 1
	v_cndmask_b32_e32 v0, v33, v3, vcc
	v_add_f32_e32 v3, 1.0, v0
	v_div_scale_f32 v5, s[0:1], v3, v3, v2
	v_rcp_f32_e32 v6, v5
	v_mul_f32_e32 v0, v2, v0
	v_fma_f32 v7, -v5, v6, 1.0
	v_fmac_f32_e32 v6, v7, v6
	v_div_scale_f32 v7, vcc, v2, v3, v2
	v_mul_f32_e32 v8, v7, v6
	v_fma_f32 v9, -v5, v8, v7
	v_fmac_f32_e32 v8, v9, v6
	v_fma_f32 v5, -v5, v8, v7
	v_div_fmas_f32 v5, v5, v6, v8
	v_div_fixup_f32 v8, v5, v3, v2
	v_div_scale_f32 v2, s[0:1], v3, v3, v0
	v_rcp_f32_e32 v5, v2
	v_readlane_b32 s0, v253, 63
	v_readlane_b32 s1, v255, 0
	v_fma_f32 v6, -v2, v5, 1.0
	v_fmac_f32_e32 v5, v6, v5
	v_div_scale_f32 v6, vcc, v0, v3, v0
	v_mul_f32_e32 v7, v6, v5
	v_fma_f32 v9, -v2, v7, v6
	v_fmac_f32_e32 v7, v9, v5
	v_fma_f32 v2, -v2, v7, v6
	v_div_fmas_f32 v2, v2, v5, v7
	v_or_b32_e32 v5, v10, v32
	v_div_fixup_f32 v2, v2, v3, v0
	v_add_u32_e32 v3, v1, v32
	v_or_b32_e32 v0, s23, v5
	v_mov_b32_e32 v1, v149
	v_mov_b32_e32 v9, 1
	v_mov_b32_e32 v6, 2
	v_mov_b32_e32 v7, 0x3080
	ds_add_rtn_u32 v7, v7, v6
	v_lshlrev_b32_e32 v0, 2, v5
	v_add_u32_e32 v0, 0x3000, v0
	ds_add_rtn_u32 v0, v0, v9
	v_lshlrev_b32_e32 v1, 2, v3
	v_add_u32_e32 v1, 0x3000, v1
	ds_add_rtn_u32 v1, v1, v9
	v_lshlrev_b32_e32 v6, 1, v4
	v_or_b32_e32 v9, 1, v6
	s_waitcnt lgkmcnt(0)
	v_lshl_or_b32 v0, v0, 5, v5
	v_lshl_or_b32 v1, v1, 5, v3
	v_lshlrev_b32_e32 v7, 4, v7
	v_add_u32_e32 v7, 0x10000, v7
	ds_write_b32 v7, v0
	ds_write_b32 v7, v6 offset:4
	ds_write_b32 v7, v8 offset:8
	ds_write_b32 v7, v1 offset:16
	ds_write_b32 v7, v9 offset:20
	ds_write_b32 v7, v2 offset:24
	s_branch .LBB0_544

; DI void row1_phase(const Params& P, int combine_l, int norm_l, int r_begin) {
;     ...
;   auto load_row = [&](int r, float4 (&xv)[4], h4 (&ya)[4], h4 (&yb)[4]) {
;     if (combine_l < 0) {
;       const float* src = r < TC ? P.ctx + (size_t)r * D : P.x + (size_t)(r - TC) * D;
; #pragma unroll
;       for (int i = 0; i < 4; i++) xv[i] = *(const float4*)(src + i * 256 + lane * 4);
;     } else {
;       const float* xm = r < TC ? P.xcbuf + (size_t)r * D : P.out + (size_t)(r - TC) * D;
;       const half_t* y0 = P.yA + (size_t)(2 * r) * D; const half_t* y1 = y0 + D;
; #pragma unroll
;       for (int i = 0; i < 4; i++) { int c = i * 256 + lane * 4; xv[i] = *(const float4*)(xm + c); ya[i] = *(const h4*)(y0 + c); yb[i] = *(const h4*)(y1 + c); }
;     }
;   };
;     ...
;   const int nrows = TA - r_begin;
;   const int r_lo = r_begin + (int)(((long long)gw * nrows) / nw), r_hi = r_begin + (int)(((long long)(gw + 1) * nrows) / nw);
; #pragma unroll 1
;   for (int r = r_lo; r < r_hi; r += 4) {
;     float4 x0[4], x1[4], x2[4], x3[4]; h4 a0[4], b0[4], a1[4], b1[4], a2[4], b2[4], a3[4], b3[4];
;     const int r1 = r + 1, r2 = r + 2, r3 = r + 3;
;     load_row(r, x0, a0, b0);
;     if (r1 < r_hi) load_row(r1, x1, a1, b1);
;     if (r2 < r_hi) load_row(r2, x2, a2, b2);
;     if (r3 < r_hi) load_row(r3, x3, a3, b3);
.LBB0_671:
	v_lshrrev_b32_e32 v152, 6, v172
	v_and_b32_e32 v153, 63, v172
	v_readfirstlane_b32 s5, v152
	v_readlane_b32 s4, v253, 0
	v_lshlrev_b32_e32 v150, 4, v153
	v_lshlrev_b32_e32 v151, 3, v153
	v_lshlrev_b32_e32 v159, 2, v153
	s_nop 2
	s_lshl_b32 s4, s4, 2
	s_add_u32 s4, s4, s5
	s_lshl_b32 s5, s4, 6
	s_add_u32 s5, s5, 0x800
	s_add_u32 s6, s5, 64
	s_add_u32 s52, s90, 0x28cbc700
	s_addc_u32 s53, s91, 0
	s_add_u32 s54, s90, 0xf8bc700
	s_addc_u32 s55, s91, 0
	s_add_u32 s56, s90, 0xce00000
	s_addc_u32 s57, s91, 0
	s_add_u32 s48, s90, 0xf05c700
	s_addc_u32 s49, s91, 0
	v_readlane_b32 s50, v253, 49
	v_readlane_b32 s51, v253, 50
	v_readlane_b32 s58, v255, 15
	v_readlane_b32 s59, v255, 16
	s_nop 3
	s_sub_u32 s50, s50, 0x800000
	s_subb_u32 s51, s51, 0
	s_mov_b32 s8, -1
	s_mov_b32 s7, s5
	s_cmp_lt_u32 s7, 0x800
	s_cselect_b64 s[60:61], s[48:49], s[50:51]
	s_lshl_b32 s10, s7, 12
	s_add_u32 s60, s60, s10
	s_addc_u32 s61, s61, 0
	global_load_dwordx4 a[0:3], v150, s[60:61] offset:0 nt
	global_load_dwordx4 a[4:7], v150, s[60:61] offset:1024 nt
	global_load_dwordx4 a[8:11], v150, s[60:61] offset:2048 nt
	global_load_dwordx4 a[12:15], v150, s[60:61] offset:3072 nt
	s_add_u32 s62, s52, s10
	s_addc_u32 s63, s53, 0
	global_load_dwordx2 a[16:17], v151, s[62:63] offset:0 nt
	global_load_dwordx2 a[18:19], v151, s[62:63] offset:512 nt
	global_load_dwordx2 a[20:21], v151, s[62:63] offset:1024 nt
	global_load_dwordx2 a[22:23], v151, s[62:63] offset:1536 nt
	global_load_dwordx2 a[24:25], v151, s[62:63] offset:2048 nt
	global_load_dwordx2 a[26:27], v151, s[62:63] offset:2560 nt
	global_load_dwordx2 a[28:29], v151, s[62:63] offset:3072 nt
	global_load_dwordx2 a[30:31], v151, s[62:63] offset:3584 nt
	s_add_u32 s7, s7, 1
	s_cmp_lt_u32 s7, 0x800
	s_cselect_b64 s[60:61], s[48:49], s[50:51]
	s_lshl_b32 s10, s7, 12
	s_add_u32 s60, s60, s10
	s_addc_u32 s61, s61, 0
	global_load_dwordx4 a[32:35], v150, s[60:61] offset:0 nt
	global_load_dwordx4 a[36:39], v150, s[60:61] offset:1024 nt
	global_load_dwordx4 a[40:43], v150, s[60:61] offset:2048 nt
	global_load_dwordx4 a[44:47], v150, s[60:61] offset:3072 nt
	s_add_u32 s62, s52, s10
	s_addc_u32 s63, s53, 0
	global_load_dwordx2 a[48:49], v151, s[62:63] offset:0 nt
	global_load_dwordx2 a[50:51], v151, s[62:63] offset:512 nt
	global_load_dwordx2 a[52:53], v151, s[62:63] offset:1024 nt
	global_load_dwordx2 a[54:55], v151, s[62:63] offset:1536 nt
	global_load_dwordx2 a[56:57], v151, s[62:63] offset:2048 nt
	global_load_dwordx2 a[58:59], v151, s[62:63] offset:2560 nt
	global_load_dwordx2 a[60:61], v151, s[62:63] offset:3072 nt
	global_load_dwordx2 a[62:63], v151, s[62:63] offset:3584 nt
	s_add_u32 s7, s7, 1
	s_cmp_lt_u32 s7, 0x800
	s_cselect_b64 s[60:61], s[48:49], s[50:51]
	s_lshl_b32 s10, s7, 12
	s_add_u32 s60, s60, s10
	s_addc_u32 s61, s61, 0
	global_load_dwordx4 a[64:67], v150, s[60:61] offset:0 nt
	global_load_dwordx4 a[68:71], v150, s[60:61] offset:1024 nt
	global_load_dwordx4 a[72:75], v150, s[60:61] offset:2048 nt
	global_load_dwordx4 a[76:79], v150, s[60:61] offset:3072 nt
	s_add_u32 s62, s52, s10
	s_addc_u32 s63, s53, 0
	global_load_dwordx2 a[80:81], v151, s[62:63] offset:0 nt
	global_load_dwordx2 a[82:83], v151, s[62:63] offset:512 nt
	global_load_dwordx2 a[84:85], v151, s[62:63] offset:1024 nt
	global_load_dwordx2 a[86:87], v151, s[62:63] offset:1536 nt
	global_load_dwordx2 a[88:89], v151, s[62:63] offset:2048 nt
	global_load_dwordx2 a[90:91], v151, s[62:63] offset:2560 nt
	global_load_dwordx2 a[92:93], v151, s[62:63] offset:3072 nt
	global_load_dwordx2 a[94:95], v151, s[62:63] offset:3584 nt
	s_add_u32 s7, s7, 1
	s_cmp_lt_u32 s7, 0x800
	s_cselect_b64 s[60:61], s[48:49], s[50:51]
	s_lshl_b32 s10, s7, 12
	s_add_u32 s60, s60, s10
	s_addc_u32 s61, s61, 0
	global_load_dwordx4 a[96:99], v150, s[60:61] offset:0 nt
	global_load_dwordx4 a[100:103], v150, s[60:61] offset:1024 nt
	global_load_dwordx4 a[104:107], v150, s[60:61] offset:2048 nt
	global_load_dwordx4 a[108:111], v150, s[60:61] offset:3072 nt
	s_add_u32 s62, s52, s10
	s_addc_u32 s63, s53, 0
	global_load_dwordx2 a[112:113], v151, s[62:63] offset:0 nt
	global_load_dwordx2 a[114:115], v151, s[62:63] offset:512 nt
	global_load_dwordx2 a[116:117], v151, s[62:63] offset:1024 nt
	global_load_dwordx2 a[118:119], v151, s[62:63] offset:1536 nt
	global_load_dwordx2 a[120:121], v151, s[62:63] offset:2048 nt
	global_load_dwordx2 a[122:123], v151, s[62:63] offset:2560 nt
	global_load_dwordx2 a[124:125], v151, s[62:63] offset:3072 nt
	global_load_dwordx2 a[126:127], v151, s[62:63] offset:3584 nt
	s_add_u32 s7, s7, 1
	s_mov_b32 s98, 15

; DI void row1_phase(const Params& P, int combine_l, int norm_l, int r_begin) {
;     ...
;       const float* xm = r < TC ? P.xcbuf + (size_t)r * D : P.out + (size_t)(r - TC) * D;
;       const half_t* y0 = P.yA + (size_t)(2 * r) * D; const half_t* y1 = y0 + D;
; #pragma unroll
;       for (int i = 0; i < 4; i++) { int c = i * 256 + lane * 4; xv[i] = *(const float4*)(xm + c); ya[i] = *(const h4*)(y0 + c); yb[i] = *(const h4*)(y1 + c); }
;     }
;   };
;   auto process = [&](int r, float4 (&xv)[4], h4 (&ya)[4], h4 (&yb)[4]) {
;     const int n = row_mod(r);
;     if (combine_l >= 0) {
;       float* xm = r < TC ? P.xcbuf + (size_t)r * D : P.out + (size_t)(r - TC) * D;
;       const float* g2 = P.mod + (size_t)(combine_l * 9 + n) * 6144 + 5 * 1024;
; #pragma unroll
;       for (int i = 0; i < 4; i++) {
;         int c = i * 256 + lane * 4;
;         float4 g = *(const float4*)(g2 + c); float4 t = xv[i];
;         t.x += g.x * ((float)ya[i][0] + (float)yb[i][0]); t.y += g.y * ((float)ya[i][1] + (float)yb[i][1]);
;         t.z += g.z * ((float)ya[i][2] + (float)yb[i][2]); t.w += g.w * ((float)ya[i][3] + (float)yb[i][3]);
;         *(float4*)(xm + c) = t; xv[i] = t;
;       }
.Lr1c_nr1:
	s_waitcnt vmcnt(40)
	v_accvgpr_read_b32 v54, a0
	v_accvgpr_read_b32 v55, a1
	v_accvgpr_read_b32 v56, a2
	v_accvgpr_read_b32 v57, a3
	v_accvgpr_read_b32 v58, a4
	v_accvgpr_read_b32 v59, a5
	v_accvgpr_read_b32 v60, a6
	v_accvgpr_read_b32 v61, a7
	v_accvgpr_read_b32 v62, a8
	v_accvgpr_read_b32 v63, a9
	v_accvgpr_read_b32 v64, a10
	v_accvgpr_read_b32 v65, a11
	v_accvgpr_read_b32 v66, a12
	v_accvgpr_read_b32 v67, a13
	v_accvgpr_read_b32 v68, a14
	v_accvgpr_read_b32 v69, a15
	v_accvgpr_read_b32 v70, a16
	v_accvgpr_read_b32 v71, a17
	v_accvgpr_read_b32 v72, a18
	v_accvgpr_read_b32 v73, a19
	v_accvgpr_read_b32 v74, a20
	v_accvgpr_read_b32 v75, a21
	v_accvgpr_read_b32 v76, a22
	v_accvgpr_read_b32 v77, a23
	v_accvgpr_read_b32 v78, a24
	v_accvgpr_read_b32 v79, a25
	v_accvgpr_read_b32 v80, a26
	v_accvgpr_read_b32 v81, a27
	v_accvgpr_read_b32 v82, a28
	v_accvgpr_read_b32 v83, a29
	v_accvgpr_read_b32 v84, a30
	v_accvgpr_read_b32 v85, a31
	s_lshl_b32 s10, s5, 12
	s_cmp_lt_u32 s5, 0x800
	s_cselect_b64 s[34:35], s[48:49], s[50:51]
	s_add_u32 s34, s34, s10
	s_addc_u32 s35, s35, 0
	s_cmp_lt_u32 s7, 0x800
	s_cselect_b64 s[60:61], s[48:49], s[50:51]
	s_lshl_b32 s10, s7, 12
	s_add_u32 s60, s60, s10
	s_addc_u32 s61, s61, 0
	global_load_dwordx4 a[0:3], v150, s[60:61] offset:0 nt
	global_load_dwordx4 a[4:7], v150, s[60:61] offset:1024 nt
	global_load_dwordx4 a[8:11], v150, s[60:61] offset:2048 nt
	global_load_dwordx4 a[12:15], v150, s[60:61] offset:3072 nt
	s_add_u32 s62, s52, s10
	s_addc_u32 s63, s53, 0
	global_load_dwordx2 a[16:17], v151, s[62:63] offset:0 nt
	global_load_dwordx2 a[18:19], v151, s[62:63] offset:512 nt
	global_load_dwordx2 a[20:21], v151, s[62:63] offset:1024 nt
	global_load_dwordx2 a[22:23], v151, s[62:63] offset:1536 nt
	global_load_dwordx2 a[24:25], v151, s[62:63] offset:2048 nt
	global_load_dwordx2 a[26:27], v151, s[62:63] offset:2560 nt
	global_load_dwordx2 a[28:29], v151, s[62:63] offset:3072 nt
	global_load_dwordx2 a[30:31], v151, s[62:63] offset:3584 nt
	s_add_u32 s7, s7, 1
	v_cvt_f32_f16_e32 v154, v70
	v_cvt_f32_f16_e32 v155, v78
	v_add_f32_e32 v154, v154, v155
	v_fmac_f32_e32 v54, v32, v154
	v_cvt_f32_f16_sdwa v156, v70 dst_sel:DWORD dst_unused:UNUSED_PAD src0_sel:WORD_1
	v_cvt_f32_f16_sdwa v157, v78 dst_sel:DWORD dst_unused:UNUSED_PAD src0_sel:WORD_1
	v_add_f32_e32 v156, v156, v157
	v_fmac_f32_e32 v55, v33, v156
	v_cvt_f32_f16_e32 v154, v71
	v_cvt_f32_f16_e32 v155, v79
	v_add_f32_e32 v154, v154, v155
	v_fmac_f32_e32 v56, v34, v154
	v_cvt_f32_f16_sdwa v156, v71 dst_sel:DWORD dst_unused:UNUSED_PAD src0_sel:WORD_1
	v_cvt_f32_f16_sdwa v157, v79 dst_sel:DWORD dst_unused:UNUSED_PAD src0_sel:WORD_1
	v_add_f32_e32 v156, v156, v157
	v_fmac_f32_e32 v57, v35, v156
	v_cvt_f32_f16_e32 v154, v72
	v_cvt_f32_f16_e32 v155, v80
	v_add_f32_e32 v154, v154, v155
	v_fmac_f32_e32 v58, v36, v154
	v_cvt_f32_f16_sdwa v156, v72 dst_sel:DWORD dst_unused:UNUSED_PAD src0_sel:WORD_1
	v_cvt_f32_f16_sdwa v157, v80 dst_sel:DWORD dst_unused:UNUSED_PAD src0_sel:WORD_1
	v_add_f32_e32 v156, v156, v157
	v_fmac_f32_e32 v59, v37, v156
	v_cvt_f32_f16_e32 v154, v73
	v_cvt_f32_f16_e32 v155, v81
	v_add_f32_e32 v154, v154, v155
	v_fmac_f32_e32 v60, v38, v154
	v_cvt_f32_f16_sdwa v156, v73 dst_sel:DWORD dst_unused:UNUSED_PAD src0_sel:WORD_1
	v_cvt_f32_f16_sdwa v157, v81 dst_sel:DWORD dst_unused:UNUSED_PAD src0_sel:WORD_1
	v_add_f32_e32 v156, v156, v157
	v_fmac_f32_e32 v61, v39, v156
	v_cvt_f32_f16_e32 v154, v74
	v_cvt_f32_f16_e32 v155, v82
	v_add_f32_e32 v154, v154, v155
	v_fmac_f32_e32 v62, v40, v154
	v_cvt_f32_f16_sdwa v156, v74 dst_sel:DWORD dst_unused:UNUSED_PAD src0_sel:WORD_1
	v_cvt_f32_f16_sdwa v157, v82 dst_sel:DWORD dst_unused:UNUSED_PAD src0_sel:WORD_1
	v_add_f32_e32 v156, v156, v157
	v_fmac_f32_e32 v63, v41, v156
	v_cvt_f32_f16_e32 v154, v75
	v_cvt_f32_f16_e32 v155, v83
	v_add_f32_e32 v154, v154, v155
	v_fmac_f32_e32 v64, v42, v154
	v_cvt_f32_f16_sdwa v156, v75 dst_sel:DWORD dst_unused:UNUSED_PAD src0_sel:WORD_1
	v_cvt_f32_f16_sdwa v157, v83 dst_sel:DWORD dst_unused:UNUSED_PAD src0_sel:WORD_1
	v_add_f32_e32 v156, v156, v157
	v_fmac_f32_e32 v65, v43, v156
	v_cvt_f32_f16_e32 v154, v76
	v_cvt_f32_f16_e32 v155, v84
	v_add_f32_e32 v154, v154, v155
	v_fmac_f32_e32 v66, v44, v154
	v_cvt_f32_f16_sdwa v156, v76 dst_sel:DWORD dst_unused:UNUSED_PAD src0_sel:WORD_1
	v_cvt_f32_f16_sdwa v157, v84 dst_sel:DWORD dst_unused:UNUSED_PAD src0_sel:WORD_1
	v_add_f32_e32 v156, v156, v157
	v_fmac_f32_e32 v67, v45, v156
	v_cvt_f32_f16_e32 v154, v77
	v_cvt_f32_f16_e32 v155, v85
	v_add_f32_e32 v154, v154, v155
	v_fmac_f32_e32 v68, v46, v154
	v_cvt_f32_f16_sdwa v156, v77 dst_sel:DWORD dst_unused:UNUSED_PAD src0_sel:WORD_1
	v_cvt_f32_f16_sdwa v157, v85 dst_sel:DWORD dst_unused:UNUSED_PAD src0_sel:WORD_1
	v_add_f32_e32 v156, v156, v157
	v_fmac_f32_e32 v69, v47, v156
	global_store_dwordx4 v150, v[54:57], s[34:35] offset:0
	global_store_dwordx4 v150, v[58:61], s[34:35] offset:1024
	global_store_dwordx4 v150, v[62:65], s[34:35] offset:2048
	global_store_dwordx4 v150, v[66:69], s[34:35] offset:3072
	s_add_u32 s5, s5, 1
	s_sub_u32 s9, s5, 0x800
	s_lshr_b32 s9, s9, 13
	s_cmp_eq_u32 s9, s8
	s_cbranch_scc1 .Lr1c_nr2
	s_mov_b32 s8, s9
	s_waitcnt vmcnt(0)
	s_add_u32 s10, s9, 9
	s_mul_i32 s10, s10, 0x6000
	s_add_u32 s10, s10, 0x5000
	s_add_u32 s38, s56, s10
	s_addc_u32 s39, s57, 0
	global_load_dwordx4 v[32:35], v150, s[38:39] offset:0
	global_load_dwordx4 v[36:39], v150, s[38:39] offset:1024
	global_load_dwordx4 v[40:43], v150, s[38:39] offset:2048
	global_load_dwordx4 v[44:47], v150, s[38:39] offset:3072
	s_waitcnt vmcnt(0)
; DI void row1_phase(const Params& P, int combine_l, int norm_l, int r_begin) {
;     ...
;       const float* xm = r < TC ? P.xcbuf + (size_t)r * D : P.out + (size_t)(r - TC) * D;
;       const half_t* y0 = P.yA + (size_t)(2 * r) * D; const half_t* y1 = y0 + D;
; #pragma unroll
;       for (int i = 0; i < 4; i++) { int c = i * 256 + lane * 4; xv[i] = *(const float4*)(xm + c); ya[i] = *(const h4*)(y0 + c); yb[i] = *(const h4*)(y1 + c); }
;     }
;   };
;   auto process = [&](int r, float4 (&xv)[4], h4 (&ya)[4], h4 (&yb)[4]) {
;     const int n = row_mod(r);
;     if (combine_l >= 0) {
;       float* xm = r < TC ? P.xcbuf + (size_t)r * D : P.out + (size_t)(r - TC) * D;
;       const float* g2 = P.mod + (size_t)(combine_l * 9 + n) * 6144 + 5 * 1024;
; #pragma unroll
;       for (int i = 0; i < 4; i++) {
;         int c = i * 256 + lane * 4;
;         float4 g = *(const float4*)(g2 + c); float4 t = xv[i];
;         t.x += g.x * ((float)ya[i][0] + (float)yb[i][0]); t.y += g.y * ((float)ya[i][1] + (float)yb[i][1]);
;         t.z += g.z * ((float)ya[i][2] + (float)yb[i][2]); t.w += g.w * ((float)ya[i][3] + (float)yb[i][3]);
;         *(float4*)(xm + c) = t; xv[i] = t;
;       }
.Lr1c_nr2:
	s_waitcnt vmcnt(40)
	v_accvgpr_read_b32 v54, a32
	v_accvgpr_read_b32 v55, a33
	v_accvgpr_read_b32 v56, a34
	v_accvgpr_read_b32 v57, a35
	v_accvgpr_read_b32 v58, a36
	v_accvgpr_read_b32 v59, a37
	v_accvgpr_read_b32 v60, a38
	v_accvgpr_read_b32 v61, a39
	v_accvgpr_read_b32 v62, a40
	v_accvgpr_read_b32 v63, a41
	v_accvgpr_read_b32 v64, a42
	v_accvgpr_read_b32 v65, a43
	v_accvgpr_read_b32 v66, a44
	v_accvgpr_read_b32 v67, a45
	v_accvgpr_read_b32 v68, a46
	v_accvgpr_read_b32 v69, a47
	v_accvgpr_read_b32 v70, a48
	v_accvgpr_read_b32 v71, a49
	v_accvgpr_read_b32 v72, a50
	v_accvgpr_read_b32 v73, a51
	v_accvgpr_read_b32 v74, a52
	v_accvgpr_read_b32 v75, a53
	v_accvgpr_read_b32 v76, a54
	v_accvgpr_read_b32 v77, a55
	v_accvgpr_read_b32 v78, a56
	v_accvgpr_read_b32 v79, a57
	v_accvgpr_read_b32 v80, a58
	v_accvgpr_read_b32 v81, a59
	v_accvgpr_read_b32 v82, a60
	v_accvgpr_read_b32 v83, a61
	v_accvgpr_read_b32 v84, a62
	v_accvgpr_read_b32 v85, a63
	s_lshl_b32 s10, s5, 12
	s_cmp_lt_u32 s5, 0x800
	s_cselect_b64 s[34:35], s[48:49], s[50:51]
	s_add_u32 s34, s34, s10
	s_addc_u32 s35, s35, 0
	s_cmp_lt_u32 s7, 0x800
	s_cselect_b64 s[60:61], s[48:49], s[50:51]
	s_lshl_b32 s10, s7, 12
	s_add_u32 s60, s60, s10
	s_addc_u32 s61, s61, 0
	global_load_dwordx4 a[32:35], v150, s[60:61] offset:0 nt
	global_load_dwordx4 a[36:39], v150, s[60:61] offset:1024 nt
	global_load_dwordx4 a[40:43], v150, s[60:61] offset:2048 nt
	global_load_dwordx4 a[44:47], v150, s[60:61] offset:3072 nt
	s_add_u32 s62, s52, s10
	s_addc_u32 s63, s53, 0
	global_load_dwordx2 a[48:49], v151, s[62:63] offset:0 nt
	global_load_dwordx2 a[50:51], v151, s[62:63] offset:512 nt
	global_load_dwordx2 a[52:53], v151, s[62:63] offset:1024 nt
	global_load_dwordx2 a[54:55], v151, s[62:63] offset:1536 nt
	global_load_dwordx2 a[56:57], v151, s[62:63] offset:2048 nt
	global_load_dwordx2 a[58:59], v151, s[62:63] offset:2560 nt
	global_load_dwordx2 a[60:61], v151, s[62:63] offset:3072 nt
	global_load_dwordx2 a[62:63], v151, s[62:63] offset:3584 nt
	s_add_u32 s7, s7, 1
	v_cvt_f32_f16_e32 v154, v70
	v_cvt_f32_f16_e32 v155, v78
	v_add_f32_e32 v154, v154, v155
	v_fmac_f32_e32 v54, v32, v154
	v_cvt_f32_f16_sdwa v156, v70 dst_sel:DWORD dst_unused:UNUSED_PAD src0_sel:WORD_1
	v_cvt_f32_f16_sdwa v157, v78 dst_sel:DWORD dst_unused:UNUSED_PAD src0_sel:WORD_1
	v_add_f32_e32 v156, v156, v157
	v_fmac_f32_e32 v55, v33, v156
	v_cvt_f32_f16_e32 v154, v71
	v_cvt_f32_f16_e32 v155, v79
	v_add_f32_e32 v154, v154, v155
	v_fmac_f32_e32 v56, v34, v154
	v_cvt_f32_f16_sdwa v156, v71 dst_sel:DWORD dst_unused:UNUSED_PAD src0_sel:WORD_1
	v_cvt_f32_f16_sdwa v157, v79 dst_sel:DWORD dst_unused:UNUSED_PAD src0_sel:WORD_1
	v_add_f32_e32 v156, v156, v157
	v_fmac_f32_e32 v57, v35, v156
	v_cvt_f32_f16_e32 v154, v72
	v_cvt_f32_f16_e32 v155, v80
	v_add_f32_e32 v154, v154, v155
	v_fmac_f32_e32 v58, v36, v154
	v_cvt_f32_f16_sdwa v156, v72 dst_sel:DWORD dst_unused:UNUSED_PAD src0_sel:WORD_1
	v_cvt_f32_f16_sdwa v157, v80 dst_sel:DWORD dst_unused:UNUSED_PAD src0_sel:WORD_1
	v_add_f32_e32 v156, v156, v157
	v_fmac_f32_e32 v59, v37, v156
	v_cvt_f32_f16_e32 v154, v73
	v_cvt_f32_f16_e32 v155, v81
	v_add_f32_e32 v154, v154, v155
	v_fmac_f32_e32 v60, v38, v154
	v_cvt_f32_f16_sdwa v156, v73 dst_sel:DWORD dst_unused:UNUSED_PAD src0_sel:WORD_1
	v_cvt_f32_f16_sdwa v157, v81 dst_sel:DWORD dst_unused:UNUSED_PAD src0_sel:WORD_1
	v_add_f32_e32 v156, v156, v157
	v_fmac_f32_e32 v61, v39, v156
	v_cvt_f32_f16_e32 v154, v74
	v_cvt_f32_f16_e32 v155, v82
	v_add_f32_e32 v154, v154, v155
	v_fmac_f32_e32 v62, v40, v154
	v_cvt_f32_f16_sdwa v156, v74 dst_sel:DWORD dst_unused:UNUSED_PAD src0_sel:WORD_1
	v_cvt_f32_f16_sdwa v157, v82 dst_sel:DWORD dst_unused:UNUSED_PAD src0_sel:WORD_1
	v_add_f32_e32 v156, v156, v157
	v_fmac_f32_e32 v63, v41, v156
	v_cvt_f32_f16_e32 v154, v75
	v_cvt_f32_f16_e32 v155, v83
	v_add_f32_e32 v154, v154, v155
	v_fmac_f32_e32 v64, v42, v154
	v_cvt_f32_f16_sdwa v156, v75 dst_sel:DWORD dst_unused:UNUSED_PAD src0_sel:WORD_1
	v_cvt_f32_f16_sdwa v157, v83 dst_sel:DWORD dst_unused:UNUSED_PAD src0_sel:WORD_1
	v_add_f32_e32 v156, v156, v157
	v_fmac_f32_e32 v65, v43, v156
	v_cvt_f32_f16_e32 v154, v76
	v_cvt_f32_f16_e32 v155, v84
	v_add_f32_e32 v154, v154, v155
	v_fmac_f32_e32 v66, v44, v154
	v_cvt_f32_f16_sdwa v156, v76 dst_sel:DWORD dst_unused:UNUSED_PAD src0_sel:WORD_1
	v_cvt_f32_f16_sdwa v157, v84 dst_sel:DWORD dst_unused:UNUSED_PAD src0_sel:WORD_1
	v_add_f32_e32 v156, v156, v157
	v_fmac_f32_e32 v67, v45, v156
	v_cvt_f32_f16_e32 v154, v77
	v_cvt_f32_f16_e32 v155, v85
	v_add_f32_e32 v154, v154, v155
	v_fmac_f32_e32 v68, v46, v154
	v_cvt_f32_f16_sdwa v156, v77 dst_sel:DWORD dst_unused:UNUSED_PAD src0_sel:WORD_1
	v_cvt_f32_f16_sdwa v157, v85 dst_sel:DWORD dst_unused:UNUSED_PAD src0_sel:WORD_1
	v_add_f32_e32 v156, v156, v157
	v_fmac_f32_e32 v69, v47, v156
	global_store_dwordx4 v150, v[54:57], s[34:35] offset:0
	global_store_dwordx4 v150, v[58:61], s[34:35] offset:1024
	global_store_dwordx4 v150, v[62:65], s[34:35] offset:2048
	global_store_dwordx4 v150, v[66:69], s[34:35] offset:3072
	s_add_u32 s5, s5, 1
	s_sub_u32 s9, s5, 0x800
	s_lshr_b32 s9, s9, 13
	s_cmp_eq_u32 s9, s8
	s_cbranch_scc1 .Lr1c_nr3
	s_mov_b32 s8, s9
	s_waitcnt vmcnt(0)
	s_add_u32 s10, s9, 9
	s_mul_i32 s10, s10, 0x6000
	s_add_u32 s10, s10, 0x5000
	s_add_u32 s38, s56, s10
	s_addc_u32 s39, s57, 0
	global_load_dwordx4 v[32:35], v150, s[38:39] offset:0
	global_load_dwordx4 v[36:39], v150, s[38:39] offset:1024
	global_load_dwordx4 v[40:43], v150, s[38:39] offset:2048
	global_load_dwordx4 v[44:47], v150, s[38:39] offset:3072
	s_waitcnt vmcnt(0)
; DI void row1_phase(const Params& P, int combine_l, int norm_l, int r_begin) {
;     ...
;       const float* xm = r < TC ? P.xcbuf + (size_t)r * D : P.out + (size_t)(r - TC) * D;
;       const half_t* y0 = P.yA + (size_t)(2 * r) * D; const half_t* y1 = y0 + D;
; #pragma unroll
;       for (int i = 0; i < 4; i++) { int c = i * 256 + lane * 4; xv[i] = *(const float4*)(xm + c); ya[i] = *(const h4*)(y0 + c); yb[i] = *(const h4*)(y1 + c); }
;     }
;   };
;   auto process = [&](int r, float4 (&xv)[4], h4 (&ya)[4], h4 (&yb)[4]) {
;     const int n = row_mod(r);
;     if (combine_l >= 0) {
;       float* xm = r < TC ? P.xcbuf + (size_t)r * D : P.out + (size_t)(r - TC) * D;
;       const float* g2 = P.mod + (size_t)(combine_l * 9 + n) * 6144 + 5 * 1024;
; #pragma unroll
;       for (int i = 0; i < 4; i++) {
;         int c = i * 256 + lane * 4;
;         float4 g = *(const float4*)(g2 + c); float4 t = xv[i];
;         t.x += g.x * ((float)ya[i][0] + (float)yb[i][0]); t.y += g.y * ((float)ya[i][1] + (float)yb[i][1]);
;         t.z += g.z * ((float)ya[i][2] + (float)yb[i][2]); t.w += g.w * ((float)ya[i][3] + (float)yb[i][3]);
;         *(float4*)(xm + c) = t; xv[i] = t;
;       }
.Lr1c_nr3:
	s_waitcnt vmcnt(40)
	v_accvgpr_read_b32 v54, a64
	v_accvgpr_read_b32 v55, a65
	v_accvgpr_read_b32 v56, a66
	v_accvgpr_read_b32 v57, a67
	v_accvgpr_read_b32 v58, a68
	v_accvgpr_read_b32 v59, a69
	v_accvgpr_read_b32 v60, a70
	v_accvgpr_read_b32 v61, a71
	v_accvgpr_read_b32 v62, a72
	v_accvgpr_read_b32 v63, a73
	v_accvgpr_read_b32 v64, a74
	v_accvgpr_read_b32 v65, a75
	v_accvgpr_read_b32 v66, a76
	v_accvgpr_read_b32 v67, a77
	v_accvgpr_read_b32 v68, a78
	v_accvgpr_read_b32 v69, a79
	v_accvgpr_read_b32 v70, a80
	v_accvgpr_read_b32 v71, a81
	v_accvgpr_read_b32 v72, a82
	v_accvgpr_read_b32 v73, a83
	v_accvgpr_read_b32 v74, a84
	v_accvgpr_read_b32 v75, a85
	v_accvgpr_read_b32 v76, a86
	v_accvgpr_read_b32 v77, a87
	v_accvgpr_read_b32 v78, a88
	v_accvgpr_read_b32 v79, a89
	v_accvgpr_read_b32 v80, a90
	v_accvgpr_read_b32 v81, a91
	v_accvgpr_read_b32 v82, a92
	v_accvgpr_read_b32 v83, a93
	v_accvgpr_read_b32 v84, a94
	v_accvgpr_read_b32 v85, a95
	s_lshl_b32 s10, s5, 12
	s_cmp_lt_u32 s5, 0x800
	s_cselect_b64 s[34:35], s[48:49], s[50:51]
	s_add_u32 s34, s34, s10
	s_addc_u32 s35, s35, 0
	s_cmp_lt_u32 s7, 0x800
	s_cselect_b64 s[60:61], s[48:49], s[50:51]
	s_lshl_b32 s10, s7, 12
	s_add_u32 s60, s60, s10
	s_addc_u32 s61, s61, 0
	global_load_dwordx4 a[64:67], v150, s[60:61] offset:0 nt
	global_load_dwordx4 a[68:71], v150, s[60:61] offset:1024 nt
	global_load_dwordx4 a[72:75], v150, s[60:61] offset:2048 nt
	global_load_dwordx4 a[76:79], v150, s[60:61] offset:3072 nt
	s_add_u32 s62, s52, s10
	s_addc_u32 s63, s53, 0
	global_load_dwordx2 a[80:81], v151, s[62:63] offset:0 nt
	global_load_dwordx2 a[82:83], v151, s[62:63] offset:512 nt
	global_load_dwordx2 a[84:85], v151, s[62:63] offset:1024 nt
	global_load_dwordx2 a[86:87], v151, s[62:63] offset:1536 nt
	global_load_dwordx2 a[88:89], v151, s[62:63] offset:2048 nt
	global_load_dwordx2 a[90:91], v151, s[62:63] offset:2560 nt
	global_load_dwordx2 a[92:93], v151, s[62:63] offset:3072 nt
	global_load_dwordx2 a[94:95], v151, s[62:63] offset:3584 nt
	s_add_u32 s7, s7, 1
	v_cvt_f32_f16_e32 v154, v70
	v_cvt_f32_f16_e32 v155, v78
	v_add_f32_e32 v154, v154, v155
	v_fmac_f32_e32 v54, v32, v154
	v_cvt_f32_f16_sdwa v156, v70 dst_sel:DWORD dst_unused:UNUSED_PAD src0_sel:WORD_1
	v_cvt_f32_f16_sdwa v157, v78 dst_sel:DWORD dst_unused:UNUSED_PAD src0_sel:WORD_1
	v_add_f32_e32 v156, v156, v157
	v_fmac_f32_e32 v55, v33, v156
	v_cvt_f32_f16_e32 v154, v71
	v_cvt_f32_f16_e32 v155, v79
	v_add_f32_e32 v154, v154, v155
	v_fmac_f32_e32 v56, v34, v154
	v_cvt_f32_f16_sdwa v156, v71 dst_sel:DWORD dst_unused:UNUSED_PAD src0_sel:WORD_1
	v_cvt_f32_f16_sdwa v157, v79 dst_sel:DWORD dst_unused:UNUSED_PAD src0_sel:WORD_1
	v_add_f32_e32 v156, v156, v157
	v_fmac_f32_e32 v57, v35, v156
	v_cvt_f32_f16_e32 v154, v72
	v_cvt_f32_f16_e32 v155, v80
	v_add_f32_e32 v154, v154, v155
	v_fmac_f32_e32 v58, v36, v154
	v_cvt_f32_f16_sdwa v156, v72 dst_sel:DWORD dst_unused:UNUSED_PAD src0_sel:WORD_1
	v_cvt_f32_f16_sdwa v157, v80 dst_sel:DWORD dst_unused:UNUSED_PAD src0_sel:WORD_1
	v_add_f32_e32 v156, v156, v157
	v_fmac_f32_e32 v59, v37, v156
	v_cvt_f32_f16_e32 v154, v73
	v_cvt_f32_f16_e32 v155, v81
	v_add_f32_e32 v154, v154, v155
	v_fmac_f32_e32 v60, v38, v154
	v_cvt_f32_f16_sdwa v156, v73 dst_sel:DWORD dst_unused:UNUSED_PAD src0_sel:WORD_1
	v_cvt_f32_f16_sdwa v157, v81 dst_sel:DWORD dst_unused:UNUSED_PAD src0_sel:WORD_1
	v_add_f32_e32 v156, v156, v157
	v_fmac_f32_e32 v61, v39, v156
	v_cvt_f32_f16_e32 v154, v74
	v_cvt_f32_f16_e32 v155, v82
	v_add_f32_e32 v154, v154, v155
	v_fmac_f32_e32 v62, v40, v154
	v_cvt_f32_f16_sdwa v156, v74 dst_sel:DWORD dst_unused:UNUSED_PAD src0_sel:WORD_1
	v_cvt_f32_f16_sdwa v157, v82 dst_sel:DWORD dst_unused:UNUSED_PAD src0_sel:WORD_1
	v_add_f32_e32 v156, v156, v157
	v_fmac_f32_e32 v63, v41, v156
	v_cvt_f32_f16_e32 v154, v75
	v_cvt_f32_f16_e32 v155, v83
	v_add_f32_e32 v154, v154, v155
	v_fmac_f32_e32 v64, v42, v154
	v_cvt_f32_f16_sdwa v156, v75 dst_sel:DWORD dst_unused:UNUSED_PAD src0_sel:WORD_1
	v_cvt_f32_f16_sdwa v157, v83 dst_sel:DWORD dst_unused:UNUSED_PAD src0_sel:WORD_1
	v_add_f32_e32 v156, v156, v157
	v_fmac_f32_e32 v65, v43, v156
	v_cvt_f32_f16_e32 v154, v76
	v_cvt_f32_f16_e32 v155, v84
	v_add_f32_e32 v154, v154, v155
	v_fmac_f32_e32 v66, v44, v154
	v_cvt_f32_f16_sdwa v156, v76 dst_sel:DWORD dst_unused:UNUSED_PAD src0_sel:WORD_1
	v_cvt_f32_f16_sdwa v157, v84 dst_sel:DWORD dst_unused:UNUSED_PAD src0_sel:WORD_1
	v_add_f32_e32 v156, v156, v157
	v_fmac_f32_e32 v67, v45, v156
	v_cvt_f32_f16_e32 v154, v77
	v_cvt_f32_f16_e32 v155, v85
	v_add_f32_e32 v154, v154, v155
	v_fmac_f32_e32 v68, v46, v154
	v_cvt_f32_f16_sdwa v156, v77 dst_sel:DWORD dst_unused:UNUSED_PAD src0_sel:WORD_1
	v_cvt_f32_f16_sdwa v157, v85 dst_sel:DWORD dst_unused:UNUSED_PAD src0_sel:WORD_1
	v_add_f32_e32 v156, v156, v157
	v_fmac_f32_e32 v69, v47, v156
	global_store_dwordx4 v150, v[54:57], s[34:35] offset:0
	global_store_dwordx4 v150, v[58:61], s[34:35] offset:1024
	global_store_dwordx4 v150, v[62:65], s[34:35] offset:2048
	global_store_dwordx4 v150, v[66:69], s[34:35] offset:3072
	s_add_u32 s5, s5, 1
	s_sub_u32 s9, s5, 0x800
	s_lshr_b32 s9, s9, 13
	s_cmp_eq_u32 s9, s8
	s_cbranch_scc1 .Lr1c_nr4
	s_mov_b32 s8, s9
	s_waitcnt vmcnt(0)
	s_add_u32 s10, s9, 9
	s_mul_i32 s10, s10, 0x6000
	s_add_u32 s10, s10, 0x5000
	s_add_u32 s38, s56, s10
	s_addc_u32 s39, s57, 0
	global_load_dwordx4 v[32:35], v150, s[38:39] offset:0
	global_load_dwordx4 v[36:39], v150, s[38:39] offset:1024
	global_load_dwordx4 v[40:43], v150, s[38:39] offset:2048
	global_load_dwordx4 v[44:47], v150, s[38:39] offset:3072
	s_waitcnt vmcnt(0)
; DI void row1_phase(const Params& P, int combine_l, int norm_l, int r_begin) {
;     ...
;       const float* xm = r < TC ? P.xcbuf + (size_t)r * D : P.out + (size_t)(r - TC) * D;
;       const half_t* y0 = P.yA + (size_t)(2 * r) * D; const half_t* y1 = y0 + D;
; #pragma unroll
;       for (int i = 0; i < 4; i++) { int c = i * 256 + lane * 4; xv[i] = *(const float4*)(xm + c); ya[i] = *(const h4*)(y0 + c); yb[i] = *(const h4*)(y1 + c); }
;     }
;   };
;   auto process = [&](int r, float4 (&xv)[4], h4 (&ya)[4], h4 (&yb)[4]) {
;     const int n = row_mod(r);
;     if (combine_l >= 0) {
;       float* xm = r < TC ? P.xcbuf + (size_t)r * D : P.out + (size_t)(r - TC) * D;
;       const float* g2 = P.mod + (size_t)(combine_l * 9 + n) * 6144 + 5 * 1024;
; #pragma unroll
;       for (int i = 0; i < 4; i++) {
;         int c = i * 256 + lane * 4;
;         float4 g = *(const float4*)(g2 + c); float4 t = xv[i];
;         t.x += g.x * ((float)ya[i][0] + (float)yb[i][0]); t.y += g.y * ((float)ya[i][1] + (float)yb[i][1]);
;         t.z += g.z * ((float)ya[i][2] + (float)yb[i][2]); t.w += g.w * ((float)ya[i][3] + (float)yb[i][3]);
;         *(float4*)(xm + c) = t; xv[i] = t;
;       }
;     ...
;   for (int r = r_lo; r < r_hi; r += 4) {
;     float4 x0[4], x1[4], x2[4], x3[4]; h4 a0[4], b0[4], a1[4], b1[4], a2[4], b2[4], a3[4], b3[4];
;     const int r1 = r + 1, r2 = r + 2, r3 = r + 3;
;     load_row(r, x0, a0, b0);
;     if (r1 < r_hi) load_row(r1, x1, a1, b1);
;     if (r2 < r_hi) load_row(r2, x2, a2, b2);
;     if (r3 < r_hi) load_row(r3, x3, a3, b3);
;     process(r, x0, a0, b0);
;     if (r1 < r_hi) process(r1, x1, a1, b1);
;     if (r2 < r_hi) process(r2, x2, a2, b2);
;     if (r3 < r_hi) process(r3, x3, a3, b3);
;   }
.Lr1c_nr4:
	s_waitcnt vmcnt(40)
	v_accvgpr_read_b32 v54, a96
	v_accvgpr_read_b32 v55, a97
	v_accvgpr_read_b32 v56, a98
	v_accvgpr_read_b32 v57, a99
	v_accvgpr_read_b32 v58, a100
	v_accvgpr_read_b32 v59, a101
	v_accvgpr_read_b32 v60, a102
	v_accvgpr_read_b32 v61, a103
	v_accvgpr_read_b32 v62, a104
	v_accvgpr_read_b32 v63, a105
	v_accvgpr_read_b32 v64, a106
	v_accvgpr_read_b32 v65, a107
	v_accvgpr_read_b32 v66, a108
	v_accvgpr_read_b32 v67, a109
	v_accvgpr_read_b32 v68, a110
	v_accvgpr_read_b32 v69, a111
	v_accvgpr_read_b32 v70, a112
	v_accvgpr_read_b32 v71, a113
	v_accvgpr_read_b32 v72, a114
	v_accvgpr_read_b32 v73, a115
	v_accvgpr_read_b32 v74, a116
	v_accvgpr_read_b32 v75, a117
	v_accvgpr_read_b32 v76, a118
	v_accvgpr_read_b32 v77, a119
	v_accvgpr_read_b32 v78, a120
	v_accvgpr_read_b32 v79, a121
	v_accvgpr_read_b32 v80, a122
	v_accvgpr_read_b32 v81, a123
	v_accvgpr_read_b32 v82, a124
	v_accvgpr_read_b32 v83, a125
	v_accvgpr_read_b32 v84, a126
	v_accvgpr_read_b32 v85, a127
	s_lshl_b32 s10, s5, 12
	s_cmp_lt_u32 s5, 0x800
	s_cselect_b64 s[34:35], s[48:49], s[50:51]
	s_add_u32 s34, s34, s10
	s_addc_u32 s35, s35, 0
	s_cmp_lt_u32 s7, 0x800
	s_cselect_b64 s[60:61], s[48:49], s[50:51]
	s_lshl_b32 s10, s7, 12
	s_add_u32 s60, s60, s10
	s_addc_u32 s61, s61, 0
	global_load_dwordx4 a[96:99], v150, s[60:61] offset:0 nt
	global_load_dwordx4 a[100:103], v150, s[60:61] offset:1024 nt
	global_load_dwordx4 a[104:107], v150, s[60:61] offset:2048 nt
	global_load_dwordx4 a[108:111], v150, s[60:61] offset:3072 nt
	s_add_u32 s62, s52, s10
	s_addc_u32 s63, s53, 0
	global_load_dwordx2 a[112:113], v151, s[62:63] offset:0 nt
	global_load_dwordx2 a[114:115], v151, s[62:63] offset:512 nt
	global_load_dwordx2 a[116:117], v151, s[62:63] offset:1024 nt
	global_load_dwordx2 a[118:119], v151, s[62:63] offset:1536 nt
	global_load_dwordx2 a[120:121], v151, s[62:63] offset:2048 nt
	global_load_dwordx2 a[122:123], v151, s[62:63] offset:2560 nt
	global_load_dwordx2 a[124:125], v151, s[62:63] offset:3072 nt
	global_load_dwordx2 a[126:127], v151, s[62:63] offset:3584 nt
	s_add_u32 s7, s7, 1
	v_cvt_f32_f16_e32 v154, v70
	v_cvt_f32_f16_e32 v155, v78
	v_add_f32_e32 v154, v154, v155
	v_fmac_f32_e32 v54, v32, v154
	v_cvt_f32_f16_sdwa v156, v70 dst_sel:DWORD dst_unused:UNUSED_PAD src0_sel:WORD_1
	v_cvt_f32_f16_sdwa v157, v78 dst_sel:DWORD dst_unused:UNUSED_PAD src0_sel:WORD_1
	v_add_f32_e32 v156, v156, v157
	v_fmac_f32_e32 v55, v33, v156
	v_cvt_f32_f16_e32 v154, v71
	v_cvt_f32_f16_e32 v155, v79
	v_add_f32_e32 v154, v154, v155
	v_fmac_f32_e32 v56, v34, v154
	v_cvt_f32_f16_sdwa v156, v71 dst_sel:DWORD dst_unused:UNUSED_PAD src0_sel:WORD_1
	v_cvt_f32_f16_sdwa v157, v79 dst_sel:DWORD dst_unused:UNUSED_PAD src0_sel:WORD_1
	v_add_f32_e32 v156, v156, v157
	v_fmac_f32_e32 v57, v35, v156
	v_cvt_f32_f16_e32 v154, v72
	v_cvt_f32_f16_e32 v155, v80
	v_add_f32_e32 v154, v154, v155
	v_fmac_f32_e32 v58, v36, v154
	v_cvt_f32_f16_sdwa v156, v72 dst_sel:DWORD dst_unused:UNUSED_PAD src0_sel:WORD_1
	v_cvt_f32_f16_sdwa v157, v80 dst_sel:DWORD dst_unused:UNUSED_PAD src0_sel:WORD_1
	v_add_f32_e32 v156, v156, v157
	v_fmac_f32_e32 v59, v37, v156
	v_cvt_f32_f16_e32 v154, v73
	v_cvt_f32_f16_e32 v155, v81
	v_add_f32_e32 v154, v154, v155
	v_fmac_f32_e32 v60, v38, v154
	v_cvt_f32_f16_sdwa v156, v73 dst_sel:DWORD dst_unused:UNUSED_PAD src0_sel:WORD_1
	v_cvt_f32_f16_sdwa v157, v81 dst_sel:DWORD dst_unused:UNUSED_PAD src0_sel:WORD_1
	v_add_f32_e32 v156, v156, v157
	v_fmac_f32_e32 v61, v39, v156
	v_cvt_f32_f16_e32 v154, v74
	v_cvt_f32_f16_e32 v155, v82
	v_add_f32_e32 v154, v154, v155
	v_fmac_f32_e32 v62, v40, v154
	v_cvt_f32_f16_sdwa v156, v74 dst_sel:DWORD dst_unused:UNUSED_PAD src0_sel:WORD_1
	v_cvt_f32_f16_sdwa v157, v82 dst_sel:DWORD dst_unused:UNUSED_PAD src0_sel:WORD_1
	v_add_f32_e32 v156, v156, v157
	v_fmac_f32_e32 v63, v41, v156
	v_cvt_f32_f16_e32 v154, v75
	v_cvt_f32_f16_e32 v155, v83
	v_add_f32_e32 v154, v154, v155
	v_fmac_f32_e32 v64, v42, v154
	v_cvt_f32_f16_sdwa v156, v75 dst_sel:DWORD dst_unused:UNUSED_PAD src0_sel:WORD_1
	v_cvt_f32_f16_sdwa v157, v83 dst_sel:DWORD dst_unused:UNUSED_PAD src0_sel:WORD_1
	v_add_f32_e32 v156, v156, v157
	v_fmac_f32_e32 v65, v43, v156
	v_cvt_f32_f16_e32 v154, v76
	v_cvt_f32_f16_e32 v155, v84
	v_add_f32_e32 v154, v154, v155
	v_fmac_f32_e32 v66, v44, v154
	v_cvt_f32_f16_sdwa v156, v76 dst_sel:DWORD dst_unused:UNUSED_PAD src0_sel:WORD_1
	v_cvt_f32_f16_sdwa v157, v84 dst_sel:DWORD dst_unused:UNUSED_PAD src0_sel:WORD_1
	v_add_f32_e32 v156, v156, v157
	v_fmac_f32_e32 v67, v45, v156
	v_cvt_f32_f16_e32 v154, v77
	v_cvt_f32_f16_e32 v155, v85
	v_add_f32_e32 v154, v154, v155
	v_fmac_f32_e32 v68, v46, v154
	v_cvt_f32_f16_sdwa v156, v77 dst_sel:DWORD dst_unused:UNUSED_PAD src0_sel:WORD_1
	v_cvt_f32_f16_sdwa v157, v85 dst_sel:DWORD dst_unused:UNUSED_PAD src0_sel:WORD_1
	v_add_f32_e32 v156, v156, v157
	v_fmac_f32_e32 v69, v47, v156
	global_store_dwordx4 v150, v[54:57], s[34:35] offset:0
	global_store_dwordx4 v150, v[58:61], s[34:35] offset:1024
	global_store_dwordx4 v150, v[62:65], s[34:35] offset:2048
	global_store_dwordx4 v150, v[66:69], s[34:35] offset:3072
	s_add_u32 s5, s5, 1
	s_sub_u32 s98, s98, 1
	s_cmp_lg_u32 s98, 0
	s_cbranch_scc1 .Lr1c_loop
	s_sub_u32 s9, s5, 0x800
	s_lshr_b32 s9, s9, 13
	s_cmp_eq_u32 s9, s8
	s_cbranch_scc1 .Lr1c_nr5
	s_mov_b32 s8, s9
	s_waitcnt vmcnt(0)
	s_add_u32 s10, s9, 9
	s_mul_i32 s10, s10, 0x6000
	s_add_u32 s10, s10, 0x5000
	s_add_u32 s38, s56, s10
	s_addc_u32 s39, s57, 0
	global_load_dwordx4 v[32:35], v150, s[38:39] offset:0
	global_load_dwordx4 v[36:39], v150, s[38:39] offset:1024
	global_load_dwordx4 v[40:43], v150, s[38:39] offset:2048
	global_load_dwordx4 v[44:47], v150, s[38:39] offset:3072
	s_waitcnt vmcnt(0)
